# U pass as two 4-token sweeps with four row buffers (three row groups in flight); second half's x rows fetched between the sweeps
# speedup vs baseline: 1.0358x; 1.0082x over previous
; DI float bflo(unsigned u) { return __uint_as_float(u << 16); }
; DI float bfhi(unsigned u) { return __uint_as_float(u & 0xffff0000u); }
; template <bool STORE>
; DI void peer_item(const Params& p, int item, char* smem) {
;     ...
;   const unsigned char* U8 = (const unsigned char*)(ws + WS_UBF);
;   const float* SU = (const float*)(ws + WS_SU);
;   const float* SV = (const float*)(ws + WS_SV);
;   int* EG = (int*)(ws + WS_XN);
;   float* AG = (float*)(ws + WS_XN + (size_t)T_TOK * 128 * 4);
;   const bool b5 = (lane & 32) != 0, b4 = (lane & 16) != 0, b3 = (lane & 8) != 0;
; #pragma unroll 1
;   for (int ti = 0; ti < 8; ++ti) {
;     const int tl = wave * 8 + ti;
;     const size_t tok = (size_t)tok0 + tl;
;     float xf[16];
;     {
; #pragma unroll
;       for (int i = 0; i < 4; ++i) {
;         const uint2 xv = *(const uint2*)(XN2 + tok * 1024 + 256 * i + lane * 4);
;         xf[4 * i] = bflo(xv.x); xf[4 * i + 1] = bfhi(xv.x); xf[4 * i + 2] = bflo(xv.y); xf[4 * i + 3] = bfhi(xv.y);
;       }
;     }
.LBB0_1058:
	s_or_b64 exec, exec, s[0:1]
	s_waitcnt vmcnt(0) lgkmcnt(0)
	v_writelane_b32 v254, s6, 0
	v_writelane_b32 v254, s7, 1
	v_writelane_b32 v254, s12, 2
	v_writelane_b32 v254, s13, 3
	v_writelane_b32 v254, s14, 4
	v_writelane_b32 v254, s15, 5
	v_writelane_b32 v254, s16, 6
	v_writelane_b32 v254, s17, 7
	v_writelane_b32 v254, s18, 8
	v_writelane_b32 v254, s19, 9
	v_writelane_b32 v254, s20, 10
	v_writelane_b32 v254, s21, 11
	v_writelane_b32 v254, s22, 12
	v_writelane_b32 v254, s23, 13
	v_writelane_b32 v254, s24, 14
	v_writelane_b32 v254, s25, 15
	v_writelane_b32 v254, s26, 16
	v_writelane_b32 v254, s27, 17
	v_writelane_b32 v254, s28, 18
	v_writelane_b32 v254, s29, 19
	v_writelane_b32 v254, s30, 20
	v_writelane_b32 v254, s31, 21
	v_writelane_b32 v254, s33, 22
	v_writelane_b32 v254, s34, 23
	v_writelane_b32 v254, s35, 24
	v_writelane_b32 v254, s36, 25
	v_writelane_b32 v254, s37, 26
	v_writelane_b32 v254, s38, 27
	v_writelane_b32 v254, s39, 28
	v_writelane_b32 v254, s40, 29
	v_writelane_b32 v254, s41, 30
	v_writelane_b32 v254, s42, 31
	v_writelane_b32 v254, s44, 32
	v_writelane_b32 v254, s45, 33
	v_writelane_b32 v254, s48, 34
	v_writelane_b32 v254, s49, 35
	v_writelane_b32 v254, s50, 36
	v_writelane_b32 v254, s51, 37
	v_writelane_b32 v254, s52, 38
	v_writelane_b32 v254, s53, 39
	v_writelane_b32 v254, s55, 40
	v_writelane_b32 v254, s60, 41
	v_writelane_b32 v254, s61, 42
	v_writelane_b32 v254, s62, 43
	v_writelane_b32 v254, s63, 44
	v_writelane_b32 v254, s66, 45
	v_writelane_b32 v254, s67, 46
	v_writelane_b32 v254, s68, 47
	v_writelane_b32 v254, s69, 48
	v_writelane_b32 v254, s74, 49
	v_writelane_b32 v254, s75, 50
	v_writelane_b32 v254, s76, 51
	v_writelane_b32 v254, s77, 52
	v_writelane_b32 v254, s78, 53
	v_writelane_b32 v254, s79, 54
	v_writelane_b32 v254, s88, 55
	s_mov_b32 s16, s33
	s_mov_b32 s14, s42
	v_readlane_b32 s56, v253, 48
	v_readlane_b32 s57, v253, 49
	v_readfirstlane_b32 s13, v211
	v_mbcnt_lo_u32_b32 v213, -1, 0
	v_mbcnt_hi_u32_b32 v213, -1, v213
	s_nop 3
	s_bfe_u32 s17, s13, 0x20006
	s_add_u32 s0, s56, 0x1200200
	s_addc_u32 s1, s57, 0
	s_add_u32 s2, s56, 0x7200200
	s_addc_u32 s3, s57, 0
	s_add_u32 s4, s56, 0x5200200
	s_addc_u32 s5, s57, 0
	s_add_u32 s6, s56, 0x5a00200
	s_addc_u32 s7, s57, 0
	s_add_u32 s8, s56, 0x2200200
	s_addc_u32 s9, s57, 0
	s_add_u32 s10, s56, 0x4200200
	s_addc_u32 s11, s57, 0
	s_lshl_b32 s13, s17, 3
	s_add_u32 s14, s14, s13
	s_mul_i32 s18, s17, 7680
	s_add_u32 s18, s18, s16
	s_add_u32 s18, s18, 49152
	s_lshl_b32 s19, s17, 12
	s_add_u32 s19, s19, s16
	v_lshlrev_b32_e32 v238, 2, v213
	v_lshlrev_b32_e32 v234, 4, v213
	v_add_u32_e32 v236, s18, v238
	v_add_u32_e32 v237, s19, v238
	ds_write_b32 v236, v3 offset:512
	ds_write_b32 v236, v53 offset:768
	ds_write_b32 v236, v64 offset:1024
	ds_write_b32 v236, v65 offset:1280
	ds_write_b32 v236, v66 offset:1536
	ds_write_b32 v236, v67 offset:1792
	ds_write_b32 v236, v68 offset:2048
	ds_write_b32 v236, v69 offset:2304
	ds_write_b32 v236, v70 offset:2560
	ds_write_b32 v236, v71 offset:2816
	ds_write_b32 v236, v72 offset:3072
	ds_write_b32 v236, v73 offset:3328
	ds_write_b32 v236, v74 offset:3584
	ds_write_b32 v236, v75 offset:3840
	ds_write_b32 v236, v76 offset:4096
	ds_write_b32 v236, v77 offset:4352
	ds_write_b32 v236, v78 offset:4608
	ds_write_b32 v236, v79 offset:4864
	ds_write_b32 v236, v80 offset:5120
	ds_write_b32 v236, v81 offset:5376
	ds_write_b32 v236, v82 offset:5632
	ds_write_b32 v236, v83 offset:5888
	ds_write_b32 v236, v96 offset:6144
	ds_write_b32 v236, v210 offset:6400
	ds_write_b32 v236, v211 offset:6656
	ds_write_b32 v236, v212 offset:6912
	s_mov_b32 s24, 0xff00ff00
	s_mov_b32 s25, 0xff00ff00
	s_mov_b32 s80, 0x378e98ab
	s_mov_b32 s81, 0x3b7cd369
	s_mov_b32 s82, 0xbcc618b2
	s_mov_b32 s83, 0x3dda74e4
	s_mov_b32 s84, 0x3f228afd
	s_mov_b32 s85, 0x3e03c728
	s_mov_b32 s86, 0xbfb8aa3b
	s_mov_b32 s87, 0x42ce8ed0
	s_mov_b32 s88, 0xc2b17218
	s_mov_b32 s89, 0x7fffffff
	s_waitcnt lgkmcnt(0)
	s_lshl_b32 s13, s14, 11
	s_add_u32 s32, s2, s13
	s_addc_u32 s33, s3, 0
	v_lshlrev_b32_e32 v239, 3, v213
	s_add_u32 s34, s32, 0
	s_addc_u32 s35, s33, 0
	global_load_dwordx2 v[2:3], v239, s[34:35] offset:0
	global_load_dwordx2 v[6:7], v239, s[34:35] offset:512
	global_load_dwordx2 v[10:11], v239, s[34:35] offset:1024
	global_load_dwordx2 v[14:15], v239, s[34:35] offset:1536
	s_add_u32 s34, s32, 2048
	s_addc_u32 s35, s33, 0
	global_load_dwordx2 v[18:19], v239, s[34:35] offset:0
	global_load_dwordx2 v[22:23], v239, s[34:35] offset:512
	global_load_dwordx2 v[26:27], v239, s[34:35] offset:1024
	global_load_dwordx2 v[30:31], v239, s[34:35] offset:1536
	s_add_u32 s34, s32, 4096
	s_addc_u32 s35, s33, 0
	global_load_dwordx2 v[34:35], v239, s[34:35] offset:0
	global_load_dwordx2 v[38:39], v239, s[34:35] offset:512
	global_load_dwordx2 v[42:43], v239, s[34:35] offset:1024
	global_load_dwordx2 v[46:47], v239, s[34:35] offset:1536
	s_add_u32 s34, s32, 6144
	s_addc_u32 s35, s33, 0
	global_load_dwordx2 v[50:51], v239, s[34:35] offset:0
	global_load_dwordx2 v[54:55], v239, s[34:35] offset:512
	global_load_dwordx2 v[58:59], v239, s[34:35] offset:1024
	global_load_dwordx2 v[62:63], v239, s[34:35] offset:1536
	v_mov_b32_e32 v144, v236
	v_mov_b32_e32 v145, 0
	v_mov_b32_e32 v146, 1
	v_lshrrev_b32_e32 v147, 3, v213
	v_and_b32_e32 v148, 7, v213
	v_lshlrev_b32_e32 v147, 6, v147
	v_lshl_add_u32 v147, v148, 2, v147
	v_add_u32_e32 v147, s19, v147
	v_subrev_u32_e32 v149, 1, v213
	v_subrev_u32_e32 v150, 2, v213
	v_subrev_u32_e32 v151, 4, v213
	v_subrev_u32_e32 v152, 8, v213
	v_subrev_u32_e32 v153, 16, v213
	v_subrev_u32_e32 v154, 32, v213
	v_lshlrev_b32_e32 v149, 2, v149
	v_lshlrev_b32_e32 v150, 2, v150
	v_lshlrev_b32_e32 v151, 2, v151
	v_lshlrev_b32_e32 v152, 2, v152
	v_lshlrev_b32_e32 v153, 2, v153
	v_lshlrev_b32_e32 v154, 2, v154
	ds_read_b32 v166, v237 offset:0
	ds_read_b32 v167, v237 offset:256
	ds_read_b32 v168, v237 offset:16384
	ds_read_b32 v169, v237 offset:16640
	ds_write_b32 v144, v145 offset:0
	ds_write_b32 v144, v145 offset:256
	ds_read_b32 v180, v237 offset:512
	ds_read_b32 v181, v237 offset:768
	ds_read_b32 v182, v237 offset:16896
	ds_read_b32 v183, v237 offset:17152
	ds_write_b32 v144, v145 offset:7168
	ds_write_b32 v144, v145 offset:7424
	s_waitcnt lgkmcnt(0)
; template <bool STORE>
; DI void peer_item(const Params& p, int item, char* smem) {
;     ...
; #pragma unroll 2
;     for (int k = 0; k < 128; k += 8) {
;       u32x4 uq[8];
;       const int emine = e_s[tl * 128 + k + (lane >> 3)];
;       const float gmine = g_s[tl * 128 + k + (lane >> 3)];
;       const float su = SU[emine], sv = SV[emine];
; #pragma unroll
;       for (int u = 0; u < 8; ++u) {
;         int e = e_s[tl * 128 + k + u];
;         uq[u] = *(const u32x4*)(U8 + (size_t)e * 1024 + lane * 16);
	v_lshrrev_b32_e32 v156, 5, v166
	v_and_b32_e32 v156, 0x1fc, v156
	v_add_u32_e32 v156, s18, v156
	v_lshrrev_b32_e32 v157, 5, v167
	v_and_b32_e32 v157, 0x1fc, v157
	v_add_u32_e32 v157, s18, v157
	v_lshrrev_b32_e32 v170, 5, v180
	v_and_b32_e32 v170, 0x1fc, v170
	v_add_u32_e32 v170, s18, v170
	v_add_u32_e32 v170, 7168, v170
	v_lshrrev_b32_e32 v171, 5, v181
	v_and_b32_e32 v171, 0x1fc, v171
	v_add_u32_e32 v171, s18, v171
	v_add_u32_e32 v171, 7168, v171
	ds_add_rtn_u32 v158, v156, v146
	ds_add_rtn_u32 v159, v157, v146
	ds_add_rtn_u32 v172, v170, v146
	ds_add_rtn_u32 v173, v171, v146
	ds_read_b32 v160, v144 offset:0
	ds_read_b32 v161, v144 offset:256
	ds_read_b32 v174, v144 offset:7168
	ds_read_b32 v175, v144 offset:7424
	s_waitcnt lgkmcnt(0)
	v_mov_b32_e32 v164, v160
	v_mov_b32_e32 v165, v161
	v_mov_b32_e32 v178, v174
	v_mov_b32_e32 v179, v175
	v_cmp_le_u32_e32 vcc, 1, v213
	ds_bpermute_b32 v162, v149, v164
	ds_bpermute_b32 v163, v149, v165
	ds_bpermute_b32 v176, v149, v178
	ds_bpermute_b32 v177, v149, v179
	s_waitcnt lgkmcnt(0)
	v_cndmask_b32_e32 v162, 0, v162, vcc
	v_cndmask_b32_e32 v163, 0, v163, vcc
	v_add_u32_e32 v164, v164, v162
	v_add_u32_e32 v165, v165, v163
	v_cndmask_b32_e32 v176, 0, v176, vcc
	v_cndmask_b32_e32 v177, 0, v177, vcc
	v_add_u32_e32 v178, v178, v176
	v_add_u32_e32 v179, v179, v177
	v_cmp_le_u32_e32 vcc, 2, v213
	ds_bpermute_b32 v162, v150, v164
	ds_bpermute_b32 v163, v150, v165
	ds_bpermute_b32 v176, v150, v178
	ds_bpermute_b32 v177, v150, v179
	s_waitcnt lgkmcnt(0)
	v_cndmask_b32_e32 v162, 0, v162, vcc
	v_cndmask_b32_e32 v163, 0, v163, vcc
	v_add_u32_e32 v164, v164, v162
	v_add_u32_e32 v165, v165, v163
	v_cndmask_b32_e32 v176, 0, v176, vcc
	v_cndmask_b32_e32 v177, 0, v177, vcc
	v_add_u32_e32 v178, v178, v176
	v_add_u32_e32 v179, v179, v177
	v_cmp_le_u32_e32 vcc, 4, v213
	ds_bpermute_b32 v162, v151, v164
	ds_bpermute_b32 v163, v151, v165
	ds_bpermute_b32 v176, v151, v178
	ds_bpermute_b32 v177, v151, v179
	s_waitcnt lgkmcnt(0)
	v_cndmask_b32_e32 v162, 0, v162, vcc
	v_cndmask_b32_e32 v163, 0, v163, vcc
	v_add_u32_e32 v164, v164, v162
	v_add_u32_e32 v165, v165, v163
	v_cndmask_b32_e32 v176, 0, v176, vcc
	v_cndmask_b32_e32 v177, 0, v177, vcc
	v_add_u32_e32 v178, v178, v176
	v_add_u32_e32 v179, v179, v177
	v_cmp_le_u32_e32 vcc, 8, v213
	ds_bpermute_b32 v162, v152, v164
	ds_bpermute_b32 v163, v152, v165
	ds_bpermute_b32 v176, v152, v178
	ds_bpermute_b32 v177, v152, v179
	s_waitcnt lgkmcnt(0)
	v_cndmask_b32_e32 v162, 0, v162, vcc
	v_cndmask_b32_e32 v163, 0, v163, vcc
	v_add_u32_e32 v164, v164, v162
	v_add_u32_e32 v165, v165, v163
	v_cndmask_b32_e32 v176, 0, v176, vcc
	v_cndmask_b32_e32 v177, 0, v177, vcc
	v_add_u32_e32 v178, v178, v176
	v_add_u32_e32 v179, v179, v177
	v_cmp_le_u32_e32 vcc, 16, v213
	ds_bpermute_b32 v162, v153, v164
	ds_bpermute_b32 v163, v153, v165
	ds_bpermute_b32 v176, v153, v178
	ds_bpermute_b32 v177, v153, v179
	s_waitcnt lgkmcnt(0)
	v_cndmask_b32_e32 v162, 0, v162, vcc
	v_cndmask_b32_e32 v163, 0, v163, vcc
	v_add_u32_e32 v164, v164, v162
	v_add_u32_e32 v165, v165, v163
	v_cndmask_b32_e32 v176, 0, v176, vcc
	v_cndmask_b32_e32 v177, 0, v177, vcc
	v_add_u32_e32 v178, v178, v176
	v_add_u32_e32 v179, v179, v177
	v_cmp_le_u32_e32 vcc, 32, v213
	ds_bpermute_b32 v162, v154, v164
	ds_bpermute_b32 v163, v154, v165
	ds_bpermute_b32 v176, v154, v178
	ds_bpermute_b32 v177, v154, v179
	s_waitcnt lgkmcnt(0)
	v_cndmask_b32_e32 v162, 0, v162, vcc
	v_cndmask_b32_e32 v163, 0, v163, vcc
	v_add_u32_e32 v164, v164, v162
	v_add_u32_e32 v165, v165, v163
	v_cndmask_b32_e32 v176, 0, v176, vcc
	v_cndmask_b32_e32 v177, 0, v177, vcc
	v_add_u32_e32 v178, v178, v176
	v_add_u32_e32 v179, v179, v177
	s_nop 0
	v_readlane_b32 s13, v164, 63
	v_sub_u32_e32 v164, v164, v160
	v_sub_u32_e32 v165, v165, v161
	s_nop 0
	v_add_u32_e32 v165, s13, v165
	s_nop 0
	v_readlane_b32 s13, v178, 63
	v_sub_u32_e32 v178, v178, v174
	v_sub_u32_e32 v179, v179, v175
	s_nop 0
	v_add_u32_e32 v179, s13, v179
	ds_write_b32 v144, v164 offset:0
	ds_write_b32 v144, v165 offset:256
	ds_write_b32 v144, v178 offset:7168
	ds_write_b32 v144, v179 offset:7424
	ds_read_b32 v160, v156
	ds_read_b32 v161, v157
	ds_read_b32 v174, v170
	ds_read_b32 v175, v171
	s_waitcnt lgkmcnt(0)
	v_add_u32_e32 v160, v160, v158
	v_add_u32_e32 v161, v161, v159
	v_lshl_add_u32 v160, v160, 2, s19
	v_lshl_add_u32 v161, v161, 2, s19
	v_add_u32_e32 v174, v174, v172
	v_add_u32_e32 v175, v175, v173
	v_lshl_add_u32 v174, v174, 2, s19
	v_lshl_add_u32 v175, v175, 2, s19
	ds_write_b32 v160, v166 offset:0
	ds_write_b32 v160, v168 offset:16384
	ds_write_b32 v161, v167 offset:0
	ds_write_b32 v161, v169 offset:16384
	ds_write_b32 v174, v180 offset:512
	ds_write_b32 v174, v182 offset:16896
	ds_write_b32 v175, v181 offset:512
	ds_write_b32 v175, v183 offset:16896
	ds_read_b32 v128, v147 offset:0
	ds_read_b32 v129, v147 offset:32
	ds_read_b32 v130, v147 offset:512
	ds_read_b32 v131, v147 offset:544
	s_waitcnt lgkmcnt(0)
	v_lshlrev_b32_e32 v128, 10, v128
	v_lshlrev_b32_e32 v129, 10, v129
	v_lshlrev_b32_e32 v130, 10, v130
	v_lshlrev_b32_e32 v131, 10, v131
	ds_read_b32 v166, v237 offset:1024
	ds_read_b32 v167, v237 offset:1280
	ds_read_b32 v168, v237 offset:17408
	ds_read_b32 v169, v237 offset:17664
	ds_write_b32 v144, v145 offset:0
	ds_write_b32 v144, v145 offset:256
	ds_read_b32 v180, v237 offset:1536
	ds_read_b32 v181, v237 offset:1792
	ds_read_b32 v182, v237 offset:17920
	ds_read_b32 v183, v237 offset:18176
	ds_write_b32 v144, v145 offset:7168
	ds_write_b32 v144, v145 offset:7424
	s_waitcnt lgkmcnt(0)
; template <bool STORE>
; DI void peer_item(const Params& p, int item, char* smem) {
;     ...
; #pragma unroll 2
;     for (int k = 0; k < 128; k += 8) {
;       u32x4 uq[8];
;       const int emine = e_s[tl * 128 + k + (lane >> 3)];
;       const float gmine = g_s[tl * 128 + k + (lane >> 3)];
;       const float su = SU[emine], sv = SV[emine];
; #pragma unroll
;       for (int u = 0; u < 8; ++u) {
;         int e = e_s[tl * 128 + k + u];
;         uq[u] = *(const u32x4*)(U8 + (size_t)e * 1024 + lane * 16);
	v_lshrrev_b32_e32 v156, 5, v166
	v_and_b32_e32 v156, 0x1fc, v156
	v_add_u32_e32 v156, s18, v156
	v_lshrrev_b32_e32 v157, 5, v167
	v_and_b32_e32 v157, 0x1fc, v157
	v_add_u32_e32 v157, s18, v157
	v_lshrrev_b32_e32 v170, 5, v180
	v_and_b32_e32 v170, 0x1fc, v170
	v_add_u32_e32 v170, s18, v170
	v_add_u32_e32 v170, 7168, v170
	v_lshrrev_b32_e32 v171, 5, v181
	v_and_b32_e32 v171, 0x1fc, v171
	v_add_u32_e32 v171, s18, v171
	v_add_u32_e32 v171, 7168, v171
	ds_add_rtn_u32 v158, v156, v146
	ds_add_rtn_u32 v159, v157, v146
	ds_add_rtn_u32 v172, v170, v146
	ds_add_rtn_u32 v173, v171, v146
	ds_read_b32 v160, v144 offset:0
	ds_read_b32 v161, v144 offset:256
	ds_read_b32 v174, v144 offset:7168
	ds_read_b32 v175, v144 offset:7424
	s_waitcnt lgkmcnt(0)
	v_mov_b32_e32 v164, v160
	v_mov_b32_e32 v165, v161
	v_mov_b32_e32 v178, v174
	v_mov_b32_e32 v179, v175
	v_cmp_le_u32_e32 vcc, 1, v213
	ds_bpermute_b32 v162, v149, v164
	ds_bpermute_b32 v163, v149, v165
	ds_bpermute_b32 v176, v149, v178
	ds_bpermute_b32 v177, v149, v179
	s_waitcnt lgkmcnt(0)
	v_cndmask_b32_e32 v162, 0, v162, vcc
	v_cndmask_b32_e32 v163, 0, v163, vcc
	v_add_u32_e32 v164, v164, v162
	v_add_u32_e32 v165, v165, v163
	v_cndmask_b32_e32 v176, 0, v176, vcc
	v_cndmask_b32_e32 v177, 0, v177, vcc
	v_add_u32_e32 v178, v178, v176
	v_add_u32_e32 v179, v179, v177
	v_cmp_le_u32_e32 vcc, 2, v213
	ds_bpermute_b32 v162, v150, v164
	ds_bpermute_b32 v163, v150, v165
	ds_bpermute_b32 v176, v150, v178
	ds_bpermute_b32 v177, v150, v179
	s_waitcnt lgkmcnt(0)
	v_cndmask_b32_e32 v162, 0, v162, vcc
	v_cndmask_b32_e32 v163, 0, v163, vcc
	v_add_u32_e32 v164, v164, v162
	v_add_u32_e32 v165, v165, v163
	v_cndmask_b32_e32 v176, 0, v176, vcc
	v_cndmask_b32_e32 v177, 0, v177, vcc
	v_add_u32_e32 v178, v178, v176
	v_add_u32_e32 v179, v179, v177
	v_cmp_le_u32_e32 vcc, 4, v213
	ds_bpermute_b32 v162, v151, v164
	ds_bpermute_b32 v163, v151, v165
	ds_bpermute_b32 v176, v151, v178
	ds_bpermute_b32 v177, v151, v179
	s_waitcnt lgkmcnt(0)
	v_cndmask_b32_e32 v162, 0, v162, vcc
	v_cndmask_b32_e32 v163, 0, v163, vcc
	v_add_u32_e32 v164, v164, v162
	v_add_u32_e32 v165, v165, v163
	v_cndmask_b32_e32 v176, 0, v176, vcc
	v_cndmask_b32_e32 v177, 0, v177, vcc
	v_add_u32_e32 v178, v178, v176
	v_add_u32_e32 v179, v179, v177
	v_cmp_le_u32_e32 vcc, 8, v213
	ds_bpermute_b32 v162, v152, v164
	ds_bpermute_b32 v163, v152, v165
	ds_bpermute_b32 v176, v152, v178
	ds_bpermute_b32 v177, v152, v179
	s_waitcnt lgkmcnt(0)
	v_cndmask_b32_e32 v162, 0, v162, vcc
	v_cndmask_b32_e32 v163, 0, v163, vcc
	v_add_u32_e32 v164, v164, v162
	v_add_u32_e32 v165, v165, v163
	v_cndmask_b32_e32 v176, 0, v176, vcc
	v_cndmask_b32_e32 v177, 0, v177, vcc
	v_add_u32_e32 v178, v178, v176
	v_add_u32_e32 v179, v179, v177
	v_cmp_le_u32_e32 vcc, 16, v213
	ds_bpermute_b32 v162, v153, v164
	ds_bpermute_b32 v163, v153, v165
	ds_bpermute_b32 v176, v153, v178
	ds_bpermute_b32 v177, v153, v179
	s_waitcnt lgkmcnt(0)
	v_cndmask_b32_e32 v162, 0, v162, vcc
	v_cndmask_b32_e32 v163, 0, v163, vcc
	v_add_u32_e32 v164, v164, v162
	v_add_u32_e32 v165, v165, v163
	v_cndmask_b32_e32 v176, 0, v176, vcc
	v_cndmask_b32_e32 v177, 0, v177, vcc
	v_add_u32_e32 v178, v178, v176
	v_add_u32_e32 v179, v179, v177
	v_cmp_le_u32_e32 vcc, 32, v213
	ds_bpermute_b32 v162, v154, v164
	ds_bpermute_b32 v163, v154, v165
	ds_bpermute_b32 v176, v154, v178
	ds_bpermute_b32 v177, v154, v179
	s_waitcnt lgkmcnt(0)
	v_cndmask_b32_e32 v162, 0, v162, vcc
	v_cndmask_b32_e32 v163, 0, v163, vcc
	v_add_u32_e32 v164, v164, v162
	v_add_u32_e32 v165, v165, v163
	v_cndmask_b32_e32 v176, 0, v176, vcc
	v_cndmask_b32_e32 v177, 0, v177, vcc
	v_add_u32_e32 v178, v178, v176
	v_add_u32_e32 v179, v179, v177
	s_nop 0
	v_readlane_b32 s13, v164, 63
	v_sub_u32_e32 v164, v164, v160
	v_sub_u32_e32 v165, v165, v161
	s_nop 0
	v_add_u32_e32 v165, s13, v165
	s_nop 0
	v_readlane_b32 s13, v178, 63
	v_sub_u32_e32 v178, v178, v174
	v_sub_u32_e32 v179, v179, v175
	s_nop 0
	v_add_u32_e32 v179, s13, v179
	ds_write_b32 v144, v164 offset:0
	ds_write_b32 v144, v165 offset:256
	ds_write_b32 v144, v178 offset:7168
	ds_write_b32 v144, v179 offset:7424
	ds_read_b32 v160, v156
	ds_read_b32 v161, v157
	ds_read_b32 v174, v170
	ds_read_b32 v175, v171
	s_waitcnt lgkmcnt(0)
	v_add_u32_e32 v160, v160, v158
	v_add_u32_e32 v161, v161, v159
	v_lshl_add_u32 v160, v160, 2, s19
	v_lshl_add_u32 v161, v161, 2, s19
	v_add_u32_e32 v174, v174, v172
	v_add_u32_e32 v175, v175, v173
	v_lshl_add_u32 v174, v174, 2, s19
	v_lshl_add_u32 v175, v175, 2, s19
	ds_write_b32 v160, v166 offset:1024
	ds_write_b32 v160, v168 offset:17408
	ds_write_b32 v161, v167 offset:1024
	ds_write_b32 v161, v169 offset:17408
	ds_write_b32 v174, v180 offset:1536
	ds_write_b32 v174, v182 offset:17920
	ds_write_b32 v175, v181 offset:1536
	ds_write_b32 v175, v183 offset:17920
	ds_read_b32 v132, v147 offset:1024
	ds_read_b32 v133, v147 offset:1056
	ds_read_b32 v134, v147 offset:1536
	ds_read_b32 v135, v147 offset:1568
	s_waitcnt lgkmcnt(0)
	v_lshlrev_b32_e32 v132, 10, v132
	v_lshlrev_b32_e32 v133, 10, v133
	v_lshlrev_b32_e32 v134, 10, v134
	v_lshlrev_b32_e32 v135, 10, v135
	ds_read_b32 v166, v237 offset:2048
	ds_read_b32 v167, v237 offset:2304
	ds_read_b32 v168, v237 offset:18432
	ds_read_b32 v169, v237 offset:18688
	ds_write_b32 v144, v145 offset:0
	ds_write_b32 v144, v145 offset:256
	ds_read_b32 v180, v237 offset:2560
	ds_read_b32 v181, v237 offset:2816
	ds_read_b32 v182, v237 offset:18944
	ds_read_b32 v183, v237 offset:19200
	ds_write_b32 v144, v145 offset:7168
	ds_write_b32 v144, v145 offset:7424
	s_waitcnt lgkmcnt(0)
; template <bool STORE>
; DI void peer_item(const Params& p, int item, char* smem) {
;     ...
; #pragma unroll 2
;     for (int k = 0; k < 128; k += 8) {
;       u32x4 uq[8];
;       const int emine = e_s[tl * 128 + k + (lane >> 3)];
;       const float gmine = g_s[tl * 128 + k + (lane >> 3)];
;       const float su = SU[emine], sv = SV[emine];
; #pragma unroll
;       for (int u = 0; u < 8; ++u) {
;         int e = e_s[tl * 128 + k + u];
;         uq[u] = *(const u32x4*)(U8 + (size_t)e * 1024 + lane * 16);
	v_lshrrev_b32_e32 v156, 5, v166
	v_and_b32_e32 v156, 0x1fc, v156
	v_add_u32_e32 v156, s18, v156
	v_lshrrev_b32_e32 v157, 5, v167
	v_and_b32_e32 v157, 0x1fc, v157
	v_add_u32_e32 v157, s18, v157
	v_lshrrev_b32_e32 v170, 5, v180
	v_and_b32_e32 v170, 0x1fc, v170
	v_add_u32_e32 v170, s18, v170
	v_add_u32_e32 v170, 7168, v170
	v_lshrrev_b32_e32 v171, 5, v181
	v_and_b32_e32 v171, 0x1fc, v171
	v_add_u32_e32 v171, s18, v171
	v_add_u32_e32 v171, 7168, v171
	ds_add_rtn_u32 v158, v156, v146
	ds_add_rtn_u32 v159, v157, v146
	ds_add_rtn_u32 v172, v170, v146
	ds_add_rtn_u32 v173, v171, v146
	ds_read_b32 v160, v144 offset:0
	ds_read_b32 v161, v144 offset:256
	ds_read_b32 v174, v144 offset:7168
	ds_read_b32 v175, v144 offset:7424
	s_waitcnt lgkmcnt(0)
	v_mov_b32_e32 v164, v160
	v_mov_b32_e32 v165, v161
	v_mov_b32_e32 v178, v174
	v_mov_b32_e32 v179, v175
	v_cmp_le_u32_e32 vcc, 1, v213
	ds_bpermute_b32 v162, v149, v164
	ds_bpermute_b32 v163, v149, v165
	ds_bpermute_b32 v176, v149, v178
	ds_bpermute_b32 v177, v149, v179
	s_waitcnt lgkmcnt(0)
	v_cndmask_b32_e32 v162, 0, v162, vcc
	v_cndmask_b32_e32 v163, 0, v163, vcc
	v_add_u32_e32 v164, v164, v162
	v_add_u32_e32 v165, v165, v163
	v_cndmask_b32_e32 v176, 0, v176, vcc
	v_cndmask_b32_e32 v177, 0, v177, vcc
	v_add_u32_e32 v178, v178, v176
	v_add_u32_e32 v179, v179, v177
	v_cmp_le_u32_e32 vcc, 2, v213
	ds_bpermute_b32 v162, v150, v164
	ds_bpermute_b32 v163, v150, v165
	ds_bpermute_b32 v176, v150, v178
	ds_bpermute_b32 v177, v150, v179
	s_waitcnt lgkmcnt(0)
	v_cndmask_b32_e32 v162, 0, v162, vcc
	v_cndmask_b32_e32 v163, 0, v163, vcc
	v_add_u32_e32 v164, v164, v162
	v_add_u32_e32 v165, v165, v163
	v_cndmask_b32_e32 v176, 0, v176, vcc
	v_cndmask_b32_e32 v177, 0, v177, vcc
	v_add_u32_e32 v178, v178, v176
	v_add_u32_e32 v179, v179, v177
	v_cmp_le_u32_e32 vcc, 4, v213
	ds_bpermute_b32 v162, v151, v164
	ds_bpermute_b32 v163, v151, v165
	ds_bpermute_b32 v176, v151, v178
	ds_bpermute_b32 v177, v151, v179
	s_waitcnt lgkmcnt(0)
	v_cndmask_b32_e32 v162, 0, v162, vcc
	v_cndmask_b32_e32 v163, 0, v163, vcc
	v_add_u32_e32 v164, v164, v162
	v_add_u32_e32 v165, v165, v163
	v_cndmask_b32_e32 v176, 0, v176, vcc
	v_cndmask_b32_e32 v177, 0, v177, vcc
	v_add_u32_e32 v178, v178, v176
	v_add_u32_e32 v179, v179, v177
	v_cmp_le_u32_e32 vcc, 8, v213
	ds_bpermute_b32 v162, v152, v164
	ds_bpermute_b32 v163, v152, v165
	ds_bpermute_b32 v176, v152, v178
	ds_bpermute_b32 v177, v152, v179
	s_waitcnt lgkmcnt(0)
	v_cndmask_b32_e32 v162, 0, v162, vcc
	v_cndmask_b32_e32 v163, 0, v163, vcc
	v_add_u32_e32 v164, v164, v162
	v_add_u32_e32 v165, v165, v163
	v_cndmask_b32_e32 v176, 0, v176, vcc
	v_cndmask_b32_e32 v177, 0, v177, vcc
	v_add_u32_e32 v178, v178, v176
	v_add_u32_e32 v179, v179, v177
	v_cmp_le_u32_e32 vcc, 16, v213
	ds_bpermute_b32 v162, v153, v164
	ds_bpermute_b32 v163, v153, v165
	ds_bpermute_b32 v176, v153, v178
	ds_bpermute_b32 v177, v153, v179
	s_waitcnt lgkmcnt(0)
	v_cndmask_b32_e32 v162, 0, v162, vcc
	v_cndmask_b32_e32 v163, 0, v163, vcc
	v_add_u32_e32 v164, v164, v162
	v_add_u32_e32 v165, v165, v163
	v_cndmask_b32_e32 v176, 0, v176, vcc
	v_cndmask_b32_e32 v177, 0, v177, vcc
	v_add_u32_e32 v178, v178, v176
	v_add_u32_e32 v179, v179, v177
	v_cmp_le_u32_e32 vcc, 32, v213
	ds_bpermute_b32 v162, v154, v164
	ds_bpermute_b32 v163, v154, v165
	ds_bpermute_b32 v176, v154, v178
	ds_bpermute_b32 v177, v154, v179
	s_waitcnt lgkmcnt(0)
	v_cndmask_b32_e32 v162, 0, v162, vcc
	v_cndmask_b32_e32 v163, 0, v163, vcc
	v_add_u32_e32 v164, v164, v162
	v_add_u32_e32 v165, v165, v163
	v_cndmask_b32_e32 v176, 0, v176, vcc
	v_cndmask_b32_e32 v177, 0, v177, vcc
	v_add_u32_e32 v178, v178, v176
	v_add_u32_e32 v179, v179, v177
	s_nop 0
	v_readlane_b32 s13, v164, 63
	v_sub_u32_e32 v164, v164, v160
	v_sub_u32_e32 v165, v165, v161
	s_nop 0
	v_add_u32_e32 v165, s13, v165
	s_nop 0
	v_readlane_b32 s13, v178, 63
	v_sub_u32_e32 v178, v178, v174
	v_sub_u32_e32 v179, v179, v175
	s_nop 0
	v_add_u32_e32 v179, s13, v179
	ds_write_b32 v144, v164 offset:0
	ds_write_b32 v144, v165 offset:256
	ds_write_b32 v144, v178 offset:7168
	ds_write_b32 v144, v179 offset:7424
	ds_read_b32 v160, v156
	ds_read_b32 v161, v157
	ds_read_b32 v174, v170
	ds_read_b32 v175, v171
	s_waitcnt lgkmcnt(0)
	v_add_u32_e32 v160, v160, v158
	v_add_u32_e32 v161, v161, v159
	v_lshl_add_u32 v160, v160, 2, s19
	v_lshl_add_u32 v161, v161, 2, s19
	v_add_u32_e32 v174, v174, v172
	v_add_u32_e32 v175, v175, v173
	v_lshl_add_u32 v174, v174, 2, s19
	v_lshl_add_u32 v175, v175, 2, s19
	ds_write_b32 v160, v166 offset:2048
	ds_write_b32 v160, v168 offset:18432
	ds_write_b32 v161, v167 offset:2048
	ds_write_b32 v161, v169 offset:18432
	ds_write_b32 v174, v180 offset:2560
	ds_write_b32 v174, v182 offset:18944
	ds_write_b32 v175, v181 offset:2560
	ds_write_b32 v175, v183 offset:18944
	ds_read_b32 v136, v147 offset:2048
	ds_read_b32 v137, v147 offset:2080
	ds_read_b32 v138, v147 offset:2560
	ds_read_b32 v139, v147 offset:2592
	s_waitcnt lgkmcnt(0)
	v_lshlrev_b32_e32 v136, 10, v136
	v_lshlrev_b32_e32 v137, 10, v137
	v_lshlrev_b32_e32 v138, 10, v138
	v_lshlrev_b32_e32 v139, 10, v139
	ds_read_b32 v166, v237 offset:3072
	ds_read_b32 v167, v237 offset:3328
	ds_read_b32 v168, v237 offset:19456
	ds_read_b32 v169, v237 offset:19712
	ds_write_b32 v144, v145 offset:0
	ds_write_b32 v144, v145 offset:256
	ds_read_b32 v180, v237 offset:3584
	ds_read_b32 v181, v237 offset:3840
	ds_read_b32 v182, v237 offset:19968
	ds_read_b32 v183, v237 offset:20224
	ds_write_b32 v144, v145 offset:7168
	ds_write_b32 v144, v145 offset:7424
	s_waitcnt lgkmcnt(0)
; template <bool STORE>
; DI void peer_item(const Params& p, int item, char* smem) {
;     ...
; #pragma unroll 2
;     for (int k = 0; k < 128; k += 8) {
;       u32x4 uq[8];
;       const int emine = e_s[tl * 128 + k + (lane >> 3)];
;       const float gmine = g_s[tl * 128 + k + (lane >> 3)];
;       const float su = SU[emine], sv = SV[emine];
; #pragma unroll
;       for (int u = 0; u < 8; ++u) {
;         int e = e_s[tl * 128 + k + u];
;         uq[u] = *(const u32x4*)(U8 + (size_t)e * 1024 + lane * 16);
	v_lshrrev_b32_e32 v156, 5, v166
	v_and_b32_e32 v156, 0x1fc, v156
	v_add_u32_e32 v156, s18, v156
	v_lshrrev_b32_e32 v157, 5, v167
	v_and_b32_e32 v157, 0x1fc, v157
	v_add_u32_e32 v157, s18, v157
	v_lshrrev_b32_e32 v170, 5, v180
	v_and_b32_e32 v170, 0x1fc, v170
	v_add_u32_e32 v170, s18, v170
	v_add_u32_e32 v170, 7168, v170
	v_lshrrev_b32_e32 v171, 5, v181
	v_and_b32_e32 v171, 0x1fc, v171
	v_add_u32_e32 v171, s18, v171
	v_add_u32_e32 v171, 7168, v171
	ds_add_rtn_u32 v158, v156, v146
	ds_add_rtn_u32 v159, v157, v146
	ds_add_rtn_u32 v172, v170, v146
	ds_add_rtn_u32 v173, v171, v146
	ds_read_b32 v160, v144 offset:0
	ds_read_b32 v161, v144 offset:256
	ds_read_b32 v174, v144 offset:7168
	ds_read_b32 v175, v144 offset:7424
	s_waitcnt lgkmcnt(0)
	v_mov_b32_e32 v164, v160
	v_mov_b32_e32 v165, v161
	v_mov_b32_e32 v178, v174
	v_mov_b32_e32 v179, v175
	v_cmp_le_u32_e32 vcc, 1, v213
	ds_bpermute_b32 v162, v149, v164
	ds_bpermute_b32 v163, v149, v165
	ds_bpermute_b32 v176, v149, v178
	ds_bpermute_b32 v177, v149, v179
	s_waitcnt lgkmcnt(0)
	v_cndmask_b32_e32 v162, 0, v162, vcc
	v_cndmask_b32_e32 v163, 0, v163, vcc
	v_add_u32_e32 v164, v164, v162
	v_add_u32_e32 v165, v165, v163
	v_cndmask_b32_e32 v176, 0, v176, vcc
	v_cndmask_b32_e32 v177, 0, v177, vcc
	v_add_u32_e32 v178, v178, v176
	v_add_u32_e32 v179, v179, v177
	v_cmp_le_u32_e32 vcc, 2, v213
	ds_bpermute_b32 v162, v150, v164
	ds_bpermute_b32 v163, v150, v165
	ds_bpermute_b32 v176, v150, v178
	ds_bpermute_b32 v177, v150, v179
	s_waitcnt lgkmcnt(0)
	v_cndmask_b32_e32 v162, 0, v162, vcc
	v_cndmask_b32_e32 v163, 0, v163, vcc
	v_add_u32_e32 v164, v164, v162
	v_add_u32_e32 v165, v165, v163
	v_cndmask_b32_e32 v176, 0, v176, vcc
	v_cndmask_b32_e32 v177, 0, v177, vcc
	v_add_u32_e32 v178, v178, v176
	v_add_u32_e32 v179, v179, v177
	v_cmp_le_u32_e32 vcc, 4, v213
	ds_bpermute_b32 v162, v151, v164
	ds_bpermute_b32 v163, v151, v165
	ds_bpermute_b32 v176, v151, v178
	ds_bpermute_b32 v177, v151, v179
	s_waitcnt lgkmcnt(0)
	v_cndmask_b32_e32 v162, 0, v162, vcc
	v_cndmask_b32_e32 v163, 0, v163, vcc
	v_add_u32_e32 v164, v164, v162
	v_add_u32_e32 v165, v165, v163
	v_cndmask_b32_e32 v176, 0, v176, vcc
	v_cndmask_b32_e32 v177, 0, v177, vcc
	v_add_u32_e32 v178, v178, v176
	v_add_u32_e32 v179, v179, v177
	v_cmp_le_u32_e32 vcc, 8, v213
	ds_bpermute_b32 v162, v152, v164
	ds_bpermute_b32 v163, v152, v165
	ds_bpermute_b32 v176, v152, v178
	ds_bpermute_b32 v177, v152, v179
	s_waitcnt lgkmcnt(0)
	v_cndmask_b32_e32 v162, 0, v162, vcc
	v_cndmask_b32_e32 v163, 0, v163, vcc
	v_add_u32_e32 v164, v164, v162
	v_add_u32_e32 v165, v165, v163
	v_cndmask_b32_e32 v176, 0, v176, vcc
	v_cndmask_b32_e32 v177, 0, v177, vcc
	v_add_u32_e32 v178, v178, v176
	v_add_u32_e32 v179, v179, v177
	v_cmp_le_u32_e32 vcc, 16, v213
	ds_bpermute_b32 v162, v153, v164
	ds_bpermute_b32 v163, v153, v165
	ds_bpermute_b32 v176, v153, v178
	ds_bpermute_b32 v177, v153, v179
	s_waitcnt lgkmcnt(0)
	v_cndmask_b32_e32 v162, 0, v162, vcc
	v_cndmask_b32_e32 v163, 0, v163, vcc
	v_add_u32_e32 v164, v164, v162
	v_add_u32_e32 v165, v165, v163
	v_cndmask_b32_e32 v176, 0, v176, vcc
	v_cndmask_b32_e32 v177, 0, v177, vcc
	v_add_u32_e32 v178, v178, v176
	v_add_u32_e32 v179, v179, v177
	v_cmp_le_u32_e32 vcc, 32, v213
	ds_bpermute_b32 v162, v154, v164
	ds_bpermute_b32 v163, v154, v165
	ds_bpermute_b32 v176, v154, v178
	ds_bpermute_b32 v177, v154, v179
	s_waitcnt lgkmcnt(0)
	v_cndmask_b32_e32 v162, 0, v162, vcc
	v_cndmask_b32_e32 v163, 0, v163, vcc
	v_add_u32_e32 v164, v164, v162
	v_add_u32_e32 v165, v165, v163
	v_cndmask_b32_e32 v176, 0, v176, vcc
	v_cndmask_b32_e32 v177, 0, v177, vcc
	v_add_u32_e32 v178, v178, v176
	v_add_u32_e32 v179, v179, v177
	s_nop 0
	v_readlane_b32 s13, v164, 63
	v_sub_u32_e32 v164, v164, v160
	v_sub_u32_e32 v165, v165, v161
	s_nop 0
	v_add_u32_e32 v165, s13, v165
	s_nop 0
	v_readlane_b32 s13, v178, 63
	v_sub_u32_e32 v178, v178, v174
	v_sub_u32_e32 v179, v179, v175
	s_nop 0
	v_add_u32_e32 v179, s13, v179
	ds_write_b32 v144, v164 offset:0
	ds_write_b32 v144, v165 offset:256
	ds_write_b32 v144, v178 offset:7168
	ds_write_b32 v144, v179 offset:7424
	ds_read_b32 v160, v156
	ds_read_b32 v161, v157
	ds_read_b32 v174, v170
	ds_read_b32 v175, v171
	s_waitcnt lgkmcnt(0)
	v_add_u32_e32 v160, v160, v158
	v_add_u32_e32 v161, v161, v159
	v_lshl_add_u32 v160, v160, 2, s19
	v_lshl_add_u32 v161, v161, 2, s19
	v_add_u32_e32 v174, v174, v172
	v_add_u32_e32 v175, v175, v173
	v_lshl_add_u32 v174, v174, 2, s19
	v_lshl_add_u32 v175, v175, 2, s19
	ds_write_b32 v160, v166 offset:3072
	ds_write_b32 v160, v168 offset:19456
	ds_write_b32 v161, v167 offset:3072
	ds_write_b32 v161, v169 offset:19456
	ds_write_b32 v174, v180 offset:3584
	ds_write_b32 v174, v182 offset:19968
	ds_write_b32 v175, v181 offset:3584
	ds_write_b32 v175, v183 offset:19968
	ds_read_b32 v140, v147 offset:3072
	ds_read_b32 v141, v147 offset:3104
	ds_read_b32 v142, v147 offset:3584
	ds_read_b32 v143, v147 offset:3616
	s_waitcnt lgkmcnt(0)
	v_lshlrev_b32_e32 v140, 10, v140
	v_lshlrev_b32_e32 v141, 10, v141
	v_lshlrev_b32_e32 v142, 10, v142
	v_lshlrev_b32_e32 v143, 10, v143
	s_waitcnt vmcnt(0)
; DI float bflo(unsigned u) { return __uint_as_float(u << 16); }
; DI float bfhi(unsigned u) { return __uint_as_float(u & 0xffff0000u); }
; template <bool STORE>
; DI void peer_item(const Params& p, int item, char* smem) {
;     ...
;     float xf[16];
;     {
; #pragma unroll
;       for (int i = 0; i < 4; ++i) {
;         const uint2 xv = *(const uint2*)(XN2 + tok * 1024 + 256 * i + lane * 4);
;         xf[4 * i] = bflo(xv.x); xf[4 * i + 1] = bfhi(xv.x); xf[4 * i + 2] = bflo(xv.y); xf[4 * i + 3] = bfhi(xv.y);
;       }
;     }
; #pragma unroll 2
;     for (int k = 0; k < 128; k += 8) {
;       u32x4 uq[8];
;       const int emine = e_s[tl * 128 + k + (lane >> 3)];
;       const float gmine = g_s[tl * 128 + k + (lane >> 3)];
;       const float su = SU[emine], sv = SV[emine];
; #pragma unroll
;       for (int u = 0; u < 8; ++u) {
;         int e = e_s[tl * 128 + k + u];
;         uq[u] = *(const u32x4*)(U8 + (size_t)e * 1024 + lane * 16);
	v_lshlrev_b32_e32 v0, 16, v2
	v_and_b32_e32 v1, 0xffff0000, v2
	v_lshlrev_b32_e32 v2, 16, v3
	v_and_b32_e32 v3, 0xffff0000, v3
	v_lshlrev_b32_e32 v4, 16, v6
	v_and_b32_e32 v5, 0xffff0000, v6
	v_lshlrev_b32_e32 v6, 16, v7
	v_and_b32_e32 v7, 0xffff0000, v7
	v_lshlrev_b32_e32 v8, 16, v10
	v_and_b32_e32 v9, 0xffff0000, v10
	v_lshlrev_b32_e32 v10, 16, v11
	v_and_b32_e32 v11, 0xffff0000, v11
	v_lshlrev_b32_e32 v12, 16, v14
	v_and_b32_e32 v13, 0xffff0000, v14
	v_lshlrev_b32_e32 v14, 16, v15
	v_and_b32_e32 v15, 0xffff0000, v15
	v_lshlrev_b32_e32 v16, 16, v18
	v_and_b32_e32 v17, 0xffff0000, v18
	v_lshlrev_b32_e32 v18, 16, v19
	v_and_b32_e32 v19, 0xffff0000, v19
	v_lshlrev_b32_e32 v20, 16, v22
	v_and_b32_e32 v21, 0xffff0000, v22
	v_lshlrev_b32_e32 v22, 16, v23
	v_and_b32_e32 v23, 0xffff0000, v23
	v_lshlrev_b32_e32 v24, 16, v26
	v_and_b32_e32 v25, 0xffff0000, v26
	v_lshlrev_b32_e32 v26, 16, v27
	v_and_b32_e32 v27, 0xffff0000, v27
	v_lshlrev_b32_e32 v28, 16, v30
	v_and_b32_e32 v29, 0xffff0000, v30
	v_lshlrev_b32_e32 v30, 16, v31
	v_and_b32_e32 v31, 0xffff0000, v31
	v_lshlrev_b32_e32 v32, 16, v34
	v_and_b32_e32 v33, 0xffff0000, v34
	v_lshlrev_b32_e32 v34, 16, v35
	v_and_b32_e32 v35, 0xffff0000, v35
	v_lshlrev_b32_e32 v36, 16, v38
	v_and_b32_e32 v37, 0xffff0000, v38
	v_lshlrev_b32_e32 v38, 16, v39
	v_and_b32_e32 v39, 0xffff0000, v39
	v_lshlrev_b32_e32 v40, 16, v42
	v_and_b32_e32 v41, 0xffff0000, v42
	v_lshlrev_b32_e32 v42, 16, v43
	v_and_b32_e32 v43, 0xffff0000, v43
	v_lshlrev_b32_e32 v44, 16, v46
	v_and_b32_e32 v45, 0xffff0000, v46
	v_lshlrev_b32_e32 v46, 16, v47
	v_and_b32_e32 v47, 0xffff0000, v47
	v_lshlrev_b32_e32 v48, 16, v50
	v_and_b32_e32 v49, 0xffff0000, v50
	v_lshlrev_b32_e32 v50, 16, v51
	v_and_b32_e32 v51, 0xffff0000, v51
	v_lshlrev_b32_e32 v52, 16, v54
	v_and_b32_e32 v53, 0xffff0000, v54
	v_lshlrev_b32_e32 v54, 16, v55
	v_and_b32_e32 v55, 0xffff0000, v55
	v_lshlrev_b32_e32 v56, 16, v58
	v_and_b32_e32 v57, 0xffff0000, v58
	v_lshlrev_b32_e32 v58, 16, v59
	v_and_b32_e32 v59, 0xffff0000, v59
	v_lshlrev_b32_e32 v60, 16, v62
	v_and_b32_e32 v61, 0xffff0000, v62
	v_lshlrev_b32_e32 v62, 16, v63
	v_and_b32_e32 v63, 0xffff0000, v63
	v_lshrrev_b32_e32 v235, 3, v213
	v_lshl_add_u32 v235, v235, 2, s19
	s_mov_b32 s72, 0
	s_mov_b32 s73, 1
	s_mov_b32 s74, 2
	s_mov_b32 s75, 3
	s_mov_b32 s76, 4
	s_mov_b32 s77, 5
	s_mov_b32 s78, 6
	s_mov_b32 s79, 7
	s_mov_b32 s58, 8
	s_mov_b32 s59, 9
	s_mov_b32 s60, 10
	s_mov_b32 s61, 11
	s_mov_b32 s62, 12
	s_mov_b32 s63, 13
	s_mov_b32 s64, 14
	s_mov_b32 s65, 15
	s_nop 0
	v_readlane_b32 s48, v128, s72
	v_readlane_b32 s49, v128, s73
	v_readlane_b32 s50, v128, s74
	v_readlane_b32 s51, v128, s75
	v_readlane_b32 s52, v128, s76
	v_readlane_b32 s53, v128, s77
	v_readlane_b32 s54, v128, s78
	v_readlane_b32 s55, v128, s79
	s_add_u32 s32, s0, s48
	s_addc_u32 s33, s1, 0
	s_add_u32 s34, s0, s49
	s_addc_u32 s35, s1, 0
	s_add_u32 s36, s0, s50
	s_addc_u32 s37, s1, 0
	s_add_u32 s38, s0, s51
	s_addc_u32 s39, s1, 0
	s_add_u32 s40, s0, s52
	s_addc_u32 s41, s1, 0
	s_add_u32 s42, s0, s53
	s_addc_u32 s43, s1, 0
	s_add_u32 s44, s0, s54
	s_addc_u32 s45, s1, 0
	s_add_u32 s46, s0, s55
	s_addc_u32 s47, s1, 0
	global_load_dwordx4 v[144:147], v234, s[32:33]
	global_load_dwordx4 v[148:151], v234, s[34:35]
	global_load_dwordx4 v[152:155], v234, s[36:37]
	global_load_dwordx4 v[156:159], v234, s[38:39]
	global_load_dwordx4 v[160:163], v234, s[40:41]
	global_load_dwordx4 v[164:167], v234, s[42:43]
	global_load_dwordx4 v[168:171], v234, s[44:45]
	global_load_dwordx4 v[172:175], v234, s[46:47]
	v_readlane_b32 s48, v130, s72
	v_readlane_b32 s49, v130, s73
	v_readlane_b32 s50, v130, s74
	v_readlane_b32 s51, v130, s75
	v_readlane_b32 s52, v130, s76
	v_readlane_b32 s53, v130, s77
	v_readlane_b32 s54, v130, s78
	v_readlane_b32 s55, v130, s79
	s_add_u32 s32, s0, s48
	s_addc_u32 s33, s1, 0
	s_add_u32 s34, s0, s49
	s_addc_u32 s35, s1, 0
	s_add_u32 s36, s0, s50
	s_addc_u32 s37, s1, 0
	s_add_u32 s38, s0, s51
	s_addc_u32 s39, s1, 0
	s_add_u32 s40, s0, s52
	s_addc_u32 s41, s1, 0
	s_add_u32 s42, s0, s53
	s_addc_u32 s43, s1, 0
	s_add_u32 s44, s0, s54
	s_addc_u32 s45, s1, 0
	s_add_u32 s46, s0, s55
	s_addc_u32 s47, s1, 0
	global_load_dwordx4 v[176:179], v234, s[32:33]
	global_load_dwordx4 v[180:183], v234, s[34:35]
	global_load_dwordx4 v[184:187], v234, s[36:37]
	global_load_dwordx4 v[188:191], v234, s[38:39]
	global_load_dwordx4 v[192:195], v234, s[40:41]
	global_load_dwordx4 v[196:199], v234, s[42:43]
	global_load_dwordx4 v[200:203], v234, s[44:45]
	global_load_dwordx4 v[204:207], v234, s[46:47]
	v_readlane_b32 s48, v132, s72
	v_readlane_b32 s49, v132, s73
	v_readlane_b32 s50, v132, s74
	v_readlane_b32 s51, v132, s75
	v_readlane_b32 s52, v132, s76
	v_readlane_b32 s53, v132, s77
	v_readlane_b32 s54, v132, s78
	v_readlane_b32 s55, v132, s79
	s_add_u32 s32, s0, s48
	s_addc_u32 s33, s1, 0
	s_add_u32 s34, s0, s49
	s_addc_u32 s35, s1, 0
	s_add_u32 s36, s0, s50
	s_addc_u32 s37, s1, 0
	s_add_u32 s38, s0, s51
	s_addc_u32 s39, s1, 0
	s_add_u32 s40, s0, s52
	s_addc_u32 s41, s1, 0
	s_add_u32 s42, s0, s53
	s_addc_u32 s43, s1, 0
	s_add_u32 s44, s0, s54
	s_addc_u32 s45, s1, 0
	s_add_u32 s46, s0, s55
	s_addc_u32 s47, s1, 0
	global_load_dwordx4 v[64:67], v234, s[32:33]
	global_load_dwordx4 v[68:71], v234, s[34:35]
	global_load_dwordx4 v[72:75], v234, s[36:37]
	global_load_dwordx4 v[76:79], v234, s[38:39]
	global_load_dwordx4 v[80:83], v234, s[40:41]
	global_load_dwordx4 v[84:87], v234, s[42:43]
	global_load_dwordx4 v[88:91], v234, s[44:45]
	global_load_dwordx4 v[92:95], v234, s[46:47]
	s_mov_b32 s12, 0
; template <bool STORE>
; DI void peer_item(const Params& p, int item, char* smem) {
;     ...
; #pragma unroll 2
;     for (int k = 0; k < 128; k += 8) {
;       u32x4 uq[8];
;       const int emine = e_s[tl * 128 + k + (lane >> 3)];
;       const float gmine = g_s[tl * 128 + k + (lane >> 3)];
;       const float su = SU[emine], sv = SV[emine];
; #pragma unroll
;       for (int u = 0; u < 8; ++u) {
;         int e = e_s[tl * 128 + k + u];
;         uq[u] = *(const u32x4*)(U8 + (size_t)e * 1024 + lane * 16);
;       }
;       float part[8];
; #pragma unroll
;       for (int u = 0; u < 8; ++u) {
;         float d = 0.f;
; #pragma unroll
;         for (int i = 0; i < 4; ++i) {
;           f32x2_t lo = __builtin_amdgcn_cvt_pk_f32_fp8((int)uq[u][i], false);
;           f32x2_t hi = __builtin_amdgcn_cvt_pk_f32_fp8((int)uq[u][i], true);
;           d += xf[4 * i] * lo.x + xf[4 * i + 1] * lo.y + xf[4 * i + 2] * hi.x + xf[4 * i + 3] * hi.y;
;         }
;         part[u] = d;
;       }
;       float q4[4], r2[2], h;
; #pragma unroll
;       for (int j = 0; j < 4; ++j) {
;         float mine = b5 ? part[j + 4] : part[j];
;         float other = b5 ? part[j] : part[j + 4];
;         q4[j] = mine + __shfl_xor(other, 32);
;       }
; #pragma unroll
;       for (int j = 0; j < 2; ++j) {
;         float mine = b4 ? q4[j + 2] : q4[j];
;         float other = b4 ? q4[j] : q4[j + 2];
;         r2[j] = mine + __shfl_xor(other, 16);
;       }
;       {
;         float mine = b3 ? r2[1] : r2[0];
;         float other = b3 ? r2[0] : r2[1];
;         h = mine + __shfl_xor(other, 8);
;       }
;       h += __shfl_xor(h, 4);
;       h += __shfl_xor(h, 2);
;       h += __shfl_xor(h, 1);
.Lup_kA:
	v_readlane_b32 s48, v134, s72
	v_readlane_b32 s49, v134, s73
	v_readlane_b32 s50, v134, s74
	v_readlane_b32 s51, v134, s75
	v_readlane_b32 s52, v134, s76
	v_readlane_b32 s53, v134, s77
	v_readlane_b32 s54, v134, s78
	v_readlane_b32 s55, v134, s79
	s_add_u32 s32, s0, s48
	s_addc_u32 s33, s1, 0
	s_add_u32 s34, s0, s49
	s_addc_u32 s35, s1, 0
	s_add_u32 s36, s0, s50
	s_addc_u32 s37, s1, 0
	s_add_u32 s38, s0, s51
	s_addc_u32 s39, s1, 0
	s_add_u32 s40, s0, s52
	s_addc_u32 s41, s1, 0
	s_add_u32 s42, s0, s53
	s_addc_u32 s43, s1, 0
	s_add_u32 s44, s0, s54
	s_addc_u32 s45, s1, 0
	s_add_u32 s46, s0, s55
	s_addc_u32 s47, s1, 0
	global_load_dwordx4 v[96:99], v234, s[32:33]
	global_load_dwordx4 v[100:103], v234, s[34:35]
	global_load_dwordx4 v[104:107], v234, s[36:37]
	global_load_dwordx4 v[108:111], v234, s[38:39]
	global_load_dwordx4 v[112:115], v234, s[40:41]
	global_load_dwordx4 v[116:119], v234, s[42:43]
	global_load_dwordx4 v[120:123], v234, s[44:45]
	global_load_dwordx4 v[124:127], v234, s[46:47]
	s_waitcnt vmcnt(24)
	v_cvt_pk_f32_fp8_e32 v[214:215], v144
	v_cvt_pk_f32_fp8_sdwa v[216:217], v144 src0_sel:WORD_1
	v_cvt_pk_f32_fp8_e32 v[218:219], v145
	v_cvt_pk_f32_fp8_sdwa v[220:221], v145 src0_sel:WORD_1
	v_pk_mul_f32 v[222:223], v[0:1], v[214:215]
	v_pk_mul_f32 v[224:225], v[2:3], v[216:217]
	v_cvt_pk_f32_fp8_e32 v[214:215], v146
	v_cvt_pk_f32_fp8_sdwa v[216:217], v146 src0_sel:WORD_1
	v_pk_fma_f32 v[222:223], v[4:5], v[218:219], v[222:223]
	v_pk_fma_f32 v[224:225], v[6:7], v[220:221], v[224:225]
	v_cvt_pk_f32_fp8_e32 v[218:219], v147
	v_cvt_pk_f32_fp8_sdwa v[220:221], v147 src0_sel:WORD_1
	v_pk_fma_f32 v[222:223], v[8:9], v[214:215], v[222:223]
	v_pk_fma_f32 v[224:225], v[10:11], v[216:217], v[224:225]
	v_pk_fma_f32 v[222:223], v[12:13], v[218:219], v[222:223]
	v_pk_fma_f32 v[224:225], v[14:15], v[220:221], v[224:225]
	v_pk_add_f32 v[222:223], v[222:223], v[224:225]
	s_nop 0
	v_add_f32_e32 v226, v222, v223
	v_cvt_pk_f32_fp8_e32 v[214:215], v148
	v_cvt_pk_f32_fp8_sdwa v[216:217], v148 src0_sel:WORD_1
	v_cvt_pk_f32_fp8_e32 v[218:219], v149
	v_cvt_pk_f32_fp8_sdwa v[220:221], v149 src0_sel:WORD_1
	v_pk_mul_f32 v[222:223], v[0:1], v[214:215]
	v_pk_mul_f32 v[224:225], v[2:3], v[216:217]
	v_cvt_pk_f32_fp8_e32 v[214:215], v150
	v_cvt_pk_f32_fp8_sdwa v[216:217], v150 src0_sel:WORD_1
	v_pk_fma_f32 v[222:223], v[4:5], v[218:219], v[222:223]
	v_pk_fma_f32 v[224:225], v[6:7], v[220:221], v[224:225]
	v_cvt_pk_f32_fp8_e32 v[218:219], v151
	v_cvt_pk_f32_fp8_sdwa v[220:221], v151 src0_sel:WORD_1
	v_pk_fma_f32 v[222:223], v[8:9], v[214:215], v[222:223]
	v_pk_fma_f32 v[224:225], v[10:11], v[216:217], v[224:225]
	v_pk_fma_f32 v[222:223], v[12:13], v[218:219], v[222:223]
	v_pk_fma_f32 v[224:225], v[14:15], v[220:221], v[224:225]
	v_pk_add_f32 v[222:223], v[222:223], v[224:225]
	s_nop 0
	v_add_f32_e32 v227, v222, v223
	v_cvt_pk_f32_fp8_e32 v[214:215], v152
	v_cvt_pk_f32_fp8_sdwa v[216:217], v152 src0_sel:WORD_1
	v_cvt_pk_f32_fp8_e32 v[218:219], v153
	v_cvt_pk_f32_fp8_sdwa v[220:221], v153 src0_sel:WORD_1
	v_pk_mul_f32 v[222:223], v[0:1], v[214:215]
	v_pk_mul_f32 v[224:225], v[2:3], v[216:217]
	v_cvt_pk_f32_fp8_e32 v[214:215], v154
	v_cvt_pk_f32_fp8_sdwa v[216:217], v154 src0_sel:WORD_1
	v_pk_fma_f32 v[222:223], v[4:5], v[218:219], v[222:223]
	v_pk_fma_f32 v[224:225], v[6:7], v[220:221], v[224:225]
	v_cvt_pk_f32_fp8_e32 v[218:219], v155
	v_cvt_pk_f32_fp8_sdwa v[220:221], v155 src0_sel:WORD_1
	v_pk_fma_f32 v[222:223], v[8:9], v[214:215], v[222:223]
	v_pk_fma_f32 v[224:225], v[10:11], v[216:217], v[224:225]
	v_pk_fma_f32 v[222:223], v[12:13], v[218:219], v[222:223]
	v_pk_fma_f32 v[224:225], v[14:15], v[220:221], v[224:225]
	v_pk_add_f32 v[222:223], v[222:223], v[224:225]
	s_nop 0
	v_add_f32_e32 v228, v222, v223
	v_cvt_pk_f32_fp8_e32 v[214:215], v156
	v_cvt_pk_f32_fp8_sdwa v[216:217], v156 src0_sel:WORD_1
	v_cvt_pk_f32_fp8_e32 v[218:219], v157
	v_cvt_pk_f32_fp8_sdwa v[220:221], v157 src0_sel:WORD_1
	v_pk_mul_f32 v[222:223], v[0:1], v[214:215]
	v_pk_mul_f32 v[224:225], v[2:3], v[216:217]
	v_cvt_pk_f32_fp8_e32 v[214:215], v158
	v_cvt_pk_f32_fp8_sdwa v[216:217], v158 src0_sel:WORD_1
	v_pk_fma_f32 v[222:223], v[4:5], v[218:219], v[222:223]
	v_pk_fma_f32 v[224:225], v[6:7], v[220:221], v[224:225]
	v_cvt_pk_f32_fp8_e32 v[218:219], v159
	v_cvt_pk_f32_fp8_sdwa v[220:221], v159 src0_sel:WORD_1
	v_pk_fma_f32 v[222:223], v[8:9], v[214:215], v[222:223]
	v_pk_fma_f32 v[224:225], v[10:11], v[216:217], v[224:225]
	v_pk_fma_f32 v[222:223], v[12:13], v[218:219], v[222:223]
	v_pk_fma_f32 v[224:225], v[14:15], v[220:221], v[224:225]
	v_pk_add_f32 v[222:223], v[222:223], v[224:225]
	s_nop 0
	v_add_f32_e32 v229, v222, v223
	v_cvt_pk_f32_fp8_e32 v[214:215], v160
	v_cvt_pk_f32_fp8_sdwa v[216:217], v160 src0_sel:WORD_1
	v_cvt_pk_f32_fp8_e32 v[218:219], v161
	v_cvt_pk_f32_fp8_sdwa v[220:221], v161 src0_sel:WORD_1
	v_pk_mul_f32 v[222:223], v[0:1], v[214:215]
	v_pk_mul_f32 v[224:225], v[2:3], v[216:217]
	v_cvt_pk_f32_fp8_e32 v[214:215], v162
	v_cvt_pk_f32_fp8_sdwa v[216:217], v162 src0_sel:WORD_1
	v_pk_fma_f32 v[222:223], v[4:5], v[218:219], v[222:223]
	v_pk_fma_f32 v[224:225], v[6:7], v[220:221], v[224:225]
	v_cvt_pk_f32_fp8_e32 v[218:219], v163
	v_cvt_pk_f32_fp8_sdwa v[220:221], v163 src0_sel:WORD_1
	v_pk_fma_f32 v[222:223], v[8:9], v[214:215], v[222:223]
	v_pk_fma_f32 v[224:225], v[10:11], v[216:217], v[224:225]
	v_pk_fma_f32 v[222:223], v[12:13], v[218:219], v[222:223]
	v_pk_fma_f32 v[224:225], v[14:15], v[220:221], v[224:225]
	v_pk_add_f32 v[222:223], v[222:223], v[224:225]
	s_nop 0
	v_add_f32_e32 v230, v222, v223
	v_cvt_pk_f32_fp8_e32 v[214:215], v164
; template <bool STORE>
; DI void peer_item(const Params& p, int item, char* smem) {
;     ...
;       for (int j = 0; j < 4; ++j) {
;         float mine = b5 ? part[j + 4] : part[j];
;         float other = b5 ? part[j] : part[j + 4];
;         q4[j] = mine + __shfl_xor(other, 32);
;       }
; #pragma unroll
;       for (int j = 0; j < 2; ++j) {
;         float mine = b4 ? q4[j + 2] : q4[j];
;         float other = b4 ? q4[j] : q4[j + 2];
;         r2[j] = mine + __shfl_xor(other, 16);
;       }
;       {
;         float mine = b3 ? r2[1] : r2[0];
;         float other = b3 ? r2[0] : r2[1];
;         h = mine + __shfl_xor(other, 8);
;       }
;       h += __shfl_xor(h, 4);
;       h += __shfl_xor(h, 2);
;       h += __shfl_xor(h, 1);
	v_cvt_pk_f32_fp8_sdwa v[216:217], v164 src0_sel:WORD_1
	v_cvt_pk_f32_fp8_e32 v[218:219], v165
	v_cvt_pk_f32_fp8_sdwa v[220:221], v165 src0_sel:WORD_1
	v_pk_mul_f32 v[222:223], v[0:1], v[214:215]
	v_pk_mul_f32 v[224:225], v[2:3], v[216:217]
	v_cvt_pk_f32_fp8_e32 v[214:215], v166
	v_cvt_pk_f32_fp8_sdwa v[216:217], v166 src0_sel:WORD_1
	v_pk_fma_f32 v[222:223], v[4:5], v[218:219], v[222:223]
	v_pk_fma_f32 v[224:225], v[6:7], v[220:221], v[224:225]
	v_cvt_pk_f32_fp8_e32 v[218:219], v167
	v_cvt_pk_f32_fp8_sdwa v[220:221], v167 src0_sel:WORD_1
	v_pk_fma_f32 v[222:223], v[8:9], v[214:215], v[222:223]
	v_pk_fma_f32 v[224:225], v[10:11], v[216:217], v[224:225]
	v_pk_fma_f32 v[222:223], v[12:13], v[218:219], v[222:223]
	v_pk_fma_f32 v[224:225], v[14:15], v[220:221], v[224:225]
	v_pk_add_f32 v[222:223], v[222:223], v[224:225]
	s_nop 0
	v_add_f32_e32 v231, v222, v223
	v_cvt_pk_f32_fp8_e32 v[214:215], v168
	v_cvt_pk_f32_fp8_sdwa v[216:217], v168 src0_sel:WORD_1
	v_cvt_pk_f32_fp8_e32 v[218:219], v169
	v_cvt_pk_f32_fp8_sdwa v[220:221], v169 src0_sel:WORD_1
	v_pk_mul_f32 v[222:223], v[0:1], v[214:215]
	v_pk_mul_f32 v[224:225], v[2:3], v[216:217]
	v_cvt_pk_f32_fp8_e32 v[214:215], v170
	v_cvt_pk_f32_fp8_sdwa v[216:217], v170 src0_sel:WORD_1
	v_pk_fma_f32 v[222:223], v[4:5], v[218:219], v[222:223]
	v_pk_fma_f32 v[224:225], v[6:7], v[220:221], v[224:225]
	v_cvt_pk_f32_fp8_e32 v[218:219], v171
	v_cvt_pk_f32_fp8_sdwa v[220:221], v171 src0_sel:WORD_1
	v_pk_fma_f32 v[222:223], v[8:9], v[214:215], v[222:223]
	v_pk_fma_f32 v[224:225], v[10:11], v[216:217], v[224:225]
	v_pk_fma_f32 v[222:223], v[12:13], v[218:219], v[222:223]
	v_pk_fma_f32 v[224:225], v[14:15], v[220:221], v[224:225]
	v_pk_add_f32 v[222:223], v[222:223], v[224:225]
	s_nop 0
	v_add_f32_e32 v232, v222, v223
	v_cvt_pk_f32_fp8_e32 v[214:215], v172
	v_cvt_pk_f32_fp8_sdwa v[216:217], v172 src0_sel:WORD_1
	v_cvt_pk_f32_fp8_e32 v[218:219], v173
	v_cvt_pk_f32_fp8_sdwa v[220:221], v173 src0_sel:WORD_1
	v_pk_mul_f32 v[222:223], v[0:1], v[214:215]
	v_pk_mul_f32 v[224:225], v[2:3], v[216:217]
	v_cvt_pk_f32_fp8_e32 v[214:215], v174
	v_cvt_pk_f32_fp8_sdwa v[216:217], v174 src0_sel:WORD_1
	v_pk_fma_f32 v[222:223], v[4:5], v[218:219], v[222:223]
	v_pk_fma_f32 v[224:225], v[6:7], v[220:221], v[224:225]
	v_cvt_pk_f32_fp8_e32 v[218:219], v175
	v_cvt_pk_f32_fp8_sdwa v[220:221], v175 src0_sel:WORD_1
	v_pk_fma_f32 v[222:223], v[8:9], v[214:215], v[222:223]
	v_pk_fma_f32 v[224:225], v[10:11], v[216:217], v[224:225]
	v_pk_fma_f32 v[222:223], v[12:13], v[218:219], v[222:223]
	v_pk_fma_f32 v[224:225], v[14:15], v[220:221], v[224:225]
	v_pk_add_f32 v[222:223], v[222:223], v[224:225]
	s_nop 0
	v_add_f32_e32 v233, v222, v223
	v_permlane32_swap_b32_e32 v226, v230
	v_permlane32_swap_b32_e32 v227, v231
	v_permlane32_swap_b32_e32 v228, v232
	v_permlane32_swap_b32_e32 v229, v233
	v_add_f32_e32 v226, v226, v230
	v_add_f32_e32 v228, v228, v232
	v_add_f32_e32 v227, v227, v231
	v_add_f32_e32 v229, v229, v233
	s_nop 1
	v_permlane16_swap_b32_e32 v226, v228
	v_permlane16_swap_b32_e32 v227, v229
	v_add_f32_e32 v226, v226, v228
	v_add_f32_e32 v227, v227, v229
	s_nop 0
	v_cndmask_b32_e64 v230, v226, v227, s[24:25]
	v_cndmask_b32_e64 v231, v227, v226, s[24:25]
	s_nop 1
	v_add_f32_dpp v232, v231, v230 row_ror:8 row_mask:0xf bank_mask:0xf
	s_nop 1
	v_add_f32_dpp v233, v232, v232 quad_perm:[1,0,3,2] row_mask:0xf bank_mask:0xf
	s_nop 1
	v_add_f32_dpp v232, v233, v233 quad_perm:[2,3,0,1] row_mask:0xf bank_mask:0xf
	s_nop 1
	v_add_f32_dpp v233, v232, v232 row_half_mirror row_mask:0xf bank_mask:0xf
	ds_write_b32 v235, v233 offset:32768
	v_readlane_b32 s48, v129, s72
	v_readlane_b32 s49, v129, s73
	v_readlane_b32 s50, v129, s74
	v_readlane_b32 s51, v129, s75
	v_readlane_b32 s52, v129, s76
	v_readlane_b32 s53, v129, s77
	v_readlane_b32 s54, v129, s78
	v_readlane_b32 s55, v129, s79
	s_add_u32 s32, s0, s48
	s_addc_u32 s33, s1, 0
	s_add_u32 s34, s0, s49
	s_addc_u32 s35, s1, 0
	s_add_u32 s36, s0, s50
	s_addc_u32 s37, s1, 0
	s_add_u32 s38, s0, s51
	s_addc_u32 s39, s1, 0
	s_add_u32 s40, s0, s52
	s_addc_u32 s41, s1, 0
	s_add_u32 s42, s0, s53
	s_addc_u32 s43, s1, 0
	s_add_u32 s44, s0, s54
	s_addc_u32 s45, s1, 0
	s_add_u32 s46, s0, s55
	s_addc_u32 s47, s1, 0
	global_load_dwordx4 v[144:147], v234, s[32:33]
	global_load_dwordx4 v[148:151], v234, s[34:35]
	global_load_dwordx4 v[152:155], v234, s[36:37]
	global_load_dwordx4 v[156:159], v234, s[38:39]
	global_load_dwordx4 v[160:163], v234, s[40:41]
	global_load_dwordx4 v[164:167], v234, s[42:43]
	global_load_dwordx4 v[168:171], v234, s[44:45]
	global_load_dwordx4 v[172:175], v234, s[46:47]
	s_waitcnt vmcnt(24)
; template <bool STORE>
; DI void peer_item(const Params& p, int item, char* smem) {
;     ...
; #pragma unroll 2
;     for (int k = 0; k < 128; k += 8) {
;       u32x4 uq[8];
;       const int emine = e_s[tl * 128 + k + (lane >> 3)];
;       const float gmine = g_s[tl * 128 + k + (lane >> 3)];
;       const float su = SU[emine], sv = SV[emine];
; #pragma unroll
;       for (int u = 0; u < 8; ++u) {
;         int e = e_s[tl * 128 + k + u];
;         uq[u] = *(const u32x4*)(U8 + (size_t)e * 1024 + lane * 16);
;       }
;       float part[8];
; #pragma unroll
;       for (int u = 0; u < 8; ++u) {
;         float d = 0.f;
; #pragma unroll
;         for (int i = 0; i < 4; ++i) {
;           f32x2_t lo = __builtin_amdgcn_cvt_pk_f32_fp8((int)uq[u][i], false);
;           f32x2_t hi = __builtin_amdgcn_cvt_pk_f32_fp8((int)uq[u][i], true);
;           d += xf[4 * i] * lo.x + xf[4 * i + 1] * lo.y + xf[4 * i + 2] * hi.x + xf[4 * i + 3] * hi.y;
;         }
;         part[u] = d;
;       }
	v_cvt_pk_f32_fp8_e32 v[214:215], v176
	v_cvt_pk_f32_fp8_sdwa v[216:217], v176 src0_sel:WORD_1
	v_cvt_pk_f32_fp8_e32 v[218:219], v177
	v_cvt_pk_f32_fp8_sdwa v[220:221], v177 src0_sel:WORD_1
	v_pk_mul_f32 v[222:223], v[16:17], v[214:215]
	v_pk_mul_f32 v[224:225], v[18:19], v[216:217]
	v_cvt_pk_f32_fp8_e32 v[214:215], v178
	v_cvt_pk_f32_fp8_sdwa v[216:217], v178 src0_sel:WORD_1
	v_pk_fma_f32 v[222:223], v[20:21], v[218:219], v[222:223]
	v_pk_fma_f32 v[224:225], v[22:23], v[220:221], v[224:225]
	v_cvt_pk_f32_fp8_e32 v[218:219], v179
	v_cvt_pk_f32_fp8_sdwa v[220:221], v179 src0_sel:WORD_1
	v_pk_fma_f32 v[222:223], v[24:25], v[214:215], v[222:223]
	v_pk_fma_f32 v[224:225], v[26:27], v[216:217], v[224:225]
	v_pk_fma_f32 v[222:223], v[28:29], v[218:219], v[222:223]
	v_pk_fma_f32 v[224:225], v[30:31], v[220:221], v[224:225]
	v_pk_add_f32 v[222:223], v[222:223], v[224:225]
	s_nop 0
	v_add_f32_e32 v226, v222, v223
	v_cvt_pk_f32_fp8_e32 v[214:215], v180
	v_cvt_pk_f32_fp8_sdwa v[216:217], v180 src0_sel:WORD_1
	v_cvt_pk_f32_fp8_e32 v[218:219], v181
	v_cvt_pk_f32_fp8_sdwa v[220:221], v181 src0_sel:WORD_1
	v_pk_mul_f32 v[222:223], v[16:17], v[214:215]
	v_pk_mul_f32 v[224:225], v[18:19], v[216:217]
	v_cvt_pk_f32_fp8_e32 v[214:215], v182
	v_cvt_pk_f32_fp8_sdwa v[216:217], v182 src0_sel:WORD_1
	v_pk_fma_f32 v[222:223], v[20:21], v[218:219], v[222:223]
	v_pk_fma_f32 v[224:225], v[22:23], v[220:221], v[224:225]
	v_cvt_pk_f32_fp8_e32 v[218:219], v183
	v_cvt_pk_f32_fp8_sdwa v[220:221], v183 src0_sel:WORD_1
	v_pk_fma_f32 v[222:223], v[24:25], v[214:215], v[222:223]
	v_pk_fma_f32 v[224:225], v[26:27], v[216:217], v[224:225]
	v_pk_fma_f32 v[222:223], v[28:29], v[218:219], v[222:223]
	v_pk_fma_f32 v[224:225], v[30:31], v[220:221], v[224:225]
	v_pk_add_f32 v[222:223], v[222:223], v[224:225]
	s_nop 0
	v_add_f32_e32 v227, v222, v223
	v_cvt_pk_f32_fp8_e32 v[214:215], v184
	v_cvt_pk_f32_fp8_sdwa v[216:217], v184 src0_sel:WORD_1
	v_cvt_pk_f32_fp8_e32 v[218:219], v185
	v_cvt_pk_f32_fp8_sdwa v[220:221], v185 src0_sel:WORD_1
	v_pk_mul_f32 v[222:223], v[16:17], v[214:215]
	v_pk_mul_f32 v[224:225], v[18:19], v[216:217]
	v_cvt_pk_f32_fp8_e32 v[214:215], v186
	v_cvt_pk_f32_fp8_sdwa v[216:217], v186 src0_sel:WORD_1
	v_pk_fma_f32 v[222:223], v[20:21], v[218:219], v[222:223]
	v_pk_fma_f32 v[224:225], v[22:23], v[220:221], v[224:225]
	v_cvt_pk_f32_fp8_e32 v[218:219], v187
	v_cvt_pk_f32_fp8_sdwa v[220:221], v187 src0_sel:WORD_1
	v_pk_fma_f32 v[222:223], v[24:25], v[214:215], v[222:223]
	v_pk_fma_f32 v[224:225], v[26:27], v[216:217], v[224:225]
	v_pk_fma_f32 v[222:223], v[28:29], v[218:219], v[222:223]
	v_pk_fma_f32 v[224:225], v[30:31], v[220:221], v[224:225]
	v_pk_add_f32 v[222:223], v[222:223], v[224:225]
	s_nop 0
	v_add_f32_e32 v228, v222, v223
	v_cvt_pk_f32_fp8_e32 v[214:215], v188
	v_cvt_pk_f32_fp8_sdwa v[216:217], v188 src0_sel:WORD_1
	v_cvt_pk_f32_fp8_e32 v[218:219], v189
	v_cvt_pk_f32_fp8_sdwa v[220:221], v189 src0_sel:WORD_1
	v_pk_mul_f32 v[222:223], v[16:17], v[214:215]
	v_pk_mul_f32 v[224:225], v[18:19], v[216:217]
	v_cvt_pk_f32_fp8_e32 v[214:215], v190
	v_cvt_pk_f32_fp8_sdwa v[216:217], v190 src0_sel:WORD_1
	v_pk_fma_f32 v[222:223], v[20:21], v[218:219], v[222:223]
	v_pk_fma_f32 v[224:225], v[22:23], v[220:221], v[224:225]
	v_cvt_pk_f32_fp8_e32 v[218:219], v191
	v_cvt_pk_f32_fp8_sdwa v[220:221], v191 src0_sel:WORD_1
	v_pk_fma_f32 v[222:223], v[24:25], v[214:215], v[222:223]
	v_pk_fma_f32 v[224:225], v[26:27], v[216:217], v[224:225]
	v_pk_fma_f32 v[222:223], v[28:29], v[218:219], v[222:223]
	v_pk_fma_f32 v[224:225], v[30:31], v[220:221], v[224:225]
	v_pk_add_f32 v[222:223], v[222:223], v[224:225]
	s_nop 0
	v_add_f32_e32 v229, v222, v223
	v_cvt_pk_f32_fp8_e32 v[214:215], v192
	v_cvt_pk_f32_fp8_sdwa v[216:217], v192 src0_sel:WORD_1
	v_cvt_pk_f32_fp8_e32 v[218:219], v193
	v_cvt_pk_f32_fp8_sdwa v[220:221], v193 src0_sel:WORD_1
	v_pk_mul_f32 v[222:223], v[16:17], v[214:215]
	v_pk_mul_f32 v[224:225], v[18:19], v[216:217]
	v_cvt_pk_f32_fp8_e32 v[214:215], v194
	v_cvt_pk_f32_fp8_sdwa v[216:217], v194 src0_sel:WORD_1
	v_pk_fma_f32 v[222:223], v[20:21], v[218:219], v[222:223]
	v_pk_fma_f32 v[224:225], v[22:23], v[220:221], v[224:225]
	v_cvt_pk_f32_fp8_e32 v[218:219], v195
	v_cvt_pk_f32_fp8_sdwa v[220:221], v195 src0_sel:WORD_1
	v_pk_fma_f32 v[222:223], v[24:25], v[214:215], v[222:223]
	v_pk_fma_f32 v[224:225], v[26:27], v[216:217], v[224:225]
	v_pk_fma_f32 v[222:223], v[28:29], v[218:219], v[222:223]
	v_pk_fma_f32 v[224:225], v[30:31], v[220:221], v[224:225]
	v_pk_add_f32 v[222:223], v[222:223], v[224:225]
	s_nop 0
	v_add_f32_e32 v230, v222, v223
	v_cvt_pk_f32_fp8_e32 v[214:215], v196
	v_cvt_pk_f32_fp8_sdwa v[216:217], v196 src0_sel:WORD_1
	v_cvt_pk_f32_fp8_e32 v[218:219], v197
	v_cvt_pk_f32_fp8_sdwa v[220:221], v197 src0_sel:WORD_1
	v_pk_mul_f32 v[222:223], v[16:17], v[214:215]
	v_pk_mul_f32 v[224:225], v[18:19], v[216:217]
	v_cvt_pk_f32_fp8_e32 v[214:215], v198
	v_cvt_pk_f32_fp8_sdwa v[216:217], v198 src0_sel:WORD_1
	v_pk_fma_f32 v[222:223], v[20:21], v[218:219], v[222:223]
	v_pk_fma_f32 v[224:225], v[22:23], v[220:221], v[224:225]
	v_cvt_pk_f32_fp8_e32 v[218:219], v199
	v_cvt_pk_f32_fp8_sdwa v[220:221], v199 src0_sel:WORD_1
	v_pk_fma_f32 v[222:223], v[24:25], v[214:215], v[222:223]
	v_pk_fma_f32 v[224:225], v[26:27], v[216:217], v[224:225]
	v_pk_fma_f32 v[222:223], v[28:29], v[218:219], v[222:223]
	v_pk_fma_f32 v[224:225], v[30:31], v[220:221], v[224:225]
	v_pk_add_f32 v[222:223], v[222:223], v[224:225]
	s_nop 0
	v_add_f32_e32 v231, v222, v223
	v_cvt_pk_f32_fp8_e32 v[214:215], v200
	v_cvt_pk_f32_fp8_sdwa v[216:217], v200 src0_sel:WORD_1
	v_cvt_pk_f32_fp8_e32 v[218:219], v201
; DI float gelu_exact(float x) { return 0.5f * x * (1.f + erff(x * 0.7071067811865476f)); }
; template <bool STORE>
; DI void peer_item(const Params& p, int item, char* smem) {
;     ...
;       float q4[4], r2[2], h;
; #pragma unroll
;       for (int j = 0; j < 4; ++j) {
;         float mine = b5 ? part[j + 4] : part[j];
;         float other = b5 ? part[j] : part[j + 4];
;         q4[j] = mine + __shfl_xor(other, 32);
;       }
; #pragma unroll
;       for (int j = 0; j < 2; ++j) {
;         float mine = b4 ? q4[j + 2] : q4[j];
;         float other = b4 ? q4[j] : q4[j + 2];
;         r2[j] = mine + __shfl_xor(other, 16);
;       }
;       {
;         float mine = b3 ? r2[1] : r2[0];
;         float other = b3 ? r2[0] : r2[1];
;         h = mine + __shfl_xor(other, 8);
;       }
;       h += __shfl_xor(h, 4);
;       h += __shfl_xor(h, 2);
;       h += __shfl_xor(h, 1);
;       const float amine = gelu_exact(h * su) * gmine * sv;
;       if ((lane & 7) == 0) {
;         EG[tok * 128 + k + (lane >> 3)] = emine;
;         AG[tok * 128 + k + (lane >> 3)] = amine;
;       }
;     }
	v_cvt_pk_f32_fp8_sdwa v[220:221], v201 src0_sel:WORD_1
	v_pk_mul_f32 v[222:223], v[16:17], v[214:215]
	v_pk_mul_f32 v[224:225], v[18:19], v[216:217]
	v_cvt_pk_f32_fp8_e32 v[214:215], v202
	v_cvt_pk_f32_fp8_sdwa v[216:217], v202 src0_sel:WORD_1
	v_pk_fma_f32 v[222:223], v[20:21], v[218:219], v[222:223]
	v_pk_fma_f32 v[224:225], v[22:23], v[220:221], v[224:225]
	v_cvt_pk_f32_fp8_e32 v[218:219], v203
	v_cvt_pk_f32_fp8_sdwa v[220:221], v203 src0_sel:WORD_1
	v_pk_fma_f32 v[222:223], v[24:25], v[214:215], v[222:223]
	v_pk_fma_f32 v[224:225], v[26:27], v[216:217], v[224:225]
	v_pk_fma_f32 v[222:223], v[28:29], v[218:219], v[222:223]
	v_pk_fma_f32 v[224:225], v[30:31], v[220:221], v[224:225]
	v_pk_add_f32 v[222:223], v[222:223], v[224:225]
	s_nop 0
	v_add_f32_e32 v232, v222, v223
	v_cvt_pk_f32_fp8_e32 v[214:215], v204
	v_cvt_pk_f32_fp8_sdwa v[216:217], v204 src0_sel:WORD_1
	v_cvt_pk_f32_fp8_e32 v[218:219], v205
	v_cvt_pk_f32_fp8_sdwa v[220:221], v205 src0_sel:WORD_1
	v_pk_mul_f32 v[222:223], v[16:17], v[214:215]
	v_pk_mul_f32 v[224:225], v[18:19], v[216:217]
	v_cvt_pk_f32_fp8_e32 v[214:215], v206
	v_cvt_pk_f32_fp8_sdwa v[216:217], v206 src0_sel:WORD_1
	v_pk_fma_f32 v[222:223], v[20:21], v[218:219], v[222:223]
	v_pk_fma_f32 v[224:225], v[22:23], v[220:221], v[224:225]
	v_cvt_pk_f32_fp8_e32 v[218:219], v207
	v_cvt_pk_f32_fp8_sdwa v[220:221], v207 src0_sel:WORD_1
	v_pk_fma_f32 v[222:223], v[24:25], v[214:215], v[222:223]
	v_pk_fma_f32 v[224:225], v[26:27], v[216:217], v[224:225]
	v_pk_fma_f32 v[222:223], v[28:29], v[218:219], v[222:223]
	v_pk_fma_f32 v[224:225], v[30:31], v[220:221], v[224:225]
	v_pk_add_f32 v[222:223], v[222:223], v[224:225]
	s_nop 0
	v_add_f32_e32 v233, v222, v223
	v_permlane32_swap_b32_e32 v226, v230
	v_permlane32_swap_b32_e32 v227, v231
	v_permlane32_swap_b32_e32 v228, v232
	v_permlane32_swap_b32_e32 v229, v233
	v_add_f32_e32 v226, v226, v230
	v_add_f32_e32 v228, v228, v232
	v_add_f32_e32 v227, v227, v231
	v_add_f32_e32 v229, v229, v233
	s_nop 1
	v_permlane16_swap_b32_e32 v226, v228
	v_permlane16_swap_b32_e32 v227, v229
	v_add_f32_e32 v226, v226, v228
	v_add_f32_e32 v227, v227, v229
	s_nop 0
	v_cndmask_b32_e64 v230, v226, v227, s[24:25]
	v_cndmask_b32_e64 v231, v227, v226, s[24:25]
	s_nop 1
	v_add_f32_dpp v232, v231, v230 row_ror:8 row_mask:0xf bank_mask:0xf
	s_nop 1
	v_add_f32_dpp v233, v232, v232 quad_perm:[1,0,3,2] row_mask:0xf bank_mask:0xf
	s_nop 1
	v_add_f32_dpp v232, v233, v233 quad_perm:[2,3,0,1] row_mask:0xf bank_mask:0xf
	s_nop 1
	v_add_f32_dpp v233, v232, v232 row_half_mirror row_mask:0xf bank_mask:0xf
	ds_write_b32 v235, v233 offset:33280
	v_readlane_b32 s48, v131, s72
	v_readlane_b32 s49, v131, s73
	v_readlane_b32 s50, v131, s74
	v_readlane_b32 s51, v131, s75
	v_readlane_b32 s52, v131, s76
	v_readlane_b32 s53, v131, s77
	v_readlane_b32 s54, v131, s78
	v_readlane_b32 s55, v131, s79
	s_add_u32 s32, s0, s48
	s_addc_u32 s33, s1, 0
	s_add_u32 s34, s0, s49
	s_addc_u32 s35, s1, 0
	s_add_u32 s36, s0, s50
	s_addc_u32 s37, s1, 0
	s_add_u32 s38, s0, s51
	s_addc_u32 s39, s1, 0
	s_add_u32 s40, s0, s52
	s_addc_u32 s41, s1, 0
	s_add_u32 s42, s0, s53
	s_addc_u32 s43, s1, 0
	s_add_u32 s44, s0, s54
	s_addc_u32 s45, s1, 0
	s_add_u32 s46, s0, s55
	s_addc_u32 s47, s1, 0
	global_load_dwordx4 v[176:179], v234, s[32:33]
	global_load_dwordx4 v[180:183], v234, s[34:35]
	global_load_dwordx4 v[184:187], v234, s[36:37]
	global_load_dwordx4 v[188:191], v234, s[38:39]
	global_load_dwordx4 v[192:195], v234, s[40:41]
	global_load_dwordx4 v[196:199], v234, s[42:43]
	global_load_dwordx4 v[200:203], v234, s[44:45]
	global_load_dwordx4 v[204:207], v234, s[46:47]
	s_waitcnt vmcnt(24)
	v_cvt_pk_f32_fp8_e32 v[214:215], v64
	v_cvt_pk_f32_fp8_sdwa v[216:217], v64 src0_sel:WORD_1
	v_cvt_pk_f32_fp8_e32 v[218:219], v65
	v_cvt_pk_f32_fp8_sdwa v[220:221], v65 src0_sel:WORD_1
	v_pk_mul_f32 v[222:223], v[32:33], v[214:215]
	v_pk_mul_f32 v[224:225], v[34:35], v[216:217]
	v_cvt_pk_f32_fp8_e32 v[214:215], v66
	v_cvt_pk_f32_fp8_sdwa v[216:217], v66 src0_sel:WORD_1
	v_pk_fma_f32 v[222:223], v[36:37], v[218:219], v[222:223]
	v_pk_fma_f32 v[224:225], v[38:39], v[220:221], v[224:225]
	v_cvt_pk_f32_fp8_e32 v[218:219], v67
	v_cvt_pk_f32_fp8_sdwa v[220:221], v67 src0_sel:WORD_1
	v_pk_fma_f32 v[222:223], v[40:41], v[214:215], v[222:223]
	v_pk_fma_f32 v[224:225], v[42:43], v[216:217], v[224:225]
	v_pk_fma_f32 v[222:223], v[44:45], v[218:219], v[222:223]
	v_pk_fma_f32 v[224:225], v[46:47], v[220:221], v[224:225]
	v_pk_add_f32 v[222:223], v[222:223], v[224:225]
	s_nop 0
	v_add_f32_e32 v226, v222, v223
	v_cvt_pk_f32_fp8_e32 v[214:215], v68
	v_cvt_pk_f32_fp8_sdwa v[216:217], v68 src0_sel:WORD_1
	v_cvt_pk_f32_fp8_e32 v[218:219], v69
	v_cvt_pk_f32_fp8_sdwa v[220:221], v69 src0_sel:WORD_1
	v_pk_mul_f32 v[222:223], v[32:33], v[214:215]
	v_pk_mul_f32 v[224:225], v[34:35], v[216:217]
	v_cvt_pk_f32_fp8_e32 v[214:215], v70
	v_cvt_pk_f32_fp8_sdwa v[216:217], v70 src0_sel:WORD_1
	v_pk_fma_f32 v[222:223], v[36:37], v[218:219], v[222:223]
	v_pk_fma_f32 v[224:225], v[38:39], v[220:221], v[224:225]
	v_cvt_pk_f32_fp8_e32 v[218:219], v71
	v_cvt_pk_f32_fp8_sdwa v[220:221], v71 src0_sel:WORD_1
	v_pk_fma_f32 v[222:223], v[40:41], v[214:215], v[222:223]
	v_pk_fma_f32 v[224:225], v[42:43], v[216:217], v[224:225]
	v_pk_fma_f32 v[222:223], v[44:45], v[218:219], v[222:223]
	v_pk_fma_f32 v[224:225], v[46:47], v[220:221], v[224:225]
	v_pk_add_f32 v[222:223], v[222:223], v[224:225]
	s_nop 0
	v_add_f32_e32 v227, v222, v223
	v_cvt_pk_f32_fp8_e32 v[214:215], v72
	v_cvt_pk_f32_fp8_sdwa v[216:217], v72 src0_sel:WORD_1
	v_cvt_pk_f32_fp8_e32 v[218:219], v73
	v_cvt_pk_f32_fp8_sdwa v[220:221], v73 src0_sel:WORD_1
; template <bool STORE>
; DI void peer_item(const Params& p, int item, char* smem) {
;     ...
;       float part[8];
; #pragma unroll
;       for (int u = 0; u < 8; ++u) {
;         float d = 0.f;
; #pragma unroll
;         for (int i = 0; i < 4; ++i) {
;           f32x2_t lo = __builtin_amdgcn_cvt_pk_f32_fp8((int)uq[u][i], false);
;           f32x2_t hi = __builtin_amdgcn_cvt_pk_f32_fp8((int)uq[u][i], true);
;           d += xf[4 * i] * lo.x + xf[4 * i + 1] * lo.y + xf[4 * i + 2] * hi.x + xf[4 * i + 3] * hi.y;
;         }
;         part[u] = d;
;       }
;       float q4[4], r2[2], h;
; #pragma unroll
;       for (int j = 0; j < 4; ++j) {
;         float mine = b5 ? part[j + 4] : part[j];
;         float other = b5 ? part[j] : part[j + 4];
;         q4[j] = mine + __shfl_xor(other, 32);
;       }
	v_pk_mul_f32 v[222:223], v[32:33], v[214:215]
	v_pk_mul_f32 v[224:225], v[34:35], v[216:217]
	v_cvt_pk_f32_fp8_e32 v[214:215], v74
	v_cvt_pk_f32_fp8_sdwa v[216:217], v74 src0_sel:WORD_1
	v_pk_fma_f32 v[222:223], v[36:37], v[218:219], v[222:223]
	v_pk_fma_f32 v[224:225], v[38:39], v[220:221], v[224:225]
	v_cvt_pk_f32_fp8_e32 v[218:219], v75
	v_cvt_pk_f32_fp8_sdwa v[220:221], v75 src0_sel:WORD_1
	v_pk_fma_f32 v[222:223], v[40:41], v[214:215], v[222:223]
	v_pk_fma_f32 v[224:225], v[42:43], v[216:217], v[224:225]
	v_pk_fma_f32 v[222:223], v[44:45], v[218:219], v[222:223]
	v_pk_fma_f32 v[224:225], v[46:47], v[220:221], v[224:225]
	v_pk_add_f32 v[222:223], v[222:223], v[224:225]
	s_nop 0
	v_add_f32_e32 v228, v222, v223
	v_cvt_pk_f32_fp8_e32 v[214:215], v76
	v_cvt_pk_f32_fp8_sdwa v[216:217], v76 src0_sel:WORD_1
	v_cvt_pk_f32_fp8_e32 v[218:219], v77
	v_cvt_pk_f32_fp8_sdwa v[220:221], v77 src0_sel:WORD_1
	v_pk_mul_f32 v[222:223], v[32:33], v[214:215]
	v_pk_mul_f32 v[224:225], v[34:35], v[216:217]
	v_cvt_pk_f32_fp8_e32 v[214:215], v78
	v_cvt_pk_f32_fp8_sdwa v[216:217], v78 src0_sel:WORD_1
	v_pk_fma_f32 v[222:223], v[36:37], v[218:219], v[222:223]
	v_pk_fma_f32 v[224:225], v[38:39], v[220:221], v[224:225]
	v_cvt_pk_f32_fp8_e32 v[218:219], v79
	v_cvt_pk_f32_fp8_sdwa v[220:221], v79 src0_sel:WORD_1
	v_pk_fma_f32 v[222:223], v[40:41], v[214:215], v[222:223]
	v_pk_fma_f32 v[224:225], v[42:43], v[216:217], v[224:225]
	v_pk_fma_f32 v[222:223], v[44:45], v[218:219], v[222:223]
	v_pk_fma_f32 v[224:225], v[46:47], v[220:221], v[224:225]
	v_pk_add_f32 v[222:223], v[222:223], v[224:225]
	s_nop 0
	v_add_f32_e32 v229, v222, v223
	v_cvt_pk_f32_fp8_e32 v[214:215], v80
	v_cvt_pk_f32_fp8_sdwa v[216:217], v80 src0_sel:WORD_1
	v_cvt_pk_f32_fp8_e32 v[218:219], v81
	v_cvt_pk_f32_fp8_sdwa v[220:221], v81 src0_sel:WORD_1
	v_pk_mul_f32 v[222:223], v[32:33], v[214:215]
	v_pk_mul_f32 v[224:225], v[34:35], v[216:217]
	v_cvt_pk_f32_fp8_e32 v[214:215], v82
	v_cvt_pk_f32_fp8_sdwa v[216:217], v82 src0_sel:WORD_1
	v_pk_fma_f32 v[222:223], v[36:37], v[218:219], v[222:223]
	v_pk_fma_f32 v[224:225], v[38:39], v[220:221], v[224:225]
	v_cvt_pk_f32_fp8_e32 v[218:219], v83
	v_cvt_pk_f32_fp8_sdwa v[220:221], v83 src0_sel:WORD_1
	v_pk_fma_f32 v[222:223], v[40:41], v[214:215], v[222:223]
	v_pk_fma_f32 v[224:225], v[42:43], v[216:217], v[224:225]
	v_pk_fma_f32 v[222:223], v[44:45], v[218:219], v[222:223]
	v_pk_fma_f32 v[224:225], v[46:47], v[220:221], v[224:225]
	v_pk_add_f32 v[222:223], v[222:223], v[224:225]
	s_nop 0
	v_add_f32_e32 v230, v222, v223
	v_cvt_pk_f32_fp8_e32 v[214:215], v84
	v_cvt_pk_f32_fp8_sdwa v[216:217], v84 src0_sel:WORD_1
	v_cvt_pk_f32_fp8_e32 v[218:219], v85
	v_cvt_pk_f32_fp8_sdwa v[220:221], v85 src0_sel:WORD_1
	v_pk_mul_f32 v[222:223], v[32:33], v[214:215]
	v_pk_mul_f32 v[224:225], v[34:35], v[216:217]
	v_cvt_pk_f32_fp8_e32 v[214:215], v86
	v_cvt_pk_f32_fp8_sdwa v[216:217], v86 src0_sel:WORD_1
	v_pk_fma_f32 v[222:223], v[36:37], v[218:219], v[222:223]
	v_pk_fma_f32 v[224:225], v[38:39], v[220:221], v[224:225]
	v_cvt_pk_f32_fp8_e32 v[218:219], v87
	v_cvt_pk_f32_fp8_sdwa v[220:221], v87 src0_sel:WORD_1
	v_pk_fma_f32 v[222:223], v[40:41], v[214:215], v[222:223]
	v_pk_fma_f32 v[224:225], v[42:43], v[216:217], v[224:225]
	v_pk_fma_f32 v[222:223], v[44:45], v[218:219], v[222:223]
	v_pk_fma_f32 v[224:225], v[46:47], v[220:221], v[224:225]
	v_pk_add_f32 v[222:223], v[222:223], v[224:225]
	s_nop 0
	v_add_f32_e32 v231, v222, v223
	v_cvt_pk_f32_fp8_e32 v[214:215], v88
	v_cvt_pk_f32_fp8_sdwa v[216:217], v88 src0_sel:WORD_1
	v_cvt_pk_f32_fp8_e32 v[218:219], v89
	v_cvt_pk_f32_fp8_sdwa v[220:221], v89 src0_sel:WORD_1
	v_pk_mul_f32 v[222:223], v[32:33], v[214:215]
	v_pk_mul_f32 v[224:225], v[34:35], v[216:217]
	v_cvt_pk_f32_fp8_e32 v[214:215], v90
	v_cvt_pk_f32_fp8_sdwa v[216:217], v90 src0_sel:WORD_1
	v_pk_fma_f32 v[222:223], v[36:37], v[218:219], v[222:223]
	v_pk_fma_f32 v[224:225], v[38:39], v[220:221], v[224:225]
	v_cvt_pk_f32_fp8_e32 v[218:219], v91
	v_cvt_pk_f32_fp8_sdwa v[220:221], v91 src0_sel:WORD_1
	v_pk_fma_f32 v[222:223], v[40:41], v[214:215], v[222:223]
	v_pk_fma_f32 v[224:225], v[42:43], v[216:217], v[224:225]
	v_pk_fma_f32 v[222:223], v[44:45], v[218:219], v[222:223]
	v_pk_fma_f32 v[224:225], v[46:47], v[220:221], v[224:225]
	v_pk_add_f32 v[222:223], v[222:223], v[224:225]
	s_nop 0
	v_add_f32_e32 v232, v222, v223
	v_cvt_pk_f32_fp8_e32 v[214:215], v92
	v_cvt_pk_f32_fp8_sdwa v[216:217], v92 src0_sel:WORD_1
	v_cvt_pk_f32_fp8_e32 v[218:219], v93
	v_cvt_pk_f32_fp8_sdwa v[220:221], v93 src0_sel:WORD_1
	v_pk_mul_f32 v[222:223], v[32:33], v[214:215]
	v_pk_mul_f32 v[224:225], v[34:35], v[216:217]
	v_cvt_pk_f32_fp8_e32 v[214:215], v94
	v_cvt_pk_f32_fp8_sdwa v[216:217], v94 src0_sel:WORD_1
	v_pk_fma_f32 v[222:223], v[36:37], v[218:219], v[222:223]
	v_pk_fma_f32 v[224:225], v[38:39], v[220:221], v[224:225]
	v_cvt_pk_f32_fp8_e32 v[218:219], v95
	v_cvt_pk_f32_fp8_sdwa v[220:221], v95 src0_sel:WORD_1
	v_pk_fma_f32 v[222:223], v[40:41], v[214:215], v[222:223]
	v_pk_fma_f32 v[224:225], v[42:43], v[216:217], v[224:225]
	v_pk_fma_f32 v[222:223], v[44:45], v[218:219], v[222:223]
	v_pk_fma_f32 v[224:225], v[46:47], v[220:221], v[224:225]
	v_pk_add_f32 v[222:223], v[222:223], v[224:225]
	s_nop 0
	v_add_f32_e32 v233, v222, v223
	v_permlane32_swap_b32_e32 v226, v230
	v_permlane32_swap_b32_e32 v227, v231
	v_permlane32_swap_b32_e32 v228, v232
	v_permlane32_swap_b32_e32 v229, v233
	v_add_f32_e32 v226, v226, v230
	v_add_f32_e32 v228, v228, v232
	v_add_f32_e32 v227, v227, v231
	v_add_f32_e32 v229, v229, v233
	s_nop 1
	v_permlane16_swap_b32_e32 v226, v228
	v_permlane16_swap_b32_e32 v227, v229
; DI float gelu_exact(float x) { return 0.5f * x * (1.f + erff(x * 0.7071067811865476f)); }
; template <bool STORE>
; DI void peer_item(const Params& p, int item, char* smem) {
;     ...
;       for (int j = 0; j < 4; ++j) {
;         float mine = b5 ? part[j + 4] : part[j];
;         float other = b5 ? part[j] : part[j + 4];
;         q4[j] = mine + __shfl_xor(other, 32);
;       }
; #pragma unroll
;       for (int j = 0; j < 2; ++j) {
;         float mine = b4 ? q4[j + 2] : q4[j];
;         float other = b4 ? q4[j] : q4[j + 2];
;         r2[j] = mine + __shfl_xor(other, 16);
;       }
;       {
;         float mine = b3 ? r2[1] : r2[0];
;         float other = b3 ? r2[0] : r2[1];
;         h = mine + __shfl_xor(other, 8);
;       }
;       h += __shfl_xor(h, 4);
;       h += __shfl_xor(h, 2);
;       h += __shfl_xor(h, 1);
;       const float amine = gelu_exact(h * su) * gmine * sv;
;       if ((lane & 7) == 0) {
;         EG[tok * 128 + k + (lane >> 3)] = emine;
;         AG[tok * 128 + k + (lane >> 3)] = amine;
;       }
;     }
	v_add_f32_e32 v226, v226, v228
	v_add_f32_e32 v227, v227, v229
	s_nop 0
	v_cndmask_b32_e64 v230, v226, v227, s[24:25]
	v_cndmask_b32_e64 v231, v227, v226, s[24:25]
	s_nop 1
	v_add_f32_dpp v232, v231, v230 row_ror:8 row_mask:0xf bank_mask:0xf
	s_nop 1
	v_add_f32_dpp v233, v232, v232 quad_perm:[1,0,3,2] row_mask:0xf bank_mask:0xf
	s_nop 1
	v_add_f32_dpp v232, v233, v233 quad_perm:[2,3,0,1] row_mask:0xf bank_mask:0xf
	s_nop 1
	v_add_f32_dpp v233, v232, v232 row_half_mirror row_mask:0xf bank_mask:0xf
	ds_write_b32 v235, v233 offset:33792
	v_readlane_b32 s48, v133, s72
	v_readlane_b32 s49, v133, s73
	v_readlane_b32 s50, v133, s74
	v_readlane_b32 s51, v133, s75
	v_readlane_b32 s52, v133, s76
	v_readlane_b32 s53, v133, s77
	v_readlane_b32 s54, v133, s78
	v_readlane_b32 s55, v133, s79
	s_add_u32 s32, s0, s48
	s_addc_u32 s33, s1, 0
	s_add_u32 s34, s0, s49
	s_addc_u32 s35, s1, 0
	s_add_u32 s36, s0, s50
	s_addc_u32 s37, s1, 0
	s_add_u32 s38, s0, s51
	s_addc_u32 s39, s1, 0
	s_add_u32 s40, s0, s52
	s_addc_u32 s41, s1, 0
	s_add_u32 s42, s0, s53
	s_addc_u32 s43, s1, 0
	s_add_u32 s44, s0, s54
	s_addc_u32 s45, s1, 0
	s_add_u32 s46, s0, s55
	s_addc_u32 s47, s1, 0
	global_load_dwordx4 v[64:67], v234, s[32:33]
	global_load_dwordx4 v[68:71], v234, s[34:35]
	global_load_dwordx4 v[72:75], v234, s[36:37]
	global_load_dwordx4 v[76:79], v234, s[38:39]
	global_load_dwordx4 v[80:83], v234, s[40:41]
	global_load_dwordx4 v[84:87], v234, s[42:43]
	global_load_dwordx4 v[88:91], v234, s[44:45]
	global_load_dwordx4 v[92:95], v234, s[46:47]
	s_waitcnt vmcnt(24)
	v_cvt_pk_f32_fp8_e32 v[214:215], v96
	v_cvt_pk_f32_fp8_sdwa v[216:217], v96 src0_sel:WORD_1
	v_cvt_pk_f32_fp8_e32 v[218:219], v97
	v_cvt_pk_f32_fp8_sdwa v[220:221], v97 src0_sel:WORD_1
	v_pk_mul_f32 v[222:223], v[48:49], v[214:215]
	v_pk_mul_f32 v[224:225], v[50:51], v[216:217]
	v_cvt_pk_f32_fp8_e32 v[214:215], v98
	v_cvt_pk_f32_fp8_sdwa v[216:217], v98 src0_sel:WORD_1
	v_pk_fma_f32 v[222:223], v[52:53], v[218:219], v[222:223]
	v_pk_fma_f32 v[224:225], v[54:55], v[220:221], v[224:225]
	v_cvt_pk_f32_fp8_e32 v[218:219], v99
	v_cvt_pk_f32_fp8_sdwa v[220:221], v99 src0_sel:WORD_1
	v_pk_fma_f32 v[222:223], v[56:57], v[214:215], v[222:223]
	v_pk_fma_f32 v[224:225], v[58:59], v[216:217], v[224:225]
	v_pk_fma_f32 v[222:223], v[60:61], v[218:219], v[222:223]
	v_pk_fma_f32 v[224:225], v[62:63], v[220:221], v[224:225]
	v_pk_add_f32 v[222:223], v[222:223], v[224:225]
	s_nop 0
	v_add_f32_e32 v226, v222, v223
	v_cvt_pk_f32_fp8_e32 v[214:215], v100
	v_cvt_pk_f32_fp8_sdwa v[216:217], v100 src0_sel:WORD_1
	v_cvt_pk_f32_fp8_e32 v[218:219], v101
	v_cvt_pk_f32_fp8_sdwa v[220:221], v101 src0_sel:WORD_1
	v_pk_mul_f32 v[222:223], v[48:49], v[214:215]
	v_pk_mul_f32 v[224:225], v[50:51], v[216:217]
	v_cvt_pk_f32_fp8_e32 v[214:215], v102
	v_cvt_pk_f32_fp8_sdwa v[216:217], v102 src0_sel:WORD_1
	v_pk_fma_f32 v[222:223], v[52:53], v[218:219], v[222:223]
	v_pk_fma_f32 v[224:225], v[54:55], v[220:221], v[224:225]
	v_cvt_pk_f32_fp8_e32 v[218:219], v103
	v_cvt_pk_f32_fp8_sdwa v[220:221], v103 src0_sel:WORD_1
	v_pk_fma_f32 v[222:223], v[56:57], v[214:215], v[222:223]
	v_pk_fma_f32 v[224:225], v[58:59], v[216:217], v[224:225]
	v_pk_fma_f32 v[222:223], v[60:61], v[218:219], v[222:223]
	v_pk_fma_f32 v[224:225], v[62:63], v[220:221], v[224:225]
	v_pk_add_f32 v[222:223], v[222:223], v[224:225]
	s_nop 0
	v_add_f32_e32 v227, v222, v223
	v_cvt_pk_f32_fp8_e32 v[214:215], v104
	v_cvt_pk_f32_fp8_sdwa v[216:217], v104 src0_sel:WORD_1
	v_cvt_pk_f32_fp8_e32 v[218:219], v105
	v_cvt_pk_f32_fp8_sdwa v[220:221], v105 src0_sel:WORD_1
	v_pk_mul_f32 v[222:223], v[48:49], v[214:215]
	v_pk_mul_f32 v[224:225], v[50:51], v[216:217]
	v_cvt_pk_f32_fp8_e32 v[214:215], v106
	v_cvt_pk_f32_fp8_sdwa v[216:217], v106 src0_sel:WORD_1
	v_pk_fma_f32 v[222:223], v[52:53], v[218:219], v[222:223]
	v_pk_fma_f32 v[224:225], v[54:55], v[220:221], v[224:225]
	v_cvt_pk_f32_fp8_e32 v[218:219], v107
	v_cvt_pk_f32_fp8_sdwa v[220:221], v107 src0_sel:WORD_1
	v_pk_fma_f32 v[222:223], v[56:57], v[214:215], v[222:223]
	v_pk_fma_f32 v[224:225], v[58:59], v[216:217], v[224:225]
	v_pk_fma_f32 v[222:223], v[60:61], v[218:219], v[222:223]
	v_pk_fma_f32 v[224:225], v[62:63], v[220:221], v[224:225]
	v_pk_add_f32 v[222:223], v[222:223], v[224:225]
	s_nop 0
	v_add_f32_e32 v228, v222, v223
	v_cvt_pk_f32_fp8_e32 v[214:215], v108
	v_cvt_pk_f32_fp8_sdwa v[216:217], v108 src0_sel:WORD_1
	v_cvt_pk_f32_fp8_e32 v[218:219], v109
	v_cvt_pk_f32_fp8_sdwa v[220:221], v109 src0_sel:WORD_1
	v_pk_mul_f32 v[222:223], v[48:49], v[214:215]
	v_pk_mul_f32 v[224:225], v[50:51], v[216:217]
	v_cvt_pk_f32_fp8_e32 v[214:215], v110
	v_cvt_pk_f32_fp8_sdwa v[216:217], v110 src0_sel:WORD_1
	v_pk_fma_f32 v[222:223], v[52:53], v[218:219], v[222:223]
	v_pk_fma_f32 v[224:225], v[54:55], v[220:221], v[224:225]
	v_cvt_pk_f32_fp8_e32 v[218:219], v111
	v_cvt_pk_f32_fp8_sdwa v[220:221], v111 src0_sel:WORD_1
	v_pk_fma_f32 v[222:223], v[56:57], v[214:215], v[222:223]
	v_pk_fma_f32 v[224:225], v[58:59], v[216:217], v[224:225]
	v_pk_fma_f32 v[222:223], v[60:61], v[218:219], v[222:223]
	v_pk_fma_f32 v[224:225], v[62:63], v[220:221], v[224:225]
	v_pk_add_f32 v[222:223], v[222:223], v[224:225]
	s_nop 0
	v_add_f32_e32 v229, v222, v223
	v_cvt_pk_f32_fp8_e32 v[214:215], v112
	v_cvt_pk_f32_fp8_sdwa v[216:217], v112 src0_sel:WORD_1
	v_cvt_pk_f32_fp8_e32 v[218:219], v113
	v_cvt_pk_f32_fp8_sdwa v[220:221], v113 src0_sel:WORD_1
	v_pk_mul_f32 v[222:223], v[48:49], v[214:215]
	v_pk_mul_f32 v[224:225], v[50:51], v[216:217]
	v_cvt_pk_f32_fp8_e32 v[214:215], v114
	v_cvt_pk_f32_fp8_sdwa v[216:217], v114 src0_sel:WORD_1
	v_pk_fma_f32 v[222:223], v[52:53], v[218:219], v[222:223]
; DI float gelu_exact(float x) { return 0.5f * x * (1.f + erff(x * 0.7071067811865476f)); }
; template <bool STORE>
; DI void peer_item(const Params& p, int item, char* smem) {
;     ...
;       float part[8];
; #pragma unroll
;       for (int u = 0; u < 8; ++u) {
;         float d = 0.f;
; #pragma unroll
;         for (int i = 0; i < 4; ++i) {
;           f32x2_t lo = __builtin_amdgcn_cvt_pk_f32_fp8((int)uq[u][i], false);
;           f32x2_t hi = __builtin_amdgcn_cvt_pk_f32_fp8((int)uq[u][i], true);
;           d += xf[4 * i] * lo.x + xf[4 * i + 1] * lo.y + xf[4 * i + 2] * hi.x + xf[4 * i + 3] * hi.y;
;         }
;         part[u] = d;
;       }
;       float q4[4], r2[2], h;
; #pragma unroll
;       for (int j = 0; j < 4; ++j) {
;         float mine = b5 ? part[j + 4] : part[j];
;         float other = b5 ? part[j] : part[j + 4];
;         q4[j] = mine + __shfl_xor(other, 32);
;       }
; #pragma unroll
;       for (int j = 0; j < 2; ++j) {
;         float mine = b4 ? q4[j + 2] : q4[j];
;         float other = b4 ? q4[j] : q4[j + 2];
;         r2[j] = mine + __shfl_xor(other, 16);
;       }
;       {
;         float mine = b3 ? r2[1] : r2[0];
;         float other = b3 ? r2[0] : r2[1];
;         h = mine + __shfl_xor(other, 8);
;       }
;       h += __shfl_xor(h, 4);
;       h += __shfl_xor(h, 2);
;       h += __shfl_xor(h, 1);
;       const float amine = gelu_exact(h * su) * gmine * sv;
;       if ((lane & 7) == 0) {
;         EG[tok * 128 + k + (lane >> 3)] = emine;
;         AG[tok * 128 + k + (lane >> 3)] = amine;
;       }
;     }
	v_pk_fma_f32 v[224:225], v[54:55], v[220:221], v[224:225]
	v_cvt_pk_f32_fp8_e32 v[218:219], v115
	v_cvt_pk_f32_fp8_sdwa v[220:221], v115 src0_sel:WORD_1
	v_pk_fma_f32 v[222:223], v[56:57], v[214:215], v[222:223]
	v_pk_fma_f32 v[224:225], v[58:59], v[216:217], v[224:225]
	v_pk_fma_f32 v[222:223], v[60:61], v[218:219], v[222:223]
	v_pk_fma_f32 v[224:225], v[62:63], v[220:221], v[224:225]
	v_pk_add_f32 v[222:223], v[222:223], v[224:225]
	s_nop 0
	v_add_f32_e32 v230, v222, v223
	v_cvt_pk_f32_fp8_e32 v[214:215], v116
	v_cvt_pk_f32_fp8_sdwa v[216:217], v116 src0_sel:WORD_1
	v_cvt_pk_f32_fp8_e32 v[218:219], v117
	v_cvt_pk_f32_fp8_sdwa v[220:221], v117 src0_sel:WORD_1
	v_pk_mul_f32 v[222:223], v[48:49], v[214:215]
	v_pk_mul_f32 v[224:225], v[50:51], v[216:217]
	v_cvt_pk_f32_fp8_e32 v[214:215], v118
	v_cvt_pk_f32_fp8_sdwa v[216:217], v118 src0_sel:WORD_1
	v_pk_fma_f32 v[222:223], v[52:53], v[218:219], v[222:223]
	v_pk_fma_f32 v[224:225], v[54:55], v[220:221], v[224:225]
	v_cvt_pk_f32_fp8_e32 v[218:219], v119
	v_cvt_pk_f32_fp8_sdwa v[220:221], v119 src0_sel:WORD_1
	v_pk_fma_f32 v[222:223], v[56:57], v[214:215], v[222:223]
	v_pk_fma_f32 v[224:225], v[58:59], v[216:217], v[224:225]
	v_pk_fma_f32 v[222:223], v[60:61], v[218:219], v[222:223]
	v_pk_fma_f32 v[224:225], v[62:63], v[220:221], v[224:225]
	v_pk_add_f32 v[222:223], v[222:223], v[224:225]
	s_nop 0
	v_add_f32_e32 v231, v222, v223
	v_cvt_pk_f32_fp8_e32 v[214:215], v120
	v_cvt_pk_f32_fp8_sdwa v[216:217], v120 src0_sel:WORD_1
	v_cvt_pk_f32_fp8_e32 v[218:219], v121
	v_cvt_pk_f32_fp8_sdwa v[220:221], v121 src0_sel:WORD_1
	v_pk_mul_f32 v[222:223], v[48:49], v[214:215]
	v_pk_mul_f32 v[224:225], v[50:51], v[216:217]
	v_cvt_pk_f32_fp8_e32 v[214:215], v122
	v_cvt_pk_f32_fp8_sdwa v[216:217], v122 src0_sel:WORD_1
	v_pk_fma_f32 v[222:223], v[52:53], v[218:219], v[222:223]
	v_pk_fma_f32 v[224:225], v[54:55], v[220:221], v[224:225]
	v_cvt_pk_f32_fp8_e32 v[218:219], v123
	v_cvt_pk_f32_fp8_sdwa v[220:221], v123 src0_sel:WORD_1
	v_pk_fma_f32 v[222:223], v[56:57], v[214:215], v[222:223]
	v_pk_fma_f32 v[224:225], v[58:59], v[216:217], v[224:225]
	v_pk_fma_f32 v[222:223], v[60:61], v[218:219], v[222:223]
	v_pk_fma_f32 v[224:225], v[62:63], v[220:221], v[224:225]
	v_pk_add_f32 v[222:223], v[222:223], v[224:225]
	s_nop 0
	v_add_f32_e32 v232, v222, v223
	v_cvt_pk_f32_fp8_e32 v[214:215], v124
	v_cvt_pk_f32_fp8_sdwa v[216:217], v124 src0_sel:WORD_1
	v_cvt_pk_f32_fp8_e32 v[218:219], v125
	v_cvt_pk_f32_fp8_sdwa v[220:221], v125 src0_sel:WORD_1
	v_pk_mul_f32 v[222:223], v[48:49], v[214:215]
	v_pk_mul_f32 v[224:225], v[50:51], v[216:217]
	v_cvt_pk_f32_fp8_e32 v[214:215], v126
	v_cvt_pk_f32_fp8_sdwa v[216:217], v126 src0_sel:WORD_1
	v_pk_fma_f32 v[222:223], v[52:53], v[218:219], v[222:223]
	v_pk_fma_f32 v[224:225], v[54:55], v[220:221], v[224:225]
	v_cvt_pk_f32_fp8_e32 v[218:219], v127
	v_cvt_pk_f32_fp8_sdwa v[220:221], v127 src0_sel:WORD_1
	v_pk_fma_f32 v[222:223], v[56:57], v[214:215], v[222:223]
	v_pk_fma_f32 v[224:225], v[58:59], v[216:217], v[224:225]
	v_pk_fma_f32 v[222:223], v[60:61], v[218:219], v[222:223]
	v_pk_fma_f32 v[224:225], v[62:63], v[220:221], v[224:225]
	v_pk_add_f32 v[222:223], v[222:223], v[224:225]
	s_nop 0
	v_add_f32_e32 v233, v222, v223
	v_permlane32_swap_b32_e32 v226, v230
	v_permlane32_swap_b32_e32 v227, v231
	v_permlane32_swap_b32_e32 v228, v232
	v_permlane32_swap_b32_e32 v229, v233
	v_add_f32_e32 v226, v226, v230
	v_add_f32_e32 v228, v228, v232
	v_add_f32_e32 v227, v227, v231
	v_add_f32_e32 v229, v229, v233
	s_nop 1
	v_permlane16_swap_b32_e32 v226, v228
	v_permlane16_swap_b32_e32 v227, v229
	v_add_f32_e32 v226, v226, v228
	v_add_f32_e32 v227, v227, v229
	s_nop 0
	v_cndmask_b32_e64 v230, v226, v227, s[24:25]
	v_cndmask_b32_e64 v231, v227, v226, s[24:25]
	s_nop 1
	v_add_f32_dpp v232, v231, v230 row_ror:8 row_mask:0xf bank_mask:0xf
	s_nop 1
	v_add_f32_dpp v233, v232, v232 quad_perm:[1,0,3,2] row_mask:0xf bank_mask:0xf
	s_nop 1
	v_add_f32_dpp v232, v233, v233 quad_perm:[2,3,0,1] row_mask:0xf bank_mask:0xf
	s_nop 1
	v_add_f32_dpp v233, v232, v232 row_half_mirror row_mask:0xf bank_mask:0xf
	ds_write_b32 v235, v233 offset:34304
	v_readlane_b32 s48, v135, s72
	v_readlane_b32 s49, v135, s73
	v_readlane_b32 s50, v135, s74
	v_readlane_b32 s51, v135, s75
	v_readlane_b32 s52, v135, s76
	v_readlane_b32 s53, v135, s77
	v_readlane_b32 s54, v135, s78
	v_readlane_b32 s55, v135, s79
	s_add_u32 s32, s0, s48
	s_addc_u32 s33, s1, 0
	s_add_u32 s34, s0, s49
	s_addc_u32 s35, s1, 0
	s_add_u32 s36, s0, s50
	s_addc_u32 s37, s1, 0
	s_add_u32 s38, s0, s51
	s_addc_u32 s39, s1, 0
	s_add_u32 s40, s0, s52
	s_addc_u32 s41, s1, 0
	s_add_u32 s42, s0, s53
	s_addc_u32 s43, s1, 0
	s_add_u32 s44, s0, s54
	s_addc_u32 s45, s1, 0
	s_add_u32 s46, s0, s55
	s_addc_u32 s47, s1, 0
	global_load_dwordx4 v[96:99], v234, s[32:33]
	global_load_dwordx4 v[100:103], v234, s[34:35]
	global_load_dwordx4 v[104:107], v234, s[36:37]
	global_load_dwordx4 v[108:111], v234, s[38:39]
	global_load_dwordx4 v[112:115], v234, s[40:41]
	global_load_dwordx4 v[116:119], v234, s[42:43]
	global_load_dwordx4 v[120:123], v234, s[44:45]
	global_load_dwordx4 v[124:127], v234, s[46:47]
	s_waitcnt vmcnt(24)
; template <bool STORE>
; DI void peer_item(const Params& p, int item, char* smem) {
;     ...
;       float part[8];
; #pragma unroll
;       for (int u = 0; u < 8; ++u) {
;         float d = 0.f;
; #pragma unroll
;         for (int i = 0; i < 4; ++i) {
;           f32x2_t lo = __builtin_amdgcn_cvt_pk_f32_fp8((int)uq[u][i], false);
;           f32x2_t hi = __builtin_amdgcn_cvt_pk_f32_fp8((int)uq[u][i], true);
;           d += xf[4 * i] * lo.x + xf[4 * i + 1] * lo.y + xf[4 * i + 2] * hi.x + xf[4 * i + 3] * hi.y;
;         }
;         part[u] = d;
;       }
	v_cvt_pk_f32_fp8_e32 v[214:215], v144
	v_cvt_pk_f32_fp8_sdwa v[216:217], v144 src0_sel:WORD_1
	v_cvt_pk_f32_fp8_e32 v[218:219], v145
	v_cvt_pk_f32_fp8_sdwa v[220:221], v145 src0_sel:WORD_1
	v_pk_mul_f32 v[222:223], v[0:1], v[214:215]
	v_pk_mul_f32 v[224:225], v[2:3], v[216:217]
	v_cvt_pk_f32_fp8_e32 v[214:215], v146
	v_cvt_pk_f32_fp8_sdwa v[216:217], v146 src0_sel:WORD_1
	v_pk_fma_f32 v[222:223], v[4:5], v[218:219], v[222:223]
	v_pk_fma_f32 v[224:225], v[6:7], v[220:221], v[224:225]
	v_cvt_pk_f32_fp8_e32 v[218:219], v147
	v_cvt_pk_f32_fp8_sdwa v[220:221], v147 src0_sel:WORD_1
	v_pk_fma_f32 v[222:223], v[8:9], v[214:215], v[222:223]
	v_pk_fma_f32 v[224:225], v[10:11], v[216:217], v[224:225]
	v_pk_fma_f32 v[222:223], v[12:13], v[218:219], v[222:223]
	v_pk_fma_f32 v[224:225], v[14:15], v[220:221], v[224:225]
	v_pk_add_f32 v[222:223], v[222:223], v[224:225]
	s_nop 0
	v_add_f32_e32 v226, v222, v223
	v_cvt_pk_f32_fp8_e32 v[214:215], v148
	v_cvt_pk_f32_fp8_sdwa v[216:217], v148 src0_sel:WORD_1
	v_cvt_pk_f32_fp8_e32 v[218:219], v149
	v_cvt_pk_f32_fp8_sdwa v[220:221], v149 src0_sel:WORD_1
	v_pk_mul_f32 v[222:223], v[0:1], v[214:215]
	v_pk_mul_f32 v[224:225], v[2:3], v[216:217]
	v_cvt_pk_f32_fp8_e32 v[214:215], v150
	v_cvt_pk_f32_fp8_sdwa v[216:217], v150 src0_sel:WORD_1
	v_pk_fma_f32 v[222:223], v[4:5], v[218:219], v[222:223]
	v_pk_fma_f32 v[224:225], v[6:7], v[220:221], v[224:225]
	v_cvt_pk_f32_fp8_e32 v[218:219], v151
	v_cvt_pk_f32_fp8_sdwa v[220:221], v151 src0_sel:WORD_1
	v_pk_fma_f32 v[222:223], v[8:9], v[214:215], v[222:223]
	v_pk_fma_f32 v[224:225], v[10:11], v[216:217], v[224:225]
	v_pk_fma_f32 v[222:223], v[12:13], v[218:219], v[222:223]
	v_pk_fma_f32 v[224:225], v[14:15], v[220:221], v[224:225]
	v_pk_add_f32 v[222:223], v[222:223], v[224:225]
	s_nop 0
	v_add_f32_e32 v227, v222, v223
	v_cvt_pk_f32_fp8_e32 v[214:215], v152
	v_cvt_pk_f32_fp8_sdwa v[216:217], v152 src0_sel:WORD_1
	v_cvt_pk_f32_fp8_e32 v[218:219], v153
	v_cvt_pk_f32_fp8_sdwa v[220:221], v153 src0_sel:WORD_1
	v_pk_mul_f32 v[222:223], v[0:1], v[214:215]
	v_pk_mul_f32 v[224:225], v[2:3], v[216:217]
	v_cvt_pk_f32_fp8_e32 v[214:215], v154
	v_cvt_pk_f32_fp8_sdwa v[216:217], v154 src0_sel:WORD_1
	v_pk_fma_f32 v[222:223], v[4:5], v[218:219], v[222:223]
	v_pk_fma_f32 v[224:225], v[6:7], v[220:221], v[224:225]
	v_cvt_pk_f32_fp8_e32 v[218:219], v155
	v_cvt_pk_f32_fp8_sdwa v[220:221], v155 src0_sel:WORD_1
	v_pk_fma_f32 v[222:223], v[8:9], v[214:215], v[222:223]
	v_pk_fma_f32 v[224:225], v[10:11], v[216:217], v[224:225]
	v_pk_fma_f32 v[222:223], v[12:13], v[218:219], v[222:223]
	v_pk_fma_f32 v[224:225], v[14:15], v[220:221], v[224:225]
	v_pk_add_f32 v[222:223], v[222:223], v[224:225]
	s_nop 0
	v_add_f32_e32 v228, v222, v223
	v_cvt_pk_f32_fp8_e32 v[214:215], v156
	v_cvt_pk_f32_fp8_sdwa v[216:217], v156 src0_sel:WORD_1
	v_cvt_pk_f32_fp8_e32 v[218:219], v157
	v_cvt_pk_f32_fp8_sdwa v[220:221], v157 src0_sel:WORD_1
	v_pk_mul_f32 v[222:223], v[0:1], v[214:215]
	v_pk_mul_f32 v[224:225], v[2:3], v[216:217]
	v_cvt_pk_f32_fp8_e32 v[214:215], v158
	v_cvt_pk_f32_fp8_sdwa v[216:217], v158 src0_sel:WORD_1
	v_pk_fma_f32 v[222:223], v[4:5], v[218:219], v[222:223]
	v_pk_fma_f32 v[224:225], v[6:7], v[220:221], v[224:225]
	v_cvt_pk_f32_fp8_e32 v[218:219], v159
	v_cvt_pk_f32_fp8_sdwa v[220:221], v159 src0_sel:WORD_1
	v_pk_fma_f32 v[222:223], v[8:9], v[214:215], v[222:223]
	v_pk_fma_f32 v[224:225], v[10:11], v[216:217], v[224:225]
	v_pk_fma_f32 v[222:223], v[12:13], v[218:219], v[222:223]
	v_pk_fma_f32 v[224:225], v[14:15], v[220:221], v[224:225]
	v_pk_add_f32 v[222:223], v[222:223], v[224:225]
	s_nop 0
	v_add_f32_e32 v229, v222, v223
	v_cvt_pk_f32_fp8_e32 v[214:215], v160
	v_cvt_pk_f32_fp8_sdwa v[216:217], v160 src0_sel:WORD_1
	v_cvt_pk_f32_fp8_e32 v[218:219], v161
	v_cvt_pk_f32_fp8_sdwa v[220:221], v161 src0_sel:WORD_1
	v_pk_mul_f32 v[222:223], v[0:1], v[214:215]
	v_pk_mul_f32 v[224:225], v[2:3], v[216:217]
	v_cvt_pk_f32_fp8_e32 v[214:215], v162
	v_cvt_pk_f32_fp8_sdwa v[216:217], v162 src0_sel:WORD_1
	v_pk_fma_f32 v[222:223], v[4:5], v[218:219], v[222:223]
	v_pk_fma_f32 v[224:225], v[6:7], v[220:221], v[224:225]
	v_cvt_pk_f32_fp8_e32 v[218:219], v163
	v_cvt_pk_f32_fp8_sdwa v[220:221], v163 src0_sel:WORD_1
	v_pk_fma_f32 v[222:223], v[8:9], v[214:215], v[222:223]
	v_pk_fma_f32 v[224:225], v[10:11], v[216:217], v[224:225]
	v_pk_fma_f32 v[222:223], v[12:13], v[218:219], v[222:223]
	v_pk_fma_f32 v[224:225], v[14:15], v[220:221], v[224:225]
	v_pk_add_f32 v[222:223], v[222:223], v[224:225]
	s_nop 0
	v_add_f32_e32 v230, v222, v223
	v_cvt_pk_f32_fp8_e32 v[214:215], v164
	v_cvt_pk_f32_fp8_sdwa v[216:217], v164 src0_sel:WORD_1
	v_cvt_pk_f32_fp8_e32 v[218:219], v165
	v_cvt_pk_f32_fp8_sdwa v[220:221], v165 src0_sel:WORD_1
	v_pk_mul_f32 v[222:223], v[0:1], v[214:215]
	v_pk_mul_f32 v[224:225], v[2:3], v[216:217]
	v_cvt_pk_f32_fp8_e32 v[214:215], v166
	v_cvt_pk_f32_fp8_sdwa v[216:217], v166 src0_sel:WORD_1
	v_pk_fma_f32 v[222:223], v[4:5], v[218:219], v[222:223]
	v_pk_fma_f32 v[224:225], v[6:7], v[220:221], v[224:225]
	v_cvt_pk_f32_fp8_e32 v[218:219], v167
	v_cvt_pk_f32_fp8_sdwa v[220:221], v167 src0_sel:WORD_1
	v_pk_fma_f32 v[222:223], v[8:9], v[214:215], v[222:223]
	v_pk_fma_f32 v[224:225], v[10:11], v[216:217], v[224:225]
	v_pk_fma_f32 v[222:223], v[12:13], v[218:219], v[222:223]
	v_pk_fma_f32 v[224:225], v[14:15], v[220:221], v[224:225]
	v_pk_add_f32 v[222:223], v[222:223], v[224:225]
	s_nop 0
	v_add_f32_e32 v231, v222, v223
	v_cvt_pk_f32_fp8_e32 v[214:215], v168
	v_cvt_pk_f32_fp8_sdwa v[216:217], v168 src0_sel:WORD_1
	v_cvt_pk_f32_fp8_e32 v[218:219], v169
	v_cvt_pk_f32_fp8_sdwa v[220:221], v169 src0_sel:WORD_1
; template <bool STORE>
; DI void peer_item(const Params& p, int item, char* smem) {
;     ...
;       for (int u = 0; u < 8; ++u) {
;         int e = e_s[tl * 128 + k + u];
;         uq[u] = *(const u32x4*)(U8 + (size_t)e * 1024 + lane * 16);
;       }
;       float part[8];
; #pragma unroll
;       for (int u = 0; u < 8; ++u) {
;         float d = 0.f;
; #pragma unroll
;         for (int i = 0; i < 4; ++i) {
;           f32x2_t lo = __builtin_amdgcn_cvt_pk_f32_fp8((int)uq[u][i], false);
;           f32x2_t hi = __builtin_amdgcn_cvt_pk_f32_fp8((int)uq[u][i], true);
;           d += xf[4 * i] * lo.x + xf[4 * i + 1] * lo.y + xf[4 * i + 2] * hi.x + xf[4 * i + 3] * hi.y;
;         }
;         part[u] = d;
;       }
;       float q4[4], r2[2], h;
; #pragma unroll
;       for (int j = 0; j < 4; ++j) {
;         float mine = b5 ? part[j + 4] : part[j];
;         float other = b5 ? part[j] : part[j + 4];
;         q4[j] = mine + __shfl_xor(other, 32);
;       }
; #pragma unroll
;       for (int j = 0; j < 2; ++j) {
;         float mine = b4 ? q4[j + 2] : q4[j];
;         float other = b4 ? q4[j] : q4[j + 2];
;         r2[j] = mine + __shfl_xor(other, 16);
;       }
;       {
;         float mine = b3 ? r2[1] : r2[0];
;         float other = b3 ? r2[0] : r2[1];
;         h = mine + __shfl_xor(other, 8);
;       }
;       h += __shfl_xor(h, 4);
;       h += __shfl_xor(h, 2);
;       h += __shfl_xor(h, 1);
	v_pk_mul_f32 v[222:223], v[0:1], v[214:215]
	v_pk_mul_f32 v[224:225], v[2:3], v[216:217]
	v_cvt_pk_f32_fp8_e32 v[214:215], v170
	v_cvt_pk_f32_fp8_sdwa v[216:217], v170 src0_sel:WORD_1
	v_pk_fma_f32 v[222:223], v[4:5], v[218:219], v[222:223]
	v_pk_fma_f32 v[224:225], v[6:7], v[220:221], v[224:225]
	v_cvt_pk_f32_fp8_e32 v[218:219], v171
	v_cvt_pk_f32_fp8_sdwa v[220:221], v171 src0_sel:WORD_1
	v_pk_fma_f32 v[222:223], v[8:9], v[214:215], v[222:223]
	v_pk_fma_f32 v[224:225], v[10:11], v[216:217], v[224:225]
	v_pk_fma_f32 v[222:223], v[12:13], v[218:219], v[222:223]
	v_pk_fma_f32 v[224:225], v[14:15], v[220:221], v[224:225]
	v_pk_add_f32 v[222:223], v[222:223], v[224:225]
	s_nop 0
	v_add_f32_e32 v232, v222, v223
	v_cvt_pk_f32_fp8_e32 v[214:215], v172
	v_cvt_pk_f32_fp8_sdwa v[216:217], v172 src0_sel:WORD_1
	v_cvt_pk_f32_fp8_e32 v[218:219], v173
	v_cvt_pk_f32_fp8_sdwa v[220:221], v173 src0_sel:WORD_1
	v_pk_mul_f32 v[222:223], v[0:1], v[214:215]
	v_pk_mul_f32 v[224:225], v[2:3], v[216:217]
	v_cvt_pk_f32_fp8_e32 v[214:215], v174
	v_cvt_pk_f32_fp8_sdwa v[216:217], v174 src0_sel:WORD_1
	v_pk_fma_f32 v[222:223], v[4:5], v[218:219], v[222:223]
	v_pk_fma_f32 v[224:225], v[6:7], v[220:221], v[224:225]
	v_cvt_pk_f32_fp8_e32 v[218:219], v175
	v_cvt_pk_f32_fp8_sdwa v[220:221], v175 src0_sel:WORD_1
	v_pk_fma_f32 v[222:223], v[8:9], v[214:215], v[222:223]
	v_pk_fma_f32 v[224:225], v[10:11], v[216:217], v[224:225]
	v_pk_fma_f32 v[222:223], v[12:13], v[218:219], v[222:223]
	v_pk_fma_f32 v[224:225], v[14:15], v[220:221], v[224:225]
	v_pk_add_f32 v[222:223], v[222:223], v[224:225]
	s_nop 0
	v_add_f32_e32 v233, v222, v223
	v_permlane32_swap_b32_e32 v226, v230
	v_permlane32_swap_b32_e32 v227, v231
	v_permlane32_swap_b32_e32 v228, v232
	v_permlane32_swap_b32_e32 v229, v233
	v_add_f32_e32 v226, v226, v230
	v_add_f32_e32 v228, v228, v232
	v_add_f32_e32 v227, v227, v231
	v_add_f32_e32 v229, v229, v233
	s_nop 1
	v_permlane16_swap_b32_e32 v226, v228
	v_permlane16_swap_b32_e32 v227, v229
	v_add_f32_e32 v226, v226, v228
	v_add_f32_e32 v227, v227, v229
	s_nop 0
	v_cndmask_b32_e64 v230, v226, v227, s[24:25]
	v_cndmask_b32_e64 v231, v227, v226, s[24:25]
	s_nop 1
	v_add_f32_dpp v232, v231, v230 row_ror:8 row_mask:0xf bank_mask:0xf
	s_nop 1
	v_add_f32_dpp v233, v232, v232 quad_perm:[1,0,3,2] row_mask:0xf bank_mask:0xf
	s_nop 1
	v_add_f32_dpp v232, v233, v233 quad_perm:[2,3,0,1] row_mask:0xf bank_mask:0xf
	s_nop 1
	v_add_f32_dpp v233, v232, v232 row_half_mirror row_mask:0xf bank_mask:0xf
	ds_write_b32 v235, v233 offset:32800
	v_readlane_b32 s48, v128, s58
	v_readlane_b32 s49, v128, s59
	v_readlane_b32 s50, v128, s60
	v_readlane_b32 s51, v128, s61
	v_readlane_b32 s52, v128, s62
	v_readlane_b32 s53, v128, s63
	v_readlane_b32 s54, v128, s64
	v_readlane_b32 s55, v128, s65
	s_add_u32 s32, s0, s48
	s_addc_u32 s33, s1, 0
	s_add_u32 s34, s0, s49
	s_addc_u32 s35, s1, 0
	s_add_u32 s36, s0, s50
	s_addc_u32 s37, s1, 0
	s_add_u32 s38, s0, s51
	s_addc_u32 s39, s1, 0
	s_add_u32 s40, s0, s52
	s_addc_u32 s41, s1, 0
	s_add_u32 s42, s0, s53
	s_addc_u32 s43, s1, 0
	s_add_u32 s44, s0, s54
	s_addc_u32 s45, s1, 0
	s_add_u32 s46, s0, s55
	s_addc_u32 s47, s1, 0
	global_load_dwordx4 v[144:147], v234, s[32:33]
	global_load_dwordx4 v[148:151], v234, s[34:35]
	global_load_dwordx4 v[152:155], v234, s[36:37]
	global_load_dwordx4 v[156:159], v234, s[38:39]
	global_load_dwordx4 v[160:163], v234, s[40:41]
	global_load_dwordx4 v[164:167], v234, s[42:43]
	global_load_dwordx4 v[168:171], v234, s[44:45]
	global_load_dwordx4 v[172:175], v234, s[46:47]
	s_waitcnt vmcnt(24)
	v_cvt_pk_f32_fp8_e32 v[214:215], v176
	v_cvt_pk_f32_fp8_sdwa v[216:217], v176 src0_sel:WORD_1
	v_cvt_pk_f32_fp8_e32 v[218:219], v177
	v_cvt_pk_f32_fp8_sdwa v[220:221], v177 src0_sel:WORD_1
	v_pk_mul_f32 v[222:223], v[16:17], v[214:215]
	v_pk_mul_f32 v[224:225], v[18:19], v[216:217]
	v_cvt_pk_f32_fp8_e32 v[214:215], v178
	v_cvt_pk_f32_fp8_sdwa v[216:217], v178 src0_sel:WORD_1
	v_pk_fma_f32 v[222:223], v[20:21], v[218:219], v[222:223]
	v_pk_fma_f32 v[224:225], v[22:23], v[220:221], v[224:225]
	v_cvt_pk_f32_fp8_e32 v[218:219], v179
	v_cvt_pk_f32_fp8_sdwa v[220:221], v179 src0_sel:WORD_1
	v_pk_fma_f32 v[222:223], v[24:25], v[214:215], v[222:223]
	v_pk_fma_f32 v[224:225], v[26:27], v[216:217], v[224:225]
	v_pk_fma_f32 v[222:223], v[28:29], v[218:219], v[222:223]
	v_pk_fma_f32 v[224:225], v[30:31], v[220:221], v[224:225]
	v_pk_add_f32 v[222:223], v[222:223], v[224:225]
	s_nop 0
	v_add_f32_e32 v226, v222, v223
	v_cvt_pk_f32_fp8_e32 v[214:215], v180
	v_cvt_pk_f32_fp8_sdwa v[216:217], v180 src0_sel:WORD_1
	v_cvt_pk_f32_fp8_e32 v[218:219], v181
	v_cvt_pk_f32_fp8_sdwa v[220:221], v181 src0_sel:WORD_1
	v_pk_mul_f32 v[222:223], v[16:17], v[214:215]
	v_pk_mul_f32 v[224:225], v[18:19], v[216:217]
	v_cvt_pk_f32_fp8_e32 v[214:215], v182
	v_cvt_pk_f32_fp8_sdwa v[216:217], v182 src0_sel:WORD_1
	v_pk_fma_f32 v[222:223], v[20:21], v[218:219], v[222:223]
	v_pk_fma_f32 v[224:225], v[22:23], v[220:221], v[224:225]
	v_cvt_pk_f32_fp8_e32 v[218:219], v183
	v_cvt_pk_f32_fp8_sdwa v[220:221], v183 src0_sel:WORD_1
	v_pk_fma_f32 v[222:223], v[24:25], v[214:215], v[222:223]
	v_pk_fma_f32 v[224:225], v[26:27], v[216:217], v[224:225]
	v_pk_fma_f32 v[222:223], v[28:29], v[218:219], v[222:223]
	v_pk_fma_f32 v[224:225], v[30:31], v[220:221], v[224:225]
	v_pk_add_f32 v[222:223], v[222:223], v[224:225]
	s_nop 0
	v_add_f32_e32 v227, v222, v223
	v_cvt_pk_f32_fp8_e32 v[214:215], v184
	v_cvt_pk_f32_fp8_sdwa v[216:217], v184 src0_sel:WORD_1
	v_cvt_pk_f32_fp8_e32 v[218:219], v185
	v_cvt_pk_f32_fp8_sdwa v[220:221], v185 src0_sel:WORD_1
	v_pk_mul_f32 v[222:223], v[16:17], v[214:215]
; template <bool STORE>
; DI void peer_item(const Params& p, int item, char* smem) {
;     ...
;       float part[8];
; #pragma unroll
;       for (int u = 0; u < 8; ++u) {
;         float d = 0.f;
; #pragma unroll
;         for (int i = 0; i < 4; ++i) {
;           f32x2_t lo = __builtin_amdgcn_cvt_pk_f32_fp8((int)uq[u][i], false);
;           f32x2_t hi = __builtin_amdgcn_cvt_pk_f32_fp8((int)uq[u][i], true);
;           d += xf[4 * i] * lo.x + xf[4 * i + 1] * lo.y + xf[4 * i + 2] * hi.x + xf[4 * i + 3] * hi.y;
;         }
;         part[u] = d;
;       }
;       float q4[4], r2[2], h;
; #pragma unroll
;       for (int j = 0; j < 4; ++j) {
;         float mine = b5 ? part[j + 4] : part[j];
;         float other = b5 ? part[j] : part[j + 4];
;         q4[j] = mine + __shfl_xor(other, 32);
;       }
; #pragma unroll
;       for (int j = 0; j < 2; ++j) {
;         float mine = b4 ? q4[j + 2] : q4[j];
;         float other = b4 ? q4[j] : q4[j + 2];
;         r2[j] = mine + __shfl_xor(other, 16);
;       }
;       {
;         float mine = b3 ? r2[1] : r2[0];
;         float other = b3 ? r2[0] : r2[1];
;         h = mine + __shfl_xor(other, 8);
;       }
;       h += __shfl_xor(h, 4);
;       h += __shfl_xor(h, 2);
;       h += __shfl_xor(h, 1);
	v_pk_mul_f32 v[224:225], v[18:19], v[216:217]
	v_cvt_pk_f32_fp8_e32 v[214:215], v186
	v_cvt_pk_f32_fp8_sdwa v[216:217], v186 src0_sel:WORD_1
	v_pk_fma_f32 v[222:223], v[20:21], v[218:219], v[222:223]
	v_pk_fma_f32 v[224:225], v[22:23], v[220:221], v[224:225]
	v_cvt_pk_f32_fp8_e32 v[218:219], v187
	v_cvt_pk_f32_fp8_sdwa v[220:221], v187 src0_sel:WORD_1
	v_pk_fma_f32 v[222:223], v[24:25], v[214:215], v[222:223]
	v_pk_fma_f32 v[224:225], v[26:27], v[216:217], v[224:225]
	v_pk_fma_f32 v[222:223], v[28:29], v[218:219], v[222:223]
	v_pk_fma_f32 v[224:225], v[30:31], v[220:221], v[224:225]
	v_pk_add_f32 v[222:223], v[222:223], v[224:225]
	s_nop 0
	v_add_f32_e32 v228, v222, v223
	v_cvt_pk_f32_fp8_e32 v[214:215], v188
	v_cvt_pk_f32_fp8_sdwa v[216:217], v188 src0_sel:WORD_1
	v_cvt_pk_f32_fp8_e32 v[218:219], v189
	v_cvt_pk_f32_fp8_sdwa v[220:221], v189 src0_sel:WORD_1
	v_pk_mul_f32 v[222:223], v[16:17], v[214:215]
	v_pk_mul_f32 v[224:225], v[18:19], v[216:217]
	v_cvt_pk_f32_fp8_e32 v[214:215], v190
	v_cvt_pk_f32_fp8_sdwa v[216:217], v190 src0_sel:WORD_1
	v_pk_fma_f32 v[222:223], v[20:21], v[218:219], v[222:223]
	v_pk_fma_f32 v[224:225], v[22:23], v[220:221], v[224:225]
	v_cvt_pk_f32_fp8_e32 v[218:219], v191
	v_cvt_pk_f32_fp8_sdwa v[220:221], v191 src0_sel:WORD_1
	v_pk_fma_f32 v[222:223], v[24:25], v[214:215], v[222:223]
	v_pk_fma_f32 v[224:225], v[26:27], v[216:217], v[224:225]
	v_pk_fma_f32 v[222:223], v[28:29], v[218:219], v[222:223]
	v_pk_fma_f32 v[224:225], v[30:31], v[220:221], v[224:225]
	v_pk_add_f32 v[222:223], v[222:223], v[224:225]
	s_nop 0
	v_add_f32_e32 v229, v222, v223
	v_cvt_pk_f32_fp8_e32 v[214:215], v192
	v_cvt_pk_f32_fp8_sdwa v[216:217], v192 src0_sel:WORD_1
	v_cvt_pk_f32_fp8_e32 v[218:219], v193
	v_cvt_pk_f32_fp8_sdwa v[220:221], v193 src0_sel:WORD_1
	v_pk_mul_f32 v[222:223], v[16:17], v[214:215]
	v_pk_mul_f32 v[224:225], v[18:19], v[216:217]
	v_cvt_pk_f32_fp8_e32 v[214:215], v194
	v_cvt_pk_f32_fp8_sdwa v[216:217], v194 src0_sel:WORD_1
	v_pk_fma_f32 v[222:223], v[20:21], v[218:219], v[222:223]
	v_pk_fma_f32 v[224:225], v[22:23], v[220:221], v[224:225]
	v_cvt_pk_f32_fp8_e32 v[218:219], v195
	v_cvt_pk_f32_fp8_sdwa v[220:221], v195 src0_sel:WORD_1
	v_pk_fma_f32 v[222:223], v[24:25], v[214:215], v[222:223]
	v_pk_fma_f32 v[224:225], v[26:27], v[216:217], v[224:225]
	v_pk_fma_f32 v[222:223], v[28:29], v[218:219], v[222:223]
	v_pk_fma_f32 v[224:225], v[30:31], v[220:221], v[224:225]
	v_pk_add_f32 v[222:223], v[222:223], v[224:225]
	s_nop 0
	v_add_f32_e32 v230, v222, v223
	v_cvt_pk_f32_fp8_e32 v[214:215], v196
	v_cvt_pk_f32_fp8_sdwa v[216:217], v196 src0_sel:WORD_1
	v_cvt_pk_f32_fp8_e32 v[218:219], v197
	v_cvt_pk_f32_fp8_sdwa v[220:221], v197 src0_sel:WORD_1
	v_pk_mul_f32 v[222:223], v[16:17], v[214:215]
	v_pk_mul_f32 v[224:225], v[18:19], v[216:217]
	v_cvt_pk_f32_fp8_e32 v[214:215], v198
	v_cvt_pk_f32_fp8_sdwa v[216:217], v198 src0_sel:WORD_1
	v_pk_fma_f32 v[222:223], v[20:21], v[218:219], v[222:223]
	v_pk_fma_f32 v[224:225], v[22:23], v[220:221], v[224:225]
	v_cvt_pk_f32_fp8_e32 v[218:219], v199
	v_cvt_pk_f32_fp8_sdwa v[220:221], v199 src0_sel:WORD_1
	v_pk_fma_f32 v[222:223], v[24:25], v[214:215], v[222:223]
	v_pk_fma_f32 v[224:225], v[26:27], v[216:217], v[224:225]
	v_pk_fma_f32 v[222:223], v[28:29], v[218:219], v[222:223]
	v_pk_fma_f32 v[224:225], v[30:31], v[220:221], v[224:225]
	v_pk_add_f32 v[222:223], v[222:223], v[224:225]
	s_nop 0
	v_add_f32_e32 v231, v222, v223
	v_cvt_pk_f32_fp8_e32 v[214:215], v200
	v_cvt_pk_f32_fp8_sdwa v[216:217], v200 src0_sel:WORD_1
	v_cvt_pk_f32_fp8_e32 v[218:219], v201
	v_cvt_pk_f32_fp8_sdwa v[220:221], v201 src0_sel:WORD_1
	v_pk_mul_f32 v[222:223], v[16:17], v[214:215]
	v_pk_mul_f32 v[224:225], v[18:19], v[216:217]
	v_cvt_pk_f32_fp8_e32 v[214:215], v202
	v_cvt_pk_f32_fp8_sdwa v[216:217], v202 src0_sel:WORD_1
	v_pk_fma_f32 v[222:223], v[20:21], v[218:219], v[222:223]
	v_pk_fma_f32 v[224:225], v[22:23], v[220:221], v[224:225]
	v_cvt_pk_f32_fp8_e32 v[218:219], v203
	v_cvt_pk_f32_fp8_sdwa v[220:221], v203 src0_sel:WORD_1
	v_pk_fma_f32 v[222:223], v[24:25], v[214:215], v[222:223]
	v_pk_fma_f32 v[224:225], v[26:27], v[216:217], v[224:225]
	v_pk_fma_f32 v[222:223], v[28:29], v[218:219], v[222:223]
	v_pk_fma_f32 v[224:225], v[30:31], v[220:221], v[224:225]
	v_pk_add_f32 v[222:223], v[222:223], v[224:225]
	s_nop 0
	v_add_f32_e32 v232, v222, v223
	v_cvt_pk_f32_fp8_e32 v[214:215], v204
	v_cvt_pk_f32_fp8_sdwa v[216:217], v204 src0_sel:WORD_1
	v_cvt_pk_f32_fp8_e32 v[218:219], v205
	v_cvt_pk_f32_fp8_sdwa v[220:221], v205 src0_sel:WORD_1
	v_pk_mul_f32 v[222:223], v[16:17], v[214:215]
	v_pk_mul_f32 v[224:225], v[18:19], v[216:217]
	v_cvt_pk_f32_fp8_e32 v[214:215], v206
	v_cvt_pk_f32_fp8_sdwa v[216:217], v206 src0_sel:WORD_1
	v_pk_fma_f32 v[222:223], v[20:21], v[218:219], v[222:223]
	v_pk_fma_f32 v[224:225], v[22:23], v[220:221], v[224:225]
	v_cvt_pk_f32_fp8_e32 v[218:219], v207
	v_cvt_pk_f32_fp8_sdwa v[220:221], v207 src0_sel:WORD_1
	v_pk_fma_f32 v[222:223], v[24:25], v[214:215], v[222:223]
	v_pk_fma_f32 v[224:225], v[26:27], v[216:217], v[224:225]
	v_pk_fma_f32 v[222:223], v[28:29], v[218:219], v[222:223]
	v_pk_fma_f32 v[224:225], v[30:31], v[220:221], v[224:225]
	v_pk_add_f32 v[222:223], v[222:223], v[224:225]
	s_nop 0
	v_add_f32_e32 v233, v222, v223
	v_permlane32_swap_b32_e32 v226, v230
	v_permlane32_swap_b32_e32 v227, v231
	v_permlane32_swap_b32_e32 v228, v232
	v_permlane32_swap_b32_e32 v229, v233
	v_add_f32_e32 v226, v226, v230
	v_add_f32_e32 v228, v228, v232
	v_add_f32_e32 v227, v227, v231
	v_add_f32_e32 v229, v229, v233
	s_nop 1
	v_permlane16_swap_b32_e32 v226, v228
	v_permlane16_swap_b32_e32 v227, v229
; template <bool STORE>
; DI void peer_item(const Params& p, int item, char* smem) {
;     ...
;       for (int u = 0; u < 8; ++u) {
;         int e = e_s[tl * 128 + k + u];
;         uq[u] = *(const u32x4*)(U8 + (size_t)e * 1024 + lane * 16);
;       }
;       float part[8];
; #pragma unroll
;       for (int u = 0; u < 8; ++u) {
;         float d = 0.f;
; #pragma unroll
;         for (int i = 0; i < 4; ++i) {
;           f32x2_t lo = __builtin_amdgcn_cvt_pk_f32_fp8((int)uq[u][i], false);
;           f32x2_t hi = __builtin_amdgcn_cvt_pk_f32_fp8((int)uq[u][i], true);
;           d += xf[4 * i] * lo.x + xf[4 * i + 1] * lo.y + xf[4 * i + 2] * hi.x + xf[4 * i + 3] * hi.y;
;         }
;         part[u] = d;
;       }
;       float q4[4], r2[2], h;
; #pragma unroll
;       for (int j = 0; j < 4; ++j) {
;         float mine = b5 ? part[j + 4] : part[j];
;         float other = b5 ? part[j] : part[j + 4];
;         q4[j] = mine + __shfl_xor(other, 32);
;       }
; #pragma unroll
;       for (int j = 0; j < 2; ++j) {
;         float mine = b4 ? q4[j + 2] : q4[j];
;         float other = b4 ? q4[j] : q4[j + 2];
;         r2[j] = mine + __shfl_xor(other, 16);
;       }
;       {
;         float mine = b3 ? r2[1] : r2[0];
;         float other = b3 ? r2[0] : r2[1];
;         h = mine + __shfl_xor(other, 8);
;       }
;       h += __shfl_xor(h, 4);
;       h += __shfl_xor(h, 2);
;       h += __shfl_xor(h, 1);
	v_add_f32_e32 v226, v226, v228
	v_add_f32_e32 v227, v227, v229
	s_nop 0
	v_cndmask_b32_e64 v230, v226, v227, s[24:25]
	v_cndmask_b32_e64 v231, v227, v226, s[24:25]
	s_nop 1
	v_add_f32_dpp v232, v231, v230 row_ror:8 row_mask:0xf bank_mask:0xf
	s_nop 1
	v_add_f32_dpp v233, v232, v232 quad_perm:[1,0,3,2] row_mask:0xf bank_mask:0xf
	s_nop 1
	v_add_f32_dpp v232, v233, v233 quad_perm:[2,3,0,1] row_mask:0xf bank_mask:0xf
	s_nop 1
	v_add_f32_dpp v233, v232, v232 row_half_mirror row_mask:0xf bank_mask:0xf
	ds_write_b32 v235, v233 offset:33312
	v_readlane_b32 s48, v130, s58
	v_readlane_b32 s49, v130, s59
	v_readlane_b32 s50, v130, s60
	v_readlane_b32 s51, v130, s61
	v_readlane_b32 s52, v130, s62
	v_readlane_b32 s53, v130, s63
	v_readlane_b32 s54, v130, s64
	v_readlane_b32 s55, v130, s65
	s_add_u32 s32, s0, s48
	s_addc_u32 s33, s1, 0
	s_add_u32 s34, s0, s49
	s_addc_u32 s35, s1, 0
	s_add_u32 s36, s0, s50
	s_addc_u32 s37, s1, 0
	s_add_u32 s38, s0, s51
	s_addc_u32 s39, s1, 0
	s_add_u32 s40, s0, s52
	s_addc_u32 s41, s1, 0
	s_add_u32 s42, s0, s53
	s_addc_u32 s43, s1, 0
	s_add_u32 s44, s0, s54
	s_addc_u32 s45, s1, 0
	s_add_u32 s46, s0, s55
	s_addc_u32 s47, s1, 0
	global_load_dwordx4 v[176:179], v234, s[32:33]
	global_load_dwordx4 v[180:183], v234, s[34:35]
	global_load_dwordx4 v[184:187], v234, s[36:37]
	global_load_dwordx4 v[188:191], v234, s[38:39]
	global_load_dwordx4 v[192:195], v234, s[40:41]
	global_load_dwordx4 v[196:199], v234, s[42:43]
	global_load_dwordx4 v[200:203], v234, s[44:45]
	global_load_dwordx4 v[204:207], v234, s[46:47]
	s_waitcnt vmcnt(24)
	v_cvt_pk_f32_fp8_e32 v[214:215], v64
	v_cvt_pk_f32_fp8_sdwa v[216:217], v64 src0_sel:WORD_1
	v_cvt_pk_f32_fp8_e32 v[218:219], v65
	v_cvt_pk_f32_fp8_sdwa v[220:221], v65 src0_sel:WORD_1
	v_pk_mul_f32 v[222:223], v[32:33], v[214:215]
	v_pk_mul_f32 v[224:225], v[34:35], v[216:217]
	v_cvt_pk_f32_fp8_e32 v[214:215], v66
	v_cvt_pk_f32_fp8_sdwa v[216:217], v66 src0_sel:WORD_1
	v_pk_fma_f32 v[222:223], v[36:37], v[218:219], v[222:223]
	v_pk_fma_f32 v[224:225], v[38:39], v[220:221], v[224:225]
	v_cvt_pk_f32_fp8_e32 v[218:219], v67
	v_cvt_pk_f32_fp8_sdwa v[220:221], v67 src0_sel:WORD_1
	v_pk_fma_f32 v[222:223], v[40:41], v[214:215], v[222:223]
	v_pk_fma_f32 v[224:225], v[42:43], v[216:217], v[224:225]
	v_pk_fma_f32 v[222:223], v[44:45], v[218:219], v[222:223]
	v_pk_fma_f32 v[224:225], v[46:47], v[220:221], v[224:225]
	v_pk_add_f32 v[222:223], v[222:223], v[224:225]
	s_nop 0
	v_add_f32_e32 v226, v222, v223
	v_cvt_pk_f32_fp8_e32 v[214:215], v68
	v_cvt_pk_f32_fp8_sdwa v[216:217], v68 src0_sel:WORD_1
	v_cvt_pk_f32_fp8_e32 v[218:219], v69
	v_cvt_pk_f32_fp8_sdwa v[220:221], v69 src0_sel:WORD_1
	v_pk_mul_f32 v[222:223], v[32:33], v[214:215]
	v_pk_mul_f32 v[224:225], v[34:35], v[216:217]
	v_cvt_pk_f32_fp8_e32 v[214:215], v70
	v_cvt_pk_f32_fp8_sdwa v[216:217], v70 src0_sel:WORD_1
	v_pk_fma_f32 v[222:223], v[36:37], v[218:219], v[222:223]
	v_pk_fma_f32 v[224:225], v[38:39], v[220:221], v[224:225]
	v_cvt_pk_f32_fp8_e32 v[218:219], v71
	v_cvt_pk_f32_fp8_sdwa v[220:221], v71 src0_sel:WORD_1
	v_pk_fma_f32 v[222:223], v[40:41], v[214:215], v[222:223]
	v_pk_fma_f32 v[224:225], v[42:43], v[216:217], v[224:225]
	v_pk_fma_f32 v[222:223], v[44:45], v[218:219], v[222:223]
	v_pk_fma_f32 v[224:225], v[46:47], v[220:221], v[224:225]
	v_pk_add_f32 v[222:223], v[222:223], v[224:225]
	s_nop 0
	v_add_f32_e32 v227, v222, v223
	v_cvt_pk_f32_fp8_e32 v[214:215], v72
	v_cvt_pk_f32_fp8_sdwa v[216:217], v72 src0_sel:WORD_1
	v_cvt_pk_f32_fp8_e32 v[218:219], v73
	v_cvt_pk_f32_fp8_sdwa v[220:221], v73 src0_sel:WORD_1
	v_pk_mul_f32 v[222:223], v[32:33], v[214:215]
	v_pk_mul_f32 v[224:225], v[34:35], v[216:217]
	v_cvt_pk_f32_fp8_e32 v[214:215], v74
	v_cvt_pk_f32_fp8_sdwa v[216:217], v74 src0_sel:WORD_1
	v_pk_fma_f32 v[222:223], v[36:37], v[218:219], v[222:223]
	v_pk_fma_f32 v[224:225], v[38:39], v[220:221], v[224:225]
	v_cvt_pk_f32_fp8_e32 v[218:219], v75
	v_cvt_pk_f32_fp8_sdwa v[220:221], v75 src0_sel:WORD_1
	v_pk_fma_f32 v[222:223], v[40:41], v[214:215], v[222:223]
	v_pk_fma_f32 v[224:225], v[42:43], v[216:217], v[224:225]
	v_pk_fma_f32 v[222:223], v[44:45], v[218:219], v[222:223]
	v_pk_fma_f32 v[224:225], v[46:47], v[220:221], v[224:225]
	v_pk_add_f32 v[222:223], v[222:223], v[224:225]
	s_nop 0
	v_add_f32_e32 v228, v222, v223
	v_cvt_pk_f32_fp8_e32 v[214:215], v76
	v_cvt_pk_f32_fp8_sdwa v[216:217], v76 src0_sel:WORD_1
	v_cvt_pk_f32_fp8_e32 v[218:219], v77
	v_cvt_pk_f32_fp8_sdwa v[220:221], v77 src0_sel:WORD_1
	v_pk_mul_f32 v[222:223], v[32:33], v[214:215]
	v_pk_mul_f32 v[224:225], v[34:35], v[216:217]
	v_cvt_pk_f32_fp8_e32 v[214:215], v78
	v_cvt_pk_f32_fp8_sdwa v[216:217], v78 src0_sel:WORD_1
	v_pk_fma_f32 v[222:223], v[36:37], v[218:219], v[222:223]
	v_pk_fma_f32 v[224:225], v[38:39], v[220:221], v[224:225]
	v_cvt_pk_f32_fp8_e32 v[218:219], v79
	v_cvt_pk_f32_fp8_sdwa v[220:221], v79 src0_sel:WORD_1
	v_pk_fma_f32 v[222:223], v[40:41], v[214:215], v[222:223]
	v_pk_fma_f32 v[224:225], v[42:43], v[216:217], v[224:225]
	v_pk_fma_f32 v[222:223], v[44:45], v[218:219], v[222:223]
	v_pk_fma_f32 v[224:225], v[46:47], v[220:221], v[224:225]
	v_pk_add_f32 v[222:223], v[222:223], v[224:225]
	s_nop 0
	v_add_f32_e32 v229, v222, v223
	v_cvt_pk_f32_fp8_e32 v[214:215], v80
	v_cvt_pk_f32_fp8_sdwa v[216:217], v80 src0_sel:WORD_1
	v_cvt_pk_f32_fp8_e32 v[218:219], v81
	v_cvt_pk_f32_fp8_sdwa v[220:221], v81 src0_sel:WORD_1
	v_pk_mul_f32 v[222:223], v[32:33], v[214:215]
	v_pk_mul_f32 v[224:225], v[34:35], v[216:217]
	v_cvt_pk_f32_fp8_e32 v[214:215], v82
	v_cvt_pk_f32_fp8_sdwa v[216:217], v82 src0_sel:WORD_1
	v_pk_fma_f32 v[222:223], v[36:37], v[218:219], v[222:223]
; template <bool STORE>
; DI void peer_item(const Params& p, int item, char* smem) {
;     ...
;       for (int u = 0; u < 8; ++u) {
;         int e = e_s[tl * 128 + k + u];
;         uq[u] = *(const u32x4*)(U8 + (size_t)e * 1024 + lane * 16);
;       }
;       float part[8];
; #pragma unroll
;       for (int u = 0; u < 8; ++u) {
;         float d = 0.f;
; #pragma unroll
;         for (int i = 0; i < 4; ++i) {
;           f32x2_t lo = __builtin_amdgcn_cvt_pk_f32_fp8((int)uq[u][i], false);
;           f32x2_t hi = __builtin_amdgcn_cvt_pk_f32_fp8((int)uq[u][i], true);
;           d += xf[4 * i] * lo.x + xf[4 * i + 1] * lo.y + xf[4 * i + 2] * hi.x + xf[4 * i + 3] * hi.y;
;         }
;         part[u] = d;
;       }
;       float q4[4], r2[2], h;
; #pragma unroll
;       for (int j = 0; j < 4; ++j) {
;         float mine = b5 ? part[j + 4] : part[j];
;         float other = b5 ? part[j] : part[j + 4];
;         q4[j] = mine + __shfl_xor(other, 32);
;       }
; #pragma unroll
;       for (int j = 0; j < 2; ++j) {
;         float mine = b4 ? q4[j + 2] : q4[j];
;         float other = b4 ? q4[j] : q4[j + 2];
;         r2[j] = mine + __shfl_xor(other, 16);
;       }
;       {
;         float mine = b3 ? r2[1] : r2[0];
;         float other = b3 ? r2[0] : r2[1];
;         h = mine + __shfl_xor(other, 8);
;       }
;       h += __shfl_xor(h, 4);
;       h += __shfl_xor(h, 2);
;       h += __shfl_xor(h, 1);
	v_pk_fma_f32 v[224:225], v[38:39], v[220:221], v[224:225]
	v_cvt_pk_f32_fp8_e32 v[218:219], v83
	v_cvt_pk_f32_fp8_sdwa v[220:221], v83 src0_sel:WORD_1
	v_pk_fma_f32 v[222:223], v[40:41], v[214:215], v[222:223]
	v_pk_fma_f32 v[224:225], v[42:43], v[216:217], v[224:225]
	v_pk_fma_f32 v[222:223], v[44:45], v[218:219], v[222:223]
	v_pk_fma_f32 v[224:225], v[46:47], v[220:221], v[224:225]
	v_pk_add_f32 v[222:223], v[222:223], v[224:225]
	s_nop 0
	v_add_f32_e32 v230, v222, v223
	v_cvt_pk_f32_fp8_e32 v[214:215], v84
	v_cvt_pk_f32_fp8_sdwa v[216:217], v84 src0_sel:WORD_1
	v_cvt_pk_f32_fp8_e32 v[218:219], v85
	v_cvt_pk_f32_fp8_sdwa v[220:221], v85 src0_sel:WORD_1
	v_pk_mul_f32 v[222:223], v[32:33], v[214:215]
	v_pk_mul_f32 v[224:225], v[34:35], v[216:217]
	v_cvt_pk_f32_fp8_e32 v[214:215], v86
	v_cvt_pk_f32_fp8_sdwa v[216:217], v86 src0_sel:WORD_1
	v_pk_fma_f32 v[222:223], v[36:37], v[218:219], v[222:223]
	v_pk_fma_f32 v[224:225], v[38:39], v[220:221], v[224:225]
	v_cvt_pk_f32_fp8_e32 v[218:219], v87
	v_cvt_pk_f32_fp8_sdwa v[220:221], v87 src0_sel:WORD_1
	v_pk_fma_f32 v[222:223], v[40:41], v[214:215], v[222:223]
	v_pk_fma_f32 v[224:225], v[42:43], v[216:217], v[224:225]
	v_pk_fma_f32 v[222:223], v[44:45], v[218:219], v[222:223]
	v_pk_fma_f32 v[224:225], v[46:47], v[220:221], v[224:225]
	v_pk_add_f32 v[222:223], v[222:223], v[224:225]
	s_nop 0
	v_add_f32_e32 v231, v222, v223
	v_cvt_pk_f32_fp8_e32 v[214:215], v88
	v_cvt_pk_f32_fp8_sdwa v[216:217], v88 src0_sel:WORD_1
	v_cvt_pk_f32_fp8_e32 v[218:219], v89
	v_cvt_pk_f32_fp8_sdwa v[220:221], v89 src0_sel:WORD_1
	v_pk_mul_f32 v[222:223], v[32:33], v[214:215]
	v_pk_mul_f32 v[224:225], v[34:35], v[216:217]
	v_cvt_pk_f32_fp8_e32 v[214:215], v90
	v_cvt_pk_f32_fp8_sdwa v[216:217], v90 src0_sel:WORD_1
	v_pk_fma_f32 v[222:223], v[36:37], v[218:219], v[222:223]
	v_pk_fma_f32 v[224:225], v[38:39], v[220:221], v[224:225]
	v_cvt_pk_f32_fp8_e32 v[218:219], v91
	v_cvt_pk_f32_fp8_sdwa v[220:221], v91 src0_sel:WORD_1
	v_pk_fma_f32 v[222:223], v[40:41], v[214:215], v[222:223]
	v_pk_fma_f32 v[224:225], v[42:43], v[216:217], v[224:225]
	v_pk_fma_f32 v[222:223], v[44:45], v[218:219], v[222:223]
	v_pk_fma_f32 v[224:225], v[46:47], v[220:221], v[224:225]
	v_pk_add_f32 v[222:223], v[222:223], v[224:225]
	s_nop 0
	v_add_f32_e32 v232, v222, v223
	v_cvt_pk_f32_fp8_e32 v[214:215], v92
	v_cvt_pk_f32_fp8_sdwa v[216:217], v92 src0_sel:WORD_1
	v_cvt_pk_f32_fp8_e32 v[218:219], v93
	v_cvt_pk_f32_fp8_sdwa v[220:221], v93 src0_sel:WORD_1
	v_pk_mul_f32 v[222:223], v[32:33], v[214:215]
	v_pk_mul_f32 v[224:225], v[34:35], v[216:217]
	v_cvt_pk_f32_fp8_e32 v[214:215], v94
	v_cvt_pk_f32_fp8_sdwa v[216:217], v94 src0_sel:WORD_1
	v_pk_fma_f32 v[222:223], v[36:37], v[218:219], v[222:223]
	v_pk_fma_f32 v[224:225], v[38:39], v[220:221], v[224:225]
	v_cvt_pk_f32_fp8_e32 v[218:219], v95
	v_cvt_pk_f32_fp8_sdwa v[220:221], v95 src0_sel:WORD_1
	v_pk_fma_f32 v[222:223], v[40:41], v[214:215], v[222:223]
	v_pk_fma_f32 v[224:225], v[42:43], v[216:217], v[224:225]
	v_pk_fma_f32 v[222:223], v[44:45], v[218:219], v[222:223]
	v_pk_fma_f32 v[224:225], v[46:47], v[220:221], v[224:225]
	v_pk_add_f32 v[222:223], v[222:223], v[224:225]
	s_nop 0
	v_add_f32_e32 v233, v222, v223
	v_permlane32_swap_b32_e32 v226, v230
	v_permlane32_swap_b32_e32 v227, v231
	v_permlane32_swap_b32_e32 v228, v232
	v_permlane32_swap_b32_e32 v229, v233
	v_add_f32_e32 v226, v226, v230
	v_add_f32_e32 v228, v228, v232
	v_add_f32_e32 v227, v227, v231
	v_add_f32_e32 v229, v229, v233
	s_nop 1
	v_permlane16_swap_b32_e32 v226, v228
	v_permlane16_swap_b32_e32 v227, v229
	v_add_f32_e32 v226, v226, v228
	v_add_f32_e32 v227, v227, v229
	s_nop 0
	v_cndmask_b32_e64 v230, v226, v227, s[24:25]
	v_cndmask_b32_e64 v231, v227, v226, s[24:25]
	s_nop 1
	v_add_f32_dpp v232, v231, v230 row_ror:8 row_mask:0xf bank_mask:0xf
	s_nop 1
	v_add_f32_dpp v233, v232, v232 quad_perm:[1,0,3,2] row_mask:0xf bank_mask:0xf
	s_nop 1
	v_add_f32_dpp v232, v233, v233 quad_perm:[2,3,0,1] row_mask:0xf bank_mask:0xf
	s_nop 1
	v_add_f32_dpp v233, v232, v232 row_half_mirror row_mask:0xf bank_mask:0xf
	ds_write_b32 v235, v233 offset:33824
	v_readlane_b32 s48, v132, s58
	v_readlane_b32 s49, v132, s59
	v_readlane_b32 s50, v132, s60
	v_readlane_b32 s51, v132, s61
	v_readlane_b32 s52, v132, s62
	v_readlane_b32 s53, v132, s63
	v_readlane_b32 s54, v132, s64
	v_readlane_b32 s55, v132, s65
	s_add_u32 s32, s0, s48
	s_addc_u32 s33, s1, 0
	s_add_u32 s34, s0, s49
	s_addc_u32 s35, s1, 0
	s_add_u32 s36, s0, s50
	s_addc_u32 s37, s1, 0
	s_add_u32 s38, s0, s51
	s_addc_u32 s39, s1, 0
	s_add_u32 s40, s0, s52
	s_addc_u32 s41, s1, 0
	s_add_u32 s42, s0, s53
	s_addc_u32 s43, s1, 0
	s_add_u32 s44, s0, s54
	s_addc_u32 s45, s1, 0
	s_add_u32 s46, s0, s55
	s_addc_u32 s47, s1, 0
	global_load_dwordx4 v[64:67], v234, s[32:33]
	global_load_dwordx4 v[68:71], v234, s[34:35]
	global_load_dwordx4 v[72:75], v234, s[36:37]
	global_load_dwordx4 v[76:79], v234, s[38:39]
	global_load_dwordx4 v[80:83], v234, s[40:41]
	global_load_dwordx4 v[84:87], v234, s[42:43]
	global_load_dwordx4 v[88:91], v234, s[44:45]
	global_load_dwordx4 v[92:95], v234, s[46:47]
	s_waitcnt vmcnt(24)
; template <bool STORE>
; DI void peer_item(const Params& p, int item, char* smem) {
;     ...
;       float part[8];
; #pragma unroll
;       for (int u = 0; u < 8; ++u) {
;         float d = 0.f;
; #pragma unroll
;         for (int i = 0; i < 4; ++i) {
;           f32x2_t lo = __builtin_amdgcn_cvt_pk_f32_fp8((int)uq[u][i], false);
;           f32x2_t hi = __builtin_amdgcn_cvt_pk_f32_fp8((int)uq[u][i], true);
;           d += xf[4 * i] * lo.x + xf[4 * i + 1] * lo.y + xf[4 * i + 2] * hi.x + xf[4 * i + 3] * hi.y;
;         }
;         part[u] = d;
;       }
	v_cvt_pk_f32_fp8_e32 v[214:215], v96
	v_cvt_pk_f32_fp8_sdwa v[216:217], v96 src0_sel:WORD_1
	v_cvt_pk_f32_fp8_e32 v[218:219], v97
	v_cvt_pk_f32_fp8_sdwa v[220:221], v97 src0_sel:WORD_1
	v_pk_mul_f32 v[222:223], v[48:49], v[214:215]
	v_pk_mul_f32 v[224:225], v[50:51], v[216:217]
	v_cvt_pk_f32_fp8_e32 v[214:215], v98
	v_cvt_pk_f32_fp8_sdwa v[216:217], v98 src0_sel:WORD_1
	v_pk_fma_f32 v[222:223], v[52:53], v[218:219], v[222:223]
	v_pk_fma_f32 v[224:225], v[54:55], v[220:221], v[224:225]
	v_cvt_pk_f32_fp8_e32 v[218:219], v99
	v_cvt_pk_f32_fp8_sdwa v[220:221], v99 src0_sel:WORD_1
	v_pk_fma_f32 v[222:223], v[56:57], v[214:215], v[222:223]
	v_pk_fma_f32 v[224:225], v[58:59], v[216:217], v[224:225]
	v_pk_fma_f32 v[222:223], v[60:61], v[218:219], v[222:223]
	v_pk_fma_f32 v[224:225], v[62:63], v[220:221], v[224:225]
	v_pk_add_f32 v[222:223], v[222:223], v[224:225]
	s_nop 0
	v_add_f32_e32 v226, v222, v223
	v_cvt_pk_f32_fp8_e32 v[214:215], v100
	v_cvt_pk_f32_fp8_sdwa v[216:217], v100 src0_sel:WORD_1
	v_cvt_pk_f32_fp8_e32 v[218:219], v101
	v_cvt_pk_f32_fp8_sdwa v[220:221], v101 src0_sel:WORD_1
	v_pk_mul_f32 v[222:223], v[48:49], v[214:215]
	v_pk_mul_f32 v[224:225], v[50:51], v[216:217]
	v_cvt_pk_f32_fp8_e32 v[214:215], v102
	v_cvt_pk_f32_fp8_sdwa v[216:217], v102 src0_sel:WORD_1
	v_pk_fma_f32 v[222:223], v[52:53], v[218:219], v[222:223]
	v_pk_fma_f32 v[224:225], v[54:55], v[220:221], v[224:225]
	v_cvt_pk_f32_fp8_e32 v[218:219], v103
	v_cvt_pk_f32_fp8_sdwa v[220:221], v103 src0_sel:WORD_1
	v_pk_fma_f32 v[222:223], v[56:57], v[214:215], v[222:223]
	v_pk_fma_f32 v[224:225], v[58:59], v[216:217], v[224:225]
	v_pk_fma_f32 v[222:223], v[60:61], v[218:219], v[222:223]
	v_pk_fma_f32 v[224:225], v[62:63], v[220:221], v[224:225]
	v_pk_add_f32 v[222:223], v[222:223], v[224:225]
	s_nop 0
	v_add_f32_e32 v227, v222, v223
	v_cvt_pk_f32_fp8_e32 v[214:215], v104
	v_cvt_pk_f32_fp8_sdwa v[216:217], v104 src0_sel:WORD_1
	v_cvt_pk_f32_fp8_e32 v[218:219], v105
	v_cvt_pk_f32_fp8_sdwa v[220:221], v105 src0_sel:WORD_1
	v_pk_mul_f32 v[222:223], v[48:49], v[214:215]
	v_pk_mul_f32 v[224:225], v[50:51], v[216:217]
	v_cvt_pk_f32_fp8_e32 v[214:215], v106
	v_cvt_pk_f32_fp8_sdwa v[216:217], v106 src0_sel:WORD_1
	v_pk_fma_f32 v[222:223], v[52:53], v[218:219], v[222:223]
	v_pk_fma_f32 v[224:225], v[54:55], v[220:221], v[224:225]
	v_cvt_pk_f32_fp8_e32 v[218:219], v107
	v_cvt_pk_f32_fp8_sdwa v[220:221], v107 src0_sel:WORD_1
	v_pk_fma_f32 v[222:223], v[56:57], v[214:215], v[222:223]
	v_pk_fma_f32 v[224:225], v[58:59], v[216:217], v[224:225]
	v_pk_fma_f32 v[222:223], v[60:61], v[218:219], v[222:223]
	v_pk_fma_f32 v[224:225], v[62:63], v[220:221], v[224:225]
	v_pk_add_f32 v[222:223], v[222:223], v[224:225]
	s_nop 0
	v_add_f32_e32 v228, v222, v223
	v_cvt_pk_f32_fp8_e32 v[214:215], v108
	v_cvt_pk_f32_fp8_sdwa v[216:217], v108 src0_sel:WORD_1
	v_cvt_pk_f32_fp8_e32 v[218:219], v109
	v_cvt_pk_f32_fp8_sdwa v[220:221], v109 src0_sel:WORD_1
	v_pk_mul_f32 v[222:223], v[48:49], v[214:215]
	v_pk_mul_f32 v[224:225], v[50:51], v[216:217]
	v_cvt_pk_f32_fp8_e32 v[214:215], v110
	v_cvt_pk_f32_fp8_sdwa v[216:217], v110 src0_sel:WORD_1
	v_pk_fma_f32 v[222:223], v[52:53], v[218:219], v[222:223]
	v_pk_fma_f32 v[224:225], v[54:55], v[220:221], v[224:225]
	v_cvt_pk_f32_fp8_e32 v[218:219], v111
	v_cvt_pk_f32_fp8_sdwa v[220:221], v111 src0_sel:WORD_1
	v_pk_fma_f32 v[222:223], v[56:57], v[214:215], v[222:223]
	v_pk_fma_f32 v[224:225], v[58:59], v[216:217], v[224:225]
	v_pk_fma_f32 v[222:223], v[60:61], v[218:219], v[222:223]
	v_pk_fma_f32 v[224:225], v[62:63], v[220:221], v[224:225]
	v_pk_add_f32 v[222:223], v[222:223], v[224:225]
	s_nop 0
	v_add_f32_e32 v229, v222, v223
	v_cvt_pk_f32_fp8_e32 v[214:215], v112
	v_cvt_pk_f32_fp8_sdwa v[216:217], v112 src0_sel:WORD_1
	v_cvt_pk_f32_fp8_e32 v[218:219], v113
	v_cvt_pk_f32_fp8_sdwa v[220:221], v113 src0_sel:WORD_1
	v_pk_mul_f32 v[222:223], v[48:49], v[214:215]
	v_pk_mul_f32 v[224:225], v[50:51], v[216:217]
	v_cvt_pk_f32_fp8_e32 v[214:215], v114
	v_cvt_pk_f32_fp8_sdwa v[216:217], v114 src0_sel:WORD_1
	v_pk_fma_f32 v[222:223], v[52:53], v[218:219], v[222:223]
	v_pk_fma_f32 v[224:225], v[54:55], v[220:221], v[224:225]
	v_cvt_pk_f32_fp8_e32 v[218:219], v115
	v_cvt_pk_f32_fp8_sdwa v[220:221], v115 src0_sel:WORD_1
	v_pk_fma_f32 v[222:223], v[56:57], v[214:215], v[222:223]
	v_pk_fma_f32 v[224:225], v[58:59], v[216:217], v[224:225]
	v_pk_fma_f32 v[222:223], v[60:61], v[218:219], v[222:223]
	v_pk_fma_f32 v[224:225], v[62:63], v[220:221], v[224:225]
	v_pk_add_f32 v[222:223], v[222:223], v[224:225]
	s_nop 0
	v_add_f32_e32 v230, v222, v223
	v_cvt_pk_f32_fp8_e32 v[214:215], v116
	v_cvt_pk_f32_fp8_sdwa v[216:217], v116 src0_sel:WORD_1
	v_cvt_pk_f32_fp8_e32 v[218:219], v117
	v_cvt_pk_f32_fp8_sdwa v[220:221], v117 src0_sel:WORD_1
	v_pk_mul_f32 v[222:223], v[48:49], v[214:215]
	v_pk_mul_f32 v[224:225], v[50:51], v[216:217]
	v_cvt_pk_f32_fp8_e32 v[214:215], v118
	v_cvt_pk_f32_fp8_sdwa v[216:217], v118 src0_sel:WORD_1
	v_pk_fma_f32 v[222:223], v[52:53], v[218:219], v[222:223]
	v_pk_fma_f32 v[224:225], v[54:55], v[220:221], v[224:225]
	v_cvt_pk_f32_fp8_e32 v[218:219], v119
	v_cvt_pk_f32_fp8_sdwa v[220:221], v119 src0_sel:WORD_1
	v_pk_fma_f32 v[222:223], v[56:57], v[214:215], v[222:223]
	v_pk_fma_f32 v[224:225], v[58:59], v[216:217], v[224:225]
	v_pk_fma_f32 v[222:223], v[60:61], v[218:219], v[222:223]
	v_pk_fma_f32 v[224:225], v[62:63], v[220:221], v[224:225]
	v_pk_add_f32 v[222:223], v[222:223], v[224:225]
	s_nop 0
	v_add_f32_e32 v231, v222, v223
	v_cvt_pk_f32_fp8_e32 v[214:215], v120
	v_cvt_pk_f32_fp8_sdwa v[216:217], v120 src0_sel:WORD_1
	v_cvt_pk_f32_fp8_e32 v[218:219], v121
; DI float bflo(unsigned u) { return __uint_as_float(u << 16); }
; DI float bfhi(unsigned u) { return __uint_as_float(u & 0xffff0000u); }
; template <bool STORE>
; DI void peer_item(const Params& p, int item, char* smem) {
;     ...
;     float xf[16];
;     {
; #pragma unroll
;       for (int i = 0; i < 4; ++i) {
;         const uint2 xv = *(const uint2*)(XN2 + tok * 1024 + 256 * i + lane * 4);
;         xf[4 * i] = bflo(xv.x); xf[4 * i + 1] = bfhi(xv.x); xf[4 * i + 2] = bflo(xv.y); xf[4 * i + 3] = bfhi(xv.y);
;       }
;     }
; #pragma unroll 2
;     for (int k = 0; k < 128; k += 8) {
;       u32x4 uq[8];
;       const int emine = e_s[tl * 128 + k + (lane >> 3)];
;       const float gmine = g_s[tl * 128 + k + (lane >> 3)];
;       const float su = SU[emine], sv = SV[emine];
; #pragma unroll
;       for (int u = 0; u < 8; ++u) {
;         int e = e_s[tl * 128 + k + u];
;         uq[u] = *(const u32x4*)(U8 + (size_t)e * 1024 + lane * 16);
;       }
;       float part[8];
; #pragma unroll
;       for (int u = 0; u < 8; ++u) {
;         float d = 0.f;
; #pragma unroll
;         for (int i = 0; i < 4; ++i) {
;           f32x2_t lo = __builtin_amdgcn_cvt_pk_f32_fp8((int)uq[u][i], false);
;           f32x2_t hi = __builtin_amdgcn_cvt_pk_f32_fp8((int)uq[u][i], true);
;           d += xf[4 * i] * lo.x + xf[4 * i + 1] * lo.y + xf[4 * i + 2] * hi.x + xf[4 * i + 3] * hi.y;
;         }
;         part[u] = d;
;       }
;       float q4[4], r2[2], h;
; #pragma unroll
;       for (int j = 0; j < 4; ++j) {
;         float mine = b5 ? part[j + 4] : part[j];
;         float other = b5 ? part[j] : part[j + 4];
;         q4[j] = mine + __shfl_xor(other, 32);
;       }
; #pragma unroll
;       for (int j = 0; j < 2; ++j) {
;         float mine = b4 ? q4[j + 2] : q4[j];
;         float other = b4 ? q4[j] : q4[j + 2];
;         r2[j] = mine + __shfl_xor(other, 16);
;       }
;       {
;         float mine = b3 ? r2[1] : r2[0];
;         float other = b3 ? r2[0] : r2[1];
;         h = mine + __shfl_xor(other, 8);
;       }
;       h += __shfl_xor(h, 4);
;       h += __shfl_xor(h, 2);
;       h += __shfl_xor(h, 1);
;       const float amine = gelu_exact(h * su) * gmine * sv;
;       if ((lane & 7) == 0) {
;         EG[tok * 128 + k + (lane >> 3)] = emine;
;         AG[tok * 128 + k + (lane >> 3)] = amine;
;       }
;     }
	v_cvt_pk_f32_fp8_sdwa v[220:221], v121 src0_sel:WORD_1
	v_pk_mul_f32 v[222:223], v[48:49], v[214:215]
	v_pk_mul_f32 v[224:225], v[50:51], v[216:217]
	v_cvt_pk_f32_fp8_e32 v[214:215], v122
	v_cvt_pk_f32_fp8_sdwa v[216:217], v122 src0_sel:WORD_1
	v_pk_fma_f32 v[222:223], v[52:53], v[218:219], v[222:223]
	v_pk_fma_f32 v[224:225], v[54:55], v[220:221], v[224:225]
	v_cvt_pk_f32_fp8_e32 v[218:219], v123
	v_cvt_pk_f32_fp8_sdwa v[220:221], v123 src0_sel:WORD_1
	v_pk_fma_f32 v[222:223], v[56:57], v[214:215], v[222:223]
	v_pk_fma_f32 v[224:225], v[58:59], v[216:217], v[224:225]
	v_pk_fma_f32 v[222:223], v[60:61], v[218:219], v[222:223]
	v_pk_fma_f32 v[224:225], v[62:63], v[220:221], v[224:225]
	v_pk_add_f32 v[222:223], v[222:223], v[224:225]
	s_nop 0
	v_add_f32_e32 v232, v222, v223
	v_cvt_pk_f32_fp8_e32 v[214:215], v124
	v_cvt_pk_f32_fp8_sdwa v[216:217], v124 src0_sel:WORD_1
	v_cvt_pk_f32_fp8_e32 v[218:219], v125
	v_cvt_pk_f32_fp8_sdwa v[220:221], v125 src0_sel:WORD_1
	v_pk_mul_f32 v[222:223], v[48:49], v[214:215]
	v_pk_mul_f32 v[224:225], v[50:51], v[216:217]
	v_cvt_pk_f32_fp8_e32 v[214:215], v126
	v_cvt_pk_f32_fp8_sdwa v[216:217], v126 src0_sel:WORD_1
	v_pk_fma_f32 v[222:223], v[52:53], v[218:219], v[222:223]
	v_pk_fma_f32 v[224:225], v[54:55], v[220:221], v[224:225]
	v_cvt_pk_f32_fp8_e32 v[218:219], v127
	v_cvt_pk_f32_fp8_sdwa v[220:221], v127 src0_sel:WORD_1
	v_pk_fma_f32 v[222:223], v[56:57], v[214:215], v[222:223]
	v_pk_fma_f32 v[224:225], v[58:59], v[216:217], v[224:225]
	v_pk_fma_f32 v[222:223], v[60:61], v[218:219], v[222:223]
	v_pk_fma_f32 v[224:225], v[62:63], v[220:221], v[224:225]
	v_pk_add_f32 v[222:223], v[222:223], v[224:225]
	s_nop 0
	v_add_f32_e32 v233, v222, v223
	v_permlane32_swap_b32_e32 v226, v230
	v_permlane32_swap_b32_e32 v227, v231
	v_permlane32_swap_b32_e32 v228, v232
	v_permlane32_swap_b32_e32 v229, v233
	v_add_f32_e32 v226, v226, v230
	v_add_f32_e32 v228, v228, v232
	v_add_f32_e32 v227, v227, v231
	v_add_f32_e32 v229, v229, v233
	s_nop 1
	v_permlane16_swap_b32_e32 v226, v228
	v_permlane16_swap_b32_e32 v227, v229
	v_add_f32_e32 v226, v226, v228
	v_add_f32_e32 v227, v227, v229
	s_nop 0
	v_cndmask_b32_e64 v230, v226, v227, s[24:25]
	v_cndmask_b32_e64 v231, v227, v226, s[24:25]
	s_nop 1
	v_add_f32_dpp v232, v231, v230 row_ror:8 row_mask:0xf bank_mask:0xf
	s_nop 1
	v_add_f32_dpp v233, v232, v232 quad_perm:[1,0,3,2] row_mask:0xf bank_mask:0xf
	s_nop 1
	v_add_f32_dpp v232, v233, v233 quad_perm:[2,3,0,1] row_mask:0xf bank_mask:0xf
	s_nop 1
	v_add_f32_dpp v233, v232, v232 row_half_mirror row_mask:0xf bank_mask:0xf
	ds_write_b32 v235, v233 offset:34336
	s_mov_b32 s72, s58
	s_mov_b32 s73, s59
	s_mov_b32 s74, s60
	s_mov_b32 s75, s61
	s_mov_b32 s76, s62
	s_mov_b32 s77, s63
	s_mov_b32 s78, s64
	s_mov_b32 s79, s65
	s_add_u32 s58, s58, 8
	s_add_u32 s59, s59, 8
	s_add_u32 s60, s60, 8
	s_add_u32 s61, s61, 8
	s_add_u32 s62, s62, 8
	s_add_u32 s63, s63, 8
	s_add_u32 s64, s64, 8
	s_add_u32 s65, s65, 8
	s_and_b32 s58, s58, 63
	s_and_b32 s59, s59, 63
	s_and_b32 s60, s60, 63
	s_and_b32 s61, s61, 63
	s_and_b32 s62, s62, 63
	s_and_b32 s63, s63, 63
	s_and_b32 s64, s64, 63
	s_and_b32 s65, s65, 63
	v_add_u32_e32 v235, 64, v235
	s_add_u32 s12, s12, 1
	s_cmp_lt_u32 s12, 8
	s_cbranch_scc1 .Lup_kA
	s_waitcnt vmcnt(0)
	s_lshl_b32 s13, s14, 11
	s_add_u32 s32, s2, s13
	s_addc_u32 s33, s3, 0
	s_add_u32 s34, s32, 8192
	s_addc_u32 s35, s33, 0
	global_load_dwordx2 v[66:67], v239, s[34:35] offset:0
	global_load_dwordx2 v[70:71], v239, s[34:35] offset:512
	global_load_dwordx2 v[74:75], v239, s[34:35] offset:1024
	global_load_dwordx2 v[78:79], v239, s[34:35] offset:1536
	s_add_u32 s34, s32, 10240
	s_addc_u32 s35, s33, 0
	global_load_dwordx2 v[82:83], v239, s[34:35] offset:0
	global_load_dwordx2 v[86:87], v239, s[34:35] offset:512
	global_load_dwordx2 v[90:91], v239, s[34:35] offset:1024
	global_load_dwordx2 v[94:95], v239, s[34:35] offset:1536
	s_add_u32 s34, s32, 12288
	s_addc_u32 s35, s33, 0
	global_load_dwordx2 v[98:99], v239, s[34:35] offset:0
	global_load_dwordx2 v[102:103], v239, s[34:35] offset:512
	global_load_dwordx2 v[106:107], v239, s[34:35] offset:1024
	global_load_dwordx2 v[110:111], v239, s[34:35] offset:1536
	s_add_u32 s34, s32, 14336
	s_addc_u32 s35, s33, 0
	global_load_dwordx2 v[114:115], v239, s[34:35] offset:0
	global_load_dwordx2 v[118:119], v239, s[34:35] offset:512
	global_load_dwordx2 v[122:123], v239, s[34:35] offset:1024
	global_load_dwordx2 v[126:127], v239, s[34:35] offset:1536
	v_subrev_u32_e32 v235, 512, v235
	s_waitcnt vmcnt(0)
; DI float bflo(unsigned u) { return __uint_as_float(u << 16); }
; DI float bfhi(unsigned u) { return __uint_as_float(u & 0xffff0000u); }
; template <bool STORE>
; DI void peer_item(const Params& p, int item, char* smem) {
;     ...
;     float xf[16];
;     {
; #pragma unroll
;       for (int i = 0; i < 4; ++i) {
;         const uint2 xv = *(const uint2*)(XN2 + tok * 1024 + 256 * i + lane * 4);
;         xf[4 * i] = bflo(xv.x); xf[4 * i + 1] = bfhi(xv.x); xf[4 * i + 2] = bflo(xv.y); xf[4 * i + 3] = bfhi(xv.y);
;       }
;     }
;     ...
; #pragma unroll
;       for (int u = 0; u < 8; ++u) {
;         int e = e_s[tl * 128 + k + u];
;         uq[u] = *(const u32x4*)(U8 + (size_t)e * 1024 + lane * 16);
;       }
	v_lshlrev_b32_e32 v64, 16, v66
	v_and_b32_e32 v65, 0xffff0000, v66
	v_lshlrev_b32_e32 v66, 16, v67
	v_and_b32_e32 v67, 0xffff0000, v67
	v_lshlrev_b32_e32 v68, 16, v70
	v_and_b32_e32 v69, 0xffff0000, v70
	v_lshlrev_b32_e32 v70, 16, v71
	v_and_b32_e32 v71, 0xffff0000, v71
	v_lshlrev_b32_e32 v72, 16, v74
	v_and_b32_e32 v73, 0xffff0000, v74
	v_lshlrev_b32_e32 v74, 16, v75
	v_and_b32_e32 v75, 0xffff0000, v75
	v_lshlrev_b32_e32 v76, 16, v78
	v_and_b32_e32 v77, 0xffff0000, v78
	v_lshlrev_b32_e32 v78, 16, v79
	v_and_b32_e32 v79, 0xffff0000, v79
	v_lshlrev_b32_e32 v80, 16, v82
	v_and_b32_e32 v81, 0xffff0000, v82
	v_lshlrev_b32_e32 v82, 16, v83
	v_and_b32_e32 v83, 0xffff0000, v83
	v_lshlrev_b32_e32 v84, 16, v86
	v_and_b32_e32 v85, 0xffff0000, v86
	v_lshlrev_b32_e32 v86, 16, v87
	v_and_b32_e32 v87, 0xffff0000, v87
	v_lshlrev_b32_e32 v88, 16, v90
	v_and_b32_e32 v89, 0xffff0000, v90
	v_lshlrev_b32_e32 v90, 16, v91
	v_and_b32_e32 v91, 0xffff0000, v91
	v_lshlrev_b32_e32 v92, 16, v94
	v_and_b32_e32 v93, 0xffff0000, v94
	v_lshlrev_b32_e32 v94, 16, v95
	v_and_b32_e32 v95, 0xffff0000, v95
	v_lshlrev_b32_e32 v96, 16, v98
	v_and_b32_e32 v97, 0xffff0000, v98
	v_lshlrev_b32_e32 v98, 16, v99
	v_and_b32_e32 v99, 0xffff0000, v99
	v_lshlrev_b32_e32 v100, 16, v102
	v_and_b32_e32 v101, 0xffff0000, v102
	v_lshlrev_b32_e32 v102, 16, v103
	v_and_b32_e32 v103, 0xffff0000, v103
	v_lshlrev_b32_e32 v104, 16, v106
	v_and_b32_e32 v105, 0xffff0000, v106
	v_lshlrev_b32_e32 v106, 16, v107
	v_and_b32_e32 v107, 0xffff0000, v107
	v_lshlrev_b32_e32 v108, 16, v110
	v_and_b32_e32 v109, 0xffff0000, v110
	v_lshlrev_b32_e32 v110, 16, v111
	v_and_b32_e32 v111, 0xffff0000, v111
	v_lshlrev_b32_e32 v112, 16, v114
	v_and_b32_e32 v113, 0xffff0000, v114
	v_lshlrev_b32_e32 v114, 16, v115
	v_and_b32_e32 v115, 0xffff0000, v115
	v_lshlrev_b32_e32 v116, 16, v118
	v_and_b32_e32 v117, 0xffff0000, v118
	v_lshlrev_b32_e32 v118, 16, v119
	v_and_b32_e32 v119, 0xffff0000, v119
	v_lshlrev_b32_e32 v120, 16, v122
	v_and_b32_e32 v121, 0xffff0000, v122
	v_lshlrev_b32_e32 v122, 16, v123
	v_and_b32_e32 v123, 0xffff0000, v123
	v_lshlrev_b32_e32 v124, 16, v126
	v_and_b32_e32 v125, 0xffff0000, v126
	v_lshlrev_b32_e32 v126, 16, v127
	v_and_b32_e32 v127, 0xffff0000, v127
	s_mov_b32 s72, 0
	s_mov_b32 s73, 1
	s_mov_b32 s74, 2
	s_mov_b32 s75, 3
	s_mov_b32 s76, 4
	s_mov_b32 s77, 5
	s_mov_b32 s78, 6
	s_mov_b32 s79, 7
	s_mov_b32 s58, 8
	s_mov_b32 s59, 9
	s_mov_b32 s60, 10
	s_mov_b32 s61, 11
	s_mov_b32 s62, 12
	s_mov_b32 s63, 13
	s_mov_b32 s64, 14
	s_mov_b32 s65, 15
	s_nop 0
	v_readlane_b32 s48, v136, s72
	v_readlane_b32 s49, v136, s73
	v_readlane_b32 s50, v136, s74
	v_readlane_b32 s51, v136, s75
	v_readlane_b32 s52, v136, s76
	v_readlane_b32 s53, v136, s77
	v_readlane_b32 s54, v136, s78
	v_readlane_b32 s55, v136, s79
	s_add_u32 s32, s0, s48
	s_addc_u32 s33, s1, 0
	s_add_u32 s34, s0, s49
	s_addc_u32 s35, s1, 0
	s_add_u32 s36, s0, s50
	s_addc_u32 s37, s1, 0
	s_add_u32 s38, s0, s51
	s_addc_u32 s39, s1, 0
	s_add_u32 s40, s0, s52
	s_addc_u32 s41, s1, 0
	s_add_u32 s42, s0, s53
	s_addc_u32 s43, s1, 0
	s_add_u32 s44, s0, s54
	s_addc_u32 s45, s1, 0
	s_add_u32 s46, s0, s55
	s_addc_u32 s47, s1, 0
	global_load_dwordx4 v[144:147], v234, s[32:33]
	global_load_dwordx4 v[148:151], v234, s[34:35]
	global_load_dwordx4 v[152:155], v234, s[36:37]
	global_load_dwordx4 v[156:159], v234, s[38:39]
	global_load_dwordx4 v[160:163], v234, s[40:41]
	global_load_dwordx4 v[164:167], v234, s[42:43]
	global_load_dwordx4 v[168:171], v234, s[44:45]
	global_load_dwordx4 v[172:175], v234, s[46:47]
	v_readlane_b32 s48, v138, s72
	v_readlane_b32 s49, v138, s73
	v_readlane_b32 s50, v138, s74
	v_readlane_b32 s51, v138, s75
	v_readlane_b32 s52, v138, s76
	v_readlane_b32 s53, v138, s77
	v_readlane_b32 s54, v138, s78
	v_readlane_b32 s55, v138, s79
	s_add_u32 s32, s0, s48
	s_addc_u32 s33, s1, 0
	s_add_u32 s34, s0, s49
	s_addc_u32 s35, s1, 0
	s_add_u32 s36, s0, s50
	s_addc_u32 s37, s1, 0
	s_add_u32 s38, s0, s51
	s_addc_u32 s39, s1, 0
	s_add_u32 s40, s0, s52
	s_addc_u32 s41, s1, 0
	s_add_u32 s42, s0, s53
	s_addc_u32 s43, s1, 0
	s_add_u32 s44, s0, s54
	s_addc_u32 s45, s1, 0
	s_add_u32 s46, s0, s55
	s_addc_u32 s47, s1, 0
	global_load_dwordx4 v[176:179], v234, s[32:33]
	global_load_dwordx4 v[180:183], v234, s[34:35]
	global_load_dwordx4 v[184:187], v234, s[36:37]
	global_load_dwordx4 v[188:191], v234, s[38:39]
	global_load_dwordx4 v[192:195], v234, s[40:41]
	global_load_dwordx4 v[196:199], v234, s[42:43]
	global_load_dwordx4 v[200:203], v234, s[44:45]
	global_load_dwordx4 v[204:207], v234, s[46:47]
	v_readlane_b32 s48, v140, s72
	v_readlane_b32 s49, v140, s73
	v_readlane_b32 s50, v140, s74
	v_readlane_b32 s51, v140, s75
	v_readlane_b32 s52, v140, s76
	v_readlane_b32 s53, v140, s77
	v_readlane_b32 s54, v140, s78
	v_readlane_b32 s55, v140, s79
	s_add_u32 s32, s0, s48
	s_addc_u32 s33, s1, 0
	s_add_u32 s34, s0, s49
	s_addc_u32 s35, s1, 0
	s_add_u32 s36, s0, s50
	s_addc_u32 s37, s1, 0
	s_add_u32 s38, s0, s51
	s_addc_u32 s39, s1, 0
	s_add_u32 s40, s0, s52
	s_addc_u32 s41, s1, 0
	s_add_u32 s42, s0, s53
	s_addc_u32 s43, s1, 0
	s_add_u32 s44, s0, s54
	s_addc_u32 s45, s1, 0
	s_add_u32 s46, s0, s55
	s_addc_u32 s47, s1, 0
	global_load_dwordx4 v[0:3], v234, s[32:33]
	global_load_dwordx4 v[4:7], v234, s[34:35]
	global_load_dwordx4 v[8:11], v234, s[36:37]
	global_load_dwordx4 v[12:15], v234, s[38:39]
	global_load_dwordx4 v[16:19], v234, s[40:41]
	global_load_dwordx4 v[20:23], v234, s[42:43]
	global_load_dwordx4 v[24:27], v234, s[44:45]
	global_load_dwordx4 v[28:31], v234, s[46:47]
	s_mov_b32 s12, 0
; template <bool STORE>
; DI void peer_item(const Params& p, int item, char* smem) {
;     ...
; #pragma unroll
;       for (int u = 0; u < 8; ++u) {
;         int e = e_s[tl * 128 + k + u];
;         uq[u] = *(const u32x4*)(U8 + (size_t)e * 1024 + lane * 16);
;       }
;       float part[8];
; #pragma unroll
;       for (int u = 0; u < 8; ++u) {
;         float d = 0.f;
; #pragma unroll
;         for (int i = 0; i < 4; ++i) {
;           f32x2_t lo = __builtin_amdgcn_cvt_pk_f32_fp8((int)uq[u][i], false);
;           f32x2_t hi = __builtin_amdgcn_cvt_pk_f32_fp8((int)uq[u][i], true);
;           d += xf[4 * i] * lo.x + xf[4 * i + 1] * lo.y + xf[4 * i + 2] * hi.x + xf[4 * i + 3] * hi.y;
;         }
;         part[u] = d;
;       }
.Lup_kB:
	v_readlane_b32 s48, v142, s72
	v_readlane_b32 s49, v142, s73
	v_readlane_b32 s50, v142, s74
	v_readlane_b32 s51, v142, s75
	v_readlane_b32 s52, v142, s76
	v_readlane_b32 s53, v142, s77
	v_readlane_b32 s54, v142, s78
	v_readlane_b32 s55, v142, s79
	s_add_u32 s32, s0, s48
	s_addc_u32 s33, s1, 0
	s_add_u32 s34, s0, s49
	s_addc_u32 s35, s1, 0
	s_add_u32 s36, s0, s50
	s_addc_u32 s37, s1, 0
	s_add_u32 s38, s0, s51
	s_addc_u32 s39, s1, 0
	s_add_u32 s40, s0, s52
	s_addc_u32 s41, s1, 0
	s_add_u32 s42, s0, s53
	s_addc_u32 s43, s1, 0
	s_add_u32 s44, s0, s54
	s_addc_u32 s45, s1, 0
	s_add_u32 s46, s0, s55
	s_addc_u32 s47, s1, 0
	global_load_dwordx4 v[32:35], v234, s[32:33]
	global_load_dwordx4 v[36:39], v234, s[34:35]
	global_load_dwordx4 v[40:43], v234, s[36:37]
	global_load_dwordx4 v[44:47], v234, s[38:39]
	global_load_dwordx4 v[48:51], v234, s[40:41]
	global_load_dwordx4 v[52:55], v234, s[42:43]
	global_load_dwordx4 v[56:59], v234, s[44:45]
	global_load_dwordx4 v[60:63], v234, s[46:47]
	s_waitcnt vmcnt(24)
	v_cvt_pk_f32_fp8_e32 v[214:215], v144
	v_cvt_pk_f32_fp8_sdwa v[216:217], v144 src0_sel:WORD_1
	v_cvt_pk_f32_fp8_e32 v[218:219], v145
	v_cvt_pk_f32_fp8_sdwa v[220:221], v145 src0_sel:WORD_1
	v_pk_mul_f32 v[222:223], v[64:65], v[214:215]
	v_pk_mul_f32 v[224:225], v[66:67], v[216:217]
	v_cvt_pk_f32_fp8_e32 v[214:215], v146
	v_cvt_pk_f32_fp8_sdwa v[216:217], v146 src0_sel:WORD_1
	v_pk_fma_f32 v[222:223], v[68:69], v[218:219], v[222:223]
	v_pk_fma_f32 v[224:225], v[70:71], v[220:221], v[224:225]
	v_cvt_pk_f32_fp8_e32 v[218:219], v147
	v_cvt_pk_f32_fp8_sdwa v[220:221], v147 src0_sel:WORD_1
	v_pk_fma_f32 v[222:223], v[72:73], v[214:215], v[222:223]
	v_pk_fma_f32 v[224:225], v[74:75], v[216:217], v[224:225]
	v_pk_fma_f32 v[222:223], v[76:77], v[218:219], v[222:223]
	v_pk_fma_f32 v[224:225], v[78:79], v[220:221], v[224:225]
	v_pk_add_f32 v[222:223], v[222:223], v[224:225]
	s_nop 0
	v_add_f32_e32 v226, v222, v223
	v_cvt_pk_f32_fp8_e32 v[214:215], v148
	v_cvt_pk_f32_fp8_sdwa v[216:217], v148 src0_sel:WORD_1
	v_cvt_pk_f32_fp8_e32 v[218:219], v149
	v_cvt_pk_f32_fp8_sdwa v[220:221], v149 src0_sel:WORD_1
	v_pk_mul_f32 v[222:223], v[64:65], v[214:215]
	v_pk_mul_f32 v[224:225], v[66:67], v[216:217]
	v_cvt_pk_f32_fp8_e32 v[214:215], v150
	v_cvt_pk_f32_fp8_sdwa v[216:217], v150 src0_sel:WORD_1
	v_pk_fma_f32 v[222:223], v[68:69], v[218:219], v[222:223]
	v_pk_fma_f32 v[224:225], v[70:71], v[220:221], v[224:225]
	v_cvt_pk_f32_fp8_e32 v[218:219], v151
	v_cvt_pk_f32_fp8_sdwa v[220:221], v151 src0_sel:WORD_1
	v_pk_fma_f32 v[222:223], v[72:73], v[214:215], v[222:223]
	v_pk_fma_f32 v[224:225], v[74:75], v[216:217], v[224:225]
	v_pk_fma_f32 v[222:223], v[76:77], v[218:219], v[222:223]
	v_pk_fma_f32 v[224:225], v[78:79], v[220:221], v[224:225]
	v_pk_add_f32 v[222:223], v[222:223], v[224:225]
	s_nop 0
	v_add_f32_e32 v227, v222, v223
	v_cvt_pk_f32_fp8_e32 v[214:215], v152
	v_cvt_pk_f32_fp8_sdwa v[216:217], v152 src0_sel:WORD_1
	v_cvt_pk_f32_fp8_e32 v[218:219], v153
	v_cvt_pk_f32_fp8_sdwa v[220:221], v153 src0_sel:WORD_1
	v_pk_mul_f32 v[222:223], v[64:65], v[214:215]
	v_pk_mul_f32 v[224:225], v[66:67], v[216:217]
	v_cvt_pk_f32_fp8_e32 v[214:215], v154
	v_cvt_pk_f32_fp8_sdwa v[216:217], v154 src0_sel:WORD_1
	v_pk_fma_f32 v[222:223], v[68:69], v[218:219], v[222:223]
	v_pk_fma_f32 v[224:225], v[70:71], v[220:221], v[224:225]
	v_cvt_pk_f32_fp8_e32 v[218:219], v155
	v_cvt_pk_f32_fp8_sdwa v[220:221], v155 src0_sel:WORD_1
	v_pk_fma_f32 v[222:223], v[72:73], v[214:215], v[222:223]
	v_pk_fma_f32 v[224:225], v[74:75], v[216:217], v[224:225]
	v_pk_fma_f32 v[222:223], v[76:77], v[218:219], v[222:223]
	v_pk_fma_f32 v[224:225], v[78:79], v[220:221], v[224:225]
	v_pk_add_f32 v[222:223], v[222:223], v[224:225]
	s_nop 0
	v_add_f32_e32 v228, v222, v223
	v_cvt_pk_f32_fp8_e32 v[214:215], v156
	v_cvt_pk_f32_fp8_sdwa v[216:217], v156 src0_sel:WORD_1
	v_cvt_pk_f32_fp8_e32 v[218:219], v157
	v_cvt_pk_f32_fp8_sdwa v[220:221], v157 src0_sel:WORD_1
	v_pk_mul_f32 v[222:223], v[64:65], v[214:215]
	v_pk_mul_f32 v[224:225], v[66:67], v[216:217]
	v_cvt_pk_f32_fp8_e32 v[214:215], v158
	v_cvt_pk_f32_fp8_sdwa v[216:217], v158 src0_sel:WORD_1
	v_pk_fma_f32 v[222:223], v[68:69], v[218:219], v[222:223]
	v_pk_fma_f32 v[224:225], v[70:71], v[220:221], v[224:225]
	v_cvt_pk_f32_fp8_e32 v[218:219], v159
	v_cvt_pk_f32_fp8_sdwa v[220:221], v159 src0_sel:WORD_1
	v_pk_fma_f32 v[222:223], v[72:73], v[214:215], v[222:223]
	v_pk_fma_f32 v[224:225], v[74:75], v[216:217], v[224:225]
	v_pk_fma_f32 v[222:223], v[76:77], v[218:219], v[222:223]
	v_pk_fma_f32 v[224:225], v[78:79], v[220:221], v[224:225]
	v_pk_add_f32 v[222:223], v[222:223], v[224:225]
	s_nop 0
	v_add_f32_e32 v229, v222, v223
	v_cvt_pk_f32_fp8_e32 v[214:215], v160
	v_cvt_pk_f32_fp8_sdwa v[216:217], v160 src0_sel:WORD_1
	v_cvt_pk_f32_fp8_e32 v[218:219], v161
	v_cvt_pk_f32_fp8_sdwa v[220:221], v161 src0_sel:WORD_1
	v_pk_mul_f32 v[222:223], v[64:65], v[214:215]
	v_pk_mul_f32 v[224:225], v[66:67], v[216:217]
	v_cvt_pk_f32_fp8_e32 v[214:215], v162
	v_cvt_pk_f32_fp8_sdwa v[216:217], v162 src0_sel:WORD_1
	v_pk_fma_f32 v[222:223], v[68:69], v[218:219], v[222:223]
	v_pk_fma_f32 v[224:225], v[70:71], v[220:221], v[224:225]
	v_cvt_pk_f32_fp8_e32 v[218:219], v163
	v_cvt_pk_f32_fp8_sdwa v[220:221], v163 src0_sel:WORD_1
	v_pk_fma_f32 v[222:223], v[72:73], v[214:215], v[222:223]
	v_pk_fma_f32 v[224:225], v[74:75], v[216:217], v[224:225]
	v_pk_fma_f32 v[222:223], v[76:77], v[218:219], v[222:223]
	v_pk_fma_f32 v[224:225], v[78:79], v[220:221], v[224:225]
	v_pk_add_f32 v[222:223], v[222:223], v[224:225]
	s_nop 0
	v_add_f32_e32 v230, v222, v223
	v_cvt_pk_f32_fp8_e32 v[214:215], v164
; template <bool STORE>
; DI void peer_item(const Params& p, int item, char* smem) {
;     ...
;       for (int u = 0; u < 8; ++u) {
;         int e = e_s[tl * 128 + k + u];
;         uq[u] = *(const u32x4*)(U8 + (size_t)e * 1024 + lane * 16);
;       }
;       float part[8];
; #pragma unroll
;       for (int u = 0; u < 8; ++u) {
;         float d = 0.f;
; #pragma unroll
;         for (int i = 0; i < 4; ++i) {
;           f32x2_t lo = __builtin_amdgcn_cvt_pk_f32_fp8((int)uq[u][i], false);
;           f32x2_t hi = __builtin_amdgcn_cvt_pk_f32_fp8((int)uq[u][i], true);
;           d += xf[4 * i] * lo.x + xf[4 * i + 1] * lo.y + xf[4 * i + 2] * hi.x + xf[4 * i + 3] * hi.y;
;         }
;         part[u] = d;
;       }
;       float q4[4], r2[2], h;
; #pragma unroll
;       for (int j = 0; j < 4; ++j) {
;         float mine = b5 ? part[j + 4] : part[j];
;         float other = b5 ? part[j] : part[j + 4];
;         q4[j] = mine + __shfl_xor(other, 32);
;       }
; #pragma unroll
;       for (int j = 0; j < 2; ++j) {
;         float mine = b4 ? q4[j + 2] : q4[j];
;         float other = b4 ? q4[j] : q4[j + 2];
;         r2[j] = mine + __shfl_xor(other, 16);
;       }
;       {
;         float mine = b3 ? r2[1] : r2[0];
;         float other = b3 ? r2[0] : r2[1];
;         h = mine + __shfl_xor(other, 8);
;       }
;       h += __shfl_xor(h, 4);
;       h += __shfl_xor(h, 2);
;       h += __shfl_xor(h, 1);
	v_cvt_pk_f32_fp8_sdwa v[216:217], v164 src0_sel:WORD_1
	v_cvt_pk_f32_fp8_e32 v[218:219], v165
	v_cvt_pk_f32_fp8_sdwa v[220:221], v165 src0_sel:WORD_1
	v_pk_mul_f32 v[222:223], v[64:65], v[214:215]
	v_pk_mul_f32 v[224:225], v[66:67], v[216:217]
	v_cvt_pk_f32_fp8_e32 v[214:215], v166
	v_cvt_pk_f32_fp8_sdwa v[216:217], v166 src0_sel:WORD_1
	v_pk_fma_f32 v[222:223], v[68:69], v[218:219], v[222:223]
	v_pk_fma_f32 v[224:225], v[70:71], v[220:221], v[224:225]
	v_cvt_pk_f32_fp8_e32 v[218:219], v167
	v_cvt_pk_f32_fp8_sdwa v[220:221], v167 src0_sel:WORD_1
	v_pk_fma_f32 v[222:223], v[72:73], v[214:215], v[222:223]
	v_pk_fma_f32 v[224:225], v[74:75], v[216:217], v[224:225]
	v_pk_fma_f32 v[222:223], v[76:77], v[218:219], v[222:223]
	v_pk_fma_f32 v[224:225], v[78:79], v[220:221], v[224:225]
	v_pk_add_f32 v[222:223], v[222:223], v[224:225]
	s_nop 0
	v_add_f32_e32 v231, v222, v223
	v_cvt_pk_f32_fp8_e32 v[214:215], v168
	v_cvt_pk_f32_fp8_sdwa v[216:217], v168 src0_sel:WORD_1
	v_cvt_pk_f32_fp8_e32 v[218:219], v169
	v_cvt_pk_f32_fp8_sdwa v[220:221], v169 src0_sel:WORD_1
	v_pk_mul_f32 v[222:223], v[64:65], v[214:215]
	v_pk_mul_f32 v[224:225], v[66:67], v[216:217]
	v_cvt_pk_f32_fp8_e32 v[214:215], v170
	v_cvt_pk_f32_fp8_sdwa v[216:217], v170 src0_sel:WORD_1
	v_pk_fma_f32 v[222:223], v[68:69], v[218:219], v[222:223]
	v_pk_fma_f32 v[224:225], v[70:71], v[220:221], v[224:225]
	v_cvt_pk_f32_fp8_e32 v[218:219], v171
	v_cvt_pk_f32_fp8_sdwa v[220:221], v171 src0_sel:WORD_1
	v_pk_fma_f32 v[222:223], v[72:73], v[214:215], v[222:223]
	v_pk_fma_f32 v[224:225], v[74:75], v[216:217], v[224:225]
	v_pk_fma_f32 v[222:223], v[76:77], v[218:219], v[222:223]
	v_pk_fma_f32 v[224:225], v[78:79], v[220:221], v[224:225]
	v_pk_add_f32 v[222:223], v[222:223], v[224:225]
	s_nop 0
	v_add_f32_e32 v232, v222, v223
	v_cvt_pk_f32_fp8_e32 v[214:215], v172
	v_cvt_pk_f32_fp8_sdwa v[216:217], v172 src0_sel:WORD_1
	v_cvt_pk_f32_fp8_e32 v[218:219], v173
	v_cvt_pk_f32_fp8_sdwa v[220:221], v173 src0_sel:WORD_1
	v_pk_mul_f32 v[222:223], v[64:65], v[214:215]
	v_pk_mul_f32 v[224:225], v[66:67], v[216:217]
	v_cvt_pk_f32_fp8_e32 v[214:215], v174
	v_cvt_pk_f32_fp8_sdwa v[216:217], v174 src0_sel:WORD_1
	v_pk_fma_f32 v[222:223], v[68:69], v[218:219], v[222:223]
	v_pk_fma_f32 v[224:225], v[70:71], v[220:221], v[224:225]
	v_cvt_pk_f32_fp8_e32 v[218:219], v175
	v_cvt_pk_f32_fp8_sdwa v[220:221], v175 src0_sel:WORD_1
	v_pk_fma_f32 v[222:223], v[72:73], v[214:215], v[222:223]
	v_pk_fma_f32 v[224:225], v[74:75], v[216:217], v[224:225]
	v_pk_fma_f32 v[222:223], v[76:77], v[218:219], v[222:223]
	v_pk_fma_f32 v[224:225], v[78:79], v[220:221], v[224:225]
	v_pk_add_f32 v[222:223], v[222:223], v[224:225]
	s_nop 0
	v_add_f32_e32 v233, v222, v223
	v_permlane32_swap_b32_e32 v226, v230
	v_permlane32_swap_b32_e32 v227, v231
	v_permlane32_swap_b32_e32 v228, v232
	v_permlane32_swap_b32_e32 v229, v233
	v_add_f32_e32 v226, v226, v230
	v_add_f32_e32 v228, v228, v232
	v_add_f32_e32 v227, v227, v231
	v_add_f32_e32 v229, v229, v233
	s_nop 1
	v_permlane16_swap_b32_e32 v226, v228
	v_permlane16_swap_b32_e32 v227, v229
	v_add_f32_e32 v226, v226, v228
	v_add_f32_e32 v227, v227, v229
	s_nop 0
	v_cndmask_b32_e64 v230, v226, v227, s[24:25]
	v_cndmask_b32_e64 v231, v227, v226, s[24:25]
	s_nop 1
	v_add_f32_dpp v232, v231, v230 row_ror:8 row_mask:0xf bank_mask:0xf
	s_nop 1
	v_add_f32_dpp v233, v232, v232 quad_perm:[1,0,3,2] row_mask:0xf bank_mask:0xf
	s_nop 1
	v_add_f32_dpp v232, v233, v233 quad_perm:[2,3,0,1] row_mask:0xf bank_mask:0xf
	s_nop 1
	v_add_f32_dpp v233, v232, v232 row_half_mirror row_mask:0xf bank_mask:0xf
	ds_write_b32 v235, v233 offset:34816
	v_readlane_b32 s48, v137, s72
	v_readlane_b32 s49, v137, s73
	v_readlane_b32 s50, v137, s74
	v_readlane_b32 s51, v137, s75
	v_readlane_b32 s52, v137, s76
	v_readlane_b32 s53, v137, s77
	v_readlane_b32 s54, v137, s78
	v_readlane_b32 s55, v137, s79
	s_add_u32 s32, s0, s48
	s_addc_u32 s33, s1, 0
	s_add_u32 s34, s0, s49
	s_addc_u32 s35, s1, 0
	s_add_u32 s36, s0, s50
	s_addc_u32 s37, s1, 0
	s_add_u32 s38, s0, s51
	s_addc_u32 s39, s1, 0
	s_add_u32 s40, s0, s52
	s_addc_u32 s41, s1, 0
	s_add_u32 s42, s0, s53
	s_addc_u32 s43, s1, 0
	s_add_u32 s44, s0, s54
	s_addc_u32 s45, s1, 0
	s_add_u32 s46, s0, s55
	s_addc_u32 s47, s1, 0
	global_load_dwordx4 v[144:147], v234, s[32:33]
	global_load_dwordx4 v[148:151], v234, s[34:35]
	global_load_dwordx4 v[152:155], v234, s[36:37]
	global_load_dwordx4 v[156:159], v234, s[38:39]
	global_load_dwordx4 v[160:163], v234, s[40:41]
	global_load_dwordx4 v[164:167], v234, s[42:43]
	global_load_dwordx4 v[168:171], v234, s[44:45]
	global_load_dwordx4 v[172:175], v234, s[46:47]
	s_waitcnt vmcnt(24)
; template <bool STORE>
; DI void peer_item(const Params& p, int item, char* smem) {
;     ...
;       float part[8];
; #pragma unroll
;       for (int u = 0; u < 8; ++u) {
;         float d = 0.f;
; #pragma unroll
;         for (int i = 0; i < 4; ++i) {
;           f32x2_t lo = __builtin_amdgcn_cvt_pk_f32_fp8((int)uq[u][i], false);
;           f32x2_t hi = __builtin_amdgcn_cvt_pk_f32_fp8((int)uq[u][i], true);
;           d += xf[4 * i] * lo.x + xf[4 * i + 1] * lo.y + xf[4 * i + 2] * hi.x + xf[4 * i + 3] * hi.y;
;         }
;         part[u] = d;
;       }
	v_cvt_pk_f32_fp8_e32 v[214:215], v176
	v_cvt_pk_f32_fp8_sdwa v[216:217], v176 src0_sel:WORD_1
	v_cvt_pk_f32_fp8_e32 v[218:219], v177
	v_cvt_pk_f32_fp8_sdwa v[220:221], v177 src0_sel:WORD_1
	v_pk_mul_f32 v[222:223], v[80:81], v[214:215]
	v_pk_mul_f32 v[224:225], v[82:83], v[216:217]
	v_cvt_pk_f32_fp8_e32 v[214:215], v178
	v_cvt_pk_f32_fp8_sdwa v[216:217], v178 src0_sel:WORD_1
	v_pk_fma_f32 v[222:223], v[84:85], v[218:219], v[222:223]
	v_pk_fma_f32 v[224:225], v[86:87], v[220:221], v[224:225]
	v_cvt_pk_f32_fp8_e32 v[218:219], v179
	v_cvt_pk_f32_fp8_sdwa v[220:221], v179 src0_sel:WORD_1
	v_pk_fma_f32 v[222:223], v[88:89], v[214:215], v[222:223]
	v_pk_fma_f32 v[224:225], v[90:91], v[216:217], v[224:225]
	v_pk_fma_f32 v[222:223], v[92:93], v[218:219], v[222:223]
	v_pk_fma_f32 v[224:225], v[94:95], v[220:221], v[224:225]
	v_pk_add_f32 v[222:223], v[222:223], v[224:225]
	s_nop 0
	v_add_f32_e32 v226, v222, v223
	v_cvt_pk_f32_fp8_e32 v[214:215], v180
	v_cvt_pk_f32_fp8_sdwa v[216:217], v180 src0_sel:WORD_1
	v_cvt_pk_f32_fp8_e32 v[218:219], v181
	v_cvt_pk_f32_fp8_sdwa v[220:221], v181 src0_sel:WORD_1
	v_pk_mul_f32 v[222:223], v[80:81], v[214:215]
	v_pk_mul_f32 v[224:225], v[82:83], v[216:217]
	v_cvt_pk_f32_fp8_e32 v[214:215], v182
	v_cvt_pk_f32_fp8_sdwa v[216:217], v182 src0_sel:WORD_1
	v_pk_fma_f32 v[222:223], v[84:85], v[218:219], v[222:223]
	v_pk_fma_f32 v[224:225], v[86:87], v[220:221], v[224:225]
	v_cvt_pk_f32_fp8_e32 v[218:219], v183
	v_cvt_pk_f32_fp8_sdwa v[220:221], v183 src0_sel:WORD_1
	v_pk_fma_f32 v[222:223], v[88:89], v[214:215], v[222:223]
	v_pk_fma_f32 v[224:225], v[90:91], v[216:217], v[224:225]
	v_pk_fma_f32 v[222:223], v[92:93], v[218:219], v[222:223]
	v_pk_fma_f32 v[224:225], v[94:95], v[220:221], v[224:225]
	v_pk_add_f32 v[222:223], v[222:223], v[224:225]
	s_nop 0
	v_add_f32_e32 v227, v222, v223
	v_cvt_pk_f32_fp8_e32 v[214:215], v184
	v_cvt_pk_f32_fp8_sdwa v[216:217], v184 src0_sel:WORD_1
	v_cvt_pk_f32_fp8_e32 v[218:219], v185
	v_cvt_pk_f32_fp8_sdwa v[220:221], v185 src0_sel:WORD_1
	v_pk_mul_f32 v[222:223], v[80:81], v[214:215]
	v_pk_mul_f32 v[224:225], v[82:83], v[216:217]
	v_cvt_pk_f32_fp8_e32 v[214:215], v186
	v_cvt_pk_f32_fp8_sdwa v[216:217], v186 src0_sel:WORD_1
	v_pk_fma_f32 v[222:223], v[84:85], v[218:219], v[222:223]
	v_pk_fma_f32 v[224:225], v[86:87], v[220:221], v[224:225]
	v_cvt_pk_f32_fp8_e32 v[218:219], v187
	v_cvt_pk_f32_fp8_sdwa v[220:221], v187 src0_sel:WORD_1
	v_pk_fma_f32 v[222:223], v[88:89], v[214:215], v[222:223]
	v_pk_fma_f32 v[224:225], v[90:91], v[216:217], v[224:225]
	v_pk_fma_f32 v[222:223], v[92:93], v[218:219], v[222:223]
	v_pk_fma_f32 v[224:225], v[94:95], v[220:221], v[224:225]
	v_pk_add_f32 v[222:223], v[222:223], v[224:225]
	s_nop 0
	v_add_f32_e32 v228, v222, v223
	v_cvt_pk_f32_fp8_e32 v[214:215], v188
	v_cvt_pk_f32_fp8_sdwa v[216:217], v188 src0_sel:WORD_1
	v_cvt_pk_f32_fp8_e32 v[218:219], v189
	v_cvt_pk_f32_fp8_sdwa v[220:221], v189 src0_sel:WORD_1
	v_pk_mul_f32 v[222:223], v[80:81], v[214:215]
	v_pk_mul_f32 v[224:225], v[82:83], v[216:217]
	v_cvt_pk_f32_fp8_e32 v[214:215], v190
	v_cvt_pk_f32_fp8_sdwa v[216:217], v190 src0_sel:WORD_1
	v_pk_fma_f32 v[222:223], v[84:85], v[218:219], v[222:223]
	v_pk_fma_f32 v[224:225], v[86:87], v[220:221], v[224:225]
	v_cvt_pk_f32_fp8_e32 v[218:219], v191
	v_cvt_pk_f32_fp8_sdwa v[220:221], v191 src0_sel:WORD_1
	v_pk_fma_f32 v[222:223], v[88:89], v[214:215], v[222:223]
	v_pk_fma_f32 v[224:225], v[90:91], v[216:217], v[224:225]
	v_pk_fma_f32 v[222:223], v[92:93], v[218:219], v[222:223]
	v_pk_fma_f32 v[224:225], v[94:95], v[220:221], v[224:225]
	v_pk_add_f32 v[222:223], v[222:223], v[224:225]
	s_nop 0
	v_add_f32_e32 v229, v222, v223
	v_cvt_pk_f32_fp8_e32 v[214:215], v192
	v_cvt_pk_f32_fp8_sdwa v[216:217], v192 src0_sel:WORD_1
	v_cvt_pk_f32_fp8_e32 v[218:219], v193
	v_cvt_pk_f32_fp8_sdwa v[220:221], v193 src0_sel:WORD_1
	v_pk_mul_f32 v[222:223], v[80:81], v[214:215]
	v_pk_mul_f32 v[224:225], v[82:83], v[216:217]
	v_cvt_pk_f32_fp8_e32 v[214:215], v194
	v_cvt_pk_f32_fp8_sdwa v[216:217], v194 src0_sel:WORD_1
	v_pk_fma_f32 v[222:223], v[84:85], v[218:219], v[222:223]
	v_pk_fma_f32 v[224:225], v[86:87], v[220:221], v[224:225]
	v_cvt_pk_f32_fp8_e32 v[218:219], v195
	v_cvt_pk_f32_fp8_sdwa v[220:221], v195 src0_sel:WORD_1
	v_pk_fma_f32 v[222:223], v[88:89], v[214:215], v[222:223]
	v_pk_fma_f32 v[224:225], v[90:91], v[216:217], v[224:225]
	v_pk_fma_f32 v[222:223], v[92:93], v[218:219], v[222:223]
	v_pk_fma_f32 v[224:225], v[94:95], v[220:221], v[224:225]
	v_pk_add_f32 v[222:223], v[222:223], v[224:225]
	s_nop 0
	v_add_f32_e32 v230, v222, v223
	v_cvt_pk_f32_fp8_e32 v[214:215], v196
	v_cvt_pk_f32_fp8_sdwa v[216:217], v196 src0_sel:WORD_1
	v_cvt_pk_f32_fp8_e32 v[218:219], v197
	v_cvt_pk_f32_fp8_sdwa v[220:221], v197 src0_sel:WORD_1
	v_pk_mul_f32 v[222:223], v[80:81], v[214:215]
	v_pk_mul_f32 v[224:225], v[82:83], v[216:217]
	v_cvt_pk_f32_fp8_e32 v[214:215], v198
	v_cvt_pk_f32_fp8_sdwa v[216:217], v198 src0_sel:WORD_1
	v_pk_fma_f32 v[222:223], v[84:85], v[218:219], v[222:223]
	v_pk_fma_f32 v[224:225], v[86:87], v[220:221], v[224:225]
	v_cvt_pk_f32_fp8_e32 v[218:219], v199
	v_cvt_pk_f32_fp8_sdwa v[220:221], v199 src0_sel:WORD_1
	v_pk_fma_f32 v[222:223], v[88:89], v[214:215], v[222:223]
	v_pk_fma_f32 v[224:225], v[90:91], v[216:217], v[224:225]
	v_pk_fma_f32 v[222:223], v[92:93], v[218:219], v[222:223]
	v_pk_fma_f32 v[224:225], v[94:95], v[220:221], v[224:225]
	v_pk_add_f32 v[222:223], v[222:223], v[224:225]
	s_nop 0
	v_add_f32_e32 v231, v222, v223
	v_cvt_pk_f32_fp8_e32 v[214:215], v200
	v_cvt_pk_f32_fp8_sdwa v[216:217], v200 src0_sel:WORD_1
	v_cvt_pk_f32_fp8_e32 v[218:219], v201
; template <bool STORE>
; DI void peer_item(const Params& p, int item, char* smem) {
;     ...
;       for (int u = 0; u < 8; ++u) {
;         int e = e_s[tl * 128 + k + u];
;         uq[u] = *(const u32x4*)(U8 + (size_t)e * 1024 + lane * 16);
;       }
;       float part[8];
; #pragma unroll
;       for (int u = 0; u < 8; ++u) {
;         float d = 0.f;
; #pragma unroll
;         for (int i = 0; i < 4; ++i) {
;           f32x2_t lo = __builtin_amdgcn_cvt_pk_f32_fp8((int)uq[u][i], false);
;           f32x2_t hi = __builtin_amdgcn_cvt_pk_f32_fp8((int)uq[u][i], true);
;           d += xf[4 * i] * lo.x + xf[4 * i + 1] * lo.y + xf[4 * i + 2] * hi.x + xf[4 * i + 3] * hi.y;
;         }
;         part[u] = d;
;       }
;       float q4[4], r2[2], h;
; #pragma unroll
;       for (int j = 0; j < 4; ++j) {
;         float mine = b5 ? part[j + 4] : part[j];
;         float other = b5 ? part[j] : part[j + 4];
;         q4[j] = mine + __shfl_xor(other, 32);
;       }
; #pragma unroll
;       for (int j = 0; j < 2; ++j) {
;         float mine = b4 ? q4[j + 2] : q4[j];
;         float other = b4 ? q4[j] : q4[j + 2];
;         r2[j] = mine + __shfl_xor(other, 16);
;       }
;       {
;         float mine = b3 ? r2[1] : r2[0];
;         float other = b3 ? r2[0] : r2[1];
;         h = mine + __shfl_xor(other, 8);
;       }
;       h += __shfl_xor(h, 4);
;       h += __shfl_xor(h, 2);
;       h += __shfl_xor(h, 1);
	v_cvt_pk_f32_fp8_sdwa v[220:221], v201 src0_sel:WORD_1
	v_pk_mul_f32 v[222:223], v[80:81], v[214:215]
	v_pk_mul_f32 v[224:225], v[82:83], v[216:217]
	v_cvt_pk_f32_fp8_e32 v[214:215], v202
	v_cvt_pk_f32_fp8_sdwa v[216:217], v202 src0_sel:WORD_1
	v_pk_fma_f32 v[222:223], v[84:85], v[218:219], v[222:223]
	v_pk_fma_f32 v[224:225], v[86:87], v[220:221], v[224:225]
	v_cvt_pk_f32_fp8_e32 v[218:219], v203
	v_cvt_pk_f32_fp8_sdwa v[220:221], v203 src0_sel:WORD_1
	v_pk_fma_f32 v[222:223], v[88:89], v[214:215], v[222:223]
	v_pk_fma_f32 v[224:225], v[90:91], v[216:217], v[224:225]
	v_pk_fma_f32 v[222:223], v[92:93], v[218:219], v[222:223]
	v_pk_fma_f32 v[224:225], v[94:95], v[220:221], v[224:225]
	v_pk_add_f32 v[222:223], v[222:223], v[224:225]
	s_nop 0
	v_add_f32_e32 v232, v222, v223
	v_cvt_pk_f32_fp8_e32 v[214:215], v204
	v_cvt_pk_f32_fp8_sdwa v[216:217], v204 src0_sel:WORD_1
	v_cvt_pk_f32_fp8_e32 v[218:219], v205
	v_cvt_pk_f32_fp8_sdwa v[220:221], v205 src0_sel:WORD_1
	v_pk_mul_f32 v[222:223], v[80:81], v[214:215]
	v_pk_mul_f32 v[224:225], v[82:83], v[216:217]
	v_cvt_pk_f32_fp8_e32 v[214:215], v206
	v_cvt_pk_f32_fp8_sdwa v[216:217], v206 src0_sel:WORD_1
	v_pk_fma_f32 v[222:223], v[84:85], v[218:219], v[222:223]
	v_pk_fma_f32 v[224:225], v[86:87], v[220:221], v[224:225]
	v_cvt_pk_f32_fp8_e32 v[218:219], v207
	v_cvt_pk_f32_fp8_sdwa v[220:221], v207 src0_sel:WORD_1
	v_pk_fma_f32 v[222:223], v[88:89], v[214:215], v[222:223]
	v_pk_fma_f32 v[224:225], v[90:91], v[216:217], v[224:225]
	v_pk_fma_f32 v[222:223], v[92:93], v[218:219], v[222:223]
	v_pk_fma_f32 v[224:225], v[94:95], v[220:221], v[224:225]
	v_pk_add_f32 v[222:223], v[222:223], v[224:225]
	s_nop 0
	v_add_f32_e32 v233, v222, v223
	v_permlane32_swap_b32_e32 v226, v230
	v_permlane32_swap_b32_e32 v227, v231
	v_permlane32_swap_b32_e32 v228, v232
	v_permlane32_swap_b32_e32 v229, v233
	v_add_f32_e32 v226, v226, v230
	v_add_f32_e32 v228, v228, v232
	v_add_f32_e32 v227, v227, v231
	v_add_f32_e32 v229, v229, v233
	s_nop 1
	v_permlane16_swap_b32_e32 v226, v228
	v_permlane16_swap_b32_e32 v227, v229
	v_add_f32_e32 v226, v226, v228
	v_add_f32_e32 v227, v227, v229
	s_nop 0
	v_cndmask_b32_e64 v230, v226, v227, s[24:25]
	v_cndmask_b32_e64 v231, v227, v226, s[24:25]
	s_nop 1
	v_add_f32_dpp v232, v231, v230 row_ror:8 row_mask:0xf bank_mask:0xf
	s_nop 1
	v_add_f32_dpp v233, v232, v232 quad_perm:[1,0,3,2] row_mask:0xf bank_mask:0xf
	s_nop 1
	v_add_f32_dpp v232, v233, v233 quad_perm:[2,3,0,1] row_mask:0xf bank_mask:0xf
	s_nop 1
	v_add_f32_dpp v233, v232, v232 row_half_mirror row_mask:0xf bank_mask:0xf
	ds_write_b32 v235, v233 offset:35328
	v_readlane_b32 s48, v139, s72
	v_readlane_b32 s49, v139, s73
	v_readlane_b32 s50, v139, s74
	v_readlane_b32 s51, v139, s75
	v_readlane_b32 s52, v139, s76
	v_readlane_b32 s53, v139, s77
	v_readlane_b32 s54, v139, s78
	v_readlane_b32 s55, v139, s79
	s_add_u32 s32, s0, s48
	s_addc_u32 s33, s1, 0
	s_add_u32 s34, s0, s49
	s_addc_u32 s35, s1, 0
	s_add_u32 s36, s0, s50
	s_addc_u32 s37, s1, 0
	s_add_u32 s38, s0, s51
	s_addc_u32 s39, s1, 0
	s_add_u32 s40, s0, s52
	s_addc_u32 s41, s1, 0
	s_add_u32 s42, s0, s53
	s_addc_u32 s43, s1, 0
	s_add_u32 s44, s0, s54
	s_addc_u32 s45, s1, 0
	s_add_u32 s46, s0, s55
	s_addc_u32 s47, s1, 0
	global_load_dwordx4 v[176:179], v234, s[32:33]
	global_load_dwordx4 v[180:183], v234, s[34:35]
	global_load_dwordx4 v[184:187], v234, s[36:37]
	global_load_dwordx4 v[188:191], v234, s[38:39]
	global_load_dwordx4 v[192:195], v234, s[40:41]
	global_load_dwordx4 v[196:199], v234, s[42:43]
	global_load_dwordx4 v[200:203], v234, s[44:45]
	global_load_dwordx4 v[204:207], v234, s[46:47]
	s_waitcnt vmcnt(24)
	v_cvt_pk_f32_fp8_e32 v[214:215], v0
	v_cvt_pk_f32_fp8_sdwa v[216:217], v0 src0_sel:WORD_1
	v_cvt_pk_f32_fp8_e32 v[218:219], v1
	v_cvt_pk_f32_fp8_sdwa v[220:221], v1 src0_sel:WORD_1
	v_pk_mul_f32 v[222:223], v[96:97], v[214:215]
	v_pk_mul_f32 v[224:225], v[98:99], v[216:217]
	v_cvt_pk_f32_fp8_e32 v[214:215], v2
	v_cvt_pk_f32_fp8_sdwa v[216:217], v2 src0_sel:WORD_1
	v_pk_fma_f32 v[222:223], v[100:101], v[218:219], v[222:223]
	v_pk_fma_f32 v[224:225], v[102:103], v[220:221], v[224:225]
	v_cvt_pk_f32_fp8_e32 v[218:219], v3
	v_cvt_pk_f32_fp8_sdwa v[220:221], v3 src0_sel:WORD_1
	v_pk_fma_f32 v[222:223], v[104:105], v[214:215], v[222:223]
	v_pk_fma_f32 v[224:225], v[106:107], v[216:217], v[224:225]
	v_pk_fma_f32 v[222:223], v[108:109], v[218:219], v[222:223]
	v_pk_fma_f32 v[224:225], v[110:111], v[220:221], v[224:225]
	v_pk_add_f32 v[222:223], v[222:223], v[224:225]
	s_nop 0
	v_add_f32_e32 v226, v222, v223
	v_cvt_pk_f32_fp8_e32 v[214:215], v4
	v_cvt_pk_f32_fp8_sdwa v[216:217], v4 src0_sel:WORD_1
	v_cvt_pk_f32_fp8_e32 v[218:219], v5
	v_cvt_pk_f32_fp8_sdwa v[220:221], v5 src0_sel:WORD_1
	v_pk_mul_f32 v[222:223], v[96:97], v[214:215]
	v_pk_mul_f32 v[224:225], v[98:99], v[216:217]
	v_cvt_pk_f32_fp8_e32 v[214:215], v6
	v_cvt_pk_f32_fp8_sdwa v[216:217], v6 src0_sel:WORD_1
	v_pk_fma_f32 v[222:223], v[100:101], v[218:219], v[222:223]
	v_pk_fma_f32 v[224:225], v[102:103], v[220:221], v[224:225]
	v_cvt_pk_f32_fp8_e32 v[218:219], v7
	v_cvt_pk_f32_fp8_sdwa v[220:221], v7 src0_sel:WORD_1
	v_pk_fma_f32 v[222:223], v[104:105], v[214:215], v[222:223]
	v_pk_fma_f32 v[224:225], v[106:107], v[216:217], v[224:225]
	v_pk_fma_f32 v[222:223], v[108:109], v[218:219], v[222:223]
	v_pk_fma_f32 v[224:225], v[110:111], v[220:221], v[224:225]
	v_pk_add_f32 v[222:223], v[222:223], v[224:225]
	s_nop 0
	v_add_f32_e32 v227, v222, v223
	v_cvt_pk_f32_fp8_e32 v[214:215], v8
	v_cvt_pk_f32_fp8_sdwa v[216:217], v8 src0_sel:WORD_1
	v_cvt_pk_f32_fp8_e32 v[218:219], v9
	v_cvt_pk_f32_fp8_sdwa v[220:221], v9 src0_sel:WORD_1
; template <bool STORE>
; DI void peer_item(const Params& p, int item, char* smem) {
;     ...
;       float part[8];
; #pragma unroll
;       for (int u = 0; u < 8; ++u) {
;         float d = 0.f;
; #pragma unroll
;         for (int i = 0; i < 4; ++i) {
;           f32x2_t lo = __builtin_amdgcn_cvt_pk_f32_fp8((int)uq[u][i], false);
;           f32x2_t hi = __builtin_amdgcn_cvt_pk_f32_fp8((int)uq[u][i], true);
;           d += xf[4 * i] * lo.x + xf[4 * i + 1] * lo.y + xf[4 * i + 2] * hi.x + xf[4 * i + 3] * hi.y;
;         }
;         part[u] = d;
;       }
;       float q4[4], r2[2], h;
; #pragma unroll
;       for (int j = 0; j < 4; ++j) {
;         float mine = b5 ? part[j + 4] : part[j];
;         float other = b5 ? part[j] : part[j + 4];
;         q4[j] = mine + __shfl_xor(other, 32);
;       }
; #pragma unroll
;       for (int j = 0; j < 2; ++j) {
;         float mine = b4 ? q4[j + 2] : q4[j];
;         float other = b4 ? q4[j] : q4[j + 2];
;         r2[j] = mine + __shfl_xor(other, 16);
;       }
	v_pk_mul_f32 v[222:223], v[96:97], v[214:215]
	v_pk_mul_f32 v[224:225], v[98:99], v[216:217]
	v_cvt_pk_f32_fp8_e32 v[214:215], v10
	v_cvt_pk_f32_fp8_sdwa v[216:217], v10 src0_sel:WORD_1
	v_pk_fma_f32 v[222:223], v[100:101], v[218:219], v[222:223]
	v_pk_fma_f32 v[224:225], v[102:103], v[220:221], v[224:225]
	v_cvt_pk_f32_fp8_e32 v[218:219], v11
	v_cvt_pk_f32_fp8_sdwa v[220:221], v11 src0_sel:WORD_1
	v_pk_fma_f32 v[222:223], v[104:105], v[214:215], v[222:223]
	v_pk_fma_f32 v[224:225], v[106:107], v[216:217], v[224:225]
	v_pk_fma_f32 v[222:223], v[108:109], v[218:219], v[222:223]
	v_pk_fma_f32 v[224:225], v[110:111], v[220:221], v[224:225]
	v_pk_add_f32 v[222:223], v[222:223], v[224:225]
	s_nop 0
	v_add_f32_e32 v228, v222, v223
	v_cvt_pk_f32_fp8_e32 v[214:215], v12
	v_cvt_pk_f32_fp8_sdwa v[216:217], v12 src0_sel:WORD_1
	v_cvt_pk_f32_fp8_e32 v[218:219], v13
	v_cvt_pk_f32_fp8_sdwa v[220:221], v13 src0_sel:WORD_1
	v_pk_mul_f32 v[222:223], v[96:97], v[214:215]
	v_pk_mul_f32 v[224:225], v[98:99], v[216:217]
	v_cvt_pk_f32_fp8_e32 v[214:215], v14
	v_cvt_pk_f32_fp8_sdwa v[216:217], v14 src0_sel:WORD_1
	v_pk_fma_f32 v[222:223], v[100:101], v[218:219], v[222:223]
	v_pk_fma_f32 v[224:225], v[102:103], v[220:221], v[224:225]
	v_cvt_pk_f32_fp8_e32 v[218:219], v15
	v_cvt_pk_f32_fp8_sdwa v[220:221], v15 src0_sel:WORD_1
	v_pk_fma_f32 v[222:223], v[104:105], v[214:215], v[222:223]
	v_pk_fma_f32 v[224:225], v[106:107], v[216:217], v[224:225]
	v_pk_fma_f32 v[222:223], v[108:109], v[218:219], v[222:223]
	v_pk_fma_f32 v[224:225], v[110:111], v[220:221], v[224:225]
	v_pk_add_f32 v[222:223], v[222:223], v[224:225]
	s_nop 0
	v_add_f32_e32 v229, v222, v223
	v_cvt_pk_f32_fp8_e32 v[214:215], v16
	v_cvt_pk_f32_fp8_sdwa v[216:217], v16 src0_sel:WORD_1
	v_cvt_pk_f32_fp8_e32 v[218:219], v17
	v_cvt_pk_f32_fp8_sdwa v[220:221], v17 src0_sel:WORD_1
	v_pk_mul_f32 v[222:223], v[96:97], v[214:215]
	v_pk_mul_f32 v[224:225], v[98:99], v[216:217]
	v_cvt_pk_f32_fp8_e32 v[214:215], v18
	v_cvt_pk_f32_fp8_sdwa v[216:217], v18 src0_sel:WORD_1
	v_pk_fma_f32 v[222:223], v[100:101], v[218:219], v[222:223]
	v_pk_fma_f32 v[224:225], v[102:103], v[220:221], v[224:225]
	v_cvt_pk_f32_fp8_e32 v[218:219], v19
	v_cvt_pk_f32_fp8_sdwa v[220:221], v19 src0_sel:WORD_1
	v_pk_fma_f32 v[222:223], v[104:105], v[214:215], v[222:223]
	v_pk_fma_f32 v[224:225], v[106:107], v[216:217], v[224:225]
	v_pk_fma_f32 v[222:223], v[108:109], v[218:219], v[222:223]
	v_pk_fma_f32 v[224:225], v[110:111], v[220:221], v[224:225]
	v_pk_add_f32 v[222:223], v[222:223], v[224:225]
	s_nop 0
	v_add_f32_e32 v230, v222, v223
	v_cvt_pk_f32_fp8_e32 v[214:215], v20
	v_cvt_pk_f32_fp8_sdwa v[216:217], v20 src0_sel:WORD_1
	v_cvt_pk_f32_fp8_e32 v[218:219], v21
	v_cvt_pk_f32_fp8_sdwa v[220:221], v21 src0_sel:WORD_1
	v_pk_mul_f32 v[222:223], v[96:97], v[214:215]
	v_pk_mul_f32 v[224:225], v[98:99], v[216:217]
	v_cvt_pk_f32_fp8_e32 v[214:215], v22
	v_cvt_pk_f32_fp8_sdwa v[216:217], v22 src0_sel:WORD_1
	v_pk_fma_f32 v[222:223], v[100:101], v[218:219], v[222:223]
	v_pk_fma_f32 v[224:225], v[102:103], v[220:221], v[224:225]
	v_cvt_pk_f32_fp8_e32 v[218:219], v23
	v_cvt_pk_f32_fp8_sdwa v[220:221], v23 src0_sel:WORD_1
	v_pk_fma_f32 v[222:223], v[104:105], v[214:215], v[222:223]
	v_pk_fma_f32 v[224:225], v[106:107], v[216:217], v[224:225]
	v_pk_fma_f32 v[222:223], v[108:109], v[218:219], v[222:223]
	v_pk_fma_f32 v[224:225], v[110:111], v[220:221], v[224:225]
	v_pk_add_f32 v[222:223], v[222:223], v[224:225]
	s_nop 0
	v_add_f32_e32 v231, v222, v223
	v_cvt_pk_f32_fp8_e32 v[214:215], v24
	v_cvt_pk_f32_fp8_sdwa v[216:217], v24 src0_sel:WORD_1
	v_cvt_pk_f32_fp8_e32 v[218:219], v25
	v_cvt_pk_f32_fp8_sdwa v[220:221], v25 src0_sel:WORD_1
	v_pk_mul_f32 v[222:223], v[96:97], v[214:215]
	v_pk_mul_f32 v[224:225], v[98:99], v[216:217]
	v_cvt_pk_f32_fp8_e32 v[214:215], v26
	v_cvt_pk_f32_fp8_sdwa v[216:217], v26 src0_sel:WORD_1
	v_pk_fma_f32 v[222:223], v[100:101], v[218:219], v[222:223]
	v_pk_fma_f32 v[224:225], v[102:103], v[220:221], v[224:225]
	v_cvt_pk_f32_fp8_e32 v[218:219], v27
	v_cvt_pk_f32_fp8_sdwa v[220:221], v27 src0_sel:WORD_1
	v_pk_fma_f32 v[222:223], v[104:105], v[214:215], v[222:223]
	v_pk_fma_f32 v[224:225], v[106:107], v[216:217], v[224:225]
	v_pk_fma_f32 v[222:223], v[108:109], v[218:219], v[222:223]
	v_pk_fma_f32 v[224:225], v[110:111], v[220:221], v[224:225]
	v_pk_add_f32 v[222:223], v[222:223], v[224:225]
	s_nop 0
	v_add_f32_e32 v232, v222, v223
	v_cvt_pk_f32_fp8_e32 v[214:215], v28
	v_cvt_pk_f32_fp8_sdwa v[216:217], v28 src0_sel:WORD_1
	v_cvt_pk_f32_fp8_e32 v[218:219], v29
	v_cvt_pk_f32_fp8_sdwa v[220:221], v29 src0_sel:WORD_1
	v_pk_mul_f32 v[222:223], v[96:97], v[214:215]
	v_pk_mul_f32 v[224:225], v[98:99], v[216:217]
	v_cvt_pk_f32_fp8_e32 v[214:215], v30
	v_cvt_pk_f32_fp8_sdwa v[216:217], v30 src0_sel:WORD_1
	v_pk_fma_f32 v[222:223], v[100:101], v[218:219], v[222:223]
	v_pk_fma_f32 v[224:225], v[102:103], v[220:221], v[224:225]
	v_cvt_pk_f32_fp8_e32 v[218:219], v31
	v_cvt_pk_f32_fp8_sdwa v[220:221], v31 src0_sel:WORD_1
	v_pk_fma_f32 v[222:223], v[104:105], v[214:215], v[222:223]
	v_pk_fma_f32 v[224:225], v[106:107], v[216:217], v[224:225]
	v_pk_fma_f32 v[222:223], v[108:109], v[218:219], v[222:223]
	v_pk_fma_f32 v[224:225], v[110:111], v[220:221], v[224:225]
	v_pk_add_f32 v[222:223], v[222:223], v[224:225]
	s_nop 0
	v_add_f32_e32 v233, v222, v223
	v_permlane32_swap_b32_e32 v226, v230
	v_permlane32_swap_b32_e32 v227, v231
	v_permlane32_swap_b32_e32 v228, v232
	v_permlane32_swap_b32_e32 v229, v233
	v_add_f32_e32 v226, v226, v230
	v_add_f32_e32 v228, v228, v232
	v_add_f32_e32 v227, v227, v231
	v_add_f32_e32 v229, v229, v233
	s_nop 1
; template <bool STORE>
; DI void peer_item(const Params& p, int item, char* smem) {
;     ...
;       for (int u = 0; u < 8; ++u) {
;         int e = e_s[tl * 128 + k + u];
;         uq[u] = *(const u32x4*)(U8 + (size_t)e * 1024 + lane * 16);
;       }
;       float part[8];
; #pragma unroll
;       for (int u = 0; u < 8; ++u) {
;         float d = 0.f;
; #pragma unroll
;         for (int i = 0; i < 4; ++i) {
;           f32x2_t lo = __builtin_amdgcn_cvt_pk_f32_fp8((int)uq[u][i], false);
;           f32x2_t hi = __builtin_amdgcn_cvt_pk_f32_fp8((int)uq[u][i], true);
;           d += xf[4 * i] * lo.x + xf[4 * i + 1] * lo.y + xf[4 * i + 2] * hi.x + xf[4 * i + 3] * hi.y;
;         }
;         part[u] = d;
;       }
;       float q4[4], r2[2], h;
; #pragma unroll
;       for (int j = 0; j < 4; ++j) {
;         float mine = b5 ? part[j + 4] : part[j];
;         float other = b5 ? part[j] : part[j + 4];
;         q4[j] = mine + __shfl_xor(other, 32);
;       }
; #pragma unroll
;       for (int j = 0; j < 2; ++j) {
;         float mine = b4 ? q4[j + 2] : q4[j];
;         float other = b4 ? q4[j] : q4[j + 2];
;         r2[j] = mine + __shfl_xor(other, 16);
;       }
;       {
;         float mine = b3 ? r2[1] : r2[0];
;         float other = b3 ? r2[0] : r2[1];
;         h = mine + __shfl_xor(other, 8);
;       }
;       h += __shfl_xor(h, 4);
;       h += __shfl_xor(h, 2);
;       h += __shfl_xor(h, 1);
	v_permlane16_swap_b32_e32 v226, v228
	v_permlane16_swap_b32_e32 v227, v229
	v_add_f32_e32 v226, v226, v228
	v_add_f32_e32 v227, v227, v229
	s_nop 0
	v_cndmask_b32_e64 v230, v226, v227, s[24:25]
	v_cndmask_b32_e64 v231, v227, v226, s[24:25]
	s_nop 1
	v_add_f32_dpp v232, v231, v230 row_ror:8 row_mask:0xf bank_mask:0xf
	s_nop 1
	v_add_f32_dpp v233, v232, v232 quad_perm:[1,0,3,2] row_mask:0xf bank_mask:0xf
	s_nop 1
	v_add_f32_dpp v232, v233, v233 quad_perm:[2,3,0,1] row_mask:0xf bank_mask:0xf
	s_nop 1
	v_add_f32_dpp v233, v232, v232 row_half_mirror row_mask:0xf bank_mask:0xf
	ds_write_b32 v235, v233 offset:35840
	v_readlane_b32 s48, v141, s72
	v_readlane_b32 s49, v141, s73
	v_readlane_b32 s50, v141, s74
	v_readlane_b32 s51, v141, s75
	v_readlane_b32 s52, v141, s76
	v_readlane_b32 s53, v141, s77
	v_readlane_b32 s54, v141, s78
	v_readlane_b32 s55, v141, s79
	s_add_u32 s32, s0, s48
	s_addc_u32 s33, s1, 0
	s_add_u32 s34, s0, s49
	s_addc_u32 s35, s1, 0
	s_add_u32 s36, s0, s50
	s_addc_u32 s37, s1, 0
	s_add_u32 s38, s0, s51
	s_addc_u32 s39, s1, 0
	s_add_u32 s40, s0, s52
	s_addc_u32 s41, s1, 0
	s_add_u32 s42, s0, s53
	s_addc_u32 s43, s1, 0
	s_add_u32 s44, s0, s54
	s_addc_u32 s45, s1, 0
	s_add_u32 s46, s0, s55
	s_addc_u32 s47, s1, 0
	global_load_dwordx4 v[0:3], v234, s[32:33]
	global_load_dwordx4 v[4:7], v234, s[34:35]
	global_load_dwordx4 v[8:11], v234, s[36:37]
	global_load_dwordx4 v[12:15], v234, s[38:39]
	global_load_dwordx4 v[16:19], v234, s[40:41]
	global_load_dwordx4 v[20:23], v234, s[42:43]
	global_load_dwordx4 v[24:27], v234, s[44:45]
	global_load_dwordx4 v[28:31], v234, s[46:47]
	s_waitcnt vmcnt(24)
	v_cvt_pk_f32_fp8_e32 v[214:215], v32
	v_cvt_pk_f32_fp8_sdwa v[216:217], v32 src0_sel:WORD_1
	v_cvt_pk_f32_fp8_e32 v[218:219], v33
	v_cvt_pk_f32_fp8_sdwa v[220:221], v33 src0_sel:WORD_1
	v_pk_mul_f32 v[222:223], v[112:113], v[214:215]
	v_pk_mul_f32 v[224:225], v[114:115], v[216:217]
	v_cvt_pk_f32_fp8_e32 v[214:215], v34
	v_cvt_pk_f32_fp8_sdwa v[216:217], v34 src0_sel:WORD_1
	v_pk_fma_f32 v[222:223], v[116:117], v[218:219], v[222:223]
	v_pk_fma_f32 v[224:225], v[118:119], v[220:221], v[224:225]
	v_cvt_pk_f32_fp8_e32 v[218:219], v35
	v_cvt_pk_f32_fp8_sdwa v[220:221], v35 src0_sel:WORD_1
	v_pk_fma_f32 v[222:223], v[120:121], v[214:215], v[222:223]
	v_pk_fma_f32 v[224:225], v[122:123], v[216:217], v[224:225]
	v_pk_fma_f32 v[222:223], v[124:125], v[218:219], v[222:223]
	v_pk_fma_f32 v[224:225], v[126:127], v[220:221], v[224:225]
	v_pk_add_f32 v[222:223], v[222:223], v[224:225]
	s_nop 0
	v_add_f32_e32 v226, v222, v223
	v_cvt_pk_f32_fp8_e32 v[214:215], v36
	v_cvt_pk_f32_fp8_sdwa v[216:217], v36 src0_sel:WORD_1
	v_cvt_pk_f32_fp8_e32 v[218:219], v37
	v_cvt_pk_f32_fp8_sdwa v[220:221], v37 src0_sel:WORD_1
	v_pk_mul_f32 v[222:223], v[112:113], v[214:215]
	v_pk_mul_f32 v[224:225], v[114:115], v[216:217]
	v_cvt_pk_f32_fp8_e32 v[214:215], v38
	v_cvt_pk_f32_fp8_sdwa v[216:217], v38 src0_sel:WORD_1
	v_pk_fma_f32 v[222:223], v[116:117], v[218:219], v[222:223]
	v_pk_fma_f32 v[224:225], v[118:119], v[220:221], v[224:225]
	v_cvt_pk_f32_fp8_e32 v[218:219], v39
	v_cvt_pk_f32_fp8_sdwa v[220:221], v39 src0_sel:WORD_1
	v_pk_fma_f32 v[222:223], v[120:121], v[214:215], v[222:223]
	v_pk_fma_f32 v[224:225], v[122:123], v[216:217], v[224:225]
	v_pk_fma_f32 v[222:223], v[124:125], v[218:219], v[222:223]
	v_pk_fma_f32 v[224:225], v[126:127], v[220:221], v[224:225]
	v_pk_add_f32 v[222:223], v[222:223], v[224:225]
	s_nop 0
	v_add_f32_e32 v227, v222, v223
	v_cvt_pk_f32_fp8_e32 v[214:215], v40
	v_cvt_pk_f32_fp8_sdwa v[216:217], v40 src0_sel:WORD_1
	v_cvt_pk_f32_fp8_e32 v[218:219], v41
	v_cvt_pk_f32_fp8_sdwa v[220:221], v41 src0_sel:WORD_1
	v_pk_mul_f32 v[222:223], v[112:113], v[214:215]
	v_pk_mul_f32 v[224:225], v[114:115], v[216:217]
	v_cvt_pk_f32_fp8_e32 v[214:215], v42
	v_cvt_pk_f32_fp8_sdwa v[216:217], v42 src0_sel:WORD_1
	v_pk_fma_f32 v[222:223], v[116:117], v[218:219], v[222:223]
	v_pk_fma_f32 v[224:225], v[118:119], v[220:221], v[224:225]
	v_cvt_pk_f32_fp8_e32 v[218:219], v43
	v_cvt_pk_f32_fp8_sdwa v[220:221], v43 src0_sel:WORD_1
	v_pk_fma_f32 v[222:223], v[120:121], v[214:215], v[222:223]
	v_pk_fma_f32 v[224:225], v[122:123], v[216:217], v[224:225]
	v_pk_fma_f32 v[222:223], v[124:125], v[218:219], v[222:223]
	v_pk_fma_f32 v[224:225], v[126:127], v[220:221], v[224:225]
	v_pk_add_f32 v[222:223], v[222:223], v[224:225]
	s_nop 0
	v_add_f32_e32 v228, v222, v223
	v_cvt_pk_f32_fp8_e32 v[214:215], v44
	v_cvt_pk_f32_fp8_sdwa v[216:217], v44 src0_sel:WORD_1
	v_cvt_pk_f32_fp8_e32 v[218:219], v45
	v_cvt_pk_f32_fp8_sdwa v[220:221], v45 src0_sel:WORD_1
	v_pk_mul_f32 v[222:223], v[112:113], v[214:215]
	v_pk_mul_f32 v[224:225], v[114:115], v[216:217]
	v_cvt_pk_f32_fp8_e32 v[214:215], v46
	v_cvt_pk_f32_fp8_sdwa v[216:217], v46 src0_sel:WORD_1
	v_pk_fma_f32 v[222:223], v[116:117], v[218:219], v[222:223]
	v_pk_fma_f32 v[224:225], v[118:119], v[220:221], v[224:225]
	v_cvt_pk_f32_fp8_e32 v[218:219], v47
	v_cvt_pk_f32_fp8_sdwa v[220:221], v47 src0_sel:WORD_1
	v_pk_fma_f32 v[222:223], v[120:121], v[214:215], v[222:223]
	v_pk_fma_f32 v[224:225], v[122:123], v[216:217], v[224:225]
	v_pk_fma_f32 v[222:223], v[124:125], v[218:219], v[222:223]
	v_pk_fma_f32 v[224:225], v[126:127], v[220:221], v[224:225]
	v_pk_add_f32 v[222:223], v[222:223], v[224:225]
	s_nop 0
	v_add_f32_e32 v229, v222, v223
	v_cvt_pk_f32_fp8_e32 v[214:215], v48
	v_cvt_pk_f32_fp8_sdwa v[216:217], v48 src0_sel:WORD_1
	v_cvt_pk_f32_fp8_e32 v[218:219], v49
	v_cvt_pk_f32_fp8_sdwa v[220:221], v49 src0_sel:WORD_1
	v_pk_mul_f32 v[222:223], v[112:113], v[214:215]
	v_pk_mul_f32 v[224:225], v[114:115], v[216:217]
	v_cvt_pk_f32_fp8_e32 v[214:215], v50
; template <bool STORE>
; DI void peer_item(const Params& p, int item, char* smem) {
;     ...
;       for (int u = 0; u < 8; ++u) {
;         int e = e_s[tl * 128 + k + u];
;         uq[u] = *(const u32x4*)(U8 + (size_t)e * 1024 + lane * 16);
;       }
;       float part[8];
; #pragma unroll
;       for (int u = 0; u < 8; ++u) {
;         float d = 0.f;
; #pragma unroll
;         for (int i = 0; i < 4; ++i) {
;           f32x2_t lo = __builtin_amdgcn_cvt_pk_f32_fp8((int)uq[u][i], false);
;           f32x2_t hi = __builtin_amdgcn_cvt_pk_f32_fp8((int)uq[u][i], true);
;           d += xf[4 * i] * lo.x + xf[4 * i + 1] * lo.y + xf[4 * i + 2] * hi.x + xf[4 * i + 3] * hi.y;
;         }
;         part[u] = d;
;       }
;       float q4[4], r2[2], h;
; #pragma unroll
;       for (int j = 0; j < 4; ++j) {
;         float mine = b5 ? part[j + 4] : part[j];
;         float other = b5 ? part[j] : part[j + 4];
;         q4[j] = mine + __shfl_xor(other, 32);
;       }
; #pragma unroll
;       for (int j = 0; j < 2; ++j) {
;         float mine = b4 ? q4[j + 2] : q4[j];
;         float other = b4 ? q4[j] : q4[j + 2];
;         r2[j] = mine + __shfl_xor(other, 16);
;       }
;       {
;         float mine = b3 ? r2[1] : r2[0];
;         float other = b3 ? r2[0] : r2[1];
;         h = mine + __shfl_xor(other, 8);
;       }
;       h += __shfl_xor(h, 4);
;       h += __shfl_xor(h, 2);
;       h += __shfl_xor(h, 1);
	v_cvt_pk_f32_fp8_sdwa v[216:217], v50 src0_sel:WORD_1
	v_pk_fma_f32 v[222:223], v[116:117], v[218:219], v[222:223]
	v_pk_fma_f32 v[224:225], v[118:119], v[220:221], v[224:225]
	v_cvt_pk_f32_fp8_e32 v[218:219], v51
	v_cvt_pk_f32_fp8_sdwa v[220:221], v51 src0_sel:WORD_1
	v_pk_fma_f32 v[222:223], v[120:121], v[214:215], v[222:223]
	v_pk_fma_f32 v[224:225], v[122:123], v[216:217], v[224:225]
	v_pk_fma_f32 v[222:223], v[124:125], v[218:219], v[222:223]
	v_pk_fma_f32 v[224:225], v[126:127], v[220:221], v[224:225]
	v_pk_add_f32 v[222:223], v[222:223], v[224:225]
	s_nop 0
	v_add_f32_e32 v230, v222, v223
	v_cvt_pk_f32_fp8_e32 v[214:215], v52
	v_cvt_pk_f32_fp8_sdwa v[216:217], v52 src0_sel:WORD_1
	v_cvt_pk_f32_fp8_e32 v[218:219], v53
	v_cvt_pk_f32_fp8_sdwa v[220:221], v53 src0_sel:WORD_1
	v_pk_mul_f32 v[222:223], v[112:113], v[214:215]
	v_pk_mul_f32 v[224:225], v[114:115], v[216:217]
	v_cvt_pk_f32_fp8_e32 v[214:215], v54
	v_cvt_pk_f32_fp8_sdwa v[216:217], v54 src0_sel:WORD_1
	v_pk_fma_f32 v[222:223], v[116:117], v[218:219], v[222:223]
	v_pk_fma_f32 v[224:225], v[118:119], v[220:221], v[224:225]
	v_cvt_pk_f32_fp8_e32 v[218:219], v55
	v_cvt_pk_f32_fp8_sdwa v[220:221], v55 src0_sel:WORD_1
	v_pk_fma_f32 v[222:223], v[120:121], v[214:215], v[222:223]
	v_pk_fma_f32 v[224:225], v[122:123], v[216:217], v[224:225]
	v_pk_fma_f32 v[222:223], v[124:125], v[218:219], v[222:223]
	v_pk_fma_f32 v[224:225], v[126:127], v[220:221], v[224:225]
	v_pk_add_f32 v[222:223], v[222:223], v[224:225]
	s_nop 0
	v_add_f32_e32 v231, v222, v223
	v_cvt_pk_f32_fp8_e32 v[214:215], v56
	v_cvt_pk_f32_fp8_sdwa v[216:217], v56 src0_sel:WORD_1
	v_cvt_pk_f32_fp8_e32 v[218:219], v57
	v_cvt_pk_f32_fp8_sdwa v[220:221], v57 src0_sel:WORD_1
	v_pk_mul_f32 v[222:223], v[112:113], v[214:215]
	v_pk_mul_f32 v[224:225], v[114:115], v[216:217]
	v_cvt_pk_f32_fp8_e32 v[214:215], v58
	v_cvt_pk_f32_fp8_sdwa v[216:217], v58 src0_sel:WORD_1
	v_pk_fma_f32 v[222:223], v[116:117], v[218:219], v[222:223]
	v_pk_fma_f32 v[224:225], v[118:119], v[220:221], v[224:225]
	v_cvt_pk_f32_fp8_e32 v[218:219], v59
	v_cvt_pk_f32_fp8_sdwa v[220:221], v59 src0_sel:WORD_1
	v_pk_fma_f32 v[222:223], v[120:121], v[214:215], v[222:223]
	v_pk_fma_f32 v[224:225], v[122:123], v[216:217], v[224:225]
	v_pk_fma_f32 v[222:223], v[124:125], v[218:219], v[222:223]
	v_pk_fma_f32 v[224:225], v[126:127], v[220:221], v[224:225]
	v_pk_add_f32 v[222:223], v[222:223], v[224:225]
	s_nop 0
	v_add_f32_e32 v232, v222, v223
	v_cvt_pk_f32_fp8_e32 v[214:215], v60
	v_cvt_pk_f32_fp8_sdwa v[216:217], v60 src0_sel:WORD_1
	v_cvt_pk_f32_fp8_e32 v[218:219], v61
	v_cvt_pk_f32_fp8_sdwa v[220:221], v61 src0_sel:WORD_1
	v_pk_mul_f32 v[222:223], v[112:113], v[214:215]
	v_pk_mul_f32 v[224:225], v[114:115], v[216:217]
	v_cvt_pk_f32_fp8_e32 v[214:215], v62
	v_cvt_pk_f32_fp8_sdwa v[216:217], v62 src0_sel:WORD_1
	v_pk_fma_f32 v[222:223], v[116:117], v[218:219], v[222:223]
	v_pk_fma_f32 v[224:225], v[118:119], v[220:221], v[224:225]
	v_cvt_pk_f32_fp8_e32 v[218:219], v63
	v_cvt_pk_f32_fp8_sdwa v[220:221], v63 src0_sel:WORD_1
	v_pk_fma_f32 v[222:223], v[120:121], v[214:215], v[222:223]
	v_pk_fma_f32 v[224:225], v[122:123], v[216:217], v[224:225]
	v_pk_fma_f32 v[222:223], v[124:125], v[218:219], v[222:223]
	v_pk_fma_f32 v[224:225], v[126:127], v[220:221], v[224:225]
	v_pk_add_f32 v[222:223], v[222:223], v[224:225]
	s_nop 0
	v_add_f32_e32 v233, v222, v223
	v_permlane32_swap_b32_e32 v226, v230
	v_permlane32_swap_b32_e32 v227, v231
	v_permlane32_swap_b32_e32 v228, v232
	v_permlane32_swap_b32_e32 v229, v233
	v_add_f32_e32 v226, v226, v230
	v_add_f32_e32 v228, v228, v232
	v_add_f32_e32 v227, v227, v231
	v_add_f32_e32 v229, v229, v233
	s_nop 1
	v_permlane16_swap_b32_e32 v226, v228
	v_permlane16_swap_b32_e32 v227, v229
	v_add_f32_e32 v226, v226, v228
	v_add_f32_e32 v227, v227, v229
	s_nop 0
	v_cndmask_b32_e64 v230, v226, v227, s[24:25]
	v_cndmask_b32_e64 v231, v227, v226, s[24:25]
	s_nop 1
	v_add_f32_dpp v232, v231, v230 row_ror:8 row_mask:0xf bank_mask:0xf
	s_nop 1
	v_add_f32_dpp v233, v232, v232 quad_perm:[1,0,3,2] row_mask:0xf bank_mask:0xf
	s_nop 1
	v_add_f32_dpp v232, v233, v233 quad_perm:[2,3,0,1] row_mask:0xf bank_mask:0xf
	s_nop 1
	v_add_f32_dpp v233, v232, v232 row_half_mirror row_mask:0xf bank_mask:0xf
	ds_write_b32 v235, v233 offset:36352
	v_readlane_b32 s48, v143, s72
	v_readlane_b32 s49, v143, s73
	v_readlane_b32 s50, v143, s74
	v_readlane_b32 s51, v143, s75
	v_readlane_b32 s52, v143, s76
	v_readlane_b32 s53, v143, s77
	v_readlane_b32 s54, v143, s78
	v_readlane_b32 s55, v143, s79
	s_add_u32 s32, s0, s48
	s_addc_u32 s33, s1, 0
	s_add_u32 s34, s0, s49
	s_addc_u32 s35, s1, 0
	s_add_u32 s36, s0, s50
	s_addc_u32 s37, s1, 0
	s_add_u32 s38, s0, s51
	s_addc_u32 s39, s1, 0
	s_add_u32 s40, s0, s52
	s_addc_u32 s41, s1, 0
	s_add_u32 s42, s0, s53
	s_addc_u32 s43, s1, 0
	s_add_u32 s44, s0, s54
	s_addc_u32 s45, s1, 0
	s_add_u32 s46, s0, s55
	s_addc_u32 s47, s1, 0
	global_load_dwordx4 v[32:35], v234, s[32:33]
	global_load_dwordx4 v[36:39], v234, s[34:35]
	global_load_dwordx4 v[40:43], v234, s[36:37]
	global_load_dwordx4 v[44:47], v234, s[38:39]
	global_load_dwordx4 v[48:51], v234, s[40:41]
	global_load_dwordx4 v[52:55], v234, s[42:43]
	global_load_dwordx4 v[56:59], v234, s[44:45]
	global_load_dwordx4 v[60:63], v234, s[46:47]
	s_waitcnt vmcnt(24)
; template <bool STORE>
; DI void peer_item(const Params& p, int item, char* smem) {
;     ...
;       float part[8];
; #pragma unroll
;       for (int u = 0; u < 8; ++u) {
;         float d = 0.f;
; #pragma unroll
;         for (int i = 0; i < 4; ++i) {
;           f32x2_t lo = __builtin_amdgcn_cvt_pk_f32_fp8((int)uq[u][i], false);
;           f32x2_t hi = __builtin_amdgcn_cvt_pk_f32_fp8((int)uq[u][i], true);
;           d += xf[4 * i] * lo.x + xf[4 * i + 1] * lo.y + xf[4 * i + 2] * hi.x + xf[4 * i + 3] * hi.y;
;         }
;         part[u] = d;
;       }
	v_cvt_pk_f32_fp8_e32 v[214:215], v144
	v_cvt_pk_f32_fp8_sdwa v[216:217], v144 src0_sel:WORD_1
	v_cvt_pk_f32_fp8_e32 v[218:219], v145
	v_cvt_pk_f32_fp8_sdwa v[220:221], v145 src0_sel:WORD_1
	v_pk_mul_f32 v[222:223], v[64:65], v[214:215]
	v_pk_mul_f32 v[224:225], v[66:67], v[216:217]
	v_cvt_pk_f32_fp8_e32 v[214:215], v146
	v_cvt_pk_f32_fp8_sdwa v[216:217], v146 src0_sel:WORD_1
	v_pk_fma_f32 v[222:223], v[68:69], v[218:219], v[222:223]
	v_pk_fma_f32 v[224:225], v[70:71], v[220:221], v[224:225]
	v_cvt_pk_f32_fp8_e32 v[218:219], v147
	v_cvt_pk_f32_fp8_sdwa v[220:221], v147 src0_sel:WORD_1
	v_pk_fma_f32 v[222:223], v[72:73], v[214:215], v[222:223]
	v_pk_fma_f32 v[224:225], v[74:75], v[216:217], v[224:225]
	v_pk_fma_f32 v[222:223], v[76:77], v[218:219], v[222:223]
	v_pk_fma_f32 v[224:225], v[78:79], v[220:221], v[224:225]
	v_pk_add_f32 v[222:223], v[222:223], v[224:225]
	s_nop 0
	v_add_f32_e32 v226, v222, v223
	v_cvt_pk_f32_fp8_e32 v[214:215], v148
	v_cvt_pk_f32_fp8_sdwa v[216:217], v148 src0_sel:WORD_1
	v_cvt_pk_f32_fp8_e32 v[218:219], v149
	v_cvt_pk_f32_fp8_sdwa v[220:221], v149 src0_sel:WORD_1
	v_pk_mul_f32 v[222:223], v[64:65], v[214:215]
	v_pk_mul_f32 v[224:225], v[66:67], v[216:217]
	v_cvt_pk_f32_fp8_e32 v[214:215], v150
	v_cvt_pk_f32_fp8_sdwa v[216:217], v150 src0_sel:WORD_1
	v_pk_fma_f32 v[222:223], v[68:69], v[218:219], v[222:223]
	v_pk_fma_f32 v[224:225], v[70:71], v[220:221], v[224:225]
	v_cvt_pk_f32_fp8_e32 v[218:219], v151
	v_cvt_pk_f32_fp8_sdwa v[220:221], v151 src0_sel:WORD_1
	v_pk_fma_f32 v[222:223], v[72:73], v[214:215], v[222:223]
	v_pk_fma_f32 v[224:225], v[74:75], v[216:217], v[224:225]
	v_pk_fma_f32 v[222:223], v[76:77], v[218:219], v[222:223]
	v_pk_fma_f32 v[224:225], v[78:79], v[220:221], v[224:225]
	v_pk_add_f32 v[222:223], v[222:223], v[224:225]
	s_nop 0
	v_add_f32_e32 v227, v222, v223
	v_cvt_pk_f32_fp8_e32 v[214:215], v152
	v_cvt_pk_f32_fp8_sdwa v[216:217], v152 src0_sel:WORD_1
	v_cvt_pk_f32_fp8_e32 v[218:219], v153
	v_cvt_pk_f32_fp8_sdwa v[220:221], v153 src0_sel:WORD_1
	v_pk_mul_f32 v[222:223], v[64:65], v[214:215]
	v_pk_mul_f32 v[224:225], v[66:67], v[216:217]
	v_cvt_pk_f32_fp8_e32 v[214:215], v154
	v_cvt_pk_f32_fp8_sdwa v[216:217], v154 src0_sel:WORD_1
	v_pk_fma_f32 v[222:223], v[68:69], v[218:219], v[222:223]
	v_pk_fma_f32 v[224:225], v[70:71], v[220:221], v[224:225]
	v_cvt_pk_f32_fp8_e32 v[218:219], v155
	v_cvt_pk_f32_fp8_sdwa v[220:221], v155 src0_sel:WORD_1
	v_pk_fma_f32 v[222:223], v[72:73], v[214:215], v[222:223]
	v_pk_fma_f32 v[224:225], v[74:75], v[216:217], v[224:225]
	v_pk_fma_f32 v[222:223], v[76:77], v[218:219], v[222:223]
	v_pk_fma_f32 v[224:225], v[78:79], v[220:221], v[224:225]
	v_pk_add_f32 v[222:223], v[222:223], v[224:225]
	s_nop 0
	v_add_f32_e32 v228, v222, v223
	v_cvt_pk_f32_fp8_e32 v[214:215], v156
	v_cvt_pk_f32_fp8_sdwa v[216:217], v156 src0_sel:WORD_1
	v_cvt_pk_f32_fp8_e32 v[218:219], v157
	v_cvt_pk_f32_fp8_sdwa v[220:221], v157 src0_sel:WORD_1
	v_pk_mul_f32 v[222:223], v[64:65], v[214:215]
	v_pk_mul_f32 v[224:225], v[66:67], v[216:217]
	v_cvt_pk_f32_fp8_e32 v[214:215], v158
	v_cvt_pk_f32_fp8_sdwa v[216:217], v158 src0_sel:WORD_1
	v_pk_fma_f32 v[222:223], v[68:69], v[218:219], v[222:223]
	v_pk_fma_f32 v[224:225], v[70:71], v[220:221], v[224:225]
	v_cvt_pk_f32_fp8_e32 v[218:219], v159
	v_cvt_pk_f32_fp8_sdwa v[220:221], v159 src0_sel:WORD_1
	v_pk_fma_f32 v[222:223], v[72:73], v[214:215], v[222:223]
	v_pk_fma_f32 v[224:225], v[74:75], v[216:217], v[224:225]
	v_pk_fma_f32 v[222:223], v[76:77], v[218:219], v[222:223]
	v_pk_fma_f32 v[224:225], v[78:79], v[220:221], v[224:225]
	v_pk_add_f32 v[222:223], v[222:223], v[224:225]
	s_nop 0
	v_add_f32_e32 v229, v222, v223
	v_cvt_pk_f32_fp8_e32 v[214:215], v160
	v_cvt_pk_f32_fp8_sdwa v[216:217], v160 src0_sel:WORD_1
	v_cvt_pk_f32_fp8_e32 v[218:219], v161
	v_cvt_pk_f32_fp8_sdwa v[220:221], v161 src0_sel:WORD_1
	v_pk_mul_f32 v[222:223], v[64:65], v[214:215]
	v_pk_mul_f32 v[224:225], v[66:67], v[216:217]
	v_cvt_pk_f32_fp8_e32 v[214:215], v162
	v_cvt_pk_f32_fp8_sdwa v[216:217], v162 src0_sel:WORD_1
	v_pk_fma_f32 v[222:223], v[68:69], v[218:219], v[222:223]
	v_pk_fma_f32 v[224:225], v[70:71], v[220:221], v[224:225]
	v_cvt_pk_f32_fp8_e32 v[218:219], v163
	v_cvt_pk_f32_fp8_sdwa v[220:221], v163 src0_sel:WORD_1
	v_pk_fma_f32 v[222:223], v[72:73], v[214:215], v[222:223]
	v_pk_fma_f32 v[224:225], v[74:75], v[216:217], v[224:225]
	v_pk_fma_f32 v[222:223], v[76:77], v[218:219], v[222:223]
	v_pk_fma_f32 v[224:225], v[78:79], v[220:221], v[224:225]
	v_pk_add_f32 v[222:223], v[222:223], v[224:225]
	s_nop 0
	v_add_f32_e32 v230, v222, v223
	v_cvt_pk_f32_fp8_e32 v[214:215], v164
	v_cvt_pk_f32_fp8_sdwa v[216:217], v164 src0_sel:WORD_1
	v_cvt_pk_f32_fp8_e32 v[218:219], v165
	v_cvt_pk_f32_fp8_sdwa v[220:221], v165 src0_sel:WORD_1
	v_pk_mul_f32 v[222:223], v[64:65], v[214:215]
	v_pk_mul_f32 v[224:225], v[66:67], v[216:217]
	v_cvt_pk_f32_fp8_e32 v[214:215], v166
	v_cvt_pk_f32_fp8_sdwa v[216:217], v166 src0_sel:WORD_1
	v_pk_fma_f32 v[222:223], v[68:69], v[218:219], v[222:223]
	v_pk_fma_f32 v[224:225], v[70:71], v[220:221], v[224:225]
	v_cvt_pk_f32_fp8_e32 v[218:219], v167
	v_cvt_pk_f32_fp8_sdwa v[220:221], v167 src0_sel:WORD_1
	v_pk_fma_f32 v[222:223], v[72:73], v[214:215], v[222:223]
	v_pk_fma_f32 v[224:225], v[74:75], v[216:217], v[224:225]
	v_pk_fma_f32 v[222:223], v[76:77], v[218:219], v[222:223]
	v_pk_fma_f32 v[224:225], v[78:79], v[220:221], v[224:225]
	v_pk_add_f32 v[222:223], v[222:223], v[224:225]
	s_nop 0
	v_add_f32_e32 v231, v222, v223
	v_cvt_pk_f32_fp8_e32 v[214:215], v168
	v_cvt_pk_f32_fp8_sdwa v[216:217], v168 src0_sel:WORD_1
	v_cvt_pk_f32_fp8_e32 v[218:219], v169
; template <bool STORE>
; DI void peer_item(const Params& p, int item, char* smem) {
;     ...
;       const int emine = e_s[tl * 128 + k + (lane >> 3)];
;       const float gmine = g_s[tl * 128 + k + (lane >> 3)];
;       const float su = SU[emine], sv = SV[emine];
; #pragma unroll
;       for (int u = 0; u < 8; ++u) {
;         int e = e_s[tl * 128 + k + u];
;         uq[u] = *(const u32x4*)(U8 + (size_t)e * 1024 + lane * 16);
;       }
;     ...
;       float q4[4], r2[2], h;
; #pragma unroll
;       for (int j = 0; j < 4; ++j) {
;         float mine = b5 ? part[j + 4] : part[j];
;         float other = b5 ? part[j] : part[j + 4];
;         q4[j] = mine + __shfl_xor(other, 32);
;       }
; #pragma unroll
;       for (int j = 0; j < 2; ++j) {
;         float mine = b4 ? q4[j + 2] : q4[j];
;         float other = b4 ? q4[j] : q4[j + 2];
;         r2[j] = mine + __shfl_xor(other, 16);
;       }
;       {
;         float mine = b3 ? r2[1] : r2[0];
;         float other = b3 ? r2[0] : r2[1];
;         h = mine + __shfl_xor(other, 8);
;       }
;       h += __shfl_xor(h, 4);
;       h += __shfl_xor(h, 2);
;       h += __shfl_xor(h, 1);
	v_cvt_pk_f32_fp8_sdwa v[220:221], v169 src0_sel:WORD_1
	v_pk_mul_f32 v[222:223], v[64:65], v[214:215]
	v_pk_mul_f32 v[224:225], v[66:67], v[216:217]
	v_cvt_pk_f32_fp8_e32 v[214:215], v170
	v_cvt_pk_f32_fp8_sdwa v[216:217], v170 src0_sel:WORD_1
	v_pk_fma_f32 v[222:223], v[68:69], v[218:219], v[222:223]
	v_pk_fma_f32 v[224:225], v[70:71], v[220:221], v[224:225]
	v_cvt_pk_f32_fp8_e32 v[218:219], v171
	v_cvt_pk_f32_fp8_sdwa v[220:221], v171 src0_sel:WORD_1
	v_pk_fma_f32 v[222:223], v[72:73], v[214:215], v[222:223]
	v_pk_fma_f32 v[224:225], v[74:75], v[216:217], v[224:225]
	v_pk_fma_f32 v[222:223], v[76:77], v[218:219], v[222:223]
	v_pk_fma_f32 v[224:225], v[78:79], v[220:221], v[224:225]
	v_pk_add_f32 v[222:223], v[222:223], v[224:225]
	s_nop 0
	v_add_f32_e32 v232, v222, v223
	v_cvt_pk_f32_fp8_e32 v[214:215], v172
	v_cvt_pk_f32_fp8_sdwa v[216:217], v172 src0_sel:WORD_1
	v_cvt_pk_f32_fp8_e32 v[218:219], v173
	v_cvt_pk_f32_fp8_sdwa v[220:221], v173 src0_sel:WORD_1
	v_pk_mul_f32 v[222:223], v[64:65], v[214:215]
	v_pk_mul_f32 v[224:225], v[66:67], v[216:217]
	v_cvt_pk_f32_fp8_e32 v[214:215], v174
	v_cvt_pk_f32_fp8_sdwa v[216:217], v174 src0_sel:WORD_1
	v_pk_fma_f32 v[222:223], v[68:69], v[218:219], v[222:223]
	v_pk_fma_f32 v[224:225], v[70:71], v[220:221], v[224:225]
	v_cvt_pk_f32_fp8_e32 v[218:219], v175
	v_cvt_pk_f32_fp8_sdwa v[220:221], v175 src0_sel:WORD_1
	v_pk_fma_f32 v[222:223], v[72:73], v[214:215], v[222:223]
	v_pk_fma_f32 v[224:225], v[74:75], v[216:217], v[224:225]
	v_pk_fma_f32 v[222:223], v[76:77], v[218:219], v[222:223]
	v_pk_fma_f32 v[224:225], v[78:79], v[220:221], v[224:225]
	v_pk_add_f32 v[222:223], v[222:223], v[224:225]
	s_nop 0
	v_add_f32_e32 v233, v222, v223
	v_permlane32_swap_b32_e32 v226, v230
	v_permlane32_swap_b32_e32 v227, v231
	v_permlane32_swap_b32_e32 v228, v232
	v_permlane32_swap_b32_e32 v229, v233
	v_add_f32_e32 v226, v226, v230
	v_add_f32_e32 v228, v228, v232
	v_add_f32_e32 v227, v227, v231
	v_add_f32_e32 v229, v229, v233
	s_nop 1
	v_permlane16_swap_b32_e32 v226, v228
	v_permlane16_swap_b32_e32 v227, v229
	v_add_f32_e32 v226, v226, v228
	v_add_f32_e32 v227, v227, v229
	s_nop 0
	v_cndmask_b32_e64 v230, v226, v227, s[24:25]
	v_cndmask_b32_e64 v231, v227, v226, s[24:25]
	s_nop 1
	v_add_f32_dpp v232, v231, v230 row_ror:8 row_mask:0xf bank_mask:0xf
	s_nop 1
	v_add_f32_dpp v233, v232, v232 quad_perm:[1,0,3,2] row_mask:0xf bank_mask:0xf
	s_nop 1
	v_add_f32_dpp v232, v233, v233 quad_perm:[2,3,0,1] row_mask:0xf bank_mask:0xf
	s_nop 1
	v_add_f32_dpp v233, v232, v232 row_half_mirror row_mask:0xf bank_mask:0xf
	ds_write_b32 v235, v233 offset:34848
	s_cmp_eq_u32 s12, 7
	s_cbranch_scc1 .Lud_last5_Lup_kB
	v_readlane_b32 s48, v136, s58
	v_readlane_b32 s49, v136, s59
	v_readlane_b32 s50, v136, s60
	v_readlane_b32 s51, v136, s61
	v_readlane_b32 s52, v136, s62
	v_readlane_b32 s53, v136, s63
	v_readlane_b32 s54, v136, s64
	v_readlane_b32 s55, v136, s65
	s_add_u32 s32, s0, s48
	s_addc_u32 s33, s1, 0
	s_add_u32 s34, s0, s49
	s_addc_u32 s35, s1, 0
	s_add_u32 s36, s0, s50
	s_addc_u32 s37, s1, 0
	s_add_u32 s38, s0, s51
	s_addc_u32 s39, s1, 0
	s_add_u32 s40, s0, s52
	s_addc_u32 s41, s1, 0
	s_add_u32 s42, s0, s53
	s_addc_u32 s43, s1, 0
	s_add_u32 s44, s0, s54
	s_addc_u32 s45, s1, 0
	s_add_u32 s46, s0, s55
	s_addc_u32 s47, s1, 0
	global_load_dwordx4 v[144:147], v234, s[32:33]
	global_load_dwordx4 v[148:151], v234, s[34:35]
	global_load_dwordx4 v[152:155], v234, s[36:37]
	global_load_dwordx4 v[156:159], v234, s[38:39]
	global_load_dwordx4 v[160:163], v234, s[40:41]
	global_load_dwordx4 v[164:167], v234, s[42:43]
	global_load_dwordx4 v[168:171], v234, s[44:45]
	global_load_dwordx4 v[172:175], v234, s[46:47]
	s_waitcnt vmcnt(24)
	s_branch .Lud_cons5_Lup_kB
.Lud_last5_Lup_kB:
	ds_read_b32 v144, v237 offset:0
	ds_read_b32 v146, v237 offset:256
	ds_read_b32 v148, v237 offset:512
	ds_read_b32 v150, v237 offset:768
	ds_read_b32 v152, v237 offset:1024
	ds_read_b32 v154, v237 offset:1280
	ds_read_b32 v156, v237 offset:1536
	ds_read_b32 v158, v237 offset:1792
	ds_read_b32 v160, v237 offset:2048
	ds_read_b32 v162, v237 offset:2304
	ds_read_b32 v164, v237 offset:2560
	ds_read_b32 v166, v237 offset:2816
	ds_read_b32 v168, v237 offset:3072
	ds_read_b32 v170, v237 offset:3328
	ds_read_b32 v172, v237 offset:3584
	ds_read_b32 v174, v237 offset:3840
	s_waitcnt lgkmcnt(0)
	v_lshlrev_b32_e32 v144, 3, v144
	v_lshlrev_b32_e32 v146, 3, v146
	v_lshlrev_b32_e32 v148, 3, v148
	v_lshlrev_b32_e32 v150, 3, v150
	v_lshlrev_b32_e32 v152, 3, v152
	v_lshlrev_b32_e32 v154, 3, v154
	v_lshlrev_b32_e32 v156, 3, v156
	v_lshlrev_b32_e32 v158, 3, v158
	v_lshlrev_b32_e32 v160, 3, v160
	v_lshlrev_b32_e32 v162, 3, v162
	v_lshlrev_b32_e32 v164, 3, v164
	v_lshlrev_b32_e32 v166, 3, v166
	v_lshlrev_b32_e32 v168, 3, v168
	v_lshlrev_b32_e32 v170, 3, v170
	v_lshlrev_b32_e32 v172, 3, v172
	v_lshlrev_b32_e32 v174, 3, v174
	global_load_dwordx2 v[144:145], v144, s[8:9]
	global_load_dwordx2 v[146:147], v146, s[8:9]
	global_load_dwordx2 v[148:149], v148, s[8:9]
	global_load_dwordx2 v[150:151], v150, s[8:9]
	global_load_dwordx2 v[152:153], v152, s[8:9]
	global_load_dwordx2 v[154:155], v154, s[8:9]
	global_load_dwordx2 v[156:157], v156, s[8:9]
	global_load_dwordx2 v[158:159], v158, s[8:9]
	global_load_dwordx2 v[160:161], v160, s[8:9]
	global_load_dwordx2 v[162:163], v162, s[8:9]
	global_load_dwordx2 v[164:165], v164, s[8:9]
	global_load_dwordx2 v[166:167], v166, s[8:9]
	global_load_dwordx2 v[168:169], v168, s[8:9]
	global_load_dwordx2 v[170:171], v170, s[8:9]
	global_load_dwordx2 v[172:173], v172, s[8:9]
	global_load_dwordx2 v[174:175], v174, s[8:9]
	s_waitcnt vmcnt(32)
; template <bool STORE>
; DI void peer_item(const Params& p, int item, char* smem) {
;     ...
;       float part[8];
; #pragma unroll
;       for (int u = 0; u < 8; ++u) {
;         float d = 0.f;
; #pragma unroll
;         for (int i = 0; i < 4; ++i) {
;           f32x2_t lo = __builtin_amdgcn_cvt_pk_f32_fp8((int)uq[u][i], false);
;           f32x2_t hi = __builtin_amdgcn_cvt_pk_f32_fp8((int)uq[u][i], true);
;           d += xf[4 * i] * lo.x + xf[4 * i + 1] * lo.y + xf[4 * i + 2] * hi.x + xf[4 * i + 3] * hi.y;
;         }
;         part[u] = d;
;       }
.Lud_cons5_Lup_kB:
	v_cvt_pk_f32_fp8_e32 v[214:215], v176
	v_cvt_pk_f32_fp8_sdwa v[216:217], v176 src0_sel:WORD_1
	v_cvt_pk_f32_fp8_e32 v[218:219], v177
	v_cvt_pk_f32_fp8_sdwa v[220:221], v177 src0_sel:WORD_1
	v_pk_mul_f32 v[222:223], v[80:81], v[214:215]
	v_pk_mul_f32 v[224:225], v[82:83], v[216:217]
	v_cvt_pk_f32_fp8_e32 v[214:215], v178
	v_cvt_pk_f32_fp8_sdwa v[216:217], v178 src0_sel:WORD_1
	v_pk_fma_f32 v[222:223], v[84:85], v[218:219], v[222:223]
	v_pk_fma_f32 v[224:225], v[86:87], v[220:221], v[224:225]
	v_cvt_pk_f32_fp8_e32 v[218:219], v179
	v_cvt_pk_f32_fp8_sdwa v[220:221], v179 src0_sel:WORD_1
	v_pk_fma_f32 v[222:223], v[88:89], v[214:215], v[222:223]
	v_pk_fma_f32 v[224:225], v[90:91], v[216:217], v[224:225]
	v_pk_fma_f32 v[222:223], v[92:93], v[218:219], v[222:223]
	v_pk_fma_f32 v[224:225], v[94:95], v[220:221], v[224:225]
	v_pk_add_f32 v[222:223], v[222:223], v[224:225]
	s_nop 0
	v_add_f32_e32 v226, v222, v223
	v_cvt_pk_f32_fp8_e32 v[214:215], v180
	v_cvt_pk_f32_fp8_sdwa v[216:217], v180 src0_sel:WORD_1
	v_cvt_pk_f32_fp8_e32 v[218:219], v181
	v_cvt_pk_f32_fp8_sdwa v[220:221], v181 src0_sel:WORD_1
	v_pk_mul_f32 v[222:223], v[80:81], v[214:215]
	v_pk_mul_f32 v[224:225], v[82:83], v[216:217]
	v_cvt_pk_f32_fp8_e32 v[214:215], v182
	v_cvt_pk_f32_fp8_sdwa v[216:217], v182 src0_sel:WORD_1
	v_pk_fma_f32 v[222:223], v[84:85], v[218:219], v[222:223]
	v_pk_fma_f32 v[224:225], v[86:87], v[220:221], v[224:225]
	v_cvt_pk_f32_fp8_e32 v[218:219], v183
	v_cvt_pk_f32_fp8_sdwa v[220:221], v183 src0_sel:WORD_1
	v_pk_fma_f32 v[222:223], v[88:89], v[214:215], v[222:223]
	v_pk_fma_f32 v[224:225], v[90:91], v[216:217], v[224:225]
	v_pk_fma_f32 v[222:223], v[92:93], v[218:219], v[222:223]
	v_pk_fma_f32 v[224:225], v[94:95], v[220:221], v[224:225]
	v_pk_add_f32 v[222:223], v[222:223], v[224:225]
	s_nop 0
	v_add_f32_e32 v227, v222, v223
	v_cvt_pk_f32_fp8_e32 v[214:215], v184
	v_cvt_pk_f32_fp8_sdwa v[216:217], v184 src0_sel:WORD_1
	v_cvt_pk_f32_fp8_e32 v[218:219], v185
	v_cvt_pk_f32_fp8_sdwa v[220:221], v185 src0_sel:WORD_1
	v_pk_mul_f32 v[222:223], v[80:81], v[214:215]
	v_pk_mul_f32 v[224:225], v[82:83], v[216:217]
	v_cvt_pk_f32_fp8_e32 v[214:215], v186
	v_cvt_pk_f32_fp8_sdwa v[216:217], v186 src0_sel:WORD_1
	v_pk_fma_f32 v[222:223], v[84:85], v[218:219], v[222:223]
	v_pk_fma_f32 v[224:225], v[86:87], v[220:221], v[224:225]
	v_cvt_pk_f32_fp8_e32 v[218:219], v187
	v_cvt_pk_f32_fp8_sdwa v[220:221], v187 src0_sel:WORD_1
	v_pk_fma_f32 v[222:223], v[88:89], v[214:215], v[222:223]
	v_pk_fma_f32 v[224:225], v[90:91], v[216:217], v[224:225]
	v_pk_fma_f32 v[222:223], v[92:93], v[218:219], v[222:223]
	v_pk_fma_f32 v[224:225], v[94:95], v[220:221], v[224:225]
	v_pk_add_f32 v[222:223], v[222:223], v[224:225]
	s_nop 0
	v_add_f32_e32 v228, v222, v223
	v_cvt_pk_f32_fp8_e32 v[214:215], v188
	v_cvt_pk_f32_fp8_sdwa v[216:217], v188 src0_sel:WORD_1
	v_cvt_pk_f32_fp8_e32 v[218:219], v189
	v_cvt_pk_f32_fp8_sdwa v[220:221], v189 src0_sel:WORD_1
	v_pk_mul_f32 v[222:223], v[80:81], v[214:215]
	v_pk_mul_f32 v[224:225], v[82:83], v[216:217]
	v_cvt_pk_f32_fp8_e32 v[214:215], v190
	v_cvt_pk_f32_fp8_sdwa v[216:217], v190 src0_sel:WORD_1
	v_pk_fma_f32 v[222:223], v[84:85], v[218:219], v[222:223]
	v_pk_fma_f32 v[224:225], v[86:87], v[220:221], v[224:225]
	v_cvt_pk_f32_fp8_e32 v[218:219], v191
	v_cvt_pk_f32_fp8_sdwa v[220:221], v191 src0_sel:WORD_1
	v_pk_fma_f32 v[222:223], v[88:89], v[214:215], v[222:223]
	v_pk_fma_f32 v[224:225], v[90:91], v[216:217], v[224:225]
	v_pk_fma_f32 v[222:223], v[92:93], v[218:219], v[222:223]
	v_pk_fma_f32 v[224:225], v[94:95], v[220:221], v[224:225]
	v_pk_add_f32 v[222:223], v[222:223], v[224:225]
	s_nop 0
	v_add_f32_e32 v229, v222, v223
	v_cvt_pk_f32_fp8_e32 v[214:215], v192
	v_cvt_pk_f32_fp8_sdwa v[216:217], v192 src0_sel:WORD_1
	v_cvt_pk_f32_fp8_e32 v[218:219], v193
	v_cvt_pk_f32_fp8_sdwa v[220:221], v193 src0_sel:WORD_1
	v_pk_mul_f32 v[222:223], v[80:81], v[214:215]
	v_pk_mul_f32 v[224:225], v[82:83], v[216:217]
	v_cvt_pk_f32_fp8_e32 v[214:215], v194
	v_cvt_pk_f32_fp8_sdwa v[216:217], v194 src0_sel:WORD_1
	v_pk_fma_f32 v[222:223], v[84:85], v[218:219], v[222:223]
	v_pk_fma_f32 v[224:225], v[86:87], v[220:221], v[224:225]
	v_cvt_pk_f32_fp8_e32 v[218:219], v195
	v_cvt_pk_f32_fp8_sdwa v[220:221], v195 src0_sel:WORD_1
	v_pk_fma_f32 v[222:223], v[88:89], v[214:215], v[222:223]
	v_pk_fma_f32 v[224:225], v[90:91], v[216:217], v[224:225]
	v_pk_fma_f32 v[222:223], v[92:93], v[218:219], v[222:223]
	v_pk_fma_f32 v[224:225], v[94:95], v[220:221], v[224:225]
	v_pk_add_f32 v[222:223], v[222:223], v[224:225]
	s_nop 0
	v_add_f32_e32 v230, v222, v223
	v_cvt_pk_f32_fp8_e32 v[214:215], v196
	v_cvt_pk_f32_fp8_sdwa v[216:217], v196 src0_sel:WORD_1
	v_cvt_pk_f32_fp8_e32 v[218:219], v197
	v_cvt_pk_f32_fp8_sdwa v[220:221], v197 src0_sel:WORD_1
	v_pk_mul_f32 v[222:223], v[80:81], v[214:215]
	v_pk_mul_f32 v[224:225], v[82:83], v[216:217]
	v_cvt_pk_f32_fp8_e32 v[214:215], v198
	v_cvt_pk_f32_fp8_sdwa v[216:217], v198 src0_sel:WORD_1
	v_pk_fma_f32 v[222:223], v[84:85], v[218:219], v[222:223]
	v_pk_fma_f32 v[224:225], v[86:87], v[220:221], v[224:225]
	v_cvt_pk_f32_fp8_e32 v[218:219], v199
	v_cvt_pk_f32_fp8_sdwa v[220:221], v199 src0_sel:WORD_1
	v_pk_fma_f32 v[222:223], v[88:89], v[214:215], v[222:223]
	v_pk_fma_f32 v[224:225], v[90:91], v[216:217], v[224:225]
	v_pk_fma_f32 v[222:223], v[92:93], v[218:219], v[222:223]
	v_pk_fma_f32 v[224:225], v[94:95], v[220:221], v[224:225]
	v_pk_add_f32 v[222:223], v[222:223], v[224:225]
	s_nop 0
	v_add_f32_e32 v231, v222, v223
	v_cvt_pk_f32_fp8_e32 v[214:215], v200
	v_cvt_pk_f32_fp8_sdwa v[216:217], v200 src0_sel:WORD_1
; template <bool STORE>
; DI void peer_item(const Params& p, int item, char* smem) {
;     ...
;       for (int u = 0; u < 8; ++u) {
;         int e = e_s[tl * 128 + k + u];
;         uq[u] = *(const u32x4*)(U8 + (size_t)e * 1024 + lane * 16);
;       }
;       float part[8];
; #pragma unroll
;       for (int u = 0; u < 8; ++u) {
;         float d = 0.f;
; #pragma unroll
;         for (int i = 0; i < 4; ++i) {
;           f32x2_t lo = __builtin_amdgcn_cvt_pk_f32_fp8((int)uq[u][i], false);
;           f32x2_t hi = __builtin_amdgcn_cvt_pk_f32_fp8((int)uq[u][i], true);
;           d += xf[4 * i] * lo.x + xf[4 * i + 1] * lo.y + xf[4 * i + 2] * hi.x + xf[4 * i + 3] * hi.y;
;         }
;         part[u] = d;
;       }
;       float q4[4], r2[2], h;
; #pragma unroll
;       for (int j = 0; j < 4; ++j) {
;         float mine = b5 ? part[j + 4] : part[j];
;         float other = b5 ? part[j] : part[j + 4];
;         q4[j] = mine + __shfl_xor(other, 32);
;       }
; #pragma unroll
;       for (int j = 0; j < 2; ++j) {
;         float mine = b4 ? q4[j + 2] : q4[j];
;         float other = b4 ? q4[j] : q4[j + 2];
;         r2[j] = mine + __shfl_xor(other, 16);
;       }
;       {
;         float mine = b3 ? r2[1] : r2[0];
;         float other = b3 ? r2[0] : r2[1];
;         h = mine + __shfl_xor(other, 8);
;       }
;       h += __shfl_xor(h, 4);
;       h += __shfl_xor(h, 2);
;       h += __shfl_xor(h, 1);
	v_cvt_pk_f32_fp8_e32 v[218:219], v201
	v_cvt_pk_f32_fp8_sdwa v[220:221], v201 src0_sel:WORD_1
	v_pk_mul_f32 v[222:223], v[80:81], v[214:215]
	v_pk_mul_f32 v[224:225], v[82:83], v[216:217]
	v_cvt_pk_f32_fp8_e32 v[214:215], v202
	v_cvt_pk_f32_fp8_sdwa v[216:217], v202 src0_sel:WORD_1
	v_pk_fma_f32 v[222:223], v[84:85], v[218:219], v[222:223]
	v_pk_fma_f32 v[224:225], v[86:87], v[220:221], v[224:225]
	v_cvt_pk_f32_fp8_e32 v[218:219], v203
	v_cvt_pk_f32_fp8_sdwa v[220:221], v203 src0_sel:WORD_1
	v_pk_fma_f32 v[222:223], v[88:89], v[214:215], v[222:223]
	v_pk_fma_f32 v[224:225], v[90:91], v[216:217], v[224:225]
	v_pk_fma_f32 v[222:223], v[92:93], v[218:219], v[222:223]
	v_pk_fma_f32 v[224:225], v[94:95], v[220:221], v[224:225]
	v_pk_add_f32 v[222:223], v[222:223], v[224:225]
	s_nop 0
	v_add_f32_e32 v232, v222, v223
	v_cvt_pk_f32_fp8_e32 v[214:215], v204
	v_cvt_pk_f32_fp8_sdwa v[216:217], v204 src0_sel:WORD_1
	v_cvt_pk_f32_fp8_e32 v[218:219], v205
	v_cvt_pk_f32_fp8_sdwa v[220:221], v205 src0_sel:WORD_1
	v_pk_mul_f32 v[222:223], v[80:81], v[214:215]
	v_pk_mul_f32 v[224:225], v[82:83], v[216:217]
	v_cvt_pk_f32_fp8_e32 v[214:215], v206
	v_cvt_pk_f32_fp8_sdwa v[216:217], v206 src0_sel:WORD_1
	v_pk_fma_f32 v[222:223], v[84:85], v[218:219], v[222:223]
	v_pk_fma_f32 v[224:225], v[86:87], v[220:221], v[224:225]
	v_cvt_pk_f32_fp8_e32 v[218:219], v207
	v_cvt_pk_f32_fp8_sdwa v[220:221], v207 src0_sel:WORD_1
	v_pk_fma_f32 v[222:223], v[88:89], v[214:215], v[222:223]
	v_pk_fma_f32 v[224:225], v[90:91], v[216:217], v[224:225]
	v_pk_fma_f32 v[222:223], v[92:93], v[218:219], v[222:223]
	v_pk_fma_f32 v[224:225], v[94:95], v[220:221], v[224:225]
	v_pk_add_f32 v[222:223], v[222:223], v[224:225]
	s_nop 0
	v_add_f32_e32 v233, v222, v223
	v_permlane32_swap_b32_e32 v226, v230
	v_permlane32_swap_b32_e32 v227, v231
	v_permlane32_swap_b32_e32 v228, v232
	v_permlane32_swap_b32_e32 v229, v233
	v_add_f32_e32 v226, v226, v230
	v_add_f32_e32 v228, v228, v232
	v_add_f32_e32 v227, v227, v231
	v_add_f32_e32 v229, v229, v233
	s_nop 1
	v_permlane16_swap_b32_e32 v226, v228
	v_permlane16_swap_b32_e32 v227, v229
	v_add_f32_e32 v226, v226, v228
	v_add_f32_e32 v227, v227, v229
	s_nop 0
	v_cndmask_b32_e64 v230, v226, v227, s[24:25]
	v_cndmask_b32_e64 v231, v227, v226, s[24:25]
	s_nop 1
	v_add_f32_dpp v232, v231, v230 row_ror:8 row_mask:0xf bank_mask:0xf
	s_nop 1
	v_add_f32_dpp v233, v232, v232 quad_perm:[1,0,3,2] row_mask:0xf bank_mask:0xf
	s_nop 1
	v_add_f32_dpp v232, v233, v233 quad_perm:[2,3,0,1] row_mask:0xf bank_mask:0xf
	s_nop 1
	v_add_f32_dpp v233, v232, v232 row_half_mirror row_mask:0xf bank_mask:0xf
	ds_write_b32 v235, v233 offset:35360
	s_cmp_eq_u32 s12, 7
	s_cbranch_scc1 .Lud_last6_Lup_kB
	v_readlane_b32 s48, v138, s58
	v_readlane_b32 s49, v138, s59
	v_readlane_b32 s50, v138, s60
	v_readlane_b32 s51, v138, s61
	v_readlane_b32 s52, v138, s62
	v_readlane_b32 s53, v138, s63
	v_readlane_b32 s54, v138, s64
	v_readlane_b32 s55, v138, s65
	s_add_u32 s32, s0, s48
	s_addc_u32 s33, s1, 0
	s_add_u32 s34, s0, s49
	s_addc_u32 s35, s1, 0
	s_add_u32 s36, s0, s50
	s_addc_u32 s37, s1, 0
	s_add_u32 s38, s0, s51
	s_addc_u32 s39, s1, 0
	s_add_u32 s40, s0, s52
	s_addc_u32 s41, s1, 0
	s_add_u32 s42, s0, s53
	s_addc_u32 s43, s1, 0
	s_add_u32 s44, s0, s54
	s_addc_u32 s45, s1, 0
	s_add_u32 s46, s0, s55
	s_addc_u32 s47, s1, 0
	global_load_dwordx4 v[176:179], v234, s[32:33]
	global_load_dwordx4 v[180:183], v234, s[34:35]
	global_load_dwordx4 v[184:187], v234, s[36:37]
	global_load_dwordx4 v[188:191], v234, s[38:39]
	global_load_dwordx4 v[192:195], v234, s[40:41]
	global_load_dwordx4 v[196:199], v234, s[42:43]
	global_load_dwordx4 v[200:203], v234, s[44:45]
	global_load_dwordx4 v[204:207], v234, s[46:47]
	s_waitcnt vmcnt(24)
	s_branch .Lud_cons6_Lup_kB
.Lud_last6_Lup_kB:
	s_waitcnt vmcnt(24)
.Lud_cons6_Lup_kB:
	v_cvt_pk_f32_fp8_e32 v[214:215], v0
	v_cvt_pk_f32_fp8_sdwa v[216:217], v0 src0_sel:WORD_1
	v_cvt_pk_f32_fp8_e32 v[218:219], v1
	v_cvt_pk_f32_fp8_sdwa v[220:221], v1 src0_sel:WORD_1
	v_pk_mul_f32 v[222:223], v[96:97], v[214:215]
	v_pk_mul_f32 v[224:225], v[98:99], v[216:217]
	v_cvt_pk_f32_fp8_e32 v[214:215], v2
	v_cvt_pk_f32_fp8_sdwa v[216:217], v2 src0_sel:WORD_1
	v_pk_fma_f32 v[222:223], v[100:101], v[218:219], v[222:223]
	v_pk_fma_f32 v[224:225], v[102:103], v[220:221], v[224:225]
	v_cvt_pk_f32_fp8_e32 v[218:219], v3
	v_cvt_pk_f32_fp8_sdwa v[220:221], v3 src0_sel:WORD_1
	v_pk_fma_f32 v[222:223], v[104:105], v[214:215], v[222:223]
	v_pk_fma_f32 v[224:225], v[106:107], v[216:217], v[224:225]
	v_pk_fma_f32 v[222:223], v[108:109], v[218:219], v[222:223]
	v_pk_fma_f32 v[224:225], v[110:111], v[220:221], v[224:225]
	v_pk_add_f32 v[222:223], v[222:223], v[224:225]
	s_nop 0
	v_add_f32_e32 v226, v222, v223
	v_cvt_pk_f32_fp8_e32 v[214:215], v4
	v_cvt_pk_f32_fp8_sdwa v[216:217], v4 src0_sel:WORD_1
	v_cvt_pk_f32_fp8_e32 v[218:219], v5
	v_cvt_pk_f32_fp8_sdwa v[220:221], v5 src0_sel:WORD_1
	v_pk_mul_f32 v[222:223], v[96:97], v[214:215]
	v_pk_mul_f32 v[224:225], v[98:99], v[216:217]
	v_cvt_pk_f32_fp8_e32 v[214:215], v6
	v_cvt_pk_f32_fp8_sdwa v[216:217], v6 src0_sel:WORD_1
	v_pk_fma_f32 v[222:223], v[100:101], v[218:219], v[222:223]
	v_pk_fma_f32 v[224:225], v[102:103], v[220:221], v[224:225]
	v_cvt_pk_f32_fp8_e32 v[218:219], v7
	v_cvt_pk_f32_fp8_sdwa v[220:221], v7 src0_sel:WORD_1
	v_pk_fma_f32 v[222:223], v[104:105], v[214:215], v[222:223]
	v_pk_fma_f32 v[224:225], v[106:107], v[216:217], v[224:225]
	v_pk_fma_f32 v[222:223], v[108:109], v[218:219], v[222:223]
	v_pk_fma_f32 v[224:225], v[110:111], v[220:221], v[224:225]
	v_pk_add_f32 v[222:223], v[222:223], v[224:225]
	s_nop 0
	v_add_f32_e32 v227, v222, v223
; template <bool STORE>
; DI void peer_item(const Params& p, int item, char* smem) {
;     ...
; #pragma unroll
;       for (int u = 0; u < 8; ++u) {
;         float d = 0.f;
; #pragma unroll
;         for (int i = 0; i < 4; ++i) {
;           f32x2_t lo = __builtin_amdgcn_cvt_pk_f32_fp8((int)uq[u][i], false);
;           f32x2_t hi = __builtin_amdgcn_cvt_pk_f32_fp8((int)uq[u][i], true);
;           d += xf[4 * i] * lo.x + xf[4 * i + 1] * lo.y + xf[4 * i + 2] * hi.x + xf[4 * i + 3] * hi.y;
;         }
;         part[u] = d;
;       }
;       float q4[4], r2[2], h;
; #pragma unroll
;       for (int j = 0; j < 4; ++j) {
;         float mine = b5 ? part[j + 4] : part[j];
;         float other = b5 ? part[j] : part[j + 4];
;         q4[j] = mine + __shfl_xor(other, 32);
;       }
; #pragma unroll
;       for (int j = 0; j < 2; ++j) {
;         float mine = b4 ? q4[j + 2] : q4[j];
;         float other = b4 ? q4[j] : q4[j + 2];
;         r2[j] = mine + __shfl_xor(other, 16);
;       }
;       {
;         float mine = b3 ? r2[1] : r2[0];
;         float other = b3 ? r2[0] : r2[1];
;         h = mine + __shfl_xor(other, 8);
;       }
;       h += __shfl_xor(h, 4);
;       h += __shfl_xor(h, 2);
;       h += __shfl_xor(h, 1);
	v_cvt_pk_f32_fp8_e32 v[214:215], v8
	v_cvt_pk_f32_fp8_sdwa v[216:217], v8 src0_sel:WORD_1
	v_cvt_pk_f32_fp8_e32 v[218:219], v9
	v_cvt_pk_f32_fp8_sdwa v[220:221], v9 src0_sel:WORD_1
	v_pk_mul_f32 v[222:223], v[96:97], v[214:215]
	v_pk_mul_f32 v[224:225], v[98:99], v[216:217]
	v_cvt_pk_f32_fp8_e32 v[214:215], v10
	v_cvt_pk_f32_fp8_sdwa v[216:217], v10 src0_sel:WORD_1
	v_pk_fma_f32 v[222:223], v[100:101], v[218:219], v[222:223]
	v_pk_fma_f32 v[224:225], v[102:103], v[220:221], v[224:225]
	v_cvt_pk_f32_fp8_e32 v[218:219], v11
	v_cvt_pk_f32_fp8_sdwa v[220:221], v11 src0_sel:WORD_1
	v_pk_fma_f32 v[222:223], v[104:105], v[214:215], v[222:223]
	v_pk_fma_f32 v[224:225], v[106:107], v[216:217], v[224:225]
	v_pk_fma_f32 v[222:223], v[108:109], v[218:219], v[222:223]
	v_pk_fma_f32 v[224:225], v[110:111], v[220:221], v[224:225]
	v_pk_add_f32 v[222:223], v[222:223], v[224:225]
	s_nop 0
	v_add_f32_e32 v228, v222, v223
	v_cvt_pk_f32_fp8_e32 v[214:215], v12
	v_cvt_pk_f32_fp8_sdwa v[216:217], v12 src0_sel:WORD_1
	v_cvt_pk_f32_fp8_e32 v[218:219], v13
	v_cvt_pk_f32_fp8_sdwa v[220:221], v13 src0_sel:WORD_1
	v_pk_mul_f32 v[222:223], v[96:97], v[214:215]
	v_pk_mul_f32 v[224:225], v[98:99], v[216:217]
	v_cvt_pk_f32_fp8_e32 v[214:215], v14
	v_cvt_pk_f32_fp8_sdwa v[216:217], v14 src0_sel:WORD_1
	v_pk_fma_f32 v[222:223], v[100:101], v[218:219], v[222:223]
	v_pk_fma_f32 v[224:225], v[102:103], v[220:221], v[224:225]
	v_cvt_pk_f32_fp8_e32 v[218:219], v15
	v_cvt_pk_f32_fp8_sdwa v[220:221], v15 src0_sel:WORD_1
	v_pk_fma_f32 v[222:223], v[104:105], v[214:215], v[222:223]
	v_pk_fma_f32 v[224:225], v[106:107], v[216:217], v[224:225]
	v_pk_fma_f32 v[222:223], v[108:109], v[218:219], v[222:223]
	v_pk_fma_f32 v[224:225], v[110:111], v[220:221], v[224:225]
	v_pk_add_f32 v[222:223], v[222:223], v[224:225]
	s_nop 0
	v_add_f32_e32 v229, v222, v223
	v_cvt_pk_f32_fp8_e32 v[214:215], v16
	v_cvt_pk_f32_fp8_sdwa v[216:217], v16 src0_sel:WORD_1
	v_cvt_pk_f32_fp8_e32 v[218:219], v17
	v_cvt_pk_f32_fp8_sdwa v[220:221], v17 src0_sel:WORD_1
	v_pk_mul_f32 v[222:223], v[96:97], v[214:215]
	v_pk_mul_f32 v[224:225], v[98:99], v[216:217]
	v_cvt_pk_f32_fp8_e32 v[214:215], v18
	v_cvt_pk_f32_fp8_sdwa v[216:217], v18 src0_sel:WORD_1
	v_pk_fma_f32 v[222:223], v[100:101], v[218:219], v[222:223]
	v_pk_fma_f32 v[224:225], v[102:103], v[220:221], v[224:225]
	v_cvt_pk_f32_fp8_e32 v[218:219], v19
	v_cvt_pk_f32_fp8_sdwa v[220:221], v19 src0_sel:WORD_1
	v_pk_fma_f32 v[222:223], v[104:105], v[214:215], v[222:223]
	v_pk_fma_f32 v[224:225], v[106:107], v[216:217], v[224:225]
	v_pk_fma_f32 v[222:223], v[108:109], v[218:219], v[222:223]
	v_pk_fma_f32 v[224:225], v[110:111], v[220:221], v[224:225]
	v_pk_add_f32 v[222:223], v[222:223], v[224:225]
	s_nop 0
	v_add_f32_e32 v230, v222, v223
	v_cvt_pk_f32_fp8_e32 v[214:215], v20
	v_cvt_pk_f32_fp8_sdwa v[216:217], v20 src0_sel:WORD_1
	v_cvt_pk_f32_fp8_e32 v[218:219], v21
	v_cvt_pk_f32_fp8_sdwa v[220:221], v21 src0_sel:WORD_1
	v_pk_mul_f32 v[222:223], v[96:97], v[214:215]
	v_pk_mul_f32 v[224:225], v[98:99], v[216:217]
	v_cvt_pk_f32_fp8_e32 v[214:215], v22
	v_cvt_pk_f32_fp8_sdwa v[216:217], v22 src0_sel:WORD_1
	v_pk_fma_f32 v[222:223], v[100:101], v[218:219], v[222:223]
	v_pk_fma_f32 v[224:225], v[102:103], v[220:221], v[224:225]
	v_cvt_pk_f32_fp8_e32 v[218:219], v23
	v_cvt_pk_f32_fp8_sdwa v[220:221], v23 src0_sel:WORD_1
	v_pk_fma_f32 v[222:223], v[104:105], v[214:215], v[222:223]
	v_pk_fma_f32 v[224:225], v[106:107], v[216:217], v[224:225]
	v_pk_fma_f32 v[222:223], v[108:109], v[218:219], v[222:223]
	v_pk_fma_f32 v[224:225], v[110:111], v[220:221], v[224:225]
	v_pk_add_f32 v[222:223], v[222:223], v[224:225]
	s_nop 0
	v_add_f32_e32 v231, v222, v223
	v_cvt_pk_f32_fp8_e32 v[214:215], v24
	v_cvt_pk_f32_fp8_sdwa v[216:217], v24 src0_sel:WORD_1
	v_cvt_pk_f32_fp8_e32 v[218:219], v25
	v_cvt_pk_f32_fp8_sdwa v[220:221], v25 src0_sel:WORD_1
	v_pk_mul_f32 v[222:223], v[96:97], v[214:215]
	v_pk_mul_f32 v[224:225], v[98:99], v[216:217]
	v_cvt_pk_f32_fp8_e32 v[214:215], v26
	v_cvt_pk_f32_fp8_sdwa v[216:217], v26 src0_sel:WORD_1
	v_pk_fma_f32 v[222:223], v[100:101], v[218:219], v[222:223]
	v_pk_fma_f32 v[224:225], v[102:103], v[220:221], v[224:225]
	v_cvt_pk_f32_fp8_e32 v[218:219], v27
	v_cvt_pk_f32_fp8_sdwa v[220:221], v27 src0_sel:WORD_1
	v_pk_fma_f32 v[222:223], v[104:105], v[214:215], v[222:223]
	v_pk_fma_f32 v[224:225], v[106:107], v[216:217], v[224:225]
	v_pk_fma_f32 v[222:223], v[108:109], v[218:219], v[222:223]
	v_pk_fma_f32 v[224:225], v[110:111], v[220:221], v[224:225]
	v_pk_add_f32 v[222:223], v[222:223], v[224:225]
	s_nop 0
	v_add_f32_e32 v232, v222, v223
	v_cvt_pk_f32_fp8_e32 v[214:215], v28
	v_cvt_pk_f32_fp8_sdwa v[216:217], v28 src0_sel:WORD_1
	v_cvt_pk_f32_fp8_e32 v[218:219], v29
	v_cvt_pk_f32_fp8_sdwa v[220:221], v29 src0_sel:WORD_1
	v_pk_mul_f32 v[222:223], v[96:97], v[214:215]
	v_pk_mul_f32 v[224:225], v[98:99], v[216:217]
	v_cvt_pk_f32_fp8_e32 v[214:215], v30
	v_cvt_pk_f32_fp8_sdwa v[216:217], v30 src0_sel:WORD_1
	v_pk_fma_f32 v[222:223], v[100:101], v[218:219], v[222:223]
	v_pk_fma_f32 v[224:225], v[102:103], v[220:221], v[224:225]
	v_cvt_pk_f32_fp8_e32 v[218:219], v31
	v_cvt_pk_f32_fp8_sdwa v[220:221], v31 src0_sel:WORD_1
	v_pk_fma_f32 v[222:223], v[104:105], v[214:215], v[222:223]
	v_pk_fma_f32 v[224:225], v[106:107], v[216:217], v[224:225]
	v_pk_fma_f32 v[222:223], v[108:109], v[218:219], v[222:223]
	v_pk_fma_f32 v[224:225], v[110:111], v[220:221], v[224:225]
	v_pk_add_f32 v[222:223], v[222:223], v[224:225]
	s_nop 0
	v_add_f32_e32 v233, v222, v223
	v_permlane32_swap_b32_e32 v226, v230
	v_permlane32_swap_b32_e32 v227, v231
	v_permlane32_swap_b32_e32 v228, v232
	v_permlane32_swap_b32_e32 v229, v233
	v_add_f32_e32 v226, v226, v230
	v_add_f32_e32 v228, v228, v232
	v_add_f32_e32 v227, v227, v231
	v_add_f32_e32 v229, v229, v233
	s_nop 1
	v_permlane16_swap_b32_e32 v226, v228
	v_permlane16_swap_b32_e32 v227, v229
	v_add_f32_e32 v226, v226, v228
	v_add_f32_e32 v227, v227, v229
	s_nop 0
	v_cndmask_b32_e64 v230, v226, v227, s[24:25]
	v_cndmask_b32_e64 v231, v227, v226, s[24:25]
	s_nop 1
	v_add_f32_dpp v232, v231, v230 row_ror:8 row_mask:0xf bank_mask:0xf
	s_nop 1
	v_add_f32_dpp v233, v232, v232 quad_perm:[1,0,3,2] row_mask:0xf bank_mask:0xf
	s_nop 1
	v_add_f32_dpp v232, v233, v233 quad_perm:[2,3,0,1] row_mask:0xf bank_mask:0xf
	s_nop 1
	v_add_f32_dpp v233, v232, v232 row_half_mirror row_mask:0xf bank_mask:0xf
	ds_write_b32 v235, v233 offset:35872
	s_cmp_eq_u32 s12, 7
	s_cbranch_scc1 .Lud_last7_Lup_kB
; template <bool STORE>
; DI void peer_item(const Params& p, int item, char* smem) {
;     ...
;       u32x4 uq[8];
;       const int emine = e_s[tl * 128 + k + (lane >> 3)];
;       const float gmine = g_s[tl * 128 + k + (lane >> 3)];
;       const float su = SU[emine], sv = SV[emine];
; #pragma unroll
;       for (int u = 0; u < 8; ++u) {
;         int e = e_s[tl * 128 + k + u];
;         uq[u] = *(const u32x4*)(U8 + (size_t)e * 1024 + lane * 16);
;       }
;       float part[8];
; #pragma unroll
;       for (int u = 0; u < 8; ++u) {
;         float d = 0.f;
; #pragma unroll
;         for (int i = 0; i < 4; ++i) {
;           f32x2_t lo = __builtin_amdgcn_cvt_pk_f32_fp8((int)uq[u][i], false);
;           f32x2_t hi = __builtin_amdgcn_cvt_pk_f32_fp8((int)uq[u][i], true);
;           d += xf[4 * i] * lo.x + xf[4 * i + 1] * lo.y + xf[4 * i + 2] * hi.x + xf[4 * i + 3] * hi.y;
;         }
;         part[u] = d;
;       }
	v_readlane_b32 s48, v140, s58
	v_readlane_b32 s49, v140, s59
	v_readlane_b32 s50, v140, s60
	v_readlane_b32 s51, v140, s61
	v_readlane_b32 s52, v140, s62
	v_readlane_b32 s53, v140, s63
	v_readlane_b32 s54, v140, s64
	v_readlane_b32 s55, v140, s65
	s_add_u32 s32, s0, s48
	s_addc_u32 s33, s1, 0
	s_add_u32 s34, s0, s49
	s_addc_u32 s35, s1, 0
	s_add_u32 s36, s0, s50
	s_addc_u32 s37, s1, 0
	s_add_u32 s38, s0, s51
	s_addc_u32 s39, s1, 0
	s_add_u32 s40, s0, s52
	s_addc_u32 s41, s1, 0
	s_add_u32 s42, s0, s53
	s_addc_u32 s43, s1, 0
	s_add_u32 s44, s0, s54
	s_addc_u32 s45, s1, 0
	s_add_u32 s46, s0, s55
	s_addc_u32 s47, s1, 0
	global_load_dwordx4 v[0:3], v234, s[32:33]
	global_load_dwordx4 v[4:7], v234, s[34:35]
	global_load_dwordx4 v[8:11], v234, s[36:37]
	global_load_dwordx4 v[12:15], v234, s[38:39]
	global_load_dwordx4 v[16:19], v234, s[40:41]
	global_load_dwordx4 v[20:23], v234, s[42:43]
	global_load_dwordx4 v[24:27], v234, s[44:45]
	global_load_dwordx4 v[28:31], v234, s[46:47]
	s_waitcnt vmcnt(24)
	s_branch .Lud_cons7_Lup_kB
.Lud_last7_Lup_kB:
	s_waitcnt vmcnt(16)
.Lud_cons7_Lup_kB:
	v_cvt_pk_f32_fp8_e32 v[214:215], v32
	v_cvt_pk_f32_fp8_sdwa v[216:217], v32 src0_sel:WORD_1
	v_cvt_pk_f32_fp8_e32 v[218:219], v33
	v_cvt_pk_f32_fp8_sdwa v[220:221], v33 src0_sel:WORD_1
	v_pk_mul_f32 v[222:223], v[112:113], v[214:215]
	v_pk_mul_f32 v[224:225], v[114:115], v[216:217]
	v_cvt_pk_f32_fp8_e32 v[214:215], v34
	v_cvt_pk_f32_fp8_sdwa v[216:217], v34 src0_sel:WORD_1
	v_pk_fma_f32 v[222:223], v[116:117], v[218:219], v[222:223]
	v_pk_fma_f32 v[224:225], v[118:119], v[220:221], v[224:225]
	v_cvt_pk_f32_fp8_e32 v[218:219], v35
	v_cvt_pk_f32_fp8_sdwa v[220:221], v35 src0_sel:WORD_1
	v_pk_fma_f32 v[222:223], v[120:121], v[214:215], v[222:223]
	v_pk_fma_f32 v[224:225], v[122:123], v[216:217], v[224:225]
	v_pk_fma_f32 v[222:223], v[124:125], v[218:219], v[222:223]
	v_pk_fma_f32 v[224:225], v[126:127], v[220:221], v[224:225]
	v_pk_add_f32 v[222:223], v[222:223], v[224:225]
	s_nop 0
	v_add_f32_e32 v226, v222, v223
	v_cvt_pk_f32_fp8_e32 v[214:215], v36
	v_cvt_pk_f32_fp8_sdwa v[216:217], v36 src0_sel:WORD_1
	v_cvt_pk_f32_fp8_e32 v[218:219], v37
	v_cvt_pk_f32_fp8_sdwa v[220:221], v37 src0_sel:WORD_1
	v_pk_mul_f32 v[222:223], v[112:113], v[214:215]
	v_pk_mul_f32 v[224:225], v[114:115], v[216:217]
	v_cvt_pk_f32_fp8_e32 v[214:215], v38
	v_cvt_pk_f32_fp8_sdwa v[216:217], v38 src0_sel:WORD_1
	v_pk_fma_f32 v[222:223], v[116:117], v[218:219], v[222:223]
	v_pk_fma_f32 v[224:225], v[118:119], v[220:221], v[224:225]
	v_cvt_pk_f32_fp8_e32 v[218:219], v39
	v_cvt_pk_f32_fp8_sdwa v[220:221], v39 src0_sel:WORD_1
	v_pk_fma_f32 v[222:223], v[120:121], v[214:215], v[222:223]
	v_pk_fma_f32 v[224:225], v[122:123], v[216:217], v[224:225]
	v_pk_fma_f32 v[222:223], v[124:125], v[218:219], v[222:223]
	v_pk_fma_f32 v[224:225], v[126:127], v[220:221], v[224:225]
	v_pk_add_f32 v[222:223], v[222:223], v[224:225]
	s_nop 0
	v_add_f32_e32 v227, v222, v223
	v_cvt_pk_f32_fp8_e32 v[214:215], v40
	v_cvt_pk_f32_fp8_sdwa v[216:217], v40 src0_sel:WORD_1
	v_cvt_pk_f32_fp8_e32 v[218:219], v41
	v_cvt_pk_f32_fp8_sdwa v[220:221], v41 src0_sel:WORD_1
	v_pk_mul_f32 v[222:223], v[112:113], v[214:215]
	v_pk_mul_f32 v[224:225], v[114:115], v[216:217]
	v_cvt_pk_f32_fp8_e32 v[214:215], v42
	v_cvt_pk_f32_fp8_sdwa v[216:217], v42 src0_sel:WORD_1
	v_pk_fma_f32 v[222:223], v[116:117], v[218:219], v[222:223]
	v_pk_fma_f32 v[224:225], v[118:119], v[220:221], v[224:225]
	v_cvt_pk_f32_fp8_e32 v[218:219], v43
	v_cvt_pk_f32_fp8_sdwa v[220:221], v43 src0_sel:WORD_1
	v_pk_fma_f32 v[222:223], v[120:121], v[214:215], v[222:223]
	v_pk_fma_f32 v[224:225], v[122:123], v[216:217], v[224:225]
	v_pk_fma_f32 v[222:223], v[124:125], v[218:219], v[222:223]
	v_pk_fma_f32 v[224:225], v[126:127], v[220:221], v[224:225]
	v_pk_add_f32 v[222:223], v[222:223], v[224:225]
	s_nop 0
	v_add_f32_e32 v228, v222, v223
	v_cvt_pk_f32_fp8_e32 v[214:215], v44
	v_cvt_pk_f32_fp8_sdwa v[216:217], v44 src0_sel:WORD_1
	v_cvt_pk_f32_fp8_e32 v[218:219], v45
	v_cvt_pk_f32_fp8_sdwa v[220:221], v45 src0_sel:WORD_1
	v_pk_mul_f32 v[222:223], v[112:113], v[214:215]
	v_pk_mul_f32 v[224:225], v[114:115], v[216:217]
	v_cvt_pk_f32_fp8_e32 v[214:215], v46
	v_cvt_pk_f32_fp8_sdwa v[216:217], v46 src0_sel:WORD_1
	v_pk_fma_f32 v[222:223], v[116:117], v[218:219], v[222:223]
	v_pk_fma_f32 v[224:225], v[118:119], v[220:221], v[224:225]
	v_cvt_pk_f32_fp8_e32 v[218:219], v47
	v_cvt_pk_f32_fp8_sdwa v[220:221], v47 src0_sel:WORD_1
	v_pk_fma_f32 v[222:223], v[120:121], v[214:215], v[222:223]
	v_pk_fma_f32 v[224:225], v[122:123], v[216:217], v[224:225]
	v_pk_fma_f32 v[222:223], v[124:125], v[218:219], v[222:223]
	v_pk_fma_f32 v[224:225], v[126:127], v[220:221], v[224:225]
	v_pk_add_f32 v[222:223], v[222:223], v[224:225]
	s_nop 0
	v_add_f32_e32 v229, v222, v223
	v_cvt_pk_f32_fp8_e32 v[214:215], v48
	v_cvt_pk_f32_fp8_sdwa v[216:217], v48 src0_sel:WORD_1
	v_cvt_pk_f32_fp8_e32 v[218:219], v49
	v_cvt_pk_f32_fp8_sdwa v[220:221], v49 src0_sel:WORD_1
	v_pk_mul_f32 v[222:223], v[112:113], v[214:215]
	v_pk_mul_f32 v[224:225], v[114:115], v[216:217]
	v_cvt_pk_f32_fp8_e32 v[214:215], v50
	v_cvt_pk_f32_fp8_sdwa v[216:217], v50 src0_sel:WORD_1
	v_pk_fma_f32 v[222:223], v[116:117], v[218:219], v[222:223]
	v_pk_fma_f32 v[224:225], v[118:119], v[220:221], v[224:225]
	v_cvt_pk_f32_fp8_e32 v[218:219], v51
	v_cvt_pk_f32_fp8_sdwa v[220:221], v51 src0_sel:WORD_1
	v_pk_fma_f32 v[222:223], v[120:121], v[214:215], v[222:223]
	v_pk_fma_f32 v[224:225], v[122:123], v[216:217], v[224:225]
	v_pk_fma_f32 v[222:223], v[124:125], v[218:219], v[222:223]
	v_pk_fma_f32 v[224:225], v[126:127], v[220:221], v[224:225]
; DI float gelu_exact(float x) { return 0.5f * x * (1.f + erff(x * 0.7071067811865476f)); }
; template <bool STORE>
; DI void peer_item(const Params& p, int item, char* smem) {
;     ...
; #pragma unroll
;       for (int u = 0; u < 8; ++u) {
;         float d = 0.f;
; #pragma unroll
;         for (int i = 0; i < 4; ++i) {
;           f32x2_t lo = __builtin_amdgcn_cvt_pk_f32_fp8((int)uq[u][i], false);
;           f32x2_t hi = __builtin_amdgcn_cvt_pk_f32_fp8((int)uq[u][i], true);
;           d += xf[4 * i] * lo.x + xf[4 * i + 1] * lo.y + xf[4 * i + 2] * hi.x + xf[4 * i + 3] * hi.y;
;         }
;         part[u] = d;
;       }
;       float q4[4], r2[2], h;
; #pragma unroll
;       for (int j = 0; j < 4; ++j) {
;         float mine = b5 ? part[j + 4] : part[j];
;         float other = b5 ? part[j] : part[j + 4];
;         q4[j] = mine + __shfl_xor(other, 32);
;       }
; #pragma unroll
;       for (int j = 0; j < 2; ++j) {
;         float mine = b4 ? q4[j + 2] : q4[j];
;         float other = b4 ? q4[j] : q4[j + 2];
;         r2[j] = mine + __shfl_xor(other, 16);
;       }
;       {
;         float mine = b3 ? r2[1] : r2[0];
;         float other = b3 ? r2[0] : r2[1];
;         h = mine + __shfl_xor(other, 8);
;       }
;       h += __shfl_xor(h, 4);
;       h += __shfl_xor(h, 2);
;       h += __shfl_xor(h, 1);
;       const float amine = gelu_exact(h * su) * gmine * sv;
;       if ((lane & 7) == 0) {
;         EG[tok * 128 + k + (lane >> 3)] = emine;
;         AG[tok * 128 + k + (lane >> 3)] = amine;
;       }
	v_pk_add_f32 v[222:223], v[222:223], v[224:225]
	s_nop 0
	v_add_f32_e32 v230, v222, v223
	v_cvt_pk_f32_fp8_e32 v[214:215], v52
	v_cvt_pk_f32_fp8_sdwa v[216:217], v52 src0_sel:WORD_1
	v_cvt_pk_f32_fp8_e32 v[218:219], v53
	v_cvt_pk_f32_fp8_sdwa v[220:221], v53 src0_sel:WORD_1
	v_pk_mul_f32 v[222:223], v[112:113], v[214:215]
	v_pk_mul_f32 v[224:225], v[114:115], v[216:217]
	v_cvt_pk_f32_fp8_e32 v[214:215], v54
	v_cvt_pk_f32_fp8_sdwa v[216:217], v54 src0_sel:WORD_1
	v_pk_fma_f32 v[222:223], v[116:117], v[218:219], v[222:223]
	v_pk_fma_f32 v[224:225], v[118:119], v[220:221], v[224:225]
	v_cvt_pk_f32_fp8_e32 v[218:219], v55
	v_cvt_pk_f32_fp8_sdwa v[220:221], v55 src0_sel:WORD_1
	v_pk_fma_f32 v[222:223], v[120:121], v[214:215], v[222:223]
	v_pk_fma_f32 v[224:225], v[122:123], v[216:217], v[224:225]
	v_pk_fma_f32 v[222:223], v[124:125], v[218:219], v[222:223]
	v_pk_fma_f32 v[224:225], v[126:127], v[220:221], v[224:225]
	v_pk_add_f32 v[222:223], v[222:223], v[224:225]
	s_nop 0
	v_add_f32_e32 v231, v222, v223
	v_cvt_pk_f32_fp8_e32 v[214:215], v56
	v_cvt_pk_f32_fp8_sdwa v[216:217], v56 src0_sel:WORD_1
	v_cvt_pk_f32_fp8_e32 v[218:219], v57
	v_cvt_pk_f32_fp8_sdwa v[220:221], v57 src0_sel:WORD_1
	v_pk_mul_f32 v[222:223], v[112:113], v[214:215]
	v_pk_mul_f32 v[224:225], v[114:115], v[216:217]
	v_cvt_pk_f32_fp8_e32 v[214:215], v58
	v_cvt_pk_f32_fp8_sdwa v[216:217], v58 src0_sel:WORD_1
	v_pk_fma_f32 v[222:223], v[116:117], v[218:219], v[222:223]
	v_pk_fma_f32 v[224:225], v[118:119], v[220:221], v[224:225]
	v_cvt_pk_f32_fp8_e32 v[218:219], v59
	v_cvt_pk_f32_fp8_sdwa v[220:221], v59 src0_sel:WORD_1
	v_pk_fma_f32 v[222:223], v[120:121], v[214:215], v[222:223]
	v_pk_fma_f32 v[224:225], v[122:123], v[216:217], v[224:225]
	v_pk_fma_f32 v[222:223], v[124:125], v[218:219], v[222:223]
	v_pk_fma_f32 v[224:225], v[126:127], v[220:221], v[224:225]
	v_pk_add_f32 v[222:223], v[222:223], v[224:225]
	s_nop 0
	v_add_f32_e32 v232, v222, v223
	v_cvt_pk_f32_fp8_e32 v[214:215], v60
	v_cvt_pk_f32_fp8_sdwa v[216:217], v60 src0_sel:WORD_1
	v_cvt_pk_f32_fp8_e32 v[218:219], v61
	v_cvt_pk_f32_fp8_sdwa v[220:221], v61 src0_sel:WORD_1
	v_pk_mul_f32 v[222:223], v[112:113], v[214:215]
	v_pk_mul_f32 v[224:225], v[114:115], v[216:217]
	v_cvt_pk_f32_fp8_e32 v[214:215], v62
	v_cvt_pk_f32_fp8_sdwa v[216:217], v62 src0_sel:WORD_1
	v_pk_fma_f32 v[222:223], v[116:117], v[218:219], v[222:223]
	v_pk_fma_f32 v[224:225], v[118:119], v[220:221], v[224:225]
	v_cvt_pk_f32_fp8_e32 v[218:219], v63
	v_cvt_pk_f32_fp8_sdwa v[220:221], v63 src0_sel:WORD_1
	v_pk_fma_f32 v[222:223], v[120:121], v[214:215], v[222:223]
	v_pk_fma_f32 v[224:225], v[122:123], v[216:217], v[224:225]
	v_pk_fma_f32 v[222:223], v[124:125], v[218:219], v[222:223]
	v_pk_fma_f32 v[224:225], v[126:127], v[220:221], v[224:225]
	v_pk_add_f32 v[222:223], v[222:223], v[224:225]
	s_nop 0
	v_add_f32_e32 v233, v222, v223
	v_permlane32_swap_b32_e32 v226, v230
	v_permlane32_swap_b32_e32 v227, v231
	v_permlane32_swap_b32_e32 v228, v232
	v_permlane32_swap_b32_e32 v229, v233
	v_add_f32_e32 v226, v226, v230
	v_add_f32_e32 v228, v228, v232
	v_add_f32_e32 v227, v227, v231
	v_add_f32_e32 v229, v229, v233
	s_nop 1
	v_permlane16_swap_b32_e32 v226, v228
	v_permlane16_swap_b32_e32 v227, v229
	v_add_f32_e32 v226, v226, v228
	v_add_f32_e32 v227, v227, v229
	s_nop 0
	v_cndmask_b32_e64 v230, v226, v227, s[24:25]
	v_cndmask_b32_e64 v231, v227, v226, s[24:25]
	s_nop 1
	v_add_f32_dpp v232, v231, v230 row_ror:8 row_mask:0xf bank_mask:0xf
	s_nop 1
	v_add_f32_dpp v233, v232, v232 quad_perm:[1,0,3,2] row_mask:0xf bank_mask:0xf
	s_nop 1
	v_add_f32_dpp v232, v233, v233 quad_perm:[2,3,0,1] row_mask:0xf bank_mask:0xf
	s_nop 1
	v_add_f32_dpp v233, v232, v232 row_half_mirror row_mask:0xf bank_mask:0xf
	ds_write_b32 v235, v233 offset:36384
	s_mov_b32 s72, s58
	s_mov_b32 s73, s59
	s_mov_b32 s74, s60
	s_mov_b32 s75, s61
	s_mov_b32 s76, s62
	s_mov_b32 s77, s63
	s_mov_b32 s78, s64
	s_mov_b32 s79, s65
	s_add_u32 s58, s58, 8
	s_add_u32 s59, s59, 8
	s_add_u32 s60, s60, 8
	s_add_u32 s61, s61, 8
	s_add_u32 s62, s62, 8
	s_add_u32 s63, s63, 8
	s_add_u32 s64, s64, 8
	s_add_u32 s65, s65, 8
	s_and_b32 s58, s58, 63
	s_and_b32 s59, s59, 63
	s_and_b32 s60, s60, 63
	s_and_b32 s61, s61, 63
	s_and_b32 s62, s62, 63
	s_and_b32 s63, s63, 63
	s_and_b32 s64, s64, 63
	s_and_b32 s65, s65, 63
	v_add_u32_e32 v235, 64, v235
	s_add_u32 s12, s12, 1
	s_cmp_lt_u32 s12, 8
	s_cbranch_scc1 .Lup_kB
; DI float gelu_exact(float x) { return 0.5f * x * (1.f + erff(x * 0.7071067811865476f)); }
; template <bool STORE>
; DI void peer_item(const Params& p, int item, char* smem) {
;     ...
;       const float amine = gelu_exact(h * su) * gmine * sv;
;       if ((lane & 7) == 0) {
	s_waitcnt lgkmcnt(0)
	s_lshl_b32 s13, s14, 9
	s_add_u32 s26, s4, s13
	s_addc_u32 s27, s5, 0
	s_add_u32 s28, s6, s13
	s_addc_u32 s29, s7, 0
	ds_read_b32 v0, v237 offset:32768
	ds_read_b32 v1, v237 offset:33024
	ds_read_b32 v2, v237 offset:0
	ds_read_b32 v3, v237 offset:256
	ds_read_b32 v4, v237 offset:16384
	ds_read_b32 v5, v237 offset:16640
	ds_read_b32 v16, v237 offset:33280
	ds_read_b32 v17, v237 offset:33536
	ds_read_b32 v18, v237 offset:512
	ds_read_b32 v19, v237 offset:768
	ds_read_b32 v20, v237 offset:16896
	ds_read_b32 v21, v237 offset:17152
	ds_read_b32 v32, v237 offset:33792
	ds_read_b32 v33, v237 offset:34048
	ds_read_b32 v34, v237 offset:1024
	ds_read_b32 v35, v237 offset:1280
	ds_read_b32 v36, v237 offset:17408
	ds_read_b32 v37, v237 offset:17664
	ds_read_b32 v48, v237 offset:34304
	ds_read_b32 v49, v237 offset:34560
	ds_read_b32 v50, v237 offset:1536
	ds_read_b32 v51, v237 offset:1792
	ds_read_b32 v52, v237 offset:17920
	ds_read_b32 v53, v237 offset:18176
	ds_read_b32 v64, v237 offset:34816
	ds_read_b32 v65, v237 offset:35072
	ds_read_b32 v66, v237 offset:2048
	ds_read_b32 v67, v237 offset:2304
	ds_read_b32 v68, v237 offset:18432
	ds_read_b32 v69, v237 offset:18688
	ds_read_b32 v80, v237 offset:35328
	ds_read_b32 v81, v237 offset:35584
	ds_read_b32 v82, v237 offset:2560
	ds_read_b32 v83, v237 offset:2816
	ds_read_b32 v84, v237 offset:18944
	ds_read_b32 v85, v237 offset:19200
	ds_read_b32 v96, v237 offset:35840
	ds_read_b32 v97, v237 offset:36096
	ds_read_b32 v98, v237 offset:3072
	ds_read_b32 v99, v237 offset:3328
	ds_read_b32 v100, v237 offset:19456
	ds_read_b32 v101, v237 offset:19712
	ds_read_b32 v112, v237 offset:36352
	ds_read_b32 v113, v237 offset:36608
	ds_read_b32 v114, v237 offset:3584
	ds_read_b32 v115, v237 offset:3840
	ds_read_b32 v116, v237 offset:19968
	ds_read_b32 v117, v237 offset:20224
	s_lshl_b32 s13, s14, 5
	s_add_u32 s32, s56, 0x9a80200
	s_addc_u32 s33, s57, 0
	s_add_u32 s32, s32, s13
	s_addc_u32 s33, s33, 0
	v_mov_b32_e32 v208, 0
	global_load_dwordx4 v[12:15], v208, s[32:33] offset:0
	global_load_dwordx4 v[6:9], v208, s[32:33] offset:16
	global_load_dwordx4 v[28:31], v208, s[32:33] offset:32
	global_load_dwordx4 v[22:25], v208, s[32:33] offset:48
	global_load_dwordx4 v[44:47], v208, s[32:33] offset:64
	global_load_dwordx4 v[38:41], v208, s[32:33] offset:80
	global_load_dwordx4 v[60:63], v208, s[32:33] offset:96
	global_load_dwordx4 v[54:57], v208, s[32:33] offset:112
	global_load_dwordx4 v[76:79], v208, s[32:33] offset:128
	global_load_dwordx4 v[70:73], v208, s[32:33] offset:144
	global_load_dwordx4 v[92:95], v208, s[32:33] offset:160
	global_load_dwordx4 v[86:89], v208, s[32:33] offset:176
	global_load_dwordx4 v[108:111], v208, s[32:33] offset:192
	global_load_dwordx4 v[102:105], v208, s[32:33] offset:208
	global_load_dwordx4 v[124:127], v208, s[32:33] offset:224
	global_load_dwordx4 v[118:121], v208, s[32:33] offset:240
	s_waitcnt lgkmcnt(15)
	s_waitcnt lgkmcnt(15)
	s_waitcnt lgkmcnt(15)
	s_waitcnt lgkmcnt(15)
	s_waitcnt lgkmcnt(15)
	s_waitcnt lgkmcnt(12)
	s_waitcnt lgkmcnt(6)
	s_waitcnt lgkmcnt(0)
	s_waitcnt vmcnt(0)
	v_pk_add_f32 v[12:13], v[12:13], v[14:15]
	v_pk_add_f32 v[6:7], v[6:7], v[8:9]
	v_mov_b32_e32 v14, 0x358637bd
	v_pk_add_f32 v[12:13], v[12:13], v[6:7]
	s_nop 0
	v_add_f32_e32 v12, v12, v13
	s_nop 0
	v_fmamk_f32 v12, v12, 0x3a800000, v14
	s_nop 0
	v_rsq_f32_e32 v12, v12
	s_nop 1
	v_mul_f32_e32 v144, v144, v12
	v_mul_f32_e32 v146, v146, v12
	v_mul_f32_e32 v176, v144, v0
	v_mul_f32_e32 v177, 0x3f3504f3, v176
	v_mov_b32_e32 v178, 0xb9c68948
	v_fma_f32 v178, |v177|, s80, v178
	v_fma_f32 v178, |v177|, v178, s81
	v_fma_f32 v178, |v177|, v178, s82
	v_fma_f32 v178, |v177|, v178, s83
	v_fma_f32 v178, |v177|, v178, s84
	v_fma_f32 v178, |v177|, v178, s85
	v_fma_f32 v178, |v177|, v178, |v177|
	v_mul_f32_e32 v179, 0xbfb8aa3b, v178
	v_fma_f32 v180, v178, s86, -v179
	v_rndne_f32_e32 v181, v179
	v_fmac_f32_e32 v180, 0xb2a5705f, v178
	v_sub_f32_e32 v179, v179, v181
	v_add_f32_e32 v179, v179, v180
	v_cvt_i32_f32_e32 v180, v181
	v_exp_f32_e32 v179, v179
	v_cmp_nlt_f32_e32 vcc, s87, v178
	v_ldexp_f32 v179, v179, v180
	s_nop 0
	v_cndmask_b32_e32 v179, 0, v179, vcc
	v_cmp_ngt_f32_e32 vcc, s88, v178
	v_mov_b32_e32 v180, 0x7f800000
	s_nop 0
	v_cndmask_b32_e32 v179, v180, v179, vcc
	v_sub_f32_e32 v179, 1.0, v179
	v_mul_f32_e32 v180, v177, v177
	v_mov_b32_e32 v181, 0x3ba10414
	v_fmamk_f32 v181, v180, 0xba1345e1, v181
	v_fmaak_f32 v181, v180, v181, 0xbcdac9b8
	v_fmaak_f32 v181, v180, v181, 0x3de703be
	v_fmaak_f32 v181, v180, v181, 0xbec09330
	v_fmaak_f32 v181, v180, v181, 0x3e0375d0
	v_fma_f32 v181, |v177|, v181, |v177|
	v_cmp_nlt_f32_e64 vcc, |v177|, 1.0
	s_nop 1
	v_cndmask_b32_e32 v179, v181, v179, vcc
	v_bfi_b32 v179, s89, v179, v177
	v_mul_f32_e32 v176, 0.5, v176
	v_add_f32_e32 v179, 1.0, v179
	v_mul_f32_e32 v176, v176, v179
	v_mul_f32_e32 v176, v4, v176
	v_mul_f32_e32 v0, v145, v176
	v_mul_f32_e32 v176, v146, v1
	v_mul_f32_e32 v177, 0x3f3504f3, v176
	v_mov_b32_e32 v178, 0xb9c68948
	v_fma_f32 v178, |v177|, s80, v178
	v_fma_f32 v178, |v177|, v178, s81
	v_fma_f32 v178, |v177|, v178, s82
	v_fma_f32 v178, |v177|, v178, s83
	v_fma_f32 v178, |v177|, v178, s84
	v_fma_f32 v178, |v177|, v178, s85
	v_fma_f32 v178, |v177|, v178, |v177|
	v_mul_f32_e32 v179, 0xbfb8aa3b, v178
	v_fma_f32 v180, v178, s86, -v179
	v_rndne_f32_e32 v181, v179
	v_fmac_f32_e32 v180, 0xb2a5705f, v178
	v_sub_f32_e32 v179, v179, v181
	v_add_f32_e32 v179, v179, v180
	v_cvt_i32_f32_e32 v180, v181
	v_exp_f32_e32 v179, v179
	v_cmp_nlt_f32_e32 vcc, s87, v178
	v_ldexp_f32 v179, v179, v180
	s_nop 0
	v_cndmask_b32_e32 v179, 0, v179, vcc
	v_cmp_ngt_f32_e32 vcc, s88, v178
; DI float gelu_exact(float x) { return 0.5f * x * (1.f + erff(x * 0.7071067811865476f)); }
; template <bool STORE>
; DI void peer_item(const Params& p, int item, char* smem) {
;     ...
;       const float amine = gelu_exact(h * su) * gmine * sv;
;       if ((lane & 7) == 0) {
	v_mov_b32_e32 v180, 0x7f800000
	s_nop 0
	v_cndmask_b32_e32 v179, v180, v179, vcc
	v_sub_f32_e32 v179, 1.0, v179
	v_mul_f32_e32 v180, v177, v177
	v_mov_b32_e32 v181, 0x3ba10414
	v_fmamk_f32 v181, v180, 0xba1345e1, v181
	v_fmaak_f32 v181, v180, v181, 0xbcdac9b8
	v_fmaak_f32 v181, v180, v181, 0x3de703be
	v_fmaak_f32 v181, v180, v181, 0xbec09330
	v_fmaak_f32 v181, v180, v181, 0x3e0375d0
	v_fma_f32 v181, |v177|, v181, |v177|
	v_cmp_nlt_f32_e64 vcc, |v177|, 1.0
	s_nop 1
	v_cndmask_b32_e32 v179, v181, v179, vcc
	v_bfi_b32 v179, s89, v179, v177
	v_mul_f32_e32 v176, 0.5, v176
	v_add_f32_e32 v179, 1.0, v179
	v_mul_f32_e32 v176, v176, v179
	v_mul_f32_e32 v176, v5, v176
	v_mul_f32_e32 v1, v147, v176
	ds_write_b32 v237, v0 offset:32768
	ds_write_b32 v237, v1 offset:33024
	v_pk_add_f32 v[28:29], v[28:29], v[30:31]
	v_pk_add_f32 v[22:23], v[22:23], v[24:25]
	v_mov_b32_e32 v30, 0x358637bd
	v_pk_add_f32 v[28:29], v[28:29], v[22:23]
	s_nop 0
	v_add_f32_e32 v28, v28, v29
	s_nop 0
	v_fmamk_f32 v28, v28, 0x3a800000, v30
	s_nop 0
	v_rsq_f32_e32 v28, v28
	s_nop 1
	v_mul_f32_e32 v148, v148, v28
	v_mul_f32_e32 v150, v150, v28
	v_mul_f32_e32 v176, v148, v16
	v_mul_f32_e32 v177, 0x3f3504f3, v176
	v_mov_b32_e32 v178, 0xb9c68948
	v_fma_f32 v178, |v177|, s80, v178
	v_fma_f32 v178, |v177|, v178, s81
	v_fma_f32 v178, |v177|, v178, s82
	v_fma_f32 v178, |v177|, v178, s83
	v_fma_f32 v178, |v177|, v178, s84
	v_fma_f32 v178, |v177|, v178, s85
	v_fma_f32 v178, |v177|, v178, |v177|
	v_mul_f32_e32 v179, 0xbfb8aa3b, v178
	v_fma_f32 v180, v178, s86, -v179
	v_rndne_f32_e32 v181, v179
	v_fmac_f32_e32 v180, 0xb2a5705f, v178
	v_sub_f32_e32 v179, v179, v181
	v_add_f32_e32 v179, v179, v180
	v_cvt_i32_f32_e32 v180, v181
	v_exp_f32_e32 v179, v179
	v_cmp_nlt_f32_e32 vcc, s87, v178
	v_ldexp_f32 v179, v179, v180
	s_nop 0
	v_cndmask_b32_e32 v179, 0, v179, vcc
	v_cmp_ngt_f32_e32 vcc, s88, v178
	v_mov_b32_e32 v180, 0x7f800000
	s_nop 0
	v_cndmask_b32_e32 v179, v180, v179, vcc
	v_sub_f32_e32 v179, 1.0, v179
	v_mul_f32_e32 v180, v177, v177
	v_mov_b32_e32 v181, 0x3ba10414
	v_fmamk_f32 v181, v180, 0xba1345e1, v181
	v_fmaak_f32 v181, v180, v181, 0xbcdac9b8
	v_fmaak_f32 v181, v180, v181, 0x3de703be
	v_fmaak_f32 v181, v180, v181, 0xbec09330
	v_fmaak_f32 v181, v180, v181, 0x3e0375d0
	v_fma_f32 v181, |v177|, v181, |v177|
	v_cmp_nlt_f32_e64 vcc, |v177|, 1.0
	s_nop 1
	v_cndmask_b32_e32 v179, v181, v179, vcc
	v_bfi_b32 v179, s89, v179, v177
	v_mul_f32_e32 v176, 0.5, v176
	v_add_f32_e32 v179, 1.0, v179
	v_mul_f32_e32 v176, v176, v179
	v_mul_f32_e32 v176, v20, v176
	v_mul_f32_e32 v16, v149, v176
	v_mul_f32_e32 v176, v150, v17
	v_mul_f32_e32 v177, 0x3f3504f3, v176
	v_mov_b32_e32 v178, 0xb9c68948
	v_fma_f32 v178, |v177|, s80, v178
	v_fma_f32 v178, |v177|, v178, s81
	v_fma_f32 v178, |v177|, v178, s82
	v_fma_f32 v178, |v177|, v178, s83
	v_fma_f32 v178, |v177|, v178, s84
	v_fma_f32 v178, |v177|, v178, s85
	v_fma_f32 v178, |v177|, v178, |v177|
	v_mul_f32_e32 v179, 0xbfb8aa3b, v178
	v_fma_f32 v180, v178, s86, -v179
	v_rndne_f32_e32 v181, v179
	v_fmac_f32_e32 v180, 0xb2a5705f, v178
	v_sub_f32_e32 v179, v179, v181
	v_add_f32_e32 v179, v179, v180
	v_cvt_i32_f32_e32 v180, v181
	v_exp_f32_e32 v179, v179
	v_cmp_nlt_f32_e32 vcc, s87, v178
	v_ldexp_f32 v179, v179, v180
	s_nop 0
	v_cndmask_b32_e32 v179, 0, v179, vcc
	v_cmp_ngt_f32_e32 vcc, s88, v178
	v_mov_b32_e32 v180, 0x7f800000
	s_nop 0
	v_cndmask_b32_e32 v179, v180, v179, vcc
	v_sub_f32_e32 v179, 1.0, v179
	v_mul_f32_e32 v180, v177, v177
	v_mov_b32_e32 v181, 0x3ba10414
	v_fmamk_f32 v181, v180, 0xba1345e1, v181
	v_fmaak_f32 v181, v180, v181, 0xbcdac9b8
	v_fmaak_f32 v181, v180, v181, 0x3de703be
	v_fmaak_f32 v181, v180, v181, 0xbec09330
	v_fmaak_f32 v181, v180, v181, 0x3e0375d0
	v_fma_f32 v181, |v177|, v181, |v177|
	v_cmp_nlt_f32_e64 vcc, |v177|, 1.0
	s_nop 1
	v_cndmask_b32_e32 v179, v181, v179, vcc
	v_bfi_b32 v179, s89, v179, v177
	v_mul_f32_e32 v176, 0.5, v176
	v_add_f32_e32 v179, 1.0, v179
	v_mul_f32_e32 v176, v176, v179
	v_mul_f32_e32 v176, v21, v176
	v_mul_f32_e32 v17, v151, v176
	ds_write_b32 v237, v16 offset:33280
	ds_write_b32 v237, v17 offset:33536
	v_pk_add_f32 v[44:45], v[44:45], v[46:47]
	v_pk_add_f32 v[38:39], v[38:39], v[40:41]
	v_mov_b32_e32 v46, 0x358637bd
	v_pk_add_f32 v[44:45], v[44:45], v[38:39]
	s_nop 0
	v_add_f32_e32 v44, v44, v45
	s_nop 0
	v_fmamk_f32 v44, v44, 0x3a800000, v46
	s_nop 0
	v_rsq_f32_e32 v44, v44
	s_nop 1
	v_mul_f32_e32 v152, v152, v44
	v_mul_f32_e32 v154, v154, v44
	v_mul_f32_e32 v176, v152, v32
	v_mul_f32_e32 v177, 0x3f3504f3, v176
	v_mov_b32_e32 v178, 0xb9c68948
	v_fma_f32 v178, |v177|, s80, v178
	v_fma_f32 v178, |v177|, v178, s81
	v_fma_f32 v178, |v177|, v178, s82
	v_fma_f32 v178, |v177|, v178, s83
	v_fma_f32 v178, |v177|, v178, s84
	v_fma_f32 v178, |v177|, v178, s85
	v_fma_f32 v178, |v177|, v178, |v177|
	v_mul_f32_e32 v179, 0xbfb8aa3b, v178
	v_fma_f32 v180, v178, s86, -v179
	v_rndne_f32_e32 v181, v179
	v_fmac_f32_e32 v180, 0xb2a5705f, v178
	v_sub_f32_e32 v179, v179, v181
	v_add_f32_e32 v179, v179, v180
	v_cvt_i32_f32_e32 v180, v181
	v_exp_f32_e32 v179, v179
	v_cmp_nlt_f32_e32 vcc, s87, v178
	v_ldexp_f32 v179, v179, v180
	s_nop 0
	v_cndmask_b32_e32 v179, 0, v179, vcc
	v_cmp_ngt_f32_e32 vcc, s88, v178
	v_mov_b32_e32 v180, 0x7f800000
	s_nop 0
	v_cndmask_b32_e32 v179, v180, v179, vcc
	v_sub_f32_e32 v179, 1.0, v179
	v_mul_f32_e32 v180, v177, v177
	v_mov_b32_e32 v181, 0x3ba10414
	v_fmamk_f32 v181, v180, 0xba1345e1, v181
	v_fmaak_f32 v181, v180, v181, 0xbcdac9b8
	v_fmaak_f32 v181, v180, v181, 0x3de703be
	v_fmaak_f32 v181, v180, v181, 0xbec09330
	v_fmaak_f32 v181, v180, v181, 0x3e0375d0
	v_fma_f32 v181, |v177|, v181, |v177|
; DI float gelu_exact(float x) { return 0.5f * x * (1.f + erff(x * 0.7071067811865476f)); }
; template <bool STORE>
; DI void peer_item(const Params& p, int item, char* smem) {
;     ...
;       const float amine = gelu_exact(h * su) * gmine * sv;
;       if ((lane & 7) == 0) {
	v_cmp_nlt_f32_e64 vcc, |v177|, 1.0
	s_nop 1
	v_cndmask_b32_e32 v179, v181, v179, vcc
	v_bfi_b32 v179, s89, v179, v177
	v_mul_f32_e32 v176, 0.5, v176
	v_add_f32_e32 v179, 1.0, v179
	v_mul_f32_e32 v176, v176, v179
	v_mul_f32_e32 v176, v36, v176
	v_mul_f32_e32 v32, v153, v176
	v_mul_f32_e32 v176, v154, v33
	v_mul_f32_e32 v177, 0x3f3504f3, v176
	v_mov_b32_e32 v178, 0xb9c68948
	v_fma_f32 v178, |v177|, s80, v178
	v_fma_f32 v178, |v177|, v178, s81
	v_fma_f32 v178, |v177|, v178, s82
	v_fma_f32 v178, |v177|, v178, s83
	v_fma_f32 v178, |v177|, v178, s84
	v_fma_f32 v178, |v177|, v178, s85
	v_fma_f32 v178, |v177|, v178, |v177|
	v_mul_f32_e32 v179, 0xbfb8aa3b, v178
	v_fma_f32 v180, v178, s86, -v179
	v_rndne_f32_e32 v181, v179
	v_fmac_f32_e32 v180, 0xb2a5705f, v178
	v_sub_f32_e32 v179, v179, v181
	v_add_f32_e32 v179, v179, v180
	v_cvt_i32_f32_e32 v180, v181
	v_exp_f32_e32 v179, v179
	v_cmp_nlt_f32_e32 vcc, s87, v178
	v_ldexp_f32 v179, v179, v180
	s_nop 0
	v_cndmask_b32_e32 v179, 0, v179, vcc
	v_cmp_ngt_f32_e32 vcc, s88, v178
	v_mov_b32_e32 v180, 0x7f800000
	s_nop 0
	v_cndmask_b32_e32 v179, v180, v179, vcc
	v_sub_f32_e32 v179, 1.0, v179
	v_mul_f32_e32 v180, v177, v177
	v_mov_b32_e32 v181, 0x3ba10414
	v_fmamk_f32 v181, v180, 0xba1345e1, v181
	v_fmaak_f32 v181, v180, v181, 0xbcdac9b8
	v_fmaak_f32 v181, v180, v181, 0x3de703be
	v_fmaak_f32 v181, v180, v181, 0xbec09330
	v_fmaak_f32 v181, v180, v181, 0x3e0375d0
	v_fma_f32 v181, |v177|, v181, |v177|
	v_cmp_nlt_f32_e64 vcc, |v177|, 1.0
	s_nop 1
	v_cndmask_b32_e32 v179, v181, v179, vcc
	v_bfi_b32 v179, s89, v179, v177
	v_mul_f32_e32 v176, 0.5, v176
	v_add_f32_e32 v179, 1.0, v179
	v_mul_f32_e32 v176, v176, v179
	v_mul_f32_e32 v176, v37, v176
	v_mul_f32_e32 v33, v155, v176
	ds_write_b32 v237, v32 offset:33792
	ds_write_b32 v237, v33 offset:34048
	v_pk_add_f32 v[60:61], v[60:61], v[62:63]
	v_pk_add_f32 v[54:55], v[54:55], v[56:57]
	v_mov_b32_e32 v62, 0x358637bd
	v_pk_add_f32 v[60:61], v[60:61], v[54:55]
	s_nop 0
	v_add_f32_e32 v60, v60, v61
	s_nop 0
	v_fmamk_f32 v60, v60, 0x3a800000, v62
	s_nop 0
	v_rsq_f32_e32 v60, v60
	s_nop 1
	v_mul_f32_e32 v156, v156, v60
	v_mul_f32_e32 v158, v158, v60
	v_mul_f32_e32 v176, v156, v48
	v_mul_f32_e32 v177, 0x3f3504f3, v176
	v_mov_b32_e32 v178, 0xb9c68948
	v_fma_f32 v178, |v177|, s80, v178
	v_fma_f32 v178, |v177|, v178, s81
	v_fma_f32 v178, |v177|, v178, s82
	v_fma_f32 v178, |v177|, v178, s83
	v_fma_f32 v178, |v177|, v178, s84
	v_fma_f32 v178, |v177|, v178, s85
	v_fma_f32 v178, |v177|, v178, |v177|
	v_mul_f32_e32 v179, 0xbfb8aa3b, v178
	v_fma_f32 v180, v178, s86, -v179
	v_rndne_f32_e32 v181, v179
	v_fmac_f32_e32 v180, 0xb2a5705f, v178
	v_sub_f32_e32 v179, v179, v181
	v_add_f32_e32 v179, v179, v180
	v_cvt_i32_f32_e32 v180, v181
	v_exp_f32_e32 v179, v179
	v_cmp_nlt_f32_e32 vcc, s87, v178
	v_ldexp_f32 v179, v179, v180
	s_nop 0
	v_cndmask_b32_e32 v179, 0, v179, vcc
	v_cmp_ngt_f32_e32 vcc, s88, v178
	v_mov_b32_e32 v180, 0x7f800000
	s_nop 0
	v_cndmask_b32_e32 v179, v180, v179, vcc
	v_sub_f32_e32 v179, 1.0, v179
	v_mul_f32_e32 v180, v177, v177
	v_mov_b32_e32 v181, 0x3ba10414
	v_fmamk_f32 v181, v180, 0xba1345e1, v181
	v_fmaak_f32 v181, v180, v181, 0xbcdac9b8
	v_fmaak_f32 v181, v180, v181, 0x3de703be
	v_fmaak_f32 v181, v180, v181, 0xbec09330
	v_fmaak_f32 v181, v180, v181, 0x3e0375d0
	v_fma_f32 v181, |v177|, v181, |v177|
	v_cmp_nlt_f32_e64 vcc, |v177|, 1.0
	s_nop 1
	v_cndmask_b32_e32 v179, v181, v179, vcc
	v_bfi_b32 v179, s89, v179, v177
	v_mul_f32_e32 v176, 0.5, v176
	v_add_f32_e32 v179, 1.0, v179
	v_mul_f32_e32 v176, v176, v179
	v_mul_f32_e32 v176, v52, v176
	v_mul_f32_e32 v48, v157, v176
	v_mul_f32_e32 v176, v158, v49
	v_mul_f32_e32 v177, 0x3f3504f3, v176
	v_mov_b32_e32 v178, 0xb9c68948
	v_fma_f32 v178, |v177|, s80, v178
	v_fma_f32 v178, |v177|, v178, s81
	v_fma_f32 v178, |v177|, v178, s82
	v_fma_f32 v178, |v177|, v178, s83
	v_fma_f32 v178, |v177|, v178, s84
	v_fma_f32 v178, |v177|, v178, s85
	v_fma_f32 v178, |v177|, v178, |v177|
	v_mul_f32_e32 v179, 0xbfb8aa3b, v178
	v_fma_f32 v180, v178, s86, -v179
	v_rndne_f32_e32 v181, v179
	v_fmac_f32_e32 v180, 0xb2a5705f, v178
	v_sub_f32_e32 v179, v179, v181
	v_add_f32_e32 v179, v179, v180
	v_cvt_i32_f32_e32 v180, v181
	v_exp_f32_e32 v179, v179
	v_cmp_nlt_f32_e32 vcc, s87, v178
	v_ldexp_f32 v179, v179, v180
	s_nop 0
	v_cndmask_b32_e32 v179, 0, v179, vcc
	v_cmp_ngt_f32_e32 vcc, s88, v178
	v_mov_b32_e32 v180, 0x7f800000
	s_nop 0
	v_cndmask_b32_e32 v179, v180, v179, vcc
	v_sub_f32_e32 v179, 1.0, v179
	v_mul_f32_e32 v180, v177, v177
	v_mov_b32_e32 v181, 0x3ba10414
	v_fmamk_f32 v181, v180, 0xba1345e1, v181
	v_fmaak_f32 v181, v180, v181, 0xbcdac9b8
	v_fmaak_f32 v181, v180, v181, 0x3de703be
	v_fmaak_f32 v181, v180, v181, 0xbec09330
	v_fmaak_f32 v181, v180, v181, 0x3e0375d0
	v_fma_f32 v181, |v177|, v181, |v177|
	v_cmp_nlt_f32_e64 vcc, |v177|, 1.0
	s_nop 1
	v_cndmask_b32_e32 v179, v181, v179, vcc
	v_bfi_b32 v179, s89, v179, v177
	v_mul_f32_e32 v176, 0.5, v176
	v_add_f32_e32 v179, 1.0, v179
	v_mul_f32_e32 v176, v176, v179
	v_mul_f32_e32 v176, v53, v176
	v_mul_f32_e32 v49, v159, v176
	ds_write_b32 v237, v48 offset:34304
	ds_write_b32 v237, v49 offset:34560
	v_pk_add_f32 v[76:77], v[76:77], v[78:79]
	v_pk_add_f32 v[70:71], v[70:71], v[72:73]
	v_mov_b32_e32 v78, 0x358637bd
	v_pk_add_f32 v[76:77], v[76:77], v[70:71]
	s_nop 0
	v_add_f32_e32 v76, v76, v77
	s_nop 0
	v_fmamk_f32 v76, v76, 0x3a800000, v78
	s_nop 0
	v_rsq_f32_e32 v76, v76
	s_nop 1
	v_mul_f32_e32 v160, v160, v76
	v_mul_f32_e32 v162, v162, v76
	v_mul_f32_e32 v176, v160, v64
	v_mul_f32_e32 v177, 0x3f3504f3, v176
	v_mov_b32_e32 v178, 0xb9c68948
	v_fma_f32 v178, |v177|, s80, v178
	v_fma_f32 v178, |v177|, v178, s81
; DI float gelu_exact(float x) { return 0.5f * x * (1.f + erff(x * 0.7071067811865476f)); }
; template <bool STORE>
; DI void peer_item(const Params& p, int item, char* smem) {
;     ...
;       const float amine = gelu_exact(h * su) * gmine * sv;
;       if ((lane & 7) == 0) {
	v_fma_f32 v178, |v177|, v178, s82
	v_fma_f32 v178, |v177|, v178, s83
	v_fma_f32 v178, |v177|, v178, s84
	v_fma_f32 v178, |v177|, v178, s85
	v_fma_f32 v178, |v177|, v178, |v177|
	v_mul_f32_e32 v179, 0xbfb8aa3b, v178
	v_fma_f32 v180, v178, s86, -v179
	v_rndne_f32_e32 v181, v179
	v_fmac_f32_e32 v180, 0xb2a5705f, v178
	v_sub_f32_e32 v179, v179, v181
	v_add_f32_e32 v179, v179, v180
	v_cvt_i32_f32_e32 v180, v181
	v_exp_f32_e32 v179, v179
	v_cmp_nlt_f32_e32 vcc, s87, v178
	v_ldexp_f32 v179, v179, v180
	s_nop 0
	v_cndmask_b32_e32 v179, 0, v179, vcc
	v_cmp_ngt_f32_e32 vcc, s88, v178
	v_mov_b32_e32 v180, 0x7f800000
	s_nop 0
	v_cndmask_b32_e32 v179, v180, v179, vcc
	v_sub_f32_e32 v179, 1.0, v179
	v_mul_f32_e32 v180, v177, v177
	v_mov_b32_e32 v181, 0x3ba10414
	v_fmamk_f32 v181, v180, 0xba1345e1, v181
	v_fmaak_f32 v181, v180, v181, 0xbcdac9b8
	v_fmaak_f32 v181, v180, v181, 0x3de703be
	v_fmaak_f32 v181, v180, v181, 0xbec09330
	v_fmaak_f32 v181, v180, v181, 0x3e0375d0
	v_fma_f32 v181, |v177|, v181, |v177|
	v_cmp_nlt_f32_e64 vcc, |v177|, 1.0
	s_nop 1
	v_cndmask_b32_e32 v179, v181, v179, vcc
	v_bfi_b32 v179, s89, v179, v177
	v_mul_f32_e32 v176, 0.5, v176
	v_add_f32_e32 v179, 1.0, v179
	v_mul_f32_e32 v176, v176, v179
	v_mul_f32_e32 v176, v68, v176
	v_mul_f32_e32 v64, v161, v176
	v_mul_f32_e32 v176, v162, v65
	v_mul_f32_e32 v177, 0x3f3504f3, v176
	v_mov_b32_e32 v178, 0xb9c68948
	v_fma_f32 v178, |v177|, s80, v178
	v_fma_f32 v178, |v177|, v178, s81
	v_fma_f32 v178, |v177|, v178, s82
	v_fma_f32 v178, |v177|, v178, s83
	v_fma_f32 v178, |v177|, v178, s84
	v_fma_f32 v178, |v177|, v178, s85
	v_fma_f32 v178, |v177|, v178, |v177|
	v_mul_f32_e32 v179, 0xbfb8aa3b, v178
	v_fma_f32 v180, v178, s86, -v179
	v_rndne_f32_e32 v181, v179
	v_fmac_f32_e32 v180, 0xb2a5705f, v178
	v_sub_f32_e32 v179, v179, v181
	v_add_f32_e32 v179, v179, v180
	v_cvt_i32_f32_e32 v180, v181
	v_exp_f32_e32 v179, v179
	v_cmp_nlt_f32_e32 vcc, s87, v178
	v_ldexp_f32 v179, v179, v180
	s_nop 0
	v_cndmask_b32_e32 v179, 0, v179, vcc
	v_cmp_ngt_f32_e32 vcc, s88, v178
	v_mov_b32_e32 v180, 0x7f800000
	s_nop 0
	v_cndmask_b32_e32 v179, v180, v179, vcc
	v_sub_f32_e32 v179, 1.0, v179
	v_mul_f32_e32 v180, v177, v177
	v_mov_b32_e32 v181, 0x3ba10414
	v_fmamk_f32 v181, v180, 0xba1345e1, v181
	v_fmaak_f32 v181, v180, v181, 0xbcdac9b8
	v_fmaak_f32 v181, v180, v181, 0x3de703be
	v_fmaak_f32 v181, v180, v181, 0xbec09330
	v_fmaak_f32 v181, v180, v181, 0x3e0375d0
	v_fma_f32 v181, |v177|, v181, |v177|
	v_cmp_nlt_f32_e64 vcc, |v177|, 1.0
	s_nop 1
	v_cndmask_b32_e32 v179, v181, v179, vcc
	v_bfi_b32 v179, s89, v179, v177
	v_mul_f32_e32 v176, 0.5, v176
	v_add_f32_e32 v179, 1.0, v179
	v_mul_f32_e32 v176, v176, v179
	v_mul_f32_e32 v176, v69, v176
	v_mul_f32_e32 v65, v163, v176
	ds_write_b32 v237, v64 offset:34816
	ds_write_b32 v237, v65 offset:35072
	v_pk_add_f32 v[92:93], v[92:93], v[94:95]
	v_pk_add_f32 v[86:87], v[86:87], v[88:89]
	v_mov_b32_e32 v94, 0x358637bd
	v_pk_add_f32 v[92:93], v[92:93], v[86:87]
	s_nop 0
	v_add_f32_e32 v92, v92, v93
	s_nop 0
	v_fmamk_f32 v92, v92, 0x3a800000, v94
	s_nop 0
	v_rsq_f32_e32 v92, v92
	s_nop 1
	v_mul_f32_e32 v164, v164, v92
	v_mul_f32_e32 v166, v166, v92
	v_mul_f32_e32 v176, v164, v80
	v_mul_f32_e32 v177, 0x3f3504f3, v176
	v_mov_b32_e32 v178, 0xb9c68948
	v_fma_f32 v178, |v177|, s80, v178
	v_fma_f32 v178, |v177|, v178, s81
	v_fma_f32 v178, |v177|, v178, s82
	v_fma_f32 v178, |v177|, v178, s83
	v_fma_f32 v178, |v177|, v178, s84
	v_fma_f32 v178, |v177|, v178, s85
	v_fma_f32 v178, |v177|, v178, |v177|
	v_mul_f32_e32 v179, 0xbfb8aa3b, v178
	v_fma_f32 v180, v178, s86, -v179
	v_rndne_f32_e32 v181, v179
	v_fmac_f32_e32 v180, 0xb2a5705f, v178
	v_sub_f32_e32 v179, v179, v181
	v_add_f32_e32 v179, v179, v180
	v_cvt_i32_f32_e32 v180, v181
	v_exp_f32_e32 v179, v179
	v_cmp_nlt_f32_e32 vcc, s87, v178
	v_ldexp_f32 v179, v179, v180
	s_nop 0
	v_cndmask_b32_e32 v179, 0, v179, vcc
	v_cmp_ngt_f32_e32 vcc, s88, v178
	v_mov_b32_e32 v180, 0x7f800000
	s_nop 0
	v_cndmask_b32_e32 v179, v180, v179, vcc
	v_sub_f32_e32 v179, 1.0, v179
	v_mul_f32_e32 v180, v177, v177
	v_mov_b32_e32 v181, 0x3ba10414
	v_fmamk_f32 v181, v180, 0xba1345e1, v181
	v_fmaak_f32 v181, v180, v181, 0xbcdac9b8
	v_fmaak_f32 v181, v180, v181, 0x3de703be
	v_fmaak_f32 v181, v180, v181, 0xbec09330
	v_fmaak_f32 v181, v180, v181, 0x3e0375d0
	v_fma_f32 v181, |v177|, v181, |v177|
	v_cmp_nlt_f32_e64 vcc, |v177|, 1.0
	s_nop 1
	v_cndmask_b32_e32 v179, v181, v179, vcc
	v_bfi_b32 v179, s89, v179, v177
	v_mul_f32_e32 v176, 0.5, v176
	v_add_f32_e32 v179, 1.0, v179
	v_mul_f32_e32 v176, v176, v179
	v_mul_f32_e32 v176, v84, v176
	v_mul_f32_e32 v80, v165, v176
	v_mul_f32_e32 v176, v166, v81
	v_mul_f32_e32 v177, 0x3f3504f3, v176
	v_mov_b32_e32 v178, 0xb9c68948
	v_fma_f32 v178, |v177|, s80, v178
	v_fma_f32 v178, |v177|, v178, s81
	v_fma_f32 v178, |v177|, v178, s82
	v_fma_f32 v178, |v177|, v178, s83
	v_fma_f32 v178, |v177|, v178, s84
	v_fma_f32 v178, |v177|, v178, s85
	v_fma_f32 v178, |v177|, v178, |v177|
	v_mul_f32_e32 v179, 0xbfb8aa3b, v178
	v_fma_f32 v180, v178, s86, -v179
	v_rndne_f32_e32 v181, v179
	v_fmac_f32_e32 v180, 0xb2a5705f, v178
	v_sub_f32_e32 v179, v179, v181
	v_add_f32_e32 v179, v179, v180
	v_cvt_i32_f32_e32 v180, v181
	v_exp_f32_e32 v179, v179
	v_cmp_nlt_f32_e32 vcc, s87, v178
	v_ldexp_f32 v179, v179, v180
	s_nop 0
	v_cndmask_b32_e32 v179, 0, v179, vcc
	v_cmp_ngt_f32_e32 vcc, s88, v178
	v_mov_b32_e32 v180, 0x7f800000
	s_nop 0
	v_cndmask_b32_e32 v179, v180, v179, vcc
	v_sub_f32_e32 v179, 1.0, v179
	v_mul_f32_e32 v180, v177, v177
	v_mov_b32_e32 v181, 0x3ba10414
	v_fmamk_f32 v181, v180, 0xba1345e1, v181
	v_fmaak_f32 v181, v180, v181, 0xbcdac9b8
; DI float gelu_exact(float x) { return 0.5f * x * (1.f + erff(x * 0.7071067811865476f)); }
; template <bool STORE>
; DI void peer_item(const Params& p, int item, char* smem) {
;     ...
;       const float amine = gelu_exact(h * su) * gmine * sv;
;       if ((lane & 7) == 0) {
	v_fmaak_f32 v181, v180, v181, 0x3de703be
	v_fmaak_f32 v181, v180, v181, 0xbec09330
	v_fmaak_f32 v181, v180, v181, 0x3e0375d0
	v_fma_f32 v181, |v177|, v181, |v177|
	v_cmp_nlt_f32_e64 vcc, |v177|, 1.0
	s_nop 1
	v_cndmask_b32_e32 v179, v181, v179, vcc
	v_bfi_b32 v179, s89, v179, v177
	v_mul_f32_e32 v176, 0.5, v176
	v_add_f32_e32 v179, 1.0, v179
	v_mul_f32_e32 v176, v176, v179
	v_mul_f32_e32 v176, v85, v176
	v_mul_f32_e32 v81, v167, v176
	ds_write_b32 v237, v80 offset:35328
	ds_write_b32 v237, v81 offset:35584
	v_pk_add_f32 v[108:109], v[108:109], v[110:111]
	v_pk_add_f32 v[102:103], v[102:103], v[104:105]
	v_mov_b32_e32 v110, 0x358637bd
	v_pk_add_f32 v[108:109], v[108:109], v[102:103]
	s_nop 0
	v_add_f32_e32 v108, v108, v109
	s_nop 0
	v_fmamk_f32 v108, v108, 0x3a800000, v110
	s_nop 0
	v_rsq_f32_e32 v108, v108
	s_nop 1
	v_mul_f32_e32 v168, v168, v108
	v_mul_f32_e32 v170, v170, v108
	v_mul_f32_e32 v176, v168, v96
	v_mul_f32_e32 v177, 0x3f3504f3, v176
	v_mov_b32_e32 v178, 0xb9c68948
	v_fma_f32 v178, |v177|, s80, v178
	v_fma_f32 v178, |v177|, v178, s81
	v_fma_f32 v178, |v177|, v178, s82
	v_fma_f32 v178, |v177|, v178, s83
	v_fma_f32 v178, |v177|, v178, s84
	v_fma_f32 v178, |v177|, v178, s85
	v_fma_f32 v178, |v177|, v178, |v177|
	v_mul_f32_e32 v179, 0xbfb8aa3b, v178
	v_fma_f32 v180, v178, s86, -v179
	v_rndne_f32_e32 v181, v179
	v_fmac_f32_e32 v180, 0xb2a5705f, v178
	v_sub_f32_e32 v179, v179, v181
	v_add_f32_e32 v179, v179, v180
	v_cvt_i32_f32_e32 v180, v181
	v_exp_f32_e32 v179, v179
	v_cmp_nlt_f32_e32 vcc, s87, v178
	v_ldexp_f32 v179, v179, v180
	s_nop 0
	v_cndmask_b32_e32 v179, 0, v179, vcc
	v_cmp_ngt_f32_e32 vcc, s88, v178
	v_mov_b32_e32 v180, 0x7f800000
	s_nop 0
	v_cndmask_b32_e32 v179, v180, v179, vcc
	v_sub_f32_e32 v179, 1.0, v179
	v_mul_f32_e32 v180, v177, v177
	v_mov_b32_e32 v181, 0x3ba10414
	v_fmamk_f32 v181, v180, 0xba1345e1, v181
	v_fmaak_f32 v181, v180, v181, 0xbcdac9b8
	v_fmaak_f32 v181, v180, v181, 0x3de703be
	v_fmaak_f32 v181, v180, v181, 0xbec09330
	v_fmaak_f32 v181, v180, v181, 0x3e0375d0
	v_fma_f32 v181, |v177|, v181, |v177|
	v_cmp_nlt_f32_e64 vcc, |v177|, 1.0
	s_nop 1
	v_cndmask_b32_e32 v179, v181, v179, vcc
	v_bfi_b32 v179, s89, v179, v177
	v_mul_f32_e32 v176, 0.5, v176
	v_add_f32_e32 v179, 1.0, v179
	v_mul_f32_e32 v176, v176, v179
	v_mul_f32_e32 v176, v100, v176
	v_mul_f32_e32 v96, v169, v176
	v_mul_f32_e32 v176, v170, v97
	v_mul_f32_e32 v177, 0x3f3504f3, v176
	v_mov_b32_e32 v178, 0xb9c68948
	v_fma_f32 v178, |v177|, s80, v178
	v_fma_f32 v178, |v177|, v178, s81
	v_fma_f32 v178, |v177|, v178, s82
	v_fma_f32 v178, |v177|, v178, s83
	v_fma_f32 v178, |v177|, v178, s84
	v_fma_f32 v178, |v177|, v178, s85
	v_fma_f32 v178, |v177|, v178, |v177|
	v_mul_f32_e32 v179, 0xbfb8aa3b, v178
	v_fma_f32 v180, v178, s86, -v179
	v_rndne_f32_e32 v181, v179
	v_fmac_f32_e32 v180, 0xb2a5705f, v178
	v_sub_f32_e32 v179, v179, v181
	v_add_f32_e32 v179, v179, v180
	v_cvt_i32_f32_e32 v180, v181
	v_exp_f32_e32 v179, v179
	v_cmp_nlt_f32_e32 vcc, s87, v178
	v_ldexp_f32 v179, v179, v180
	s_nop 0
	v_cndmask_b32_e32 v179, 0, v179, vcc
	v_cmp_ngt_f32_e32 vcc, s88, v178
	v_mov_b32_e32 v180, 0x7f800000
	s_nop 0
	v_cndmask_b32_e32 v179, v180, v179, vcc
	v_sub_f32_e32 v179, 1.0, v179
	v_mul_f32_e32 v180, v177, v177
	v_mov_b32_e32 v181, 0x3ba10414
	v_fmamk_f32 v181, v180, 0xba1345e1, v181
	v_fmaak_f32 v181, v180, v181, 0xbcdac9b8
	v_fmaak_f32 v181, v180, v181, 0x3de703be
	v_fmaak_f32 v181, v180, v181, 0xbec09330
	v_fmaak_f32 v181, v180, v181, 0x3e0375d0
	v_fma_f32 v181, |v177|, v181, |v177|
	v_cmp_nlt_f32_e64 vcc, |v177|, 1.0
	s_nop 1
	v_cndmask_b32_e32 v179, v181, v179, vcc
	v_bfi_b32 v179, s89, v179, v177
	v_mul_f32_e32 v176, 0.5, v176
	v_add_f32_e32 v179, 1.0, v179
	v_mul_f32_e32 v176, v176, v179
	v_mul_f32_e32 v176, v101, v176
	v_mul_f32_e32 v97, v171, v176
	ds_write_b32 v237, v96 offset:35840
	ds_write_b32 v237, v97 offset:36096
	v_pk_add_f32 v[124:125], v[124:125], v[126:127]
	v_pk_add_f32 v[118:119], v[118:119], v[120:121]
	v_mov_b32_e32 v126, 0x358637bd
	v_pk_add_f32 v[124:125], v[124:125], v[118:119]
	s_nop 0
	v_add_f32_e32 v124, v124, v125
	s_nop 0
	v_fmamk_f32 v124, v124, 0x3a800000, v126
	s_nop 0
	v_rsq_f32_e32 v124, v124
	s_nop 1
	v_mul_f32_e32 v172, v172, v124
	v_mul_f32_e32 v174, v174, v124
	v_mul_f32_e32 v176, v172, v112
	v_mul_f32_e32 v177, 0x3f3504f3, v176
	v_mov_b32_e32 v178, 0xb9c68948
	v_fma_f32 v178, |v177|, s80, v178
	v_fma_f32 v178, |v177|, v178, s81
	v_fma_f32 v178, |v177|, v178, s82
	v_fma_f32 v178, |v177|, v178, s83
	v_fma_f32 v178, |v177|, v178, s84
	v_fma_f32 v178, |v177|, v178, s85
	v_fma_f32 v178, |v177|, v178, |v177|
	v_mul_f32_e32 v179, 0xbfb8aa3b, v178
	v_fma_f32 v180, v178, s86, -v179
	v_rndne_f32_e32 v181, v179
	v_fmac_f32_e32 v180, 0xb2a5705f, v178
	v_sub_f32_e32 v179, v179, v181
	v_add_f32_e32 v179, v179, v180
	v_cvt_i32_f32_e32 v180, v181
	v_exp_f32_e32 v179, v179
	v_cmp_nlt_f32_e32 vcc, s87, v178
	v_ldexp_f32 v179, v179, v180
; DI void hsync() { hsync_impl(false); }
; DI float gelu_exact(float x) { return 0.5f * x * (1.f + erff(x * 0.7071067811865476f)); }
; template <bool STORE>
; DI void peer_item(const Params& p, int item, char* smem) {
;     ...
;       const float amine = gelu_exact(h * su) * gmine * sv;
;       if ((lane & 7) == 0) {
;         EG[tok * 128 + k + (lane >> 3)] = emine;
;         AG[tok * 128 + k + (lane >> 3)] = amine;
;       }
;     }
;   }
;   hsync();
	s_nop 0
	v_cndmask_b32_e32 v179, 0, v179, vcc
	v_cmp_ngt_f32_e32 vcc, s88, v178
	v_mov_b32_e32 v180, 0x7f800000
	s_nop 0
	v_cndmask_b32_e32 v179, v180, v179, vcc
	v_sub_f32_e32 v179, 1.0, v179
	v_mul_f32_e32 v180, v177, v177
	v_mov_b32_e32 v181, 0x3ba10414
	v_fmamk_f32 v181, v180, 0xba1345e1, v181
	v_fmaak_f32 v181, v180, v181, 0xbcdac9b8
	v_fmaak_f32 v181, v180, v181, 0x3de703be
	v_fmaak_f32 v181, v180, v181, 0xbec09330
	v_fmaak_f32 v181, v180, v181, 0x3e0375d0
	v_fma_f32 v181, |v177|, v181, |v177|
	v_cmp_nlt_f32_e64 vcc, |v177|, 1.0
	s_nop 1
	v_cndmask_b32_e32 v179, v181, v179, vcc
	v_bfi_b32 v179, s89, v179, v177
	v_mul_f32_e32 v176, 0.5, v176
	v_add_f32_e32 v179, 1.0, v179
	v_mul_f32_e32 v176, v176, v179
	v_mul_f32_e32 v176, v116, v176
	v_mul_f32_e32 v112, v173, v176
	v_mul_f32_e32 v176, v174, v113
	v_mul_f32_e32 v177, 0x3f3504f3, v176
	v_mov_b32_e32 v178, 0xb9c68948
	v_fma_f32 v178, |v177|, s80, v178
	v_fma_f32 v178, |v177|, v178, s81
	v_fma_f32 v178, |v177|, v178, s82
	v_fma_f32 v178, |v177|, v178, s83
	v_fma_f32 v178, |v177|, v178, s84
	v_fma_f32 v178, |v177|, v178, s85
	v_fma_f32 v178, |v177|, v178, |v177|
	v_mul_f32_e32 v179, 0xbfb8aa3b, v178
	v_fma_f32 v180, v178, s86, -v179
	v_rndne_f32_e32 v181, v179
	v_fmac_f32_e32 v180, 0xb2a5705f, v178
	v_sub_f32_e32 v179, v179, v181
	v_add_f32_e32 v179, v179, v180
	v_cvt_i32_f32_e32 v180, v181
	v_exp_f32_e32 v179, v179
	v_cmp_nlt_f32_e32 vcc, s87, v178
	v_ldexp_f32 v179, v179, v180
	s_nop 0
	v_cndmask_b32_e32 v179, 0, v179, vcc
	v_cmp_ngt_f32_e32 vcc, s88, v178
	v_mov_b32_e32 v180, 0x7f800000
	s_nop 0
	v_cndmask_b32_e32 v179, v180, v179, vcc
	v_sub_f32_e32 v179, 1.0, v179
	v_mul_f32_e32 v180, v177, v177
	v_mov_b32_e32 v181, 0x3ba10414
	v_fmamk_f32 v181, v180, 0xba1345e1, v181
	v_fmaak_f32 v181, v180, v181, 0xbcdac9b8
	v_fmaak_f32 v181, v180, v181, 0x3de703be
	v_fmaak_f32 v181, v180, v181, 0xbec09330
	v_fmaak_f32 v181, v180, v181, 0x3e0375d0
	v_fma_f32 v181, |v177|, v181, |v177|
	v_cmp_nlt_f32_e64 vcc, |v177|, 1.0
	s_nop 1
	v_cndmask_b32_e32 v179, v181, v179, vcc
	v_bfi_b32 v179, s89, v179, v177
	v_mul_f32_e32 v176, 0.5, v176
	v_add_f32_e32 v179, 1.0, v179
	v_mul_f32_e32 v176, v176, v179
	v_mul_f32_e32 v176, v117, v176
	v_mul_f32_e32 v113, v175, v176
	ds_write_b32 v237, v112 offset:36352
	ds_write_b32 v237, v113 offset:36608
	ds_read_b32 v3, v236 offset:512
	ds_read_b32 v53, v236 offset:768
	ds_read_b32 v64, v236 offset:1024
	ds_read_b32 v65, v236 offset:1280
	ds_read_b32 v66, v236 offset:1536
	ds_read_b32 v67, v236 offset:1792
	ds_read_b32 v68, v236 offset:2048
	ds_read_b32 v69, v236 offset:2304
	ds_read_b32 v70, v236 offset:2560
	ds_read_b32 v71, v236 offset:2816
	ds_read_b32 v72, v236 offset:3072
	ds_read_b32 v73, v236 offset:3328
	ds_read_b32 v74, v236 offset:3584
	ds_read_b32 v75, v236 offset:3840
	ds_read_b32 v76, v236 offset:4096
	ds_read_b32 v77, v236 offset:4352
	ds_read_b32 v78, v236 offset:4608
	ds_read_b32 v79, v236 offset:4864
	ds_read_b32 v80, v236 offset:5120
	ds_read_b32 v81, v236 offset:5376
	ds_read_b32 v82, v236 offset:5632
	ds_read_b32 v83, v236 offset:5888
	ds_read_b32 v96, v236 offset:6144
	ds_read_b32 v210, v236 offset:6400
	ds_read_b32 v211, v236 offset:6656
	ds_read_b32 v212, v236 offset:6912
	v_readlane_b32 s6, v254, 0
	v_readlane_b32 s7, v254, 1
	v_readlane_b32 s12, v254, 2
	v_readlane_b32 s13, v254, 3
	v_readlane_b32 s14, v254, 4
	v_readlane_b32 s15, v254, 5
	v_readlane_b32 s16, v254, 6
	v_readlane_b32 s17, v254, 7
	v_readlane_b32 s18, v254, 8
	v_readlane_b32 s19, v254, 9
	v_readlane_b32 s20, v254, 10
	v_readlane_b32 s21, v254, 11
	v_readlane_b32 s22, v254, 12
	v_readlane_b32 s23, v254, 13
	v_readlane_b32 s24, v254, 14
	v_readlane_b32 s25, v254, 15
	v_readlane_b32 s26, v254, 16
	v_readlane_b32 s27, v254, 17
	v_readlane_b32 s28, v254, 18
	v_readlane_b32 s29, v254, 19
	v_readlane_b32 s30, v254, 20
	v_readlane_b32 s31, v254, 21
	v_readlane_b32 s33, v254, 22
	v_readlane_b32 s34, v254, 23
	v_readlane_b32 s35, v254, 24
	v_readlane_b32 s36, v254, 25
	v_readlane_b32 s37, v254, 26
	v_readlane_b32 s38, v254, 27
	v_readlane_b32 s39, v254, 28
	v_readlane_b32 s40, v254, 29
	v_readlane_b32 s41, v254, 30
	v_readlane_b32 s42, v254, 31
	v_readlane_b32 s44, v254, 32
	v_readlane_b32 s45, v254, 33
	v_readlane_b32 s48, v254, 34
	v_readlane_b32 s49, v254, 35
	v_readlane_b32 s50, v254, 36
	v_readlane_b32 s51, v254, 37
	v_readlane_b32 s52, v254, 38
	v_readlane_b32 s53, v254, 39
	v_readlane_b32 s55, v254, 40
	v_readlane_b32 s60, v254, 41
	v_readlane_b32 s61, v254, 42
	v_readlane_b32 s62, v254, 43
	v_readlane_b32 s63, v254, 44
	v_readlane_b32 s66, v254, 45
	v_readlane_b32 s67, v254, 46
	v_readlane_b32 s68, v254, 47
	v_readlane_b32 s69, v254, 48
	v_readlane_b32 s74, v254, 49
	v_readlane_b32 s75, v254, 50
	v_readlane_b32 s76, v254, 51
	v_readlane_b32 s77, v254, 52
	v_readlane_b32 s78, v254, 53
	v_readlane_b32 s79, v254, 54
	v_readlane_b32 s88, v254, 55
	s_waitcnt lgkmcnt(0)
	s_nop 3
